# non-nt SwiGLU epilogue stores (phases 1,8); MFMA blocks 8-byte aligned by deleting duplicate lgkmcnt(0)
# speedup vs baseline: 1.0096x; 1.0096x over previous
; #define PG8_STAGE(bufoff, gbase, voff) do { _Pragma("unroll") for (int _i = 0; _i < 2; ++_i) \
;         __builtin_amdgcn_global_load_lds((const unsigned*)((const char*)(gbase) + (voff)[_i]), (LAS unsigned*)(lds + (bufoff) + ldsw + _i * 8192), 16, 0, 0); } while (0)
; #define PG8_LDA(dst, b, h) do { _Pragma("unroll") for (int m = 0; m < 4; ++m) _Pragma("unroll") for (int k = 0; k < 2; ++k) dst[m][k] = *(const LAS bf16x8*)(lds + PG8_SA(b, h) + aoff + m * 2048 + k * 1024); } while (0)
; #define PG8_LDB(dst, b, h) do { _Pragma("unroll") for (int n = 0; n < 2; ++n) _Pragma("unroll") for (int k = 0; k < 2; ++k) dst[n][k] = *(const LAS bf16x8*)(lds + PG8_SB(b, h) + boff + n * 2048 + k * 1024); } while (0)
; #define PG8_MMA(ai, bj, At, Bt) do { __builtin_amdgcn_s_setprio(1); _Pragma("unroll") for (int m = 0; m < 4; ++m) _Pragma("unroll") for (int n = 0; n < 2; ++n) _Pragma("unroll") for (int k = 0; k < 2; ++k) \
;         acc[ai][bj][m][n] = __builtin_amdgcn_mfma_f32_16x16x32_bf16(Bt[n][k], At[m][k], acc[ai][bj][m][n], 0, 0, 0); __builtin_amdgcn_s_setprio(0); } while (0)
; #define PG8_WAIT_V(n) asm volatile("s_waitcnt vmcnt(" #n ")" ::: "memory")
; #define PG8_WAIT_L(n) asm volatile("s_waitcnt lgkmcnt(" #n ")" ::: "memory")
; #define PG8_BAR __builtin_amdgcn_s_barrier()
; #define PG8_SCHED __builtin_amdgcn_sched_barrier(0)
; template <class Epi>
; __device__ __forceinline__ void gemm_phase(LAS unsigned char* lds, const GSched& S, const int K, const int lda, const int ldb, const Epi& E) {
;     ...
;             PG8_LDB(B0, 0, 0); PG8_SCHED; PG8_LDA(At, 0, 0); PG8_STAGE(PG8_SA(1, 1), a1 + hstepA, voffA);
;             PG8_WAIT_L(8); PG8_BAR; PG8_WAIT_L(0); PG8_MMA(0, 0, At, B0); PG8_BAR; PG8_SCHED;
;             if constexpr (!Epi::NARROW) PG8_LDB(B1, 0, 1); PG8_STAGE(PG8_SB(0, 0), b2, voffB);
;             PG8_BAR; PG8_WAIT_L(0); if constexpr (!Epi::NARROW) PG8_MMA(0, 1, At, B1); PG8_BAR;
;             PG8_LDA(At, 0, 1); PG8_STAGE(PG8_SA(0, 0), a2, voffA);
;             PG8_BAR; PG8_WAIT_L(0); PG8_MMA(1, 0, At, B0); PG8_BAR; PG8_SCHED;
;             PG8_STAGE(PG8_SB(0, 1), b2 + hstepB, voffB);
;             PG8_WAIT_V(6); PG8_BAR; if constexpr (!Epi::NARROW) PG8_MMA(1, 1, At, B1); PG8_BAR;
.LBB0_262:
	ds_read_b128 v[164:167], v152
	ds_read_b128 v[168:171], v152 offset:1024
	ds_read_b128 v[172:175], v152 offset:2048
	ds_read_b128 v[176:179], v152 offset:3072
	s_add_u32 s28, s26, 0x100
	s_addc_u32 s29, s27, 0
	s_cmp_eq_u32 s61, 28
	s_cselect_b32 s35, s25, s29
	s_cselect_b32 s34, s24, s28
	s_cselect_b32 s31, s7, s60
	s_cselect_b32 s30, s6, s59
	v_lshl_add_u64 v[212:213], s[26:27], 0, v[140:141]
	s_add_i32 m0, s44, 0xc000
	ds_read_b128 v[180:183], v153
	ds_read_b128 v[184:187], v153 offset:1024
	ds_read_b128 v[188:191], v153 offset:2048
	ds_read_b128 v[192:195], v153 offset:3072
	ds_read_b128 v[196:199], v153 offset:4096
	ds_read_b128 v[200:203], v153 offset:5120
	ds_read_b128 v[204:207], v153 offset:6144
	ds_read_b128 v[208:211], v153 offset:7168
	global_load_lds_dwordx4 v[212:213], off
	v_lshl_add_u64 v[212:213], s[26:27], 0, v[138:139]
	s_add_i32 m0, s44, 0xe000
	s_nop 0
	global_load_lds_dwordx4 v[212:213], off
	s_waitcnt lgkmcnt(8)
	s_barrier
	s_waitcnt lgkmcnt(0)
	s_setprio 1
	s_waitcnt lgkmcnt(0)
	v_mfma_f32_16x16x32_bf16 v[124:127], v[164:167], v[180:183], v[124:127]
	v_mfma_f32_16x16x32_bf16 v[116:119], v[172:175], v[180:183], v[116:119]
	v_mfma_f32_16x16x32_bf16 v[108:111], v[164:167], v[188:191], v[108:111]
	v_mfma_f32_16x16x32_bf16 v[100:103], v[172:175], v[188:191], v[100:103]
	v_mfma_f32_16x16x32_bf16 v[92:95], v[164:167], v[196:199], v[92:95]
	v_mfma_f32_16x16x32_bf16 v[84:87], v[172:175], v[196:199], v[84:87]
	v_mfma_f32_16x16x32_bf16 v[76:79], v[164:167], v[204:207], v[76:79]
	v_mfma_f32_16x16x32_bf16 v[68:71], v[172:175], v[204:207], v[68:71]
	v_mfma_f32_16x16x32_bf16 v[124:127], v[168:171], v[184:187], v[124:127]
	v_mfma_f32_16x16x32_bf16 v[116:119], v[176:179], v[184:187], v[116:119]
	v_mfma_f32_16x16x32_bf16 v[108:111], v[168:171], v[192:195], v[108:111]
	v_mfma_f32_16x16x32_bf16 v[100:103], v[176:179], v[192:195], v[100:103]
	v_mfma_f32_16x16x32_bf16 v[92:95], v[168:171], v[200:203], v[92:95]
	v_mfma_f32_16x16x32_bf16 v[84:87], v[176:179], v[200:203], v[84:87]
	v_mfma_f32_16x16x32_bf16 v[76:79], v[168:171], v[208:211], v[76:79]
	v_mfma_f32_16x16x32_bf16 v[68:71], v[176:179], v[208:211], v[68:71]
	s_setprio 0
	s_barrier
	s_add_i32 s3, s53, s41
	v_lshl_add_u64 v[228:229], s[30:31], 0, v[132:133]
	s_mov_b32 m0, s3
	ds_read_b128 v[212:215], v154
	ds_read_b128 v[216:219], v154 offset:1024
	ds_read_b128 v[220:223], v154 offset:2048
	ds_read_b128 v[224:227], v154 offset:3072
	global_load_lds_dwordx4 v[228:229], off
	v_lshl_add_u64 v[230:231], s[30:31], 0, v[128:129]
	s_add_i32 m0, s3, 0x2000
	s_nop 0
	global_load_lds_dwordx4 v[230:231], off
	s_barrier
	s_waitcnt lgkmcnt(0)
	s_setprio 1
	v_mfma_f32_16x16x32_bf16 v[120:123], v[212:215], v[180:183], v[120:123]
	v_mfma_f32_16x16x32_bf16 v[112:115], v[220:223], v[180:183], v[112:115]
	v_mfma_f32_16x16x32_bf16 v[104:107], v[212:215], v[188:191], v[104:107]
	v_mfma_f32_16x16x32_bf16 v[96:99], v[220:223], v[188:191], v[96:99]
	v_mfma_f32_16x16x32_bf16 v[88:91], v[212:215], v[196:199], v[88:91]
	v_mfma_f32_16x16x32_bf16 v[80:83], v[220:223], v[196:199], v[80:83]
	v_mfma_f32_16x16x32_bf16 v[72:75], v[212:215], v[204:207], v[72:75]
	v_mfma_f32_16x16x32_bf16 v[64:67], v[220:223], v[204:207], v[64:67]
	v_mfma_f32_16x16x32_bf16 v[120:123], v[216:219], v[184:187], v[120:123]
	v_mfma_f32_16x16x32_bf16 v[112:115], v[224:227], v[184:187], v[112:115]
	v_mfma_f32_16x16x32_bf16 v[104:107], v[216:219], v[192:195], v[104:107]
	v_mfma_f32_16x16x32_bf16 v[96:99], v[224:227], v[192:195], v[96:99]
	v_mfma_f32_16x16x32_bf16 v[88:91], v[216:219], v[200:203], v[88:91]
	v_mfma_f32_16x16x32_bf16 v[80:83], v[224:227], v[200:203], v[80:83]
	v_mfma_f32_16x16x32_bf16 v[72:75], v[216:219], v[208:211], v[72:75]
	v_mfma_f32_16x16x32_bf16 v[64:67], v[224:227], v[208:211], v[64:67]
	s_setprio 0
	s_mov_b32 m0, s44
	v_lshl_add_u64 v[234:235], s[34:35], 0, v[134:135]
	s_barrier
	ds_read_b128 v[180:183], v153 offset:16384
	ds_read_b128 v[184:187], v153 offset:17408
	ds_read_b128 v[188:191], v153 offset:18432
	ds_read_b128 v[192:195], v153 offset:19456
	ds_read_b128 v[196:199], v153 offset:20480
	ds_read_b128 v[200:203], v153 offset:21504
	ds_read_b128 v[204:207], v153 offset:22528
	ds_read_b128 v[208:211], v153 offset:23552
	global_load_lds_dwordx4 v[234:235], off
	v_lshl_add_u64 v[236:237], s[34:35], 0, v[130:131]
	s_mov_b32 m0, s45
	s_nop 0
	global_load_lds_dwordx4 v[236:237], off
	s_barrier
	s_waitcnt lgkmcnt(0)
	s_setprio 1
	v_mfma_f32_16x16x32_bf16 v[60:63], v[164:167], v[180:183], v[60:63]
	v_mfma_f32_16x16x32_bf16 v[52:55], v[172:175], v[180:183], v[52:55]
	v_mfma_f32_16x16x32_bf16 v[44:47], v[164:167], v[188:191], v[44:47]
	v_mfma_f32_16x16x32_bf16 v[36:39], v[172:175], v[188:191], v[36:39]
	v_mfma_f32_16x16x32_bf16 v[28:31], v[164:167], v[196:199], v[28:31]
	v_mfma_f32_16x16x32_bf16 v[20:23], v[172:175], v[196:199], v[20:23]
	v_mfma_f32_16x16x32_bf16 v[12:15], v[164:167], v[204:207], v[12:15]
	v_mfma_f32_16x16x32_bf16 v[4:7], v[172:175], v[204:207], v[4:7]
	v_mfma_f32_16x16x32_bf16 v[60:63], v[168:171], v[184:187], v[60:63]
	v_mfma_f32_16x16x32_bf16 v[52:55], v[176:179], v[184:187], v[52:55]
	v_mfma_f32_16x16x32_bf16 v[44:47], v[168:171], v[192:195], v[44:47]
	v_mfma_f32_16x16x32_bf16 v[36:39], v[176:179], v[192:195], v[36:39]
	v_mfma_f32_16x16x32_bf16 v[28:31], v[168:171], v[200:203], v[28:31]
	v_mfma_f32_16x16x32_bf16 v[20:23], v[176:179], v[200:203], v[20:23]
	v_mfma_f32_16x16x32_bf16 v[12:15], v[168:171], v[208:211], v[12:15]
	v_mfma_f32_16x16x32_bf16 v[4:7], v[176:179], v[208:211], v[4:7]
	s_setprio 0
	s_barrier
; #define PG8_STAGE(bufoff, gbase, voff) do { _Pragma("unroll") for (int _i = 0; _i < 2; ++_i) \
;         __builtin_amdgcn_global_load_lds((const unsigned*)((const char*)(gbase) + (voff)[_i]), (LAS unsigned*)(lds + (bufoff) + ldsw + _i * 8192), 16, 0, 0); } while (0)
; #define PG8_LDA(dst, b, h) do { _Pragma("unroll") for (int m = 0; m < 4; ++m) _Pragma("unroll") for (int k = 0; k < 2; ++k) dst[m][k] = *(const LAS bf16x8*)(lds + PG8_SA(b, h) + aoff + m * 2048 + k * 1024); } while (0)
; #define PG8_LDB(dst, b, h) do { _Pragma("unroll") for (int n = 0; n < 2; ++n) _Pragma("unroll") for (int k = 0; k < 2; ++k) dst[n][k] = *(const LAS bf16x8*)(lds + PG8_SB(b, h) + boff + n * 2048 + k * 1024); } while (0)
; #define PG8_MMA(ai, bj, At, Bt) do { __builtin_amdgcn_s_setprio(1); _Pragma("unroll") for (int m = 0; m < 4; ++m) _Pragma("unroll") for (int n = 0; n < 2; ++n) _Pragma("unroll") for (int k = 0; k < 2; ++k) \
;         acc[ai][bj][m][n] = __builtin_amdgcn_mfma_f32_16x16x32_bf16(Bt[n][k], At[m][k], acc[ai][bj][m][n], 0, 0, 0); __builtin_amdgcn_s_setprio(0); } while (0)
; #define PG8_WAIT_V(n) asm volatile("s_waitcnt vmcnt(" #n ")" ::: "memory")
; #define PG8_WAIT_L(n) asm volatile("s_waitcnt lgkmcnt(" #n ")" ::: "memory")
; #define PG8_BAR __builtin_amdgcn_s_barrier()
; #define PG8_SCHED __builtin_amdgcn_sched_barrier(0)
; template <class Epi>
; __device__ __forceinline__ void gemm_phase(LAS unsigned char* lds, const GSched& S, const int K, const int lda, const int ldb, const Epi& E) {
;     ...
;             PG8_STAGE(PG8_SB(0, 1), b2 + hstepB, voffB);
;             PG8_WAIT_V(6); PG8_BAR; if constexpr (!Epi::NARROW) PG8_MMA(1, 1, At, B1); PG8_BAR;
;             PG8_LDB(B0, 1, 0); PG8_SCHED; PG8_LDA(At, 1, 0); PG8_STAGE(PG8_SA(0, 1), a2 + hstepA, voffA);
;             PG8_WAIT_L(8); PG8_BAR; PG8_WAIT_L(0); PG8_MMA(0, 0, At, B0); PG8_BAR; PG8_SCHED;
;             if constexpr (!Epi::NARROW) PG8_LDB(B1, 1, 1); PG8_STAGE(PG8_SB(1, 0), b3, voffB);
;             PG8_BAR; PG8_WAIT_L(0); if constexpr (!Epi::NARROW) PG8_MMA(0, 1, At, B1); PG8_BAR;
;             PG8_LDA(At, 1, 1); PG8_STAGE(PG8_SA(1, 0), a3, voffA);
;             PG8_BAR; PG8_WAIT_L(0); PG8_MMA(1, 0, At, B0); PG8_BAR; PG8_SCHED;
	s_add_u32 s26, s30, 0x84000
	s_addc_u32 s27, s31, 0
	s_add_i32 s3, s54, s41
	v_lshl_add_u64 v[164:165], s[26:27], 0, v[132:133]
	s_mov_b32 m0, s3
	s_nop 0
	global_load_lds_dwordx4 v[164:165], off
	v_lshl_add_u64 v[164:165], s[26:27], 0, v[128:129]
	s_add_i32 m0, s3, 0x2000
	s_nop 0
	global_load_lds_dwordx4 v[164:165], off
	s_waitcnt vmcnt(6)
	s_barrier
	s_setprio 1
	v_mfma_f32_16x16x32_bf16 v[56:59], v[212:215], v[180:183], v[56:59]
	v_mfma_f32_16x16x32_bf16 v[48:51], v[220:223], v[180:183], v[48:51]
	v_mfma_f32_16x16x32_bf16 v[40:43], v[212:215], v[188:191], v[40:43]
	v_mfma_f32_16x16x32_bf16 v[32:35], v[220:223], v[188:191], v[32:35]
	v_mfma_f32_16x16x32_bf16 v[24:27], v[212:215], v[196:199], v[24:27]
	v_mfma_f32_16x16x32_bf16 v[16:19], v[220:223], v[196:199], v[16:19]
	v_mfma_f32_16x16x32_bf16 v[8:11], v[212:215], v[204:207], v[8:11]
	v_mfma_f32_16x16x32_bf16 v[0:3], v[220:223], v[204:207], v[0:3]
	v_mfma_f32_16x16x32_bf16 v[56:59], v[216:219], v[184:187], v[56:59]
	v_mfma_f32_16x16x32_bf16 v[48:51], v[224:227], v[184:187], v[48:51]
	v_mfma_f32_16x16x32_bf16 v[40:43], v[216:219], v[192:195], v[40:43]
	v_mfma_f32_16x16x32_bf16 v[32:35], v[224:227], v[192:195], v[32:35]
	v_mfma_f32_16x16x32_bf16 v[24:27], v[216:219], v[200:203], v[24:27]
	v_mfma_f32_16x16x32_bf16 v[16:19], v[224:227], v[200:203], v[16:19]
	v_mfma_f32_16x16x32_bf16 v[8:11], v[216:219], v[208:211], v[8:11]
	v_mfma_f32_16x16x32_bf16 v[0:3], v[224:227], v[208:211], v[0:3]
	s_setprio 0
	s_add_i32 s3, 0, 0x18000
	v_add_u32_e32 v163, s3, v150
	s_barrier
	ds_read_b128 v[164:167], v163
	ds_read_b128 v[168:171], v163 offset:1024
	ds_read_b128 v[172:175], v163 offset:2048
	ds_read_b128 v[176:179], v163 offset:3072
	s_add_u32 s26, s34, 0x94000
	s_addc_u32 s27, s35, 0
	s_mov_b32 m0, s46
	v_lshl_add_u64 v[212:213], s[26:27], 0, v[134:135]
	ds_read_b128 v[180:183], v153 offset:32768
	ds_read_b128 v[184:187], v153 offset:33792
	ds_read_b128 v[188:191], v153 offset:34816
	ds_read_b128 v[192:195], v153 offset:35840
	ds_read_b128 v[196:199], v153 offset:36864
	ds_read_b128 v[200:203], v153 offset:37888
	ds_read_b128 v[204:207], v153 offset:38912
	ds_read_b128 v[208:211], v153 offset:39936
	global_load_lds_dwordx4 v[212:213], off
	v_lshl_add_u64 v[212:213], s[26:27], 0, v[130:131]
	s_mov_b32 m0, s47
	s_nop 0
	global_load_lds_dwordx4 v[212:213], off
	s_waitcnt lgkmcnt(8)
	s_barrier
	s_waitcnt lgkmcnt(0)
	s_setprio 1
	s_waitcnt lgkmcnt(0)
	v_mfma_f32_16x16x32_bf16 v[124:127], v[164:167], v[180:183], v[124:127]
	v_mfma_f32_16x16x32_bf16 v[116:119], v[172:175], v[180:183], v[116:119]
	v_mfma_f32_16x16x32_bf16 v[108:111], v[164:167], v[188:191], v[108:111]
	v_mfma_f32_16x16x32_bf16 v[100:103], v[172:175], v[188:191], v[100:103]
	v_mfma_f32_16x16x32_bf16 v[92:95], v[164:167], v[196:199], v[92:95]
	v_mfma_f32_16x16x32_bf16 v[84:87], v[172:175], v[196:199], v[84:87]
	v_mfma_f32_16x16x32_bf16 v[76:79], v[164:167], v[204:207], v[76:79]
	v_mfma_f32_16x16x32_bf16 v[68:71], v[172:175], v[204:207], v[68:71]
	v_mfma_f32_16x16x32_bf16 v[124:127], v[168:171], v[184:187], v[124:127]
	v_mfma_f32_16x16x32_bf16 v[116:119], v[176:179], v[184:187], v[116:119]
	v_mfma_f32_16x16x32_bf16 v[108:111], v[168:171], v[192:195], v[108:111]
	v_mfma_f32_16x16x32_bf16 v[100:103], v[176:179], v[192:195], v[100:103]
	v_mfma_f32_16x16x32_bf16 v[92:95], v[168:171], v[200:203], v[92:95]
	v_mfma_f32_16x16x32_bf16 v[84:87], v[176:179], v[200:203], v[84:87]
	v_mfma_f32_16x16x32_bf16 v[76:79], v[168:171], v[208:211], v[76:79]
	v_mfma_f32_16x16x32_bf16 v[68:71], v[176:179], v[208:211], v[68:71]
	s_setprio 0
	s_barrier
	s_add_i32 s34, 0, 0x1c000
	s_add_i32 s3, s3, s41
	v_add_u32_e32 v163, s34, v150
	v_lshl_add_u64 v[228:229], v[228:229], 0, s[22:23]
	s_mov_b32 m0, s3
	ds_read_b128 v[212:215], v163
	ds_read_b128 v[216:219], v163 offset:1024
	ds_read_b128 v[220:223], v163 offset:2048
	ds_read_b128 v[224:227], v163 offset:3072
	global_load_lds_dwordx4 v[228:229], off
	v_lshl_add_u64 v[228:229], v[230:231], 0, s[22:23]
	s_add_i32 m0, s3, 0x2000
	s_nop 0
	global_load_lds_dwordx4 v[228:229], off
	s_barrier
	s_waitcnt lgkmcnt(0)
	s_setprio 1
	s_waitcnt lgkmcnt(0)
	v_mfma_f32_16x16x32_bf16 v[120:123], v[212:215], v[180:183], v[120:123]
	v_mfma_f32_16x16x32_bf16 v[112:115], v[220:223], v[180:183], v[112:115]
	v_mfma_f32_16x16x32_bf16 v[104:107], v[212:215], v[188:191], v[104:107]
	v_mfma_f32_16x16x32_bf16 v[96:99], v[220:223], v[188:191], v[96:99]
	v_mfma_f32_16x16x32_bf16 v[88:91], v[212:215], v[196:199], v[88:91]
	v_mfma_f32_16x16x32_bf16 v[80:83], v[220:223], v[196:199], v[80:83]
	v_mfma_f32_16x16x32_bf16 v[72:75], v[212:215], v[204:207], v[72:75]
	v_mfma_f32_16x16x32_bf16 v[64:67], v[220:223], v[204:207], v[64:67]
	v_mfma_f32_16x16x32_bf16 v[120:123], v[216:219], v[184:187], v[120:123]
	v_mfma_f32_16x16x32_bf16 v[112:115], v[224:227], v[184:187], v[112:115]
	v_mfma_f32_16x16x32_bf16 v[104:107], v[216:219], v[192:195], v[104:107]
	v_mfma_f32_16x16x32_bf16 v[96:99], v[224:227], v[192:195], v[96:99]
	v_mfma_f32_16x16x32_bf16 v[88:91], v[216:219], v[200:203], v[88:91]
	v_mfma_f32_16x16x32_bf16 v[80:83], v[224:227], v[200:203], v[80:83]
	v_mfma_f32_16x16x32_bf16 v[72:75], v[216:219], v[208:211], v[72:75]
	v_mfma_f32_16x16x32_bf16 v[64:67], v[224:227], v[208:211], v[64:67]
	s_setprio 0
	s_mov_b32 m0, s0
	v_lshl_add_u64 v[228:229], v[234:235], 0, s[22:23]
	s_barrier
	ds_read_b128 v[180:183], v153 offset:49152
	ds_read_b128 v[184:187], v153 offset:50176
	ds_read_b128 v[188:191], v153 offset:51200
	ds_read_b128 v[192:195], v153 offset:52224
	ds_read_b128 v[196:199], v153 offset:53248
	ds_read_b128 v[200:203], v153 offset:54272
	ds_read_b128 v[204:207], v153 offset:55296
	ds_read_b128 v[208:211], v153 offset:56320
	global_load_lds_dwordx4 v[228:229], off
	v_lshl_add_u64 v[228:229], v[236:237], 0, s[22:23]
	s_mov_b32 m0, s1
	s_nop 0
	global_load_lds_dwordx4 v[228:229], off
	s_barrier
; __device__ __forceinline__ void st_nt(float* p, f32x4 v) { __builtin_nontemporal_store(v, (f32x4*)p); }
; __device__ __forceinline__ void st_nt(bf16_t* p, u32x4 v) { __builtin_nontemporal_store(v, (u32x4*)p); }
; __device__ __forceinline__ u32x4 pack8(const f32x4 a, const f32x4 b) { u32x4 w; w.x = cvt_pk_bf16(a[0], a[1]); w.y = cvt_pk_bf16(a[2], a[3]); w.z = cvt_pk_bf16(b[0], b[1]); w.w = cvt_pk_bf16(b[2], b[3]); return w; }
; #define PG8_STAGE(bufoff, gbase, voff) do { _Pragma("unroll") for (int _i = 0; _i < 2; ++_i) \
;         __builtin_amdgcn_global_load_lds((const unsigned*)((const char*)(gbase) + (voff)[_i]), (LAS unsigned*)(lds + (bufoff) + ldsw + _i * 8192), 16, 0, 0); } while (0)
; #define PG8_WAIT_V(n) asm volatile("s_waitcnt vmcnt(" #n ")" ::: "memory")
; #define PG8_WAIT_L(n) asm volatile("s_waitcnt lgkmcnt(" #n ")" ::: "memory")
; #define PG8_BAR __builtin_amdgcn_s_barrier()
;     __device__ __forceinline__ void operator()(Acc& acc, const Unit& u, int wr, int wc, int fr, int fq, const float (&rsv)[8]) const {
;         const int row0 = u.pm * BM + wr * 64 + fr, col = u.pn * 128 + wc * 32 + 8 * fq;
; #pragma unroll
;         for (int ai = 0; ai < 2; ++ai)
; #pragma unroll
;             for (int m = 0; m < 4; ++m) {
;                 const int row = row0 + ai * HALF + m * 16; const float rs = rsv[ai * 4 + m];
;                 f32x4 o[2];
;                 const float rsn = rs * -1.4426950408889634f, rs2 = rs * rs;
; #pragma unroll
;                 for (int n = 0; n < 2; ++n) { const f32x4 g = acc[ai][0][m][n], uu = acc[ai][1][m][n]; const f32x4 t = g * rsn, w = (g * uu) * rs2;
; #pragma unroll
;                     for (int j = 0; j < 4; ++j) o[n][j] = w[j] * __builtin_amdgcn_rcpf(1.0f + __builtin_amdgcn_exp2f(t[j])); }
;                 st_nt(act + (size_t)row * LDACT + col, pack8(o[0], o[1]));
; template <class Epi>
; __device__ __forceinline__ void gemm_phase(LAS unsigned char* lds, const GSched& S, const int K, const int lda, const int ldb, const Epi& E) {
;     ...
;             PG8_BAR; PG8_WAIT_L(0); PG8_MMA(1, 0, At, B0); PG8_BAR; PG8_SCHED;
;             PG8_STAGE(PG8_SB(1, 1), b3 + hstepB, voffB);
;             PG8_WAIT_V(6); PG8_BAR; if constexpr (!Epi::NARROW) PG8_MMA(1, 1, At, B1); PG8_BAR;
;             if constexpr (Epi::HAS_MID) { if (t + 2 == E.mid_t) { PG8_SCHED; E.mid(acc, cur, wr, wc, fr, fq); PG8_SCHED; } }
;         }
	s_waitcnt lgkmcnt(0)
	s_setprio 1
	v_mfma_f32_16x16x32_bf16 v[60:63], v[164:167], v[180:183], v[60:63]
	v_mfma_f32_16x16x32_bf16 v[52:55], v[172:175], v[180:183], v[52:55]
	v_mfma_f32_16x16x32_bf16 v[44:47], v[164:167], v[188:191], v[44:47]
	v_mfma_f32_16x16x32_bf16 v[36:39], v[172:175], v[188:191], v[36:39]
	v_mfma_f32_16x16x32_bf16 v[28:31], v[164:167], v[196:199], v[28:31]
	v_mfma_f32_16x16x32_bf16 v[20:23], v[172:175], v[196:199], v[20:23]
	v_mfma_f32_16x16x32_bf16 v[12:15], v[164:167], v[204:207], v[12:15]
	v_mfma_f32_16x16x32_bf16 v[4:7], v[172:175], v[204:207], v[4:7]
	v_mfma_f32_16x16x32_bf16 v[60:63], v[168:171], v[184:187], v[60:63]
	v_mfma_f32_16x16x32_bf16 v[52:55], v[176:179], v[184:187], v[52:55]
	v_mfma_f32_16x16x32_bf16 v[44:47], v[168:171], v[192:195], v[44:47]
	v_mfma_f32_16x16x32_bf16 v[36:39], v[176:179], v[192:195], v[36:39]
	v_mfma_f32_16x16x32_bf16 v[28:31], v[168:171], v[200:203], v[28:31]
	v_mfma_f32_16x16x32_bf16 v[20:23], v[176:179], v[200:203], v[20:23]
	v_mfma_f32_16x16x32_bf16 v[12:15], v[168:171], v[208:211], v[12:15]
	v_mfma_f32_16x16x32_bf16 v[4:7], v[176:179], v[208:211], v[4:7]
	s_setprio 0
	s_barrier
	s_add_u32 s26, s30, 0x84080
	s_addc_u32 s27, s31, 0
	s_add_i32 s3, s34, s41
	v_lshl_add_u64 v[164:165], s[26:27], 0, v[132:133]
	s_mov_b32 m0, s3
	s_nop 0
	global_load_lds_dwordx4 v[164:165], off
	v_lshl_add_u64 v[164:165], s[26:27], 0, v[128:129]
	s_add_i32 m0, s3, 0x2000
	s_nop 0
	global_load_lds_dwordx4 v[164:165], off
	s_waitcnt vmcnt(6)
	s_barrier
	s_setprio 1
	v_mfma_f32_16x16x32_bf16 v[56:59], v[212:215], v[180:183], v[56:59]
	v_mfma_f32_16x16x32_bf16 v[48:51], v[220:223], v[180:183], v[48:51]
	v_mfma_f32_16x16x32_bf16 v[40:43], v[212:215], v[188:191], v[40:43]
	v_mfma_f32_16x16x32_bf16 v[32:35], v[220:223], v[188:191], v[32:35]
	v_mfma_f32_16x16x32_bf16 v[24:27], v[212:215], v[196:199], v[24:27]
	v_mfma_f32_16x16x32_bf16 v[16:19], v[220:223], v[196:199], v[16:19]
	v_mfma_f32_16x16x32_bf16 v[8:11], v[212:215], v[204:207], v[8:11]
	v_mfma_f32_16x16x32_bf16 v[0:3], v[220:223], v[204:207], v[0:3]
	v_mfma_f32_16x16x32_bf16 v[56:59], v[216:219], v[184:187], v[56:59]
	v_mfma_f32_16x16x32_bf16 v[48:51], v[224:227], v[184:187], v[48:51]
	v_mfma_f32_16x16x32_bf16 v[40:43], v[216:219], v[192:195], v[40:43]
	v_mfma_f32_16x16x32_bf16 v[32:35], v[224:227], v[192:195], v[32:35]
	v_mfma_f32_16x16x32_bf16 v[24:27], v[216:219], v[200:203], v[24:27]
	v_mfma_f32_16x16x32_bf16 v[16:19], v[224:227], v[200:203], v[16:19]
	v_mfma_f32_16x16x32_bf16 v[8:11], v[216:219], v[208:211], v[8:11]
	v_mfma_f32_16x16x32_bf16 v[0:3], v[224:227], v[208:211], v[0:3]
	s_setprio 0
	s_add_i32 s61, s61, 2
	s_add_u32 s59, s59, 0x100
	s_addc_u32 s60, s60, 0
	s_cmp_gt_u32 s61, 29
	s_mov_b64 s[26:27], s[28:29]
	s_barrier
	s_cbranch_scc0 .LBB0_262
	v_mul_f32_e32 v166, 0xbfb8aa3b, v155
	v_pk_mul_f32 v[168:169], v[166:167], v[124:125] op_sel_hi:[0,1]
	v_exp_f32_e32 v167, v168
	v_pk_mul_f32 v[120:121], v[124:125], v[120:121]
	v_exp_f32_e32 v169, v169
	v_mul_f32_e32 v168, v155, v155
	v_pk_mul_f32 v[170:171], v[166:167], v[126:127] op_sel_hi:[0,1]
	v_exp_f32_e32 v124, v170
	v_exp_f32_e32 v125, v171
	v_add_f32_e32 v167, 1.0, v167
	v_rcp_f32_e32 v172, v167
	v_add_f32_e32 v124, 1.0, v124
	v_add_f32_e32 v125, 1.0, v125
	v_rcp_f32_e32 v124, v124
	v_rcp_f32_e32 v125, v125
	v_add_f32_e32 v167, 1.0, v169
	v_pk_mul_f32 v[122:123], v[126:127], v[122:123]
	v_pk_mul_f32 v[126:127], v[166:167], v[116:117] op_sel_hi:[0,1]
	v_pk_mul_f32 v[122:123], v[168:169], v[122:123] op_sel_hi:[0,1]
	v_exp_f32_e32 v126, v126
	v_pk_mul_f32 v[122:123], v[124:125], v[122:123]
	v_exp_f32_e32 v127, v127
	v_pk_mul_f32 v[124:125], v[166:167], v[118:119] op_sel_hi:[0,1]
	v_exp_f32_e32 v124, v124
	v_pk_mul_f32 v[114:115], v[118:119], v[114:115]
	v_exp_f32_e32 v118, v125
	v_add_f32_e32 v126, 1.0, v126
	v_add_f32_e32 v127, 1.0, v127
	v_rcp_f32_e32 v126, v126
	v_rcp_f32_e32 v127, v127
	v_pk_mul_f32 v[112:113], v[116:117], v[112:113]
	v_add_f32_e32 v116, 1.0, v124
	v_add_f32_e32 v117, 1.0, v118
	v_rcp_f32_e32 v116, v116
	v_rcp_f32_e32 v117, v117
	v_rcp_f32_e32 v173, v167
	v_pk_mul_f32 v[112:113], v[168:169], v[112:113] op_sel_hi:[0,1]
	v_lshl_or_b32 v164, s58, 7, v151
	v_pk_mul_f32 v[118:119], v[126:127], v[112:113]
	v_pk_mul_f32 v[112:113], v[168:169], v[114:115] op_sel_hi:[0,1]
	v_lshl_add_u32 v163, s2, 8, v149
	v_ashrrev_i32_e32 v165, 31, v164
	v_pk_mul_f32 v[120:121], v[168:169], v[120:121] op_sel_hi:[0,1]
	v_pk_mul_f32 v[124:125], v[116:117], v[112:113]
	v_mov_b64_e32 v[112:113], s[20:21]
	v_pk_mul_f32 v[120:121], v[172:173], v[120:121]
	v_mad_i64_i32 v[116:117], s[26:27], v163, s55, v[112:113]
	v_lshlrev_b64 v[114:115], 1, v[164:165]
	v_lshl_add_u64 v[126:127], v[116:117], 0, v[114:115]
	v_cvt_pk_bf16_f32 v116, v120, v121
	v_cvt_pk_bf16_f32 v117, v122, v123
	v_cvt_pk_bf16_f32 v118, v118, v119
	v_cvt_pk_bf16_f32 v119, v124, v125
	global_store_dwordx4 v[126:127], v[116:119], off
	v_pk_mul_f32 v[104:105], v[108:109], v[104:105]
	v_pk_mul_f32 v[106:107], v[110:111], v[106:107]
	v_mul_f32_e32 v116, 0xbfb8aa3b, v156
	v_pk_mul_f32 v[118:119], v[116:117], v[108:109] op_sel_hi:[0,1]
	v_exp_f32_e32 v117, v118
	v_exp_f32_e32 v119, v119
	v_mul_f32_e32 v118, v156, v156
	v_pk_mul_f32 v[98:99], v[102:103], v[98:99]
	v_pk_mul_f32 v[120:121], v[116:117], v[110:111] op_sel_hi:[0,1]
	v_exp_f32_e32 v108, v120
	v_exp_f32_e32 v109, v121
	v_add_f32_e32 v117, 1.0, v117
	v_rcp_f32_e32 v122, v117
	v_add_f32_e32 v108, 1.0, v108
	v_add_f32_e32 v109, 1.0, v109
	v_rcp_f32_e32 v108, v108
	v_rcp_f32_e32 v109, v109
	v_add_f32_e32 v117, 1.0, v119
	v_pk_mul_f32 v[106:107], v[118:119], v[106:107] op_sel_hi:[0,1]
; __device__ __forceinline__ void st_nt(float* p, f32x4 v) { __builtin_nontemporal_store(v, (f32x4*)p); }
; __device__ __forceinline__ void st_nt(bf16_t* p, u32x4 v) { __builtin_nontemporal_store(v, (u32x4*)p); }
; __device__ __forceinline__ u32x4 pack8(const f32x4 a, const f32x4 b) { u32x4 w; w.x = cvt_pk_bf16(a[0], a[1]); w.y = cvt_pk_bf16(a[2], a[3]); w.z = cvt_pk_bf16(b[0], b[1]); w.w = cvt_pk_bf16(b[2], b[3]); return w; }
;     __device__ __forceinline__ void operator()(Acc& acc, const Unit& u, int wr, int wc, int fr, int fq, const float (&rsv)[8]) const {
;     ...
;         for (int ai = 0; ai < 2; ++ai)
; #pragma unroll
;             for (int m = 0; m < 4; ++m) {
;                 const int row = row0 + ai * HALF + m * 16; const float rs = rsv[ai * 4 + m];
;                 f32x4 o[2];
;                 const float rsn = rs * -1.4426950408889634f, rs2 = rs * rs;
; #pragma unroll
;                 for (int n = 0; n < 2; ++n) { const f32x4 g = acc[ai][0][m][n], uu = acc[ai][1][m][n]; const f32x4 t = g * rsn, w = (g * uu) * rs2;
; #pragma unroll
;                     for (int j = 0; j < 4; ++j) o[n][j] = w[j] * __builtin_amdgcn_rcpf(1.0f + __builtin_amdgcn_exp2f(t[j])); }
;                 st_nt(act + (size_t)row * LDACT + col, pack8(o[0], o[1]));
	v_pk_mul_f32 v[110:111], v[116:117], v[100:101] op_sel_hi:[0,1]
	v_exp_f32_e32 v110, v110
	v_pk_mul_f32 v[106:107], v[108:109], v[106:107]
	v_exp_f32_e32 v111, v111
	v_pk_mul_f32 v[108:109], v[116:117], v[102:103] op_sel_hi:[0,1]
	v_exp_f32_e32 v108, v108
	v_exp_f32_e32 v102, v109
	v_add_f32_e32 v110, 1.0, v110
	v_add_f32_e32 v111, 1.0, v111
	v_rcp_f32_e32 v110, v110
	v_rcp_f32_e32 v111, v111
	v_pk_mul_f32 v[96:97], v[100:101], v[96:97]
	v_add_f32_e32 v100, 1.0, v108
	v_add_f32_e32 v101, 1.0, v102
	v_rcp_f32_e32 v100, v100
	v_rcp_f32_e32 v101, v101
	v_rcp_f32_e32 v123, v117
	v_pk_mul_f32 v[96:97], v[118:119], v[96:97] op_sel_hi:[0,1]
	v_pk_mul_f32 v[102:103], v[110:111], v[96:97]
	v_pk_mul_f32 v[96:97], v[118:119], v[98:99] op_sel_hi:[0,1]
	v_pk_mul_f32 v[104:105], v[118:119], v[104:105] op_sel_hi:[0,1]
	v_pk_mul_f32 v[100:101], v[100:101], v[96:97]
	v_or_b32_e32 v96, 16, v163
	v_pk_mul_f32 v[104:105], v[122:123], v[104:105]
	v_mad_i64_i32 v[96:97], s[26:27], v96, s55, v[112:113]
	v_lshl_add_u64 v[108:109], v[96:97], 0, v[114:115]
	v_cvt_pk_bf16_f32 v96, v104, v105
	v_cvt_pk_bf16_f32 v97, v106, v107
	v_cvt_pk_bf16_f32 v98, v102, v103
	v_cvt_pk_bf16_f32 v99, v100, v101
	global_store_dwordx4 v[108:109], v[96:99], off
	v_pk_mul_f32 v[88:89], v[92:93], v[88:89]
	v_pk_mul_f32 v[90:91], v[94:95], v[90:91]
	v_mul_f32_e32 v96, 0xbfb8aa3b, v157
	v_pk_mul_f32 v[98:99], v[96:97], v[92:93] op_sel_hi:[0,1]
	v_exp_f32_e32 v97, v98
	v_exp_f32_e32 v99, v99
	v_mul_f32_e32 v98, v157, v157
	v_pk_mul_f32 v[82:83], v[86:87], v[82:83]
	v_pk_mul_f32 v[100:101], v[96:97], v[94:95] op_sel_hi:[0,1]
	v_exp_f32_e32 v92, v100
	v_exp_f32_e32 v93, v101
	v_add_f32_e32 v97, 1.0, v97
	v_rcp_f32_e32 v102, v97
	v_add_f32_e32 v92, 1.0, v92
	v_add_f32_e32 v93, 1.0, v93
	v_rcp_f32_e32 v92, v92
	v_rcp_f32_e32 v93, v93
	v_add_f32_e32 v97, 1.0, v99
	v_pk_mul_f32 v[90:91], v[98:99], v[90:91] op_sel_hi:[0,1]
	v_pk_mul_f32 v[94:95], v[96:97], v[84:85] op_sel_hi:[0,1]
	v_exp_f32_e32 v94, v94
	v_pk_mul_f32 v[90:91], v[92:93], v[90:91]
	v_exp_f32_e32 v95, v95
	v_pk_mul_f32 v[92:93], v[96:97], v[86:87] op_sel_hi:[0,1]
	v_exp_f32_e32 v92, v92
	v_exp_f32_e32 v86, v93
	v_add_f32_e32 v94, 1.0, v94
	v_add_f32_e32 v95, 1.0, v95
	v_rcp_f32_e32 v94, v94
	v_rcp_f32_e32 v95, v95
	v_pk_mul_f32 v[80:81], v[84:85], v[80:81]
	v_add_f32_e32 v84, 1.0, v92
	v_add_f32_e32 v85, 1.0, v86
	v_rcp_f32_e32 v84, v84
	v_rcp_f32_e32 v85, v85
	v_rcp_f32_e32 v103, v97
	v_pk_mul_f32 v[80:81], v[98:99], v[80:81] op_sel_hi:[0,1]
	v_pk_mul_f32 v[86:87], v[94:95], v[80:81]
	v_pk_mul_f32 v[80:81], v[98:99], v[82:83] op_sel_hi:[0,1]
	v_pk_mul_f32 v[88:89], v[98:99], v[88:89] op_sel_hi:[0,1]
	v_pk_mul_f32 v[84:85], v[84:85], v[80:81]
	v_or_b32_e32 v80, 32, v163
	v_pk_mul_f32 v[88:89], v[102:103], v[88:89]
	v_mad_i64_i32 v[80:81], s[26:27], v80, s55, v[112:113]
	v_lshl_add_u64 v[92:93], v[80:81], 0, v[114:115]
	v_cvt_pk_bf16_f32 v80, v88, v89
	v_cvt_pk_bf16_f32 v81, v90, v91
	v_cvt_pk_bf16_f32 v82, v86, v87
	v_cvt_pk_bf16_f32 v83, v84, v85
	global_store_dwordx4 v[92:93], v[80:83], off
	v_pk_mul_f32 v[72:73], v[76:77], v[72:73]
	v_pk_mul_f32 v[74:75], v[78:79], v[74:75]
	v_mul_f32_e32 v80, 0xbfb8aa3b, v158
	v_pk_mul_f32 v[82:83], v[80:81], v[76:77] op_sel_hi:[0,1]
	v_exp_f32_e32 v81, v82
	v_exp_f32_e32 v83, v83
	v_mul_f32_e32 v82, v158, v158
	v_pk_mul_f32 v[66:67], v[70:71], v[66:67]
	v_pk_mul_f32 v[84:85], v[80:81], v[78:79] op_sel_hi:[0,1]
	v_exp_f32_e32 v76, v84
	v_exp_f32_e32 v77, v85
	v_add_f32_e32 v81, 1.0, v81
	v_rcp_f32_e32 v86, v81
	v_add_f32_e32 v76, 1.0, v76
	v_add_f32_e32 v77, 1.0, v77
	v_rcp_f32_e32 v76, v76
	v_rcp_f32_e32 v77, v77
	v_add_f32_e32 v81, 1.0, v83
	v_pk_mul_f32 v[74:75], v[82:83], v[74:75] op_sel_hi:[0,1]
	v_pk_mul_f32 v[78:79], v[80:81], v[68:69] op_sel_hi:[0,1]
	v_exp_f32_e32 v78, v78
	v_pk_mul_f32 v[74:75], v[76:77], v[74:75]
	v_exp_f32_e32 v79, v79
	v_pk_mul_f32 v[76:77], v[80:81], v[70:71] op_sel_hi:[0,1]
	v_exp_f32_e32 v76, v76
	v_exp_f32_e32 v70, v77
	v_add_f32_e32 v78, 1.0, v78
	v_add_f32_e32 v79, 1.0, v79
	v_rcp_f32_e32 v78, v78
	v_rcp_f32_e32 v79, v79
	v_pk_mul_f32 v[64:65], v[68:69], v[64:65]
	v_add_f32_e32 v68, 1.0, v76
	v_add_f32_e32 v69, 1.0, v70
	v_rcp_f32_e32 v68, v68
	v_rcp_f32_e32 v69, v69
	v_rcp_f32_e32 v87, v81
	v_pk_mul_f32 v[64:65], v[82:83], v[64:65] op_sel_hi:[0,1]
	v_pk_mul_f32 v[70:71], v[78:79], v[64:65]
	v_pk_mul_f32 v[64:65], v[82:83], v[66:67] op_sel_hi:[0,1]
	v_pk_mul_f32 v[72:73], v[82:83], v[72:73] op_sel_hi:[0,1]
	v_pk_mul_f32 v[68:69], v[68:69], v[64:65]
	v_or_b32_e32 v64, 48, v163
	v_pk_mul_f32 v[72:73], v[86:87], v[72:73]
	v_mad_i64_i32 v[64:65], s[26:27], v64, s55, v[112:113]
	v_lshl_add_u64 v[76:77], v[64:65], 0, v[114:115]
	v_cvt_pk_bf16_f32 v64, v72, v73
	v_cvt_pk_bf16_f32 v65, v74, v75
	v_cvt_pk_bf16_f32 v66, v70, v71
	v_cvt_pk_bf16_f32 v67, v68, v69
	global_store_dwordx4 v[76:77], v[64:67], off
	v_pk_mul_f32 v[56:57], v[60:61], v[56:57]
	v_pk_mul_f32 v[58:59], v[62:63], v[58:59]
	v_add_u32_e32 v65, 0x80, v163
	v_mul_f32_e32 v64, 0xbfb8aa3b, v159
	v_pk_mul_f32 v[68:69], v[64:65], v[62:63] op_sel_hi:[0,1]
	v_pk_mul_f32 v[66:67], v[64:65], v[60:61] op_sel_hi:[0,1]
	v_exp_f32_e32 v60, v68
	v_exp_f32_e32 v61, v69
	v_exp_f32_e32 v67, v67
	v_exp_f32_e32 v70, v66
	v_add_f32_e32 v60, 1.0, v60
	v_add_f32_e32 v61, 1.0, v61
	v_rcp_f32_e32 v60, v60
	v_rcp_f32_e32 v61, v61
	v_mul_f32_e32 v66, v159, v159
	v_add_f32_e32 v67, 1.0, v67
	v_pk_mul_f32 v[58:59], v[66:67], v[58:59] op_sel_hi:[0,1]
	v_pk_mul_f32 v[62:63], v[64:65], v[52:53] op_sel_hi:[0,1]
	v_exp_f32_e32 v62, v62
	v_pk_mul_f32 v[58:59], v[60:61], v[58:59]
	v_exp_f32_e32 v63, v63
; __device__ __forceinline__ void st_nt(float* p, f32x4 v) { __builtin_nontemporal_store(v, (f32x4*)p); }
; __device__ __forceinline__ void st_nt(bf16_t* p, u32x4 v) { __builtin_nontemporal_store(v, (u32x4*)p); }
; __device__ __forceinline__ u32x4 pack8(const f32x4 a, const f32x4 b) { u32x4 w; w.x = cvt_pk_bf16(a[0], a[1]); w.y = cvt_pk_bf16(a[2], a[3]); w.z = cvt_pk_bf16(b[0], b[1]); w.w = cvt_pk_bf16(b[2], b[3]); return w; }
;     __device__ __forceinline__ void operator()(Acc& acc, const Unit& u, int wr, int wc, int fr, int fq, const float (&rsv)[8]) const {
;     ...
;         for (int ai = 0; ai < 2; ++ai)
; #pragma unroll
;             for (int m = 0; m < 4; ++m) {
;                 const int row = row0 + ai * HALF + m * 16; const float rs = rsv[ai * 4 + m];
;                 f32x4 o[2];
;                 const float rsn = rs * -1.4426950408889634f, rs2 = rs * rs;
; #pragma unroll
;                 for (int n = 0; n < 2; ++n) { const f32x4 g = acc[ai][0][m][n], uu = acc[ai][1][m][n]; const f32x4 t = g * rsn, w = (g * uu) * rs2;
; #pragma unroll
;                     for (int j = 0; j < 4; ++j) o[n][j] = w[j] * __builtin_amdgcn_rcpf(1.0f + __builtin_amdgcn_exp2f(t[j])); }
;                 st_nt(act + (size_t)row * LDACT + col, pack8(o[0], o[1]));
; template <class Epi>
; __device__ __forceinline__ void gemm_phase(LAS unsigned char* lds, const GSched& S, const int K, const int lda, const int ldb, const Epi& E) {
;     ...
;         E(acc, cur, wr, wc, fr, fq, rsv);
;         if (!has_next) break;
	v_pk_mul_f32 v[60:61], v[64:65], v[54:55] op_sel_hi:[0,1]
	v_exp_f32_e32 v60, v60
	v_pk_mul_f32 v[50:51], v[54:55], v[50:51]
	v_exp_f32_e32 v54, v61
	v_add_f32_e32 v62, 1.0, v62
	v_add_f32_e32 v63, 1.0, v63
	v_add_f32_e32 v70, 1.0, v70
	v_rcp_f32_e32 v62, v62
	v_rcp_f32_e32 v63, v63
	v_pk_mul_f32 v[48:49], v[52:53], v[48:49]
	v_add_f32_e32 v52, 1.0, v60
	v_add_f32_e32 v53, 1.0, v54
	v_rcp_f32_e32 v70, v70
	v_rcp_f32_e32 v71, v67
	v_rcp_f32_e32 v52, v52
	v_rcp_f32_e32 v53, v53
	v_pk_mul_f32 v[48:49], v[66:67], v[48:49] op_sel_hi:[0,1]
	v_pk_mul_f32 v[56:57], v[66:67], v[56:57] op_sel_hi:[0,1]
	v_pk_mul_f32 v[54:55], v[62:63], v[48:49]
	v_pk_mul_f32 v[48:49], v[66:67], v[50:51] op_sel_hi:[0,1]
	v_pk_mul_f32 v[56:57], v[70:71], v[56:57]
	v_pk_mul_f32 v[52:53], v[52:53], v[48:49]
	v_mad_i64_i32 v[48:49], s[26:27], v65, s55, v[112:113]
	v_lshl_add_u64 v[60:61], v[48:49], 0, v[114:115]
	v_cvt_pk_bf16_f32 v48, v56, v57
	v_cvt_pk_bf16_f32 v49, v58, v59
	v_cvt_pk_bf16_f32 v50, v54, v55
	v_cvt_pk_bf16_f32 v51, v52, v53
	global_store_dwordx4 v[60:61], v[48:51], off
	v_pk_mul_f32 v[40:41], v[44:45], v[40:41]
	v_pk_mul_f32 v[42:43], v[46:47], v[42:43]
	v_mul_f32_e32 v48, 0xbfb8aa3b, v160
	v_pk_mul_f32 v[50:51], v[48:49], v[44:45] op_sel_hi:[0,1]
	v_exp_f32_e32 v49, v50
	v_exp_f32_e32 v51, v51
	v_mul_f32_e32 v50, v160, v160
	v_pk_mul_f32 v[34:35], v[38:39], v[34:35]
	v_pk_mul_f32 v[52:53], v[48:49], v[46:47] op_sel_hi:[0,1]
	v_exp_f32_e32 v44, v52
	v_exp_f32_e32 v45, v53
	v_add_f32_e32 v49, 1.0, v49
	v_rcp_f32_e32 v54, v49
	v_add_f32_e32 v44, 1.0, v44
	v_add_f32_e32 v45, 1.0, v45
	v_rcp_f32_e32 v44, v44
	v_rcp_f32_e32 v45, v45
	v_add_f32_e32 v49, 1.0, v51
	v_pk_mul_f32 v[42:43], v[50:51], v[42:43] op_sel_hi:[0,1]
	v_pk_mul_f32 v[46:47], v[48:49], v[36:37] op_sel_hi:[0,1]
	v_exp_f32_e32 v46, v46
	v_pk_mul_f32 v[42:43], v[44:45], v[42:43]
	v_exp_f32_e32 v47, v47
	v_pk_mul_f32 v[44:45], v[48:49], v[38:39] op_sel_hi:[0,1]
	v_exp_f32_e32 v44, v44
	v_exp_f32_e32 v38, v45
	v_add_f32_e32 v46, 1.0, v46
	v_add_f32_e32 v47, 1.0, v47
	v_rcp_f32_e32 v46, v46
	v_rcp_f32_e32 v47, v47
	v_pk_mul_f32 v[32:33], v[36:37], v[32:33]
	v_add_f32_e32 v36, 1.0, v44
	v_add_f32_e32 v37, 1.0, v38
	v_rcp_f32_e32 v36, v36
	v_rcp_f32_e32 v37, v37
	v_rcp_f32_e32 v55, v49
	v_pk_mul_f32 v[32:33], v[50:51], v[32:33] op_sel_hi:[0,1]
	v_pk_mul_f32 v[38:39], v[46:47], v[32:33]
	v_pk_mul_f32 v[32:33], v[50:51], v[34:35] op_sel_hi:[0,1]
	v_pk_mul_f32 v[40:41], v[50:51], v[40:41] op_sel_hi:[0,1]
	v_pk_mul_f32 v[36:37], v[36:37], v[32:33]
	v_add_u32_e32 v32, 0x90, v163
	v_pk_mul_f32 v[40:41], v[54:55], v[40:41]
	v_mad_i64_i32 v[32:33], s[26:27], v32, s55, v[112:113]
	v_lshl_add_u64 v[44:45], v[32:33], 0, v[114:115]
	v_cvt_pk_bf16_f32 v32, v40, v41
	v_cvt_pk_bf16_f32 v33, v42, v43
	v_cvt_pk_bf16_f32 v34, v38, v39
	v_cvt_pk_bf16_f32 v35, v36, v37
	global_store_dwordx4 v[44:45], v[32:35], off
	v_pk_mul_f32 v[24:25], v[28:29], v[24:25]
	v_pk_mul_f32 v[26:27], v[30:31], v[26:27]
	v_mul_f32_e32 v32, 0xbfb8aa3b, v161
	v_pk_mul_f32 v[34:35], v[32:33], v[28:29] op_sel_hi:[0,1]
	v_exp_f32_e32 v33, v34
	v_exp_f32_e32 v35, v35
	v_mul_f32_e32 v34, v161, v161
	v_pk_mul_f32 v[18:19], v[22:23], v[18:19]
	v_pk_mul_f32 v[36:37], v[32:33], v[30:31] op_sel_hi:[0,1]
	v_exp_f32_e32 v28, v36
	v_exp_f32_e32 v29, v37
	v_add_f32_e32 v33, 1.0, v33
	v_rcp_f32_e32 v38, v33
	v_add_f32_e32 v28, 1.0, v28
	v_add_f32_e32 v29, 1.0, v29
	v_rcp_f32_e32 v28, v28
	v_rcp_f32_e32 v29, v29
	v_add_f32_e32 v33, 1.0, v35
	v_pk_mul_f32 v[26:27], v[34:35], v[26:27] op_sel_hi:[0,1]
	v_pk_mul_f32 v[30:31], v[32:33], v[20:21] op_sel_hi:[0,1]
	v_exp_f32_e32 v30, v30
	v_pk_mul_f32 v[26:27], v[28:29], v[26:27]
	v_exp_f32_e32 v31, v31
	v_pk_mul_f32 v[28:29], v[32:33], v[22:23] op_sel_hi:[0,1]
	v_exp_f32_e32 v28, v28
	v_exp_f32_e32 v22, v29
	v_add_f32_e32 v30, 1.0, v30
	v_add_f32_e32 v31, 1.0, v31
	v_rcp_f32_e32 v30, v30
	v_rcp_f32_e32 v31, v31
	v_pk_mul_f32 v[16:17], v[20:21], v[16:17]
	v_add_f32_e32 v20, 1.0, v28
	v_add_f32_e32 v21, 1.0, v22
	v_rcp_f32_e32 v20, v20
	v_rcp_f32_e32 v21, v21
	v_rcp_f32_e32 v39, v33
	v_pk_mul_f32 v[16:17], v[34:35], v[16:17] op_sel_hi:[0,1]
	v_pk_mul_f32 v[22:23], v[30:31], v[16:17]
	v_pk_mul_f32 v[16:17], v[34:35], v[18:19] op_sel_hi:[0,1]
	v_pk_mul_f32 v[24:25], v[34:35], v[24:25] op_sel_hi:[0,1]
	v_pk_mul_f32 v[20:21], v[20:21], v[16:17]
	v_add_u32_e32 v16, 0xa0, v163
	v_pk_mul_f32 v[24:25], v[38:39], v[24:25]
	v_mad_i64_i32 v[16:17], s[26:27], v16, s55, v[112:113]
	v_lshl_add_u64 v[28:29], v[16:17], 0, v[114:115]
	v_cvt_pk_bf16_f32 v16, v24, v25
	v_cvt_pk_bf16_f32 v17, v26, v27
	v_cvt_pk_bf16_f32 v18, v22, v23
	v_cvt_pk_bf16_f32 v19, v20, v21
	global_store_dwordx4 v[28:29], v[16:19], off
	v_pk_mul_f32 v[8:9], v[12:13], v[8:9]
	v_pk_mul_f32 v[10:11], v[14:15], v[10:11]
	v_mul_f32_e32 v16, 0xbfb8aa3b, v162
	v_pk_mul_f32 v[18:19], v[16:17], v[12:13] op_sel_hi:[0,1]
	v_exp_f32_e32 v17, v18
	v_exp_f32_e32 v19, v19
	v_mul_f32_e32 v18, v162, v162
	v_pk_mul_f32 v[2:3], v[6:7], v[2:3]
	v_pk_mul_f32 v[20:21], v[16:17], v[14:15] op_sel_hi:[0,1]
	v_exp_f32_e32 v12, v20
	v_exp_f32_e32 v13, v21
	v_add_f32_e32 v17, 1.0, v17
	v_rcp_f32_e32 v22, v17
	v_add_f32_e32 v12, 1.0, v12
	v_add_f32_e32 v13, 1.0, v13
	v_rcp_f32_e32 v12, v12
	v_rcp_f32_e32 v13, v13
	v_add_f32_e32 v17, 1.0, v19
	v_pk_mul_f32 v[10:11], v[18:19], v[10:11] op_sel_hi:[0,1]
	v_pk_mul_f32 v[14:15], v[16:17], v[4:5] op_sel_hi:[0,1]
	v_exp_f32_e32 v14, v14
	v_pk_mul_f32 v[10:11], v[12:13], v[10:11]
	v_exp_f32_e32 v15, v15
	v_pk_mul_f32 v[12:13], v[16:17], v[6:7] op_sel_hi:[0,1]
	v_exp_f32_e32 v12, v12
	v_exp_f32_e32 v6, v13
	v_add_f32_e32 v14, 1.0, v14
	v_add_f32_e32 v15, 1.0, v15
	v_rcp_f32_e32 v14, v14
	v_rcp_f32_e32 v15, v15
	v_pk_mul_f32 v[0:1], v[4:5], v[0:1]
	v_add_f32_e32 v4, 1.0, v12
	v_add_f32_e32 v5, 1.0, v6
	v_rcp_f32_e32 v4, v4
	v_rcp_f32_e32 v5, v5
	v_rcp_f32_e32 v23, v17
	v_pk_mul_f32 v[0:1], v[18:19], v[0:1] op_sel_hi:[0,1]
	v_pk_mul_f32 v[6:7], v[14:15], v[0:1]
	v_pk_mul_f32 v[0:1], v[18:19], v[2:3] op_sel_hi:[0,1]
	v_pk_mul_f32 v[8:9], v[18:19], v[8:9] op_sel_hi:[0,1]
	v_pk_mul_f32 v[4:5], v[4:5], v[0:1]
	v_add_u32_e32 v0, 0xb0, v163
	v_pk_mul_f32 v[8:9], v[22:23], v[8:9]
	v_mad_i64_i32 v[0:1], s[26:27], v0, s55, v[112:113]
	v_lshl_add_u64 v[12:13], v[0:1], 0, v[114:115]
	v_cvt_pk_bf16_f32 v0, v8, v9
	v_cvt_pk_bf16_f32 v1, v10, v11
	v_cvt_pk_bf16_f32 v2, v6, v7
	v_cvt_pk_bf16_f32 v3, v4, v5
	s_mov_b64 s[26:27], -1
	s_and_b64 vcc, exec, s[4:5]
	global_store_dwordx4 v[12:13], v[0:3], off
	s_cbranch_vccz .LBB0_254
; __device__ __forceinline__ void rstd_regs32(float (&rsv)[8], const float* part, int row0, int fq) {
;     int r0 = row0; asm volatile("" : "+v"(r0));
;     const float* q = part + (size_t)r0 * 32 + fq * 8;
;     f32x4 a[8], b[8];
; #pragma unroll
;     for (int g = 0; g < 8; ++g) { const float* p = q + (size_t)((g >> 2) * HALF + (g & 3) * 16) * 32; a[g] = *(const f32x4*)p; b[g] = *(const f32x4*)(p + 4); }
; #pragma unroll
;     for (int g = 0; g < 8; ++g) { float s = ((a[g][0] + a[g][1]) + (a[g][2] + a[g][3])) + ((b[g][0] + b[g][1]) + (b[g][2] + b[g][3]));
;         s += __shfl_xor(s, 16); s += __shfl_xor(s, 32); rsv[g] = __builtin_amdgcn_rsqf(s * (1.0f / 2048.0f) + EPS); }
; }
	s_cmp_eq_u32 s57, s2
	s_cbranch_scc1 .LBB0_253
	v_lshl_add_u32 v0, s57, 8, v149
	s_nop 0
	v_ashrrev_i32_e32 v1, 31, v0
	v_lshlrev_b64 v[0:1], 7, v[0:1]
	v_lshl_add_u64 v[48:49], v[136:137], 0, v[0:1]
	global_load_dwordx4 v[0:3], v[48:49], off
	global_load_dwordx4 v[4:7], v[48:49], off offset:16
	global_load_dwordx4 v[8:11], v[48:49], off offset:2048
	global_load_dwordx4 v[12:15], v[48:49], off offset:2064
	v_add_co_u32_e32 v28, vcc, 0x1000, v48
	v_lshl_add_u64 v[24:25], v[48:49], 0, s[8:9]
	v_lshl_add_u64 v[16:17], v[48:49], 0, s[12:13]
	v_addc_co_u32_e32 v29, vcc, 0, v49, vcc
	v_lshl_add_u64 v[32:33], v[48:49], 0, s[10:11]
	global_load_dwordx4 v[16:19], v[16:17], off offset:16
	s_nop 0
	global_load_dwordx4 v[20:23], v[28:29], off
	s_nop 0
	global_load_dwordx4 v[24:27], v[24:25], off offset:16
	s_nop 0
	global_load_dwordx4 v[28:31], v[28:29], off offset:2048
	s_nop 0
	global_load_dwordx4 v[32:35], v[32:33], off offset:16
	v_add_co_u32_e32 v50, vcc, s49, v48
	s_mov_b64 s[4:5], vcc
	v_add_co_u32_e32 v56, vcc, s50, v48
	v_lshl_add_u64 v[40:41], v[48:49], 0, s[14:15]
	s_nop 0
	v_addc_co_u32_e32 v57, vcc, 0, v49, vcc
	global_load_dwordx4 v[36:39], v[56:57], off offset:-4096
	v_lshl_add_u64 v[44:45], v[48:49], 0, s[16:17]
	global_load_dwordx4 v[40:43], v[40:41], off offset:16
	s_nop 0
	global_load_dwordx4 v[44:47], v[44:45], off offset:16
	v_lshl_add_u64 v[60:61], v[48:49], 0, s[18:19]
	v_addc_co_u32_e64 v51, vcc, 0, v49, s[4:5]
	global_load_dwordx4 v[48:51], v[50:51], off offset:2048
	s_nop 0
	global_load_dwordx4 v[52:55], v[56:57], off
	s_nop 0
	global_load_dwordx4 v[56:59], v[56:57], off offset:2048
	s_nop 0
	global_load_dwordx4 v[60:63], v[60:61], off offset:16
	s_waitcnt vmcnt(0)
	v_mov_b32_e32 v64, v0
	v_mov_b32_e32 v65, v4
	v_mov_b32_e32 v4, v1
	v_mov_b32_e32 v0, v2
	v_mov_b32_e32 v1, v6
	v_mov_b32_e32 v6, v3
	v_mov_b32_e32 v2, v8
	v_mov_b32_e32 v3, v12
	v_mov_b32_e32 v12, v9
	v_mov_b32_e32 v8, v10
	v_mov_b32_e32 v9, v14
	v_mov_b32_e32 v14, v11
	v_pk_add_f32 v[4:5], v[64:65], v[4:5]
	v_pk_add_f32 v[0:1], v[0:1], v[6:7]
	v_pk_add_f32 v[2:3], v[2:3], v[12:13]
	v_pk_add_f32 v[6:7], v[8:9], v[14:15]
	v_pk_add_f32 v[0:1], v[4:5], v[0:1]
	v_pk_add_f32 v[2:3], v[2:3], v[6:7]
	v_mov_b32_e32 v4, v20
	v_mov_b32_e32 v5, v24
	v_mov_b32_e32 v24, v21
	v_mov_b32_e32 v6, v22
	v_mov_b32_e32 v7, v26
	v_mov_b32_e32 v26, v23
	v_mov_b32_e32 v10, v28
	v_mov_b32_e32 v11, v32
	v_mov_b32_e32 v32, v29
	v_add_f32_e32 v14, v0, v1
	v_add_f32_e32 v15, v2, v3
	v_mov_b32_e32 v12, v30
	v_mov_b32_e32 v13, v34
	v_mov_b32_e32 v34, v31
	v_pk_add_f32 v[0:1], v[4:5], v[24:25]
	v_pk_add_f32 v[2:3], v[6:7], v[26:27]
	v_pk_add_f32 v[4:5], v[10:11], v[32:33]
	ds_bpermute_b32 v10, v146, v14
	ds_bpermute_b32 v11, v146, v15
	v_pk_add_f32 v[6:7], v[12:13], v[34:35]
	v_pk_add_f32 v[0:1], v[0:1], v[2:3]
	v_pk_add_f32 v[2:3], v[4:5], v[6:7]
	v_add_f32_e32 v0, v0, v1
	v_add_f32_e32 v1, v2, v3
	ds_bpermute_b32 v2, v146, v0
	ds_bpermute_b32 v3, v146, v1
	s_waitcnt lgkmcnt(0)
	v_add_f32_e32 v4, v14, v10
	v_add_f32_e32 v5, v15, v11
	ds_bpermute_b32 v6, v147, v4
	ds_bpermute_b32 v7, v147, v5
	v_add_f32_e32 v0, v0, v2
	v_add_f32_e32 v10, v1, v3
	ds_bpermute_b32 v1, v147, v0
	s_waitcnt lgkmcnt(2)
	v_add_f32_e32 v2, v4, v6
	s_waitcnt lgkmcnt(1)
	v_add_f32_e32 v3, v5, v7
	v_fmamk_f32 v2, v2, 0x3a000000, v148
	v_fmamk_f32 v3, v3, 0x3a000000, v148
	v_mov_b32_e32 v9, v16
	v_mov_b32_e32 v8, v36
	v_rsq_f32_e32 v155, v2
	v_rsq_f32_e32 v156, v3
	v_mov_b32_e32 v16, v37
	v_mov_b32_e32 v2, v38
	v_mov_b32_e32 v3, v18
	v_mov_b32_e32 v18, v39
	s_waitcnt lgkmcnt(0)
	v_add_f32_e32 v4, v0, v1
	v_pk_add_f32 v[0:1], v[8:9], v[16:17]
	v_pk_add_f32 v[2:3], v[2:3], v[18:19]
	ds_bpermute_b32 v11, v147, v10
	v_pk_add_f32 v[0:1], v[0:1], v[2:3]
	v_fmamk_f32 v2, v4, 0x3a000000, v148
	v_add_f32_e32 v0, v0, v1
	ds_bpermute_b32 v1, v146, v0
	v_rsq_f32_e32 v157, v2
	s_waitcnt lgkmcnt(1)
	v_add_f32_e32 v2, v10, v11
	v_fmamk_f32 v4, v2, 0x3a000000, v148
	v_mov_b32_e32 v2, v50
	s_waitcnt lgkmcnt(0)
	v_add_f32_e32 v5, v0, v1
	v_mov_b32_e32 v0, v48
	v_mov_b32_e32 v1, v40
	v_mov_b32_e32 v40, v49
	v_mov_b32_e32 v3, v42
	v_mov_b32_e32 v42, v51
	v_pk_add_f32 v[0:1], v[0:1], v[40:41]
	v_pk_add_f32 v[2:3], v[2:3], v[42:43]
	ds_bpermute_b32 v6, v147, v5
	v_pk_add_f32 v[0:1], v[0:1], v[2:3]
	v_rsq_f32_e32 v158, v4
	v_add_f32_e32 v0, v0, v1
	ds_bpermute_b32 v1, v146, v0
	s_waitcnt lgkmcnt(1)
	v_add_f32_e32 v2, v5, v6
	v_fmamk_f32 v2, v2, 0x3a000000, v148
	v_rsq_f32_e32 v159, v2
	v_mov_b32_e32 v2, v54
	s_waitcnt lgkmcnt(0)
	v_add_f32_e32 v4, v0, v1
	v_mov_b32_e32 v0, v52
	v_mov_b32_e32 v1, v44
	v_mov_b32_e32 v44, v53
	v_mov_b32_e32 v3, v46
	v_mov_b32_e32 v46, v55
	v_pk_add_f32 v[0:1], v[0:1], v[44:45]
	v_pk_add_f32 v[2:3], v[2:3], v[46:47]
	ds_bpermute_b32 v5, v147, v4
	v_pk_add_f32 v[0:1], v[0:1], v[2:3]
	v_mov_b32_e32 v2, v58
	v_add_f32_e32 v6, v0, v1
	v_mov_b32_e32 v0, v56
	v_mov_b32_e32 v1, v60
	v_mov_b32_e32 v60, v57
	v_mov_b32_e32 v3, v62
	v_mov_b32_e32 v62, v59
	v_pk_add_f32 v[0:1], v[0:1], v[60:61]
	v_pk_add_f32 v[2:3], v[2:3], v[62:63]
	ds_bpermute_b32 v7, v146, v6
	v_pk_add_f32 v[0:1], v[0:1], v[2:3]
	s_waitcnt lgkmcnt(1)
	v_add_f32_e32 v2, v4, v5
	v_add_f32_e32 v0, v0, v1
	ds_bpermute_b32 v1, v146, v0
	s_waitcnt lgkmcnt(1)
	v_add_f32_e32 v3, v6, v7
	ds_bpermute_b32 v4, v147, v3
	v_fmamk_f32 v2, v2, 0x3a000000, v148
	v_rsq_f32_e32 v160, v2
	s_waitcnt lgkmcnt(1)
	v_add_f32_e32 v0, v0, v1
	ds_bpermute_b32 v1, v147, v0
	s_waitcnt lgkmcnt(1)
	v_add_f32_e32 v2, v3, v4
	v_fmamk_f32 v2, v2, 0x3a000000, v148
	v_rsq_f32_e32 v161, v2
	s_waitcnt lgkmcnt(0)
	v_add_f32_e32 v0, v0, v1
	v_fmamk_f32 v0, v0, 0x3a000000, v148
	v_rsq_f32_e32 v162, v0
	s_branch .LBB0_253

; #define PG8_STAGE(bufoff, gbase, voff) do { _Pragma("unroll") for (int _i = 0; _i < 2; ++_i) \
;         __builtin_amdgcn_global_load_lds((const unsigned*)((const char*)(gbase) + (voff)[_i]), (LAS unsigned*)(lds + (bufoff) + ldsw + _i * 8192), 16, 0, 0); } while (0)
; #define PG8_LDA(dst, b, h) do { _Pragma("unroll") for (int m = 0; m < 4; ++m) _Pragma("unroll") for (int k = 0; k < 2; ++k) dst[m][k] = *(const LAS bf16x8*)(lds + PG8_SA(b, h) + aoff + m * 2048 + k * 1024); } while (0)
; #define PG8_LDB(dst, b, h) do { _Pragma("unroll") for (int n = 0; n < 2; ++n) _Pragma("unroll") for (int k = 0; k < 2; ++k) dst[n][k] = *(const LAS bf16x8*)(lds + PG8_SB(b, h) + boff + n * 2048 + k * 1024); } while (0)
; #define PG8_MMA(ai, bj, At, Bt) do { __builtin_amdgcn_s_setprio(1); _Pragma("unroll") for (int m = 0; m < 4; ++m) _Pragma("unroll") for (int n = 0; n < 2; ++n) _Pragma("unroll") for (int k = 0; k < 2; ++k) \
;         acc[ai][bj][m][n] = __builtin_amdgcn_mfma_f32_16x16x32_bf16(Bt[n][k], At[m][k], acc[ai][bj][m][n], 0, 0, 0); __builtin_amdgcn_s_setprio(0); } while (0)
; #define PG8_WAIT_V(n) asm volatile("s_waitcnt vmcnt(" #n ")" ::: "memory")
; #define PG8_WAIT_L(n) asm volatile("s_waitcnt lgkmcnt(" #n ")" ::: "memory")
; #define PG8_BAR __builtin_amdgcn_s_barrier()
; #define PG8_SCHED __builtin_amdgcn_sched_barrier(0)
; template <class Epi>
; __device__ __forceinline__ void gemm_phase(LAS unsigned char* lds, const GSched& S, const int K, const int lda, const int ldb, const Epi& E) {
;     ...
;             PG8_LDB(B0, 0, 0); PG8_SCHED; PG8_LDA(At, 0, 0); PG8_STAGE(PG8_SA(1, 1), a1 + hstepA, voffA);
;             PG8_WAIT_L(8); PG8_BAR; PG8_WAIT_L(0); PG8_MMA(0, 0, At, B0); PG8_BAR; PG8_SCHED;
;             if constexpr (!Epi::NARROW) PG8_LDB(B1, 0, 1); PG8_STAGE(PG8_SB(0, 0), b2, voffB);
;             PG8_BAR; PG8_WAIT_L(0); if constexpr (!Epi::NARROW) PG8_MMA(0, 1, At, B1); PG8_BAR;
;             PG8_LDA(At, 0, 1); PG8_STAGE(PG8_SA(0, 0), a2, voffA);
;             PG8_BAR; PG8_WAIT_L(0); PG8_MMA(1, 0, At, B0); PG8_BAR; PG8_SCHED;
;             PG8_STAGE(PG8_SB(0, 1), b2 + hstepB, voffB);
;             PG8_WAIT_V(6); PG8_BAR; if constexpr (!Epi::NARROW) PG8_MMA(1, 1, At, B1); PG8_BAR;
.LBB0_343:
	ds_read_b128 v[128:131], v205
	ds_read_b128 v[132:135], v205 offset:1024
	ds_read_b128 v[136:139], v205 offset:2048
	ds_read_b128 v[140:143], v205 offset:3072
	s_add_u32 s26, s24, 0x100
	s_addc_u32 s27, s25, 0
	s_cmpk_eq_i32 s54, 0x54
	s_cselect_b32 s31, s11, s27
	s_cselect_b32 s30, s10, s26
	s_cselect_b32 s29, s13, s53
	s_cselect_b32 s28, s12, s52
	v_lshl_add_u64 v[192:193], s[24:25], 0, v[186:187]
	s_add_i32 m0, s35, 0xc000
	ds_read_b128 v[144:147], v206
	ds_read_b128 v[148:151], v206 offset:1024
	ds_read_b128 v[152:155], v206 offset:2048
	ds_read_b128 v[156:159], v206 offset:3072
	ds_read_b128 v[160:163], v206 offset:4096
	ds_read_b128 v[164:167], v206 offset:5120
	ds_read_b128 v[168:171], v206 offset:6144
	ds_read_b128 v[172:175], v206 offset:7168
	global_load_lds_dwordx4 v[192:193], off
	v_lshl_add_u64 v[192:193], s[24:25], 0, v[184:185]
	s_add_i32 m0, s35, 0xe000
	s_nop 0
	global_load_lds_dwordx4 v[192:193], off
	s_waitcnt lgkmcnt(8)
	s_barrier
	s_waitcnt lgkmcnt(0)
	s_setprio 1
	s_waitcnt lgkmcnt(0)
	v_mfma_f32_16x16x32_bf16 v[124:127], v[128:131], v[144:147], v[124:127]
	v_mfma_f32_16x16x32_bf16 v[120:123], v[136:139], v[144:147], v[120:123]
	v_mfma_f32_16x16x32_bf16 v[108:111], v[128:131], v[152:155], v[108:111]
	v_mfma_f32_16x16x32_bf16 v[104:107], v[136:139], v[152:155], v[104:107]
	v_mfma_f32_16x16x32_bf16 v[92:95], v[128:131], v[160:163], v[92:95]
	v_mfma_f32_16x16x32_bf16 v[88:91], v[136:139], v[160:163], v[88:91]
	v_mfma_f32_16x16x32_bf16 v[76:79], v[128:131], v[168:171], v[76:79]
	v_mfma_f32_16x16x32_bf16 v[72:75], v[136:139], v[168:171], v[72:75]
	v_mfma_f32_16x16x32_bf16 v[124:127], v[132:135], v[148:151], v[124:127]
	v_mfma_f32_16x16x32_bf16 v[120:123], v[140:143], v[148:151], v[120:123]
	v_mfma_f32_16x16x32_bf16 v[108:111], v[132:135], v[156:159], v[108:111]
	v_mfma_f32_16x16x32_bf16 v[104:107], v[140:143], v[156:159], v[104:107]
	v_mfma_f32_16x16x32_bf16 v[92:95], v[132:135], v[164:167], v[92:95]
	v_mfma_f32_16x16x32_bf16 v[88:91], v[140:143], v[164:167], v[88:91]
	v_mfma_f32_16x16x32_bf16 v[76:79], v[132:135], v[172:175], v[76:79]
	v_mfma_f32_16x16x32_bf16 v[72:75], v[140:143], v[172:175], v[72:75]
	s_setprio 0
	s_barrier
	s_add_i32 s3, s45, s2
	v_lshl_add_u64 v[200:201], s[28:29], 0, v[178:179]
	s_mov_b32 m0, s3
	ds_read_b128 v[192:195], v207
	ds_read_b128 v[196:199], v207 offset:1024
	ds_read_b128 v[210:213], v207 offset:2048
	ds_read_b128 v[214:217], v207 offset:3072
	global_load_lds_dwordx4 v[200:201], off
	v_lshl_add_u64 v[218:219], s[28:29], 0, v[182:183]
	s_add_i32 m0, s3, 0x2000
	s_nop 0
	global_load_lds_dwordx4 v[218:219], off
	s_barrier
	s_waitcnt lgkmcnt(0)
	s_setprio 1
	v_mfma_f32_16x16x32_bf16 v[116:119], v[192:195], v[144:147], v[116:119]
	v_mfma_f32_16x16x32_bf16 v[112:115], v[210:213], v[144:147], v[112:115]
	v_mfma_f32_16x16x32_bf16 v[100:103], v[192:195], v[152:155], v[100:103]
	v_mfma_f32_16x16x32_bf16 v[96:99], v[210:213], v[152:155], v[96:99]
	v_mfma_f32_16x16x32_bf16 v[84:87], v[192:195], v[160:163], v[84:87]
	v_mfma_f32_16x16x32_bf16 v[80:83], v[210:213], v[160:163], v[80:83]
	v_mfma_f32_16x16x32_bf16 v[68:71], v[192:195], v[168:171], v[68:71]
	v_mfma_f32_16x16x32_bf16 v[64:67], v[210:213], v[168:171], v[64:67]
	v_mfma_f32_16x16x32_bf16 v[116:119], v[196:199], v[148:151], v[116:119]
	v_mfma_f32_16x16x32_bf16 v[112:115], v[214:217], v[148:151], v[112:115]
	v_mfma_f32_16x16x32_bf16 v[100:103], v[196:199], v[156:159], v[100:103]
	v_mfma_f32_16x16x32_bf16 v[96:99], v[214:217], v[156:159], v[96:99]
	v_mfma_f32_16x16x32_bf16 v[84:87], v[196:199], v[164:167], v[84:87]
	v_mfma_f32_16x16x32_bf16 v[80:83], v[214:217], v[164:167], v[80:83]
	v_mfma_f32_16x16x32_bf16 v[68:71], v[196:199], v[172:175], v[68:71]
	v_mfma_f32_16x16x32_bf16 v[64:67], v[214:217], v[172:175], v[64:67]
	s_setprio 0
	s_mov_b32 m0, s35
	v_lshl_add_u64 v[220:221], s[30:31], 0, v[176:177]
	s_barrier
	ds_read_b128 v[144:147], v206 offset:16384
	ds_read_b128 v[148:151], v206 offset:17408
	ds_read_b128 v[152:155], v206 offset:18432
	ds_read_b128 v[156:159], v206 offset:19456
	ds_read_b128 v[160:163], v206 offset:20480
	ds_read_b128 v[164:167], v206 offset:21504
	ds_read_b128 v[168:171], v206 offset:22528
	ds_read_b128 v[172:175], v206 offset:23552
	global_load_lds_dwordx4 v[220:221], off
	v_lshl_add_u64 v[222:223], s[30:31], 0, v[180:181]
	s_mov_b32 m0, s36
	s_nop 0
	global_load_lds_dwordx4 v[222:223], off
	s_barrier
	s_waitcnt lgkmcnt(0)
	s_setprio 1
	v_mfma_f32_16x16x32_bf16 v[60:63], v[128:131], v[144:147], v[60:63]
	v_mfma_f32_16x16x32_bf16 v[56:59], v[136:139], v[144:147], v[56:59]
	v_mfma_f32_16x16x32_bf16 v[44:47], v[128:131], v[152:155], v[44:47]
	v_mfma_f32_16x16x32_bf16 v[40:43], v[136:139], v[152:155], v[40:43]
	v_mfma_f32_16x16x32_bf16 v[28:31], v[128:131], v[160:163], v[28:31]
	v_mfma_f32_16x16x32_bf16 v[24:27], v[136:139], v[160:163], v[24:27]
	v_mfma_f32_16x16x32_bf16 v[12:15], v[128:131], v[168:171], v[12:15]
	v_mfma_f32_16x16x32_bf16 v[8:11], v[136:139], v[168:171], v[8:11]
	v_mfma_f32_16x16x32_bf16 v[60:63], v[132:135], v[148:151], v[60:63]
	v_mfma_f32_16x16x32_bf16 v[56:59], v[140:143], v[148:151], v[56:59]
	v_mfma_f32_16x16x32_bf16 v[44:47], v[132:135], v[156:159], v[44:47]
	v_mfma_f32_16x16x32_bf16 v[40:43], v[140:143], v[156:159], v[40:43]
	v_mfma_f32_16x16x32_bf16 v[28:31], v[132:135], v[164:167], v[28:31]
	v_mfma_f32_16x16x32_bf16 v[24:27], v[140:143], v[164:167], v[24:27]
	v_mfma_f32_16x16x32_bf16 v[12:15], v[132:135], v[172:175], v[12:15]
	v_mfma_f32_16x16x32_bf16 v[8:11], v[140:143], v[172:175], v[8:11]
	s_setprio 0
	s_barrier
; #define PG8_STAGE(bufoff, gbase, voff) do { _Pragma("unroll") for (int _i = 0; _i < 2; ++_i) \
;         __builtin_amdgcn_global_load_lds((const unsigned*)((const char*)(gbase) + (voff)[_i]), (LAS unsigned*)(lds + (bufoff) + ldsw + _i * 8192), 16, 0, 0); } while (0)
; #define PG8_LDA(dst, b, h) do { _Pragma("unroll") for (int m = 0; m < 4; ++m) _Pragma("unroll") for (int k = 0; k < 2; ++k) dst[m][k] = *(const LAS bf16x8*)(lds + PG8_SA(b, h) + aoff + m * 2048 + k * 1024); } while (0)
; #define PG8_LDB(dst, b, h) do { _Pragma("unroll") for (int n = 0; n < 2; ++n) _Pragma("unroll") for (int k = 0; k < 2; ++k) dst[n][k] = *(const LAS bf16x8*)(lds + PG8_SB(b, h) + boff + n * 2048 + k * 1024); } while (0)
; #define PG8_MMA(ai, bj, At, Bt) do { __builtin_amdgcn_s_setprio(1); _Pragma("unroll") for (int m = 0; m < 4; ++m) _Pragma("unroll") for (int n = 0; n < 2; ++n) _Pragma("unroll") for (int k = 0; k < 2; ++k) \
;         acc[ai][bj][m][n] = __builtin_amdgcn_mfma_f32_16x16x32_bf16(Bt[n][k], At[m][k], acc[ai][bj][m][n], 0, 0, 0); __builtin_amdgcn_s_setprio(0); } while (0)
; #define PG8_WAIT_V(n) asm volatile("s_waitcnt vmcnt(" #n ")" ::: "memory")
; #define PG8_WAIT_L(n) asm volatile("s_waitcnt lgkmcnt(" #n ")" ::: "memory")
; #define PG8_BAR __builtin_amdgcn_s_barrier()
; #define PG8_SCHED __builtin_amdgcn_sched_barrier(0)
; template <class Epi>
; __device__ __forceinline__ void gemm_phase(LAS unsigned char* lds, const GSched& S, const int K, const int lda, const int ldb, const Epi& E) {
;     ...
;             PG8_STAGE(PG8_SB(0, 1), b2 + hstepB, voffB);
;             PG8_WAIT_V(6); PG8_BAR; if constexpr (!Epi::NARROW) PG8_MMA(1, 1, At, B1); PG8_BAR;
;             PG8_LDB(B0, 1, 0); PG8_SCHED; PG8_LDA(At, 1, 0); PG8_STAGE(PG8_SA(0, 1), a2 + hstepA, voffA);
;             PG8_WAIT_L(8); PG8_BAR; PG8_WAIT_L(0); PG8_MMA(0, 0, At, B0); PG8_BAR; PG8_SCHED;
;             if constexpr (!Epi::NARROW) PG8_LDB(B1, 1, 1); PG8_STAGE(PG8_SB(1, 0), b3, voffB);
;             PG8_BAR; PG8_WAIT_L(0); if constexpr (!Epi::NARROW) PG8_MMA(0, 1, At, B1); PG8_BAR;
;             PG8_LDA(At, 1, 1); PG8_STAGE(PG8_SA(1, 0), a3, voffA);
;             PG8_BAR; PG8_WAIT_L(0); PG8_MMA(1, 0, At, B0); PG8_BAR; PG8_SCHED;
	s_add_u32 s24, s28, 0x164000
	s_addc_u32 s25, s29, 0
	s_add_i32 s3, s46, s2
	v_lshl_add_u64 v[128:129], s[24:25], 0, v[178:179]
	s_mov_b32 m0, s3
	s_nop 0
	global_load_lds_dwordx4 v[128:129], off
	v_lshl_add_u64 v[128:129], s[24:25], 0, v[182:183]
	s_add_i32 m0, s3, 0x2000
	s_nop 0
	global_load_lds_dwordx4 v[128:129], off
	s_waitcnt vmcnt(6)
	s_barrier
	s_setprio 1
	v_mfma_f32_16x16x32_bf16 v[52:55], v[192:195], v[144:147], v[52:55]
	v_mfma_f32_16x16x32_bf16 v[48:51], v[210:213], v[144:147], v[48:51]
	v_mfma_f32_16x16x32_bf16 v[36:39], v[192:195], v[152:155], v[36:39]
	v_mfma_f32_16x16x32_bf16 v[32:35], v[210:213], v[152:155], v[32:35]
	v_mfma_f32_16x16x32_bf16 v[20:23], v[192:195], v[160:163], v[20:23]
	v_mfma_f32_16x16x32_bf16 v[16:19], v[210:213], v[160:163], v[16:19]
	v_mfma_f32_16x16x32_bf16 v[4:7], v[192:195], v[168:171], v[4:7]
	v_mfma_f32_16x16x32_bf16 v[0:3], v[210:213], v[168:171], v[0:3]
	v_mfma_f32_16x16x32_bf16 v[52:55], v[196:199], v[148:151], v[52:55]
	v_mfma_f32_16x16x32_bf16 v[48:51], v[214:217], v[148:151], v[48:51]
	v_mfma_f32_16x16x32_bf16 v[36:39], v[196:199], v[156:159], v[36:39]
	v_mfma_f32_16x16x32_bf16 v[32:35], v[214:217], v[156:159], v[32:35]
	v_mfma_f32_16x16x32_bf16 v[20:23], v[196:199], v[164:167], v[20:23]
	v_mfma_f32_16x16x32_bf16 v[16:19], v[214:217], v[164:167], v[16:19]
	v_mfma_f32_16x16x32_bf16 v[4:7], v[196:199], v[172:175], v[4:7]
	v_mfma_f32_16x16x32_bf16 v[0:3], v[214:217], v[172:175], v[0:3]
	s_setprio 0
	s_add_i32 s3, 0, 0x18000
	v_add_u32_e32 v140, s3, v203
	s_barrier
	ds_read_b128 v[128:131], v140
	ds_read_b128 v[132:135], v140 offset:1024
	ds_read_b128 v[136:139], v140 offset:2048
	ds_read_b128 v[140:143], v140 offset:3072
	s_add_u32 s24, s30, 0x164000
	s_addc_u32 s25, s31, 0
	s_mov_b32 m0, s37
	v_lshl_add_u64 v[192:193], s[24:25], 0, v[176:177]
	ds_read_b128 v[144:147], v206 offset:32768
	ds_read_b128 v[148:151], v206 offset:33792
	ds_read_b128 v[152:155], v206 offset:34816
	ds_read_b128 v[156:159], v206 offset:35840
	ds_read_b128 v[160:163], v206 offset:36864
	ds_read_b128 v[164:167], v206 offset:37888
	ds_read_b128 v[168:171], v206 offset:38912
	ds_read_b128 v[172:175], v206 offset:39936
	global_load_lds_dwordx4 v[192:193], off
	v_lshl_add_u64 v[192:193], s[24:25], 0, v[180:181]
	s_mov_b32 m0, s38
	s_nop 0
	global_load_lds_dwordx4 v[192:193], off
	s_waitcnt lgkmcnt(8)
	s_barrier
	s_waitcnt lgkmcnt(0)
	s_setprio 1
	s_waitcnt lgkmcnt(0)
	v_mfma_f32_16x16x32_bf16 v[124:127], v[128:131], v[144:147], v[124:127]
	v_mfma_f32_16x16x32_bf16 v[120:123], v[136:139], v[144:147], v[120:123]
	v_mfma_f32_16x16x32_bf16 v[108:111], v[128:131], v[152:155], v[108:111]
	v_mfma_f32_16x16x32_bf16 v[104:107], v[136:139], v[152:155], v[104:107]
	v_mfma_f32_16x16x32_bf16 v[92:95], v[128:131], v[160:163], v[92:95]
	v_mfma_f32_16x16x32_bf16 v[88:91], v[136:139], v[160:163], v[88:91]
	v_mfma_f32_16x16x32_bf16 v[76:79], v[128:131], v[168:171], v[76:79]
	v_mfma_f32_16x16x32_bf16 v[72:75], v[136:139], v[168:171], v[72:75]
	v_mfma_f32_16x16x32_bf16 v[124:127], v[132:135], v[148:151], v[124:127]
	v_mfma_f32_16x16x32_bf16 v[120:123], v[140:143], v[148:151], v[120:123]
	v_mfma_f32_16x16x32_bf16 v[108:111], v[132:135], v[156:159], v[108:111]
	v_mfma_f32_16x16x32_bf16 v[104:107], v[140:143], v[156:159], v[104:107]
	v_mfma_f32_16x16x32_bf16 v[92:95], v[132:135], v[164:167], v[92:95]
	v_mfma_f32_16x16x32_bf16 v[88:91], v[140:143], v[164:167], v[88:91]
	v_mfma_f32_16x16x32_bf16 v[76:79], v[132:135], v[172:175], v[76:79]
	v_mfma_f32_16x16x32_bf16 v[72:75], v[140:143], v[172:175], v[72:75]
	s_setprio 0
	s_barrier
	s_add_i32 s30, 0, 0x1c000
	s_add_i32 s3, s3, s2
	v_add_u32_e32 v209, s30, v203
	v_lshl_add_u64 v[200:201], v[200:201], 0, s[22:23]
	s_mov_b32 m0, s3
	ds_read_b128 v[192:195], v209
	ds_read_b128 v[196:199], v209 offset:1024
	ds_read_b128 v[210:213], v209 offset:2048
	ds_read_b128 v[214:217], v209 offset:3072
	global_load_lds_dwordx4 v[200:201], off
	v_lshl_add_u64 v[200:201], v[218:219], 0, s[22:23]
	s_add_i32 m0, s3, 0x2000
	s_nop 0
	global_load_lds_dwordx4 v[200:201], off
	s_barrier
	s_waitcnt lgkmcnt(0)
	s_setprio 1
	s_waitcnt lgkmcnt(0)
	v_mfma_f32_16x16x32_bf16 v[116:119], v[192:195], v[144:147], v[116:119]
	v_mfma_f32_16x16x32_bf16 v[112:115], v[210:213], v[144:147], v[112:115]
	v_mfma_f32_16x16x32_bf16 v[100:103], v[192:195], v[152:155], v[100:103]
	v_mfma_f32_16x16x32_bf16 v[96:99], v[210:213], v[152:155], v[96:99]
	v_mfma_f32_16x16x32_bf16 v[84:87], v[192:195], v[160:163], v[84:87]
	v_mfma_f32_16x16x32_bf16 v[80:83], v[210:213], v[160:163], v[80:83]
	v_mfma_f32_16x16x32_bf16 v[68:71], v[192:195], v[168:171], v[68:71]
	v_mfma_f32_16x16x32_bf16 v[64:67], v[210:213], v[168:171], v[64:67]
	v_mfma_f32_16x16x32_bf16 v[116:119], v[196:199], v[148:151], v[116:119]
	v_mfma_f32_16x16x32_bf16 v[112:115], v[214:217], v[148:151], v[112:115]
	v_mfma_f32_16x16x32_bf16 v[100:103], v[196:199], v[156:159], v[100:103]
	v_mfma_f32_16x16x32_bf16 v[96:99], v[214:217], v[156:159], v[96:99]
	v_mfma_f32_16x16x32_bf16 v[84:87], v[196:199], v[164:167], v[84:87]
	v_mfma_f32_16x16x32_bf16 v[80:83], v[214:217], v[164:167], v[80:83]
	v_mfma_f32_16x16x32_bf16 v[68:71], v[196:199], v[172:175], v[68:71]
	v_mfma_f32_16x16x32_bf16 v[64:67], v[214:217], v[172:175], v[64:67]
	s_setprio 0
	s_mov_b32 m0, s40
	v_lshl_add_u64 v[200:201], v[220:221], 0, s[22:23]
	s_barrier
	ds_read_b128 v[144:147], v206 offset:49152
	ds_read_b128 v[148:151], v206 offset:50176
	ds_read_b128 v[152:155], v206 offset:51200
	ds_read_b128 v[156:159], v206 offset:52224
	ds_read_b128 v[160:163], v206 offset:53248
	ds_read_b128 v[164:167], v206 offset:54272
	ds_read_b128 v[168:171], v206 offset:55296
	ds_read_b128 v[172:175], v206 offset:56320
	global_load_lds_dwordx4 v[200:201], off
	v_lshl_add_u64 v[200:201], v[222:223], 0, s[22:23]
	s_mov_b32 m0, s41
	s_nop 0
	global_load_lds_dwordx4 v[200:201], off
	s_barrier
; #define PG8_STAGE(bufoff, gbase, voff) do { _Pragma("unroll") for (int _i = 0; _i < 2; ++_i) \
;         __builtin_amdgcn_global_load_lds((const unsigned*)((const char*)(gbase) + (voff)[_i]), (LAS unsigned*)(lds + (bufoff) + ldsw + _i * 8192), 16, 0, 0); } while (0)
; #define PG8_MMA(ai, bj, At, Bt) do { __builtin_amdgcn_s_setprio(1); _Pragma("unroll") for (int m = 0; m < 4; ++m) _Pragma("unroll") for (int n = 0; n < 2; ++n) _Pragma("unroll") for (int k = 0; k < 2; ++k) \
;         acc[ai][bj][m][n] = __builtin_amdgcn_mfma_f32_16x16x32_bf16(Bt[n][k], At[m][k], acc[ai][bj][m][n], 0, 0, 0); __builtin_amdgcn_s_setprio(0); } while (0)
; #define PG8_WAIT_V(n) asm volatile("s_waitcnt vmcnt(" #n ")" ::: "memory")
; #define PG8_WAIT_L(n) asm volatile("s_waitcnt lgkmcnt(" #n ")" ::: "memory")
; #define PG8_BAR __builtin_amdgcn_s_barrier()
; #define PG8_SCHED __builtin_amdgcn_sched_barrier(0)
; template <class Epi>
; __device__ __forceinline__ void gemm_phase(LAS unsigned char* lds, const GSched& S, const int K, const int lda, const int ldb, const Epi& E) {
;     ...
;             PG8_BAR; PG8_WAIT_L(0); PG8_MMA(1, 0, At, B0); PG8_BAR; PG8_SCHED;
;             PG8_STAGE(PG8_SB(1, 1), b3 + hstepB, voffB);
;             PG8_WAIT_V(6); PG8_BAR; if constexpr (!Epi::NARROW) PG8_MMA(1, 1, At, B1); PG8_BAR;
;             if constexpr (Epi::HAS_MID) { if (t + 2 == E.mid_t) { PG8_SCHED; E.mid(acc, cur, wr, wc, fr, fq); PG8_SCHED; } }
;         }
	s_waitcnt lgkmcnt(0)
	s_setprio 1
	v_mfma_f32_16x16x32_bf16 v[60:63], v[128:131], v[144:147], v[60:63]
	v_mfma_f32_16x16x32_bf16 v[56:59], v[136:139], v[144:147], v[56:59]
	v_mfma_f32_16x16x32_bf16 v[44:47], v[128:131], v[152:155], v[44:47]
	v_mfma_f32_16x16x32_bf16 v[40:43], v[136:139], v[152:155], v[40:43]
	v_mfma_f32_16x16x32_bf16 v[28:31], v[128:131], v[160:163], v[28:31]
	v_mfma_f32_16x16x32_bf16 v[24:27], v[136:139], v[160:163], v[24:27]
	v_mfma_f32_16x16x32_bf16 v[12:15], v[128:131], v[168:171], v[12:15]
	v_mfma_f32_16x16x32_bf16 v[8:11], v[136:139], v[168:171], v[8:11]
	v_mfma_f32_16x16x32_bf16 v[60:63], v[132:135], v[148:151], v[60:63]
	v_mfma_f32_16x16x32_bf16 v[56:59], v[140:143], v[148:151], v[56:59]
	v_mfma_f32_16x16x32_bf16 v[44:47], v[132:135], v[156:159], v[44:47]
	v_mfma_f32_16x16x32_bf16 v[40:43], v[140:143], v[156:159], v[40:43]
	v_mfma_f32_16x16x32_bf16 v[28:31], v[132:135], v[164:167], v[28:31]
	v_mfma_f32_16x16x32_bf16 v[24:27], v[140:143], v[164:167], v[24:27]
	v_mfma_f32_16x16x32_bf16 v[12:15], v[132:135], v[172:175], v[12:15]
	v_mfma_f32_16x16x32_bf16 v[8:11], v[140:143], v[172:175], v[8:11]
	s_setprio 0
	s_barrier
	s_add_u32 s24, s28, 0x164080
	s_addc_u32 s25, s29, 0
	s_add_i32 s3, s30, s2
	v_lshl_add_u64 v[128:129], s[24:25], 0, v[178:179]
	s_mov_b32 m0, s3
	s_nop 0
	global_load_lds_dwordx4 v[128:129], off
	v_lshl_add_u64 v[128:129], s[24:25], 0, v[182:183]
	s_add_i32 m0, s3, 0x2000
	s_nop 0
	global_load_lds_dwordx4 v[128:129], off
	s_waitcnt vmcnt(6)
	s_barrier
	s_setprio 1
	v_mfma_f32_16x16x32_bf16 v[52:55], v[192:195], v[144:147], v[52:55]
	v_mfma_f32_16x16x32_bf16 v[48:51], v[210:213], v[144:147], v[48:51]
	v_mfma_f32_16x16x32_bf16 v[36:39], v[192:195], v[152:155], v[36:39]
	v_mfma_f32_16x16x32_bf16 v[32:35], v[210:213], v[152:155], v[32:35]
	v_mfma_f32_16x16x32_bf16 v[20:23], v[192:195], v[160:163], v[20:23]
	v_mfma_f32_16x16x32_bf16 v[16:19], v[210:213], v[160:163], v[16:19]
	v_mfma_f32_16x16x32_bf16 v[4:7], v[192:195], v[168:171], v[4:7]
	v_mfma_f32_16x16x32_bf16 v[0:3], v[210:213], v[168:171], v[0:3]
	v_mfma_f32_16x16x32_bf16 v[52:55], v[196:199], v[148:151], v[52:55]
	v_mfma_f32_16x16x32_bf16 v[48:51], v[214:217], v[148:151], v[48:51]
	v_mfma_f32_16x16x32_bf16 v[36:39], v[196:199], v[156:159], v[36:39]
	v_mfma_f32_16x16x32_bf16 v[32:35], v[214:217], v[156:159], v[32:35]
	v_mfma_f32_16x16x32_bf16 v[20:23], v[196:199], v[164:167], v[20:23]
	v_mfma_f32_16x16x32_bf16 v[16:19], v[214:217], v[164:167], v[16:19]
	v_mfma_f32_16x16x32_bf16 v[4:7], v[196:199], v[172:175], v[4:7]
	v_mfma_f32_16x16x32_bf16 v[0:3], v[214:217], v[172:175], v[0:3]
	s_setprio 0
	s_add_i32 s54, s54, 2
	s_add_u32 s52, s52, 0x100
	s_addc_u32 s53, s53, 0
	s_cmpk_gt_u32 s54, 0x55
	s_mov_b64 s[24:25], s[26:27]
	s_barrier
	s_cbranch_scc0 .LBB0_343
; __device__ __forceinline__ f32x4 ld_nt(const float* p) { return __builtin_nontemporal_load((const f32x4*)p); }
; __device__ __forceinline__ u32x4 ld_nt(const bf16_t* p) { return __builtin_nontemporal_load((const u32x4*)p); }
; __device__ __forceinline__ float sumsq4(const f32x4 v) { return (v[0] * v[0] + v[1] * v[1]) + (v[2] * v[2] + v[3] * v[3]); }
; __device__ __forceinline__ u32x4 pack8(const f32x4 a, const f32x4 b) { u32x4 w; w.x = cvt_pk_bf16(a[0], a[1]); w.y = cvt_pk_bf16(a[2], a[3]); w.z = cvt_pk_bf16(b[0], b[1]); w.w = cvt_pk_bf16(b[2], b[3]); return w; }
;     __device__ __forceinline__ void operator()(Acc& acc, const Unit& u, int wr, int wc, int fr, int fq, const float (&rsv)[8]) const {
;         const int row0 = u.pm * BM + wr * 64 + fr, col0 = u.pn * BM + wc * 32 + 8 * fq;
;         if constexpr (F32IN) {
;             f32x4 w[4][4];
; #pragma unroll
;             for (int g = 0; g < 4; ++g) { const float* hp = hin + (size_t)(row0 + (g >> 2) * HALF + (g & 3) * 16) * DM + col0;
;                 w[g][0] = ld_nt(hp); w[g][1] = ld_nt(hp + 4); w[g][2] = ld_nt(hp + HALF); w[g][3] = ld_nt(hp + HALF + 4); }
; #pragma unroll
;             for (int g = 0; g < 8; ++g) {
;                 const int ai = g >> 2, m = g & 3, s = g & 3;
;                 const int row = row0 + ai * HALF + m * 16;
;                 float ss = 0.f;
; #pragma unroll
;                 for (int bj = 0; bj < 2; ++bj) {
;                     const f32x4 v0 = w[s][bj * 2] + acc[ai][bj][m][0] * scale, v1 = w[s][bj * 2 + 1] + acc[ai][bj][m][1] * scale;
;                     ss += sumsq4(v0) + sumsq4(v1);
;                     *(u32x4*)(hb + (size_t)row * LDHB + 256 + col0 + bj * HALF) = pack8(v0, v1); }
;                 ss += __shfl_xor(ss, 16); ss += __shfl_xor(ss, 32);
;                 if (fq == 0) part[(size_t)row * 32 + u.pn * 4 + wc] = ss;
;                 asm volatile("" ::: "memory");
;                 if (g + 4 < 8) { const int g4 = g + 4; const float* hp = hin + (size_t)(row0 + (g4 >> 2) * HALF + (g4 & 3) * 16) * DM + col0;
;                     w[s][0] = ld_nt(hp); w[s][1] = ld_nt(hp + 4); w[s][2] = ld_nt(hp + HALF); w[s][3] = ld_nt(hp + HALF + 4); }
;             }
	v_lshl_add_u32 v196, s51, 8, v202
	v_lshl_or_b32 v192, s16, 8, v204
	v_ashrrev_i32_e32 v193, 31, v192
	v_ashrrev_i32_e32 v197, 31, v196
	v_lshl_add_u64 v[128:129], v[192:193], 2, s[14:15]
	v_lshlrev_b64 v[130:131], 13, v[196:197]
	v_lshl_add_u64 v[130:131], v[128:129], 0, v[130:131]
	global_load_dwordx4 v[212:215], v[130:131], off nt
	global_load_dwordx4 v[216:219], v[130:131], off offset:16 nt
	global_load_dwordx4 v[220:223], v[130:131], off offset:512 nt
	global_load_dwordx4 v[224:227], v[130:131], off offset:528 nt
	v_or_b32_e32 v200, 16, v196
	v_or_b32_e32 v198, 32, v196
	v_or_b32_e32 v194, 48, v196
	v_ashrrev_i32_e32 v201, 31, v200
	v_ashrrev_i32_e32 v199, 31, v198
	v_ashrrev_i32_e32 v195, 31, v194
	v_lshlrev_b64 v[130:131], 13, v[200:201]
	v_lshlrev_b64 v[132:133], 13, v[198:199]
	v_lshlrev_b64 v[134:135], 13, v[194:195]
	v_lshl_add_u64 v[130:131], v[128:129], 0, v[130:131]
	v_lshl_add_u64 v[132:133], v[128:129], 0, v[132:133]
	v_lshl_add_u64 v[134:135], v[128:129], 0, v[134:135]
	global_load_dwordx4 v[168:171], v[130:131], off offset:16 nt
	global_load_dwordx4 v[172:175], v[130:131], off nt
	global_load_dwordx4 v[160:163], v[130:131], off offset:528 nt
	global_load_dwordx4 v[164:167], v[130:131], off offset:512 nt
	global_load_dwordx4 v[152:155], v[132:133], off offset:16 nt
	global_load_dwordx4 v[156:159], v[132:133], off nt
	global_load_dwordx4 v[144:147], v[132:133], off offset:528 nt
	global_load_dwordx4 v[148:151], v[132:133], off offset:512 nt
	global_load_dwordx4 v[136:139], v[134:135], off offset:16 nt
	global_load_dwordx4 v[140:143], v[134:135], off nt
	global_load_dwordx4 v[128:131], v[134:135], off offset:528 nt
	s_nop 0
	global_load_dwordx4 v[132:135], v[134:135], off offset:512 nt
	v_and_b32_e32 v210, 64, v208
	v_xor_b32_e32 v209, 16, v208
	v_add_u32_e32 v210, 64, v210
	v_xor_b32_e32 v211, 32, v208
	v_cmp_lt_i32_e32 vcc, v209, v210
	v_mov_b64_e32 v[228:229], s[18:19]
	s_lshl_b32 s24, s16, 2
	v_cndmask_b32_e32 v209, v208, v209, vcc
	v_cmp_lt_i32_e32 vcc, v211, v210
	v_lshlrev_b32_e32 v210, 2, v209
	s_ashr_i32 s25, s24, 31
	v_cndmask_b32_e32 v211, v208, v211, vcc
	v_lshlrev_b32_e32 v209, 2, v211
	s_waitcnt vmcnt(0)
	v_pk_fma_f32 v[126:127], v[126:127], 0.5, v[214:215] op_sel_hi:[1,0,1]
	v_pk_fma_f32 v[124:125], v[124:125], 0.5, v[212:213] op_sel_hi:[1,0,1]
	v_pk_fma_f32 v[122:123], v[122:123], 0.5, v[218:219] op_sel_hi:[1,0,1]
	v_pk_fma_f32 v[120:121], v[120:121], 0.5, v[216:217] op_sel_hi:[1,0,1]
	v_pk_fma_f32 v[118:119], v[118:119], 0.5, v[222:223] op_sel_hi:[1,0,1]
	v_pk_fma_f32 v[116:117], v[116:117], 0.5, v[220:221] op_sel_hi:[1,0,1]
	v_pk_fma_f32 v[212:213], v[114:115], 0.5, v[226:227] op_sel_hi:[1,0,1]
	v_pk_fma_f32 v[214:215], v[112:113], 0.5, v[224:225] op_sel_hi:[1,0,1]
	v_mul_f32_e32 v211, v125, v125
	v_mul_f32_e32 v216, v127, v127
	v_mul_f32_e32 v217, v121, v121
	v_mul_f32_e32 v218, v123, v123
	v_cvt_pk_bf16_f32 v112, v124, v125
	v_cvt_pk_bf16_f32 v113, v126, v127
	v_cvt_pk_bf16_f32 v114, v120, v121
	v_cvt_pk_bf16_f32 v115, v122, v123
	v_mul_f32_e32 v121, v117, v117
	v_mul_f32_e32 v123, v119, v119
	v_mul_f32_e32 v125, v215, v215
	v_mul_f32_e32 v127, v213, v213
	v_fmac_f32_e32 v211, v124, v124
	v_fmac_f32_e32 v216, v126, v126
	v_fmac_f32_e32 v217, v120, v120
	v_fmac_f32_e32 v218, v122, v122
	v_fmac_f32_e32 v121, v116, v116
	v_fmac_f32_e32 v123, v118, v118
	v_fmac_f32_e32 v125, v214, v214
	v_fmac_f32_e32 v127, v212, v212
	v_add_f32_e32 v120, v211, v216
	v_add_f32_e32 v122, v217, v218
	v_add_f32_e32 v121, v121, v123
	v_add_f32_e32 v123, v125, v127
	v_add_f32_e32 v120, v120, v122
	v_add_f32_e32 v121, v121, v123
	v_add_f32_e32 v122, v120, v121
	ds_bpermute_b32 v123, v210, v122
	v_mad_i64_i32 v[120:121], s[26:27], v196, s47, v[228:229]
	v_lshl_add_u64 v[120:121], v[192:193], 1, v[120:121]
	global_store_dwordx4 v[120:121], v[112:115], off offset:512
	s_waitcnt lgkmcnt(0)
	s_nop 0
	v_add_f32_e32 v112, v122, v123
	ds_bpermute_b32 v113, v209, v112
	v_cvt_pk_bf16_f32 v114, v116, v117
	v_cvt_pk_bf16_f32 v115, v118, v119
	v_cvt_pk_bf16_f32 v116, v214, v215
	v_cvt_pk_bf16_f32 v117, v212, v213
	global_store_dwordx4 v[120:121], v[114:117], off offset:768
	s_and_saveexec_b64 s[26:27], s[6:7]
	s_cbranch_execz .LBB0_346
	v_lshlrev_b64 v[114:115], 7, v[196:197]
	v_lshl_add_u64 v[114:115], s[20:21], 0, v[114:115]
	v_lshl_add_u64 v[114:115], s[24:25], 2, v[114:115]
	s_lshl_b32 s16, s39, 2
	v_lshl_add_u64 v[114:115], v[114:115], 0, s[16:17]
	s_waitcnt lgkmcnt(0)
	v_add_f32_e32 v112, v112, v113
	global_store_dword v[114:115], v112, off

; #define PG8_STAGE(bufoff, gbase, voff) do { _Pragma("unroll") for (int _i = 0; _i < 2; ++_i) \
;         __builtin_amdgcn_global_load_lds((const unsigned*)((const char*)(gbase) + (voff)[_i]), (LAS unsigned*)(lds + (bufoff) + ldsw + _i * 8192), 16, 0, 0); } while (0)
; #define PG8_LDA(dst, b, h) do { _Pragma("unroll") for (int m = 0; m < 4; ++m) _Pragma("unroll") for (int k = 0; k < 2; ++k) dst[m][k] = *(const LAS bf16x8*)(lds + PG8_SA(b, h) + aoff + m * 2048 + k * 1024); } while (0)
; #define PG8_LDB(dst, b, h) do { _Pragma("unroll") for (int n = 0; n < 2; ++n) _Pragma("unroll") for (int k = 0; k < 2; ++k) dst[n][k] = *(const LAS bf16x8*)(lds + PG8_SB(b, h) + boff + n * 2048 + k * 1024); } while (0)
; #define PG8_MMA(ai, bj, At, Bt) do { __builtin_amdgcn_s_setprio(1); _Pragma("unroll") for (int m = 0; m < 4; ++m) _Pragma("unroll") for (int n = 0; n < 2; ++n) _Pragma("unroll") for (int k = 0; k < 2; ++k) \
;         acc[ai][bj][m][n] = __builtin_amdgcn_mfma_f32_16x16x32_bf16(Bt[n][k], At[m][k], acc[ai][bj][m][n], 0, 0, 0); __builtin_amdgcn_s_setprio(0); } while (0)
; #define PG8_WAIT_V(n) asm volatile("s_waitcnt vmcnt(" #n ")" ::: "memory")
; #define PG8_WAIT_L(n) asm volatile("s_waitcnt lgkmcnt(" #n ")" ::: "memory")
; #define PG8_BAR __builtin_amdgcn_s_barrier()
; #define PG8_SCHED __builtin_amdgcn_sched_barrier(0)
; template <class Epi>
; __device__ __forceinline__ void gemm_phase(LAS unsigned char* lds, const GSched& S, const int K, const int lda, const int ldb, const Epi& E) {
;     ...
;             PG8_LDB(B0, 0, 0); PG8_SCHED; PG8_LDA(At, 0, 0); PG8_STAGE(PG8_SA(1, 1), a1 + hstepA, voffA);
;             PG8_WAIT_L(8); PG8_BAR; PG8_WAIT_L(0); PG8_MMA(0, 0, At, B0); PG8_BAR; PG8_SCHED;
;             if constexpr (!Epi::NARROW) PG8_LDB(B1, 0, 1); PG8_STAGE(PG8_SB(0, 0), b2, voffB);
;             PG8_BAR; PG8_WAIT_L(0); if constexpr (!Epi::NARROW) PG8_MMA(0, 1, At, B1); PG8_BAR;
;             PG8_LDA(At, 0, 1); PG8_STAGE(PG8_SA(0, 0), a2, voffA);
;             PG8_BAR; PG8_WAIT_L(0); PG8_MMA(1, 0, At, B0); PG8_BAR; PG8_SCHED;
;             PG8_STAGE(PG8_SB(0, 1), b2 + hstepB, voffB);
;             PG8_WAIT_V(6); PG8_BAR; if constexpr (!Epi::NARROW) PG8_MMA(1, 1, At, B1); PG8_BAR;
.LBB0_438:
	ds_read_b128 v[166:169], v161
	ds_read_b128 v[170:173], v161 offset:1024
	ds_read_b128 v[174:177], v161 offset:2048
	ds_read_b128 v[178:181], v161 offset:3072
	s_add_u32 s6, s14, 0x100
	s_addc_u32 s7, s15, 0
	s_cmp_eq_u32 s48, 28
	s_cselect_b32 s45, s41, s7
	s_cselect_b32 s44, s40, s6
	s_cselect_b32 s13, s43, s47
	s_cselect_b32 s12, s42, s46
	v_lshl_add_u64 v[162:163], s[14:15], 0, v[142:143]
	s_add_i32 m0, s56, 0xc000
	ds_read_b128 v[182:185], v164
	ds_read_b128 v[186:189], v164 offset:1024
	ds_read_b128 v[190:193], v164 offset:2048
	ds_read_b128 v[194:197], v164 offset:3072
	ds_read_b128 v[198:201], v164 offset:4096
	ds_read_b128 v[202:205], v164 offset:5120
	ds_read_b128 v[206:209], v164 offset:6144
	ds_read_b128 v[210:213], v164 offset:7168
	global_load_lds_dwordx4 v[162:163], off
	v_lshl_add_u64 v[162:163], s[14:15], 0, v[140:141]
	s_add_i32 m0, s56, 0xe000
	s_nop 0
	global_load_lds_dwordx4 v[162:163], off
	s_waitcnt lgkmcnt(8)
	s_barrier
	s_waitcnt lgkmcnt(0)
	s_setprio 1
	s_waitcnt lgkmcnt(0)
	v_mfma_f32_16x16x32_bf16 v[124:127], v[166:169], v[182:185], v[124:127]
	v_mfma_f32_16x16x32_bf16 v[120:123], v[174:177], v[182:185], v[120:123]
	v_mfma_f32_16x16x32_bf16 v[108:111], v[166:169], v[190:193], v[108:111]
	v_mfma_f32_16x16x32_bf16 v[104:107], v[174:177], v[190:193], v[104:107]
	v_mfma_f32_16x16x32_bf16 v[92:95], v[166:169], v[198:201], v[92:95]
	v_mfma_f32_16x16x32_bf16 v[88:91], v[174:177], v[198:201], v[88:91]
	v_mfma_f32_16x16x32_bf16 v[76:79], v[166:169], v[206:209], v[76:79]
	v_mfma_f32_16x16x32_bf16 v[72:75], v[174:177], v[206:209], v[72:75]
	v_mfma_f32_16x16x32_bf16 v[124:127], v[170:173], v[186:189], v[124:127]
	v_mfma_f32_16x16x32_bf16 v[120:123], v[178:181], v[186:189], v[120:123]
	v_mfma_f32_16x16x32_bf16 v[108:111], v[170:173], v[194:197], v[108:111]
	v_mfma_f32_16x16x32_bf16 v[104:107], v[178:181], v[194:197], v[104:107]
	v_mfma_f32_16x16x32_bf16 v[92:95], v[170:173], v[202:205], v[92:95]
	v_mfma_f32_16x16x32_bf16 v[88:91], v[178:181], v[202:205], v[88:91]
	v_mfma_f32_16x16x32_bf16 v[76:79], v[170:173], v[210:213], v[76:79]
	v_mfma_f32_16x16x32_bf16 v[72:75], v[178:181], v[210:213], v[72:75]
	s_setprio 0
	s_barrier
	s_add_i32 s3, s0, s55
	v_lshl_add_u64 v[162:163], s[12:13], 0, v[130:131]
	s_mov_b32 m0, s3
	ds_read_b128 v[214:217], v165
	ds_read_b128 v[218:221], v165 offset:1024
	ds_read_b128 v[222:225], v165 offset:2048
	ds_read_b128 v[226:229], v165 offset:3072
	global_load_lds_dwordx4 v[162:163], off
	v_lshl_add_u64 v[230:231], s[12:13], 0, v[134:135]
	s_add_i32 m0, s3, 0x2000
	s_nop 0
	global_load_lds_dwordx4 v[230:231], off
	s_barrier
	s_waitcnt lgkmcnt(0)
	s_setprio 1
	v_mfma_f32_16x16x32_bf16 v[116:119], v[214:217], v[182:185], v[116:119]
	v_mfma_f32_16x16x32_bf16 v[112:115], v[222:225], v[182:185], v[112:115]
	v_mfma_f32_16x16x32_bf16 v[100:103], v[214:217], v[190:193], v[100:103]
	v_mfma_f32_16x16x32_bf16 v[96:99], v[222:225], v[190:193], v[96:99]
	v_mfma_f32_16x16x32_bf16 v[84:87], v[214:217], v[198:201], v[84:87]
	v_mfma_f32_16x16x32_bf16 v[80:83], v[222:225], v[198:201], v[80:83]
	v_mfma_f32_16x16x32_bf16 v[68:71], v[214:217], v[206:209], v[68:71]
	v_mfma_f32_16x16x32_bf16 v[64:67], v[222:225], v[206:209], v[64:67]
	v_mfma_f32_16x16x32_bf16 v[116:119], v[218:221], v[186:189], v[116:119]
	v_mfma_f32_16x16x32_bf16 v[112:115], v[226:229], v[186:189], v[112:115]
	v_mfma_f32_16x16x32_bf16 v[100:103], v[218:221], v[194:197], v[100:103]
	v_mfma_f32_16x16x32_bf16 v[96:99], v[226:229], v[194:197], v[96:99]
	v_mfma_f32_16x16x32_bf16 v[84:87], v[218:221], v[202:205], v[84:87]
	v_mfma_f32_16x16x32_bf16 v[80:83], v[226:229], v[202:205], v[80:83]
	v_mfma_f32_16x16x32_bf16 v[68:71], v[218:221], v[210:213], v[68:71]
	v_mfma_f32_16x16x32_bf16 v[64:67], v[226:229], v[210:213], v[64:67]
	s_setprio 0
	s_mov_b32 m0, s56
	v_lshl_add_u64 v[234:235], s[44:45], 0, v[128:129]
	s_barrier
	ds_read_b128 v[182:185], v164 offset:16384
	ds_read_b128 v[186:189], v164 offset:17408
	ds_read_b128 v[190:193], v164 offset:18432
	ds_read_b128 v[194:197], v164 offset:19456
	ds_read_b128 v[198:201], v164 offset:20480
	ds_read_b128 v[202:205], v164 offset:21504
	ds_read_b128 v[206:209], v164 offset:22528
	ds_read_b128 v[210:213], v164 offset:23552
	global_load_lds_dwordx4 v[234:235], off
	v_lshl_add_u64 v[236:237], s[44:45], 0, v[132:133]
	s_mov_b32 m0, s57
	s_nop 0
	global_load_lds_dwordx4 v[236:237], off
	s_barrier
	s_waitcnt lgkmcnt(0)
	s_setprio 1
	v_mfma_f32_16x16x32_bf16 v[60:63], v[166:169], v[182:185], v[60:63]
	v_mfma_f32_16x16x32_bf16 v[56:59], v[174:177], v[182:185], v[56:59]
	v_mfma_f32_16x16x32_bf16 v[44:47], v[166:169], v[190:193], v[44:47]
	v_mfma_f32_16x16x32_bf16 v[40:43], v[174:177], v[190:193], v[40:43]
	v_mfma_f32_16x16x32_bf16 v[28:31], v[166:169], v[198:201], v[28:31]
	v_mfma_f32_16x16x32_bf16 v[24:27], v[174:177], v[198:201], v[24:27]
	v_mfma_f32_16x16x32_bf16 v[12:15], v[166:169], v[206:209], v[12:15]
	v_mfma_f32_16x16x32_bf16 v[8:11], v[174:177], v[206:209], v[8:11]
	v_mfma_f32_16x16x32_bf16 v[60:63], v[170:173], v[186:189], v[60:63]
	v_mfma_f32_16x16x32_bf16 v[56:59], v[178:181], v[186:189], v[56:59]
	v_mfma_f32_16x16x32_bf16 v[44:47], v[170:173], v[194:197], v[44:47]
	v_mfma_f32_16x16x32_bf16 v[40:43], v[178:181], v[194:197], v[40:43]
	v_mfma_f32_16x16x32_bf16 v[28:31], v[170:173], v[202:205], v[28:31]
	v_mfma_f32_16x16x32_bf16 v[24:27], v[178:181], v[202:205], v[24:27]
	v_mfma_f32_16x16x32_bf16 v[12:15], v[170:173], v[210:213], v[12:15]
	v_mfma_f32_16x16x32_bf16 v[8:11], v[178:181], v[210:213], v[8:11]
	s_setprio 0
	s_barrier
; #define PG8_STAGE(bufoff, gbase, voff) do { _Pragma("unroll") for (int _i = 0; _i < 2; ++_i) \
;         __builtin_amdgcn_global_load_lds((const unsigned*)((const char*)(gbase) + (voff)[_i]), (LAS unsigned*)(lds + (bufoff) + ldsw + _i * 8192), 16, 0, 0); } while (0)
; #define PG8_LDA(dst, b, h) do { _Pragma("unroll") for (int m = 0; m < 4; ++m) _Pragma("unroll") for (int k = 0; k < 2; ++k) dst[m][k] = *(const LAS bf16x8*)(lds + PG8_SA(b, h) + aoff + m * 2048 + k * 1024); } while (0)
; #define PG8_LDB(dst, b, h) do { _Pragma("unroll") for (int n = 0; n < 2; ++n) _Pragma("unroll") for (int k = 0; k < 2; ++k) dst[n][k] = *(const LAS bf16x8*)(lds + PG8_SB(b, h) + boff + n * 2048 + k * 1024); } while (0)
; #define PG8_MMA(ai, bj, At, Bt) do { __builtin_amdgcn_s_setprio(1); _Pragma("unroll") for (int m = 0; m < 4; ++m) _Pragma("unroll") for (int n = 0; n < 2; ++n) _Pragma("unroll") for (int k = 0; k < 2; ++k) \
;         acc[ai][bj][m][n] = __builtin_amdgcn_mfma_f32_16x16x32_bf16(Bt[n][k], At[m][k], acc[ai][bj][m][n], 0, 0, 0); __builtin_amdgcn_s_setprio(0); } while (0)
; #define PG8_WAIT_V(n) asm volatile("s_waitcnt vmcnt(" #n ")" ::: "memory")
; #define PG8_WAIT_L(n) asm volatile("s_waitcnt lgkmcnt(" #n ")" ::: "memory")
; #define PG8_BAR __builtin_amdgcn_s_barrier()
; #define PG8_SCHED __builtin_amdgcn_sched_barrier(0)
; template <class Epi>
; __device__ __forceinline__ void gemm_phase(LAS unsigned char* lds, const GSched& S, const int K, const int lda, const int ldb, const Epi& E) {
;     ...
;             PG8_STAGE(PG8_SB(0, 1), b2 + hstepB, voffB);
;             PG8_WAIT_V(6); PG8_BAR; if constexpr (!Epi::NARROW) PG8_MMA(1, 1, At, B1); PG8_BAR;
;             PG8_LDB(B0, 1, 0); PG8_SCHED; PG8_LDA(At, 1, 0); PG8_STAGE(PG8_SA(0, 1), a2 + hstepA, voffA);
;             PG8_WAIT_L(8); PG8_BAR; PG8_WAIT_L(0); PG8_MMA(0, 0, At, B0); PG8_BAR; PG8_SCHED;
;             if constexpr (!Epi::NARROW) PG8_LDB(B1, 1, 1); PG8_STAGE(PG8_SB(1, 0), b3, voffB);
;             PG8_BAR; PG8_WAIT_L(0); if constexpr (!Epi::NARROW) PG8_MMA(0, 1, At, B1); PG8_BAR;
;             PG8_LDA(At, 1, 1); PG8_STAGE(PG8_SA(1, 0), a3, voffA);
;             PG8_BAR; PG8_WAIT_L(0); PG8_MMA(1, 0, At, B0); PG8_BAR; PG8_SCHED;
	s_add_u32 s14, s12, 0x84000
	s_addc_u32 s15, s13, 0
	s_add_i32 s3, s1, s55
	v_lshl_add_u64 v[166:167], s[14:15], 0, v[130:131]
	s_mov_b32 m0, s3
	s_nop 0
	global_load_lds_dwordx4 v[166:167], off
	v_lshl_add_u64 v[166:167], s[14:15], 0, v[134:135]
	s_add_i32 m0, s3, 0x2000
	s_nop 0
	global_load_lds_dwordx4 v[166:167], off
	s_waitcnt vmcnt(6)
	s_barrier
	s_setprio 1
	v_mfma_f32_16x16x32_bf16 v[52:55], v[214:217], v[182:185], v[52:55]
	v_mfma_f32_16x16x32_bf16 v[48:51], v[222:225], v[182:185], v[48:51]
	v_mfma_f32_16x16x32_bf16 v[36:39], v[214:217], v[190:193], v[36:39]
	v_mfma_f32_16x16x32_bf16 v[32:35], v[222:225], v[190:193], v[32:35]
	v_mfma_f32_16x16x32_bf16 v[20:23], v[214:217], v[198:201], v[20:23]
	v_mfma_f32_16x16x32_bf16 v[16:19], v[222:225], v[198:201], v[16:19]
	v_mfma_f32_16x16x32_bf16 v[4:7], v[214:217], v[206:209], v[4:7]
	v_mfma_f32_16x16x32_bf16 v[0:3], v[222:225], v[206:209], v[0:3]
	v_mfma_f32_16x16x32_bf16 v[52:55], v[218:221], v[186:189], v[52:55]
	v_mfma_f32_16x16x32_bf16 v[48:51], v[226:229], v[186:189], v[48:51]
	v_mfma_f32_16x16x32_bf16 v[36:39], v[218:221], v[194:197], v[36:39]
	v_mfma_f32_16x16x32_bf16 v[32:35], v[226:229], v[194:197], v[32:35]
	v_mfma_f32_16x16x32_bf16 v[20:23], v[218:221], v[202:205], v[20:23]
	v_mfma_f32_16x16x32_bf16 v[16:19], v[226:229], v[202:205], v[16:19]
	v_mfma_f32_16x16x32_bf16 v[4:7], v[218:221], v[210:213], v[4:7]
	v_mfma_f32_16x16x32_bf16 v[0:3], v[226:229], v[210:213], v[0:3]
	s_setprio 0
	s_add_i32 s3, 0, 0x18000
	v_add_u32_e32 v178, s3, v159
	s_barrier
	ds_read_b128 v[166:169], v178
	ds_read_b128 v[170:173], v178 offset:1024
	ds_read_b128 v[174:177], v178 offset:2048
	ds_read_b128 v[178:181], v178 offset:3072
	s_add_u32 s14, s44, 0x94000
	s_addc_u32 s15, s45, 0
	s_mov_b32 m0, s58
	v_lshl_add_u64 v[214:215], s[14:15], 0, v[128:129]
	ds_read_b128 v[182:185], v164 offset:32768
	ds_read_b128 v[186:189], v164 offset:33792
	ds_read_b128 v[190:193], v164 offset:34816
	ds_read_b128 v[194:197], v164 offset:35840
	ds_read_b128 v[198:201], v164 offset:36864
	ds_read_b128 v[202:205], v164 offset:37888
	ds_read_b128 v[206:209], v164 offset:38912
	ds_read_b128 v[210:213], v164 offset:39936
	global_load_lds_dwordx4 v[214:215], off
	v_lshl_add_u64 v[214:215], s[14:15], 0, v[132:133]
	s_mov_b32 m0, s59
	s_nop 0
	global_load_lds_dwordx4 v[214:215], off
	s_waitcnt lgkmcnt(8)
	s_barrier
	s_waitcnt lgkmcnt(0)
	s_setprio 1
	s_waitcnt lgkmcnt(0)
	v_mfma_f32_16x16x32_bf16 v[124:127], v[166:169], v[182:185], v[124:127]
	v_mfma_f32_16x16x32_bf16 v[120:123], v[174:177], v[182:185], v[120:123]
	v_mfma_f32_16x16x32_bf16 v[108:111], v[166:169], v[190:193], v[108:111]
	v_mfma_f32_16x16x32_bf16 v[104:107], v[174:177], v[190:193], v[104:107]
	v_mfma_f32_16x16x32_bf16 v[92:95], v[166:169], v[198:201], v[92:95]
	v_mfma_f32_16x16x32_bf16 v[88:91], v[174:177], v[198:201], v[88:91]
	v_mfma_f32_16x16x32_bf16 v[76:79], v[166:169], v[206:209], v[76:79]
	v_mfma_f32_16x16x32_bf16 v[72:75], v[174:177], v[206:209], v[72:75]
	v_mfma_f32_16x16x32_bf16 v[124:127], v[170:173], v[186:189], v[124:127]
	v_mfma_f32_16x16x32_bf16 v[120:123], v[178:181], v[186:189], v[120:123]
	v_mfma_f32_16x16x32_bf16 v[108:111], v[170:173], v[194:197], v[108:111]
	v_mfma_f32_16x16x32_bf16 v[104:107], v[178:181], v[194:197], v[104:107]
	v_mfma_f32_16x16x32_bf16 v[92:95], v[170:173], v[202:205], v[92:95]
	v_mfma_f32_16x16x32_bf16 v[88:91], v[178:181], v[202:205], v[88:91]
	v_mfma_f32_16x16x32_bf16 v[76:79], v[170:173], v[210:213], v[76:79]
	v_mfma_f32_16x16x32_bf16 v[72:75], v[178:181], v[210:213], v[72:75]
	s_setprio 0
	s_barrier
	s_add_i32 s14, 0, 0x1c000
	s_add_i32 s3, s3, s55
	v_add_u32_e32 v226, s14, v159
	v_lshl_add_u64 v[162:163], v[162:163], 0, s[38:39]
	s_mov_b32 m0, s3
	ds_read_b128 v[214:217], v226
	ds_read_b128 v[218:221], v226 offset:1024
	ds_read_b128 v[222:225], v226 offset:2048
	ds_read_b128 v[226:229], v226 offset:3072
	global_load_lds_dwordx4 v[162:163], off
	v_lshl_add_u64 v[162:163], v[230:231], 0, s[38:39]
	s_add_i32 m0, s3, 0x2000
	s_nop 0
	global_load_lds_dwordx4 v[162:163], off
	s_barrier
	s_waitcnt lgkmcnt(0)
	s_setprio 1
	s_waitcnt lgkmcnt(0)
	v_mfma_f32_16x16x32_bf16 v[116:119], v[214:217], v[182:185], v[116:119]
	v_mfma_f32_16x16x32_bf16 v[112:115], v[222:225], v[182:185], v[112:115]
	v_mfma_f32_16x16x32_bf16 v[100:103], v[214:217], v[190:193], v[100:103]
	v_mfma_f32_16x16x32_bf16 v[96:99], v[222:225], v[190:193], v[96:99]
	v_mfma_f32_16x16x32_bf16 v[84:87], v[214:217], v[198:201], v[84:87]
	v_mfma_f32_16x16x32_bf16 v[80:83], v[222:225], v[198:201], v[80:83]
	v_mfma_f32_16x16x32_bf16 v[68:71], v[214:217], v[206:209], v[68:71]
	v_mfma_f32_16x16x32_bf16 v[64:67], v[222:225], v[206:209], v[64:67]
	v_mfma_f32_16x16x32_bf16 v[116:119], v[218:221], v[186:189], v[116:119]
	v_mfma_f32_16x16x32_bf16 v[112:115], v[226:229], v[186:189], v[112:115]
	v_mfma_f32_16x16x32_bf16 v[100:103], v[218:221], v[194:197], v[100:103]
	v_mfma_f32_16x16x32_bf16 v[96:99], v[226:229], v[194:197], v[96:99]
	v_mfma_f32_16x16x32_bf16 v[84:87], v[218:221], v[202:205], v[84:87]
	v_mfma_f32_16x16x32_bf16 v[80:83], v[226:229], v[202:205], v[80:83]
	v_mfma_f32_16x16x32_bf16 v[68:71], v[218:221], v[210:213], v[68:71]
	v_mfma_f32_16x16x32_bf16 v[64:67], v[226:229], v[210:213], v[64:67]
	s_setprio 0
	s_mov_b32 m0, s64
	v_lshl_add_u64 v[162:163], v[234:235], 0, s[38:39]
	s_barrier
	ds_read_b128 v[182:185], v164 offset:49152
	ds_read_b128 v[186:189], v164 offset:50176
	ds_read_b128 v[190:193], v164 offset:51200
	ds_read_b128 v[194:197], v164 offset:52224
	ds_read_b128 v[198:201], v164 offset:53248
	ds_read_b128 v[202:205], v164 offset:54272
	ds_read_b128 v[206:209], v164 offset:55296
	ds_read_b128 v[210:213], v164 offset:56320
	global_load_lds_dwordx4 v[162:163], off
	v_lshl_add_u64 v[162:163], v[236:237], 0, s[38:39]
	s_mov_b32 m0, s65
	s_nop 0
	global_load_lds_dwordx4 v[162:163], off
	s_barrier
; __device__ __forceinline__ void st_nt(float* p, f32x4 v) { __builtin_nontemporal_store(v, (f32x4*)p); }
; __device__ __forceinline__ void st_nt(bf16_t* p, u32x4 v) { __builtin_nontemporal_store(v, (u32x4*)p); }
; __device__ __forceinline__ float sumsq4(const f32x4 v) { return (v[0] * v[0] + v[1] * v[1]) + (v[2] * v[2] + v[3] * v[3]); }
; __device__ __forceinline__ u32x4 pack8(const f32x4 a, const f32x4 b) { u32x4 w; w.x = cvt_pk_bf16(a[0], a[1]); w.y = cvt_pk_bf16(a[2], a[3]); w.z = cvt_pk_bf16(b[0], b[1]); w.w = cvt_pk_bf16(b[2], b[3]); return w; }
; #define PG8_WAIT_V(n) asm volatile("s_waitcnt vmcnt(" #n ")" ::: "memory")
; #define PG8_WAIT_L(n) asm volatile("s_waitcnt lgkmcnt(" #n ")" ::: "memory")
; #define PG8_BAR __builtin_amdgcn_s_barrier()
;     __device__ __forceinline__ void operator()(Acc& acc, const Unit& u, int wr, int wc, int fr, int fq, const float (&rsv)[8]) const {
;         const int row0 = u.pm * BM + wr * 64 + fr, cin = wc * 32 + 8 * fq;
;         const bool is_lat = u.pn >= 12;
; #pragma unroll
;         for (int ai = 0; ai < 2; ++ai)
; #pragma unroll
;             for (int m = 0; m < 4; ++m) {
;                 const int row = row0 + ai * HALF + m * 16; const float rs = rsv[ai * 4 + m]; float ss = 0.f;
; #pragma unroll
;                 for (int bj = 0; bj < 2; ++bj) { const f32x4 v0 = acc[ai][bj][m][0] * rs, v1 = acc[ai][bj][m][1] * rs; ss += sumsq4(v0) + sumsq4(v1);
;                     bf16_t* dst = is_lat ? lat + (size_t)row * 1024 + (u.pn - 12) * BM + cin + bj * HALF : qkv + (size_t)row * 3072 + u.pn * BM + cin + bj * HALF;
;                     st_nt(dst, pack8(v0, v1)); }
;                 if (is_lat) { ss += __shfl_xor(ss, 16); ss += __shfl_xor(ss, 32); if (fq == 0) latpart[(size_t)row * 16 + (u.pn - 12) * 4 + wc] = ss; }
;             }
; template <class Epi>
; __device__ __forceinline__ void gemm_phase(LAS unsigned char* lds, const GSched& S, const int K, const int lda, const int ldb, const Epi& E) {
;     ...
;             PG8_BAR; PG8_WAIT_L(0); PG8_MMA(1, 0, At, B0); PG8_BAR; PG8_SCHED;
;             PG8_STAGE(PG8_SB(1, 1), b3 + hstepB, voffB);
;             PG8_WAIT_V(6); PG8_BAR; if constexpr (!Epi::NARROW) PG8_MMA(1, 1, At, B1); PG8_BAR;
;             if constexpr (Epi::HAS_MID) { if (t + 2 == E.mid_t) { PG8_SCHED; E.mid(acc, cur, wr, wc, fr, fq); PG8_SCHED; } }
;         }
	s_waitcnt lgkmcnt(0)
	s_setprio 1
	v_mfma_f32_16x16x32_bf16 v[60:63], v[166:169], v[182:185], v[60:63]
	v_mfma_f32_16x16x32_bf16 v[56:59], v[174:177], v[182:185], v[56:59]
	v_mfma_f32_16x16x32_bf16 v[44:47], v[166:169], v[190:193], v[44:47]
	v_mfma_f32_16x16x32_bf16 v[40:43], v[174:177], v[190:193], v[40:43]
	v_mfma_f32_16x16x32_bf16 v[28:31], v[166:169], v[198:201], v[28:31]
	v_mfma_f32_16x16x32_bf16 v[24:27], v[174:177], v[198:201], v[24:27]
	v_mfma_f32_16x16x32_bf16 v[12:15], v[166:169], v[206:209], v[12:15]
	v_mfma_f32_16x16x32_bf16 v[8:11], v[174:177], v[206:209], v[8:11]
	v_mfma_f32_16x16x32_bf16 v[60:63], v[170:173], v[186:189], v[60:63]
	v_mfma_f32_16x16x32_bf16 v[56:59], v[178:181], v[186:189], v[56:59]
	v_mfma_f32_16x16x32_bf16 v[44:47], v[170:173], v[194:197], v[44:47]
	v_mfma_f32_16x16x32_bf16 v[40:43], v[178:181], v[194:197], v[40:43]
	v_mfma_f32_16x16x32_bf16 v[28:31], v[170:173], v[202:205], v[28:31]
	v_mfma_f32_16x16x32_bf16 v[24:27], v[178:181], v[202:205], v[24:27]
	v_mfma_f32_16x16x32_bf16 v[12:15], v[170:173], v[210:213], v[12:15]
	v_mfma_f32_16x16x32_bf16 v[8:11], v[178:181], v[210:213], v[8:11]
	s_setprio 0
	s_barrier
	s_add_u32 s12, s12, 0x84080
	s_addc_u32 s13, s13, 0
	s_add_i32 s3, s14, s55
	v_lshl_add_u64 v[162:163], s[12:13], 0, v[130:131]
	s_mov_b32 m0, s3
	s_nop 0
	global_load_lds_dwordx4 v[162:163], off
	v_lshl_add_u64 v[162:163], s[12:13], 0, v[134:135]
	s_add_i32 m0, s3, 0x2000
	s_nop 0
	global_load_lds_dwordx4 v[162:163], off
	s_waitcnt vmcnt(6)
	s_barrier
	s_setprio 1
	v_mfma_f32_16x16x32_bf16 v[52:55], v[214:217], v[182:185], v[52:55]
	v_mfma_f32_16x16x32_bf16 v[48:51], v[222:225], v[182:185], v[48:51]
	v_mfma_f32_16x16x32_bf16 v[36:39], v[214:217], v[190:193], v[36:39]
	v_mfma_f32_16x16x32_bf16 v[32:35], v[222:225], v[190:193], v[32:35]
	v_mfma_f32_16x16x32_bf16 v[20:23], v[214:217], v[198:201], v[20:23]
	v_mfma_f32_16x16x32_bf16 v[16:19], v[222:225], v[198:201], v[16:19]
	v_mfma_f32_16x16x32_bf16 v[4:7], v[214:217], v[206:209], v[4:7]
	v_mfma_f32_16x16x32_bf16 v[0:3], v[222:225], v[206:209], v[0:3]
	v_mfma_f32_16x16x32_bf16 v[52:55], v[218:221], v[186:189], v[52:55]
	v_mfma_f32_16x16x32_bf16 v[48:51], v[226:229], v[186:189], v[48:51]
	v_mfma_f32_16x16x32_bf16 v[36:39], v[218:221], v[194:197], v[36:39]
	v_mfma_f32_16x16x32_bf16 v[32:35], v[226:229], v[194:197], v[32:35]
	v_mfma_f32_16x16x32_bf16 v[20:23], v[218:221], v[202:205], v[20:23]
	v_mfma_f32_16x16x32_bf16 v[16:19], v[226:229], v[202:205], v[16:19]
	v_mfma_f32_16x16x32_bf16 v[4:7], v[218:221], v[210:213], v[4:7]
	v_mfma_f32_16x16x32_bf16 v[0:3], v[226:229], v[210:213], v[0:3]
	s_setprio 0
	s_add_i32 s48, s48, 2
	s_add_u32 s46, s46, 0x100
	s_addc_u32 s47, s47, 0
	s_cmp_gt_u32 s48, 29
	s_mov_b64 s[14:15], s[6:7]
	s_barrier
	s_cbranch_scc0 .LBB0_438
	v_lshl_add_u32 v162, s62, 8, v157
	s_cmp_gt_i32 s18, 11
	s_cselect_b64 s[12:13], -1, 0
	s_lshl_b32 s44, s18, 8
	v_ashrrev_i32_e32 v163, 31, v162
	s_add_i32 s46, s44, 0xfffff400
	v_lshlrev_b64 v[166:167], 11, v[162:163]
	v_mov_b64_e32 v[168:169], s[30:31]
	s_ashr_i32 s45, s44, 31
	s_ashr_i32 s47, s46, 31
	v_lshl_add_u64 v[166:167], s[34:35], 0, v[166:167]
	v_mad_i64_i32 v[168:169], s[14:15], v162, s67, v[168:169]
	s_lshl_b32 s3, s18, 2
	v_lshl_add_u64 v[166:167], s[46:47], 1, v[166:167]
	v_lshl_add_u64 v[168:169], s[44:45], 1, v[168:169]
	s_sub_i32 s6, s3, 48
	v_pk_mul_f32 v[126:127], v[148:149], v[126:127] op_sel_hi:[0,1]
	v_pk_mul_f32 v[124:125], v[148:149], v[124:125] op_sel_hi:[0,1]
	v_pk_mul_f32 v[122:123], v[148:149], v[122:123] op_sel_hi:[0,1]
	v_pk_mul_f32 v[120:121], v[148:149], v[120:121] op_sel_hi:[0,1]
	v_cndmask_b32_e64 v167, v169, v167, s[12:13]
	v_cndmask_b32_e64 v166, v168, v166, s[12:13]
	s_ashr_i32 s7, s6, 31
	v_lshl_add_u64 v[170:171], v[166:167], 0, v[136:137]
	v_cvt_pk_bf16_f32 v166, v124, v125
	v_cvt_pk_bf16_f32 v167, v126, v127
	v_cvt_pk_bf16_f32 v168, v120, v121
	v_cvt_pk_bf16_f32 v169, v122, v123
	v_pk_mul_f32 v[118:119], v[148:149], v[118:119] op_sel_hi:[0,1]
	v_pk_mul_f32 v[116:117], v[148:149], v[116:117] op_sel_hi:[0,1]
	v_pk_mul_f32 v[114:115], v[148:149], v[114:115] op_sel_hi:[0,1]
	v_pk_mul_f32 v[112:113], v[148:149], v[112:113] op_sel_hi:[0,1]
	s_cmp_lt_i32 s18, 12
	global_store_dwordx4 v[170:171], v[166:169], off nt
	s_nop 1
	v_cvt_pk_bf16_f32 v166, v116, v117
	v_cvt_pk_bf16_f32 v167, v118, v119
	v_cvt_pk_bf16_f32 v168, v112, v113
	v_cvt_pk_bf16_f32 v169, v114, v115
	global_store_dwordx4 v[170:171], v[166:169], off offset:256 nt
	s_cbranch_scc1 .LBB0_443
	v_mul_f32_e32 v125, v125, v125
	v_mul_f32_e32 v121, v121, v121
	v_mul_f32_e32 v117, v117, v117
	v_mul_f32_e32 v113, v113, v113
	v_fmac_f32_e32 v125, v124, v124
	v_mul_f32_e32 v124, v127, v127
	v_fmac_f32_e32 v121, v120, v120
	v_mul_f32_e32 v120, v123, v123
	v_fmac_f32_e32 v117, v116, v116
	v_mul_f32_e32 v116, v119, v119
	v_fmac_f32_e32 v113, v112, v112
	v_mul_f32_e32 v112, v115, v115
	v_fmac_f32_e32 v124, v126, v126
	v_fmac_f32_e32 v120, v122, v122
	v_fmac_f32_e32 v116, v118, v118
	v_fmac_f32_e32 v112, v114, v114
	v_add_f32_e32 v124, v125, v124
	v_add_f32_e32 v120, v121, v120
	v_add_f32_e32 v116, v117, v116
	v_add_f32_e32 v112, v113, v112
	v_add_f32_e32 v120, v124, v120
	v_add_f32_e32 v112, v116, v112
	v_add_f32_e32 v112, v120, v112
	ds_bpermute_b32 v113, v153, v112
	s_waitcnt lgkmcnt(0)
	v_add_f32_e32 v112, v112, v113
	ds_bpermute_b32 v113, v155, v112
	s_and_saveexec_b64 s[14:15], s[8:9]
	s_cbranch_execz .LBB0_442
	v_lshlrev_b64 v[114:115], 6, v[162:163]
	v_lshl_add_u64 v[114:115], s[36:37], 0, v[114:115]
	v_lshl_add_u64 v[114:115], s[6:7], 2, v[114:115]
	s_lshl_b32 s18, s63, 2
	v_lshl_add_u64 v[114:115], v[114:115], 0, s[18:19]
	s_waitcnt lgkmcnt(0)
	v_add_f32_e32 v112, v112, v113
	global_store_dword v[114:115], v112, off

; #define PG8_STAGE(bufoff, gbase, voff) do { _Pragma("unroll") for (int _i = 0; _i < 2; ++_i) \
;         __builtin_amdgcn_global_load_lds((const unsigned*)((const char*)(gbase) + (voff)[_i]), (LAS unsigned*)(lds + (bufoff) + ldsw + _i * 8192), 16, 0, 0); } while (0)
; #define PG8_LDA(dst, b, h) do { _Pragma("unroll") for (int m = 0; m < 4; ++m) _Pragma("unroll") for (int k = 0; k < 2; ++k) dst[m][k] = *(const LAS bf16x8*)(lds + PG8_SA(b, h) + aoff + m * 2048 + k * 1024); } while (0)
; #define PG8_LDB(dst, b, h) do { _Pragma("unroll") for (int n = 0; n < 2; ++n) _Pragma("unroll") for (int k = 0; k < 2; ++k) dst[n][k] = *(const LAS bf16x8*)(lds + PG8_SB(b, h) + boff + n * 2048 + k * 1024); } while (0)
; #define PG8_MMA(ai, bj, At, Bt) do { __builtin_amdgcn_s_setprio(1); _Pragma("unroll") for (int m = 0; m < 4; ++m) _Pragma("unroll") for (int n = 0; n < 2; ++n) _Pragma("unroll") for (int k = 0; k < 2; ++k) \
;         acc[ai][bj][m][n] = __builtin_amdgcn_mfma_f32_16x16x32_bf16(Bt[n][k], At[m][k], acc[ai][bj][m][n], 0, 0, 0); __builtin_amdgcn_s_setprio(0); } while (0)
; #define PG8_WAIT_V(n) asm volatile("s_waitcnt vmcnt(" #n ")" ::: "memory")
; #define PG8_WAIT_L(n) asm volatile("s_waitcnt lgkmcnt(" #n ")" ::: "memory")
; #define PG8_BAR __builtin_amdgcn_s_barrier()
; #define PG8_SCHED __builtin_amdgcn_sched_barrier(0)
; template <class Epi>
; __device__ __forceinline__ void gemm_phase(LAS unsigned char* lds, const GSched& S, const int K, const int lda, const int ldb, const Epi& E) {
;     ...
;             PG8_LDB(B0, 0, 0); PG8_SCHED; PG8_LDA(At, 0, 0); PG8_STAGE(PG8_SA(1, 1), a1 + hstepA, voffA);
;             PG8_WAIT_L(8); PG8_BAR; PG8_WAIT_L(0); PG8_MMA(0, 0, At, B0); PG8_BAR; PG8_SCHED;
;             if constexpr (!Epi::NARROW) PG8_LDB(B1, 0, 1); PG8_STAGE(PG8_SB(0, 0), b2, voffB);
;             PG8_BAR; PG8_WAIT_L(0); if constexpr (!Epi::NARROW) PG8_MMA(0, 1, At, B1); PG8_BAR;
;             PG8_LDA(At, 0, 1); PG8_STAGE(PG8_SA(0, 0), a2, voffA);
;             PG8_BAR; PG8_WAIT_L(0); PG8_MMA(1, 0, At, B0); PG8_BAR; PG8_SCHED;
;             PG8_STAGE(PG8_SB(0, 1), b2 + hstepB, voffB);
;             PG8_WAIT_V(6); PG8_BAR; if constexpr (!Epi::NARROW) PG8_MMA(1, 1, At, B1); PG8_BAR;
.LBB0_543:
	ds_read_b128 v[128:131], v219
	ds_read_b128 v[132:135], v219 offset:1024
	ds_read_b128 v[136:139], v219 offset:2048
	ds_read_b128 v[140:143], v219 offset:3072
	s_add_u32 s3, s6, 0xfffc0080
	s_addc_u32 s8, s7, -1
	s_cmp_eq_u32 s77, 4
	s_cselect_b32 s11, s1, s8
	s_cselect_b32 s10, s2, s3
	s_cselect_b32 s9, s4, s45
	s_cselect_b32 s8, s5, s43
	v_lshl_add_u64 v[176:177], s[6:7], 0, v[204:205]
	s_add_i32 m0, s29, 0xc000
	ds_read_b128 v[144:147], v221
	ds_read_b128 v[148:151], v221 offset:1024
	ds_read_b128 v[152:155], v221 offset:2048
	ds_read_b128 v[156:159], v221 offset:3072
	ds_read_b128 v[160:163], v221 offset:4096
	ds_read_b128 v[164:167], v221 offset:5120
	ds_read_b128 v[168:171], v221 offset:6144
	ds_read_b128 v[172:175], v221 offset:7168
	global_load_lds_dwordx4 v[176:177], off
	v_lshl_add_u64 v[176:177], s[6:7], 0, v[202:203]
	s_add_i32 m0, s29, 0xe000
	s_nop 0
	global_load_lds_dwordx4 v[176:177], off
	s_waitcnt lgkmcnt(8)
	s_barrier
	s_waitcnt lgkmcnt(0)
	s_setprio 1
	s_waitcnt lgkmcnt(0)
	v_mfma_f32_16x16x32_bf16 v[124:127], v[128:131], v[144:147], v[124:127]
	v_mfma_f32_16x16x32_bf16 v[120:123], v[136:139], v[144:147], v[120:123]
	v_mfma_f32_16x16x32_bf16 v[108:111], v[128:131], v[152:155], v[108:111]
	v_mfma_f32_16x16x32_bf16 v[104:107], v[136:139], v[152:155], v[104:107]
	v_mfma_f32_16x16x32_bf16 v[92:95], v[128:131], v[160:163], v[92:95]
	v_mfma_f32_16x16x32_bf16 v[88:91], v[136:139], v[160:163], v[88:91]
	v_mfma_f32_16x16x32_bf16 v[76:79], v[128:131], v[168:171], v[76:79]
	v_mfma_f32_16x16x32_bf16 v[72:75], v[136:139], v[168:171], v[72:75]
	v_mfma_f32_16x16x32_bf16 v[124:127], v[132:135], v[148:151], v[124:127]
	v_mfma_f32_16x16x32_bf16 v[120:123], v[140:143], v[148:151], v[120:123]
	v_mfma_f32_16x16x32_bf16 v[108:111], v[132:135], v[156:159], v[108:111]
	v_mfma_f32_16x16x32_bf16 v[104:107], v[140:143], v[156:159], v[104:107]
	v_mfma_f32_16x16x32_bf16 v[92:95], v[132:135], v[164:167], v[92:95]
	v_mfma_f32_16x16x32_bf16 v[88:91], v[140:143], v[164:167], v[88:91]
	v_mfma_f32_16x16x32_bf16 v[76:79], v[132:135], v[172:175], v[76:79]
	v_mfma_f32_16x16x32_bf16 v[72:75], v[140:143], v[172:175], v[72:75]
	s_setprio 0
	s_barrier
	s_add_i32 s3, s71, s59
	v_lshl_add_u64 v[226:227], s[8:9], 0, v[196:197]
	s_mov_b32 m0, s3
	ds_read_b128 v[176:179], v223
	ds_read_b128 v[180:183], v223 offset:1024
	ds_read_b128 v[184:187], v223 offset:2048
	ds_read_b128 v[188:191], v223 offset:3072
	global_load_lds_dwordx4 v[226:227], off
	v_lshl_add_u64 v[228:229], s[8:9], 0, v[192:193]
	s_add_i32 m0, s3, 0x2000
	s_nop 0
	global_load_lds_dwordx4 v[228:229], off
	s_barrier
	s_waitcnt lgkmcnt(0)
	s_setprio 1
	v_mfma_f32_16x16x32_bf16 v[116:119], v[176:179], v[144:147], v[116:119]
	v_mfma_f32_16x16x32_bf16 v[112:115], v[184:187], v[144:147], v[112:115]
	v_mfma_f32_16x16x32_bf16 v[100:103], v[176:179], v[152:155], v[100:103]
	v_mfma_f32_16x16x32_bf16 v[96:99], v[184:187], v[152:155], v[96:99]
	v_mfma_f32_16x16x32_bf16 v[84:87], v[176:179], v[160:163], v[84:87]
	v_mfma_f32_16x16x32_bf16 v[80:83], v[184:187], v[160:163], v[80:83]
	v_mfma_f32_16x16x32_bf16 v[68:71], v[176:179], v[168:171], v[68:71]
	v_mfma_f32_16x16x32_bf16 v[64:67], v[184:187], v[168:171], v[64:67]
	v_mfma_f32_16x16x32_bf16 v[116:119], v[180:183], v[148:151], v[116:119]
	v_mfma_f32_16x16x32_bf16 v[112:115], v[188:191], v[148:151], v[112:115]
	v_mfma_f32_16x16x32_bf16 v[100:103], v[180:183], v[156:159], v[100:103]
	v_mfma_f32_16x16x32_bf16 v[96:99], v[188:191], v[156:159], v[96:99]
	v_mfma_f32_16x16x32_bf16 v[84:87], v[180:183], v[164:167], v[84:87]
	v_mfma_f32_16x16x32_bf16 v[80:83], v[188:191], v[164:167], v[80:83]
	v_mfma_f32_16x16x32_bf16 v[68:71], v[180:183], v[172:175], v[68:71]
	v_mfma_f32_16x16x32_bf16 v[64:67], v[188:191], v[172:175], v[64:67]
	s_setprio 0
	s_mov_b32 m0, s29
	v_lshl_add_u64 v[234:235], s[10:11], 0, v[198:199]
	s_barrier
	ds_read_b128 v[144:147], v221 offset:16384
	ds_read_b128 v[148:151], v221 offset:17408
	ds_read_b128 v[152:155], v221 offset:18432
	ds_read_b128 v[156:159], v221 offset:19456
	ds_read_b128 v[160:163], v221 offset:20480
	ds_read_b128 v[164:167], v221 offset:21504
	ds_read_b128 v[168:171], v221 offset:22528
	ds_read_b128 v[172:175], v221 offset:23552
	global_load_lds_dwordx4 v[234:235], off
	v_lshl_add_u64 v[236:237], s[10:11], 0, v[194:195]
	s_mov_b32 m0, s60
	s_nop 0
	global_load_lds_dwordx4 v[236:237], off
	s_barrier
	s_waitcnt lgkmcnt(0)
	s_setprio 1
	v_mfma_f32_16x16x32_bf16 v[60:63], v[128:131], v[144:147], v[60:63]
	v_mfma_f32_16x16x32_bf16 v[56:59], v[136:139], v[144:147], v[56:59]
	v_mfma_f32_16x16x32_bf16 v[44:47], v[128:131], v[152:155], v[44:47]
	v_mfma_f32_16x16x32_bf16 v[40:43], v[136:139], v[152:155], v[40:43]
	v_mfma_f32_16x16x32_bf16 v[28:31], v[128:131], v[160:163], v[28:31]
	v_mfma_f32_16x16x32_bf16 v[24:27], v[136:139], v[160:163], v[24:27]
	v_mfma_f32_16x16x32_bf16 v[12:15], v[128:131], v[168:171], v[12:15]
	v_mfma_f32_16x16x32_bf16 v[8:11], v[136:139], v[168:171], v[8:11]
	v_mfma_f32_16x16x32_bf16 v[60:63], v[132:135], v[148:151], v[60:63]
	v_mfma_f32_16x16x32_bf16 v[56:59], v[140:143], v[148:151], v[56:59]
	v_mfma_f32_16x16x32_bf16 v[44:47], v[132:135], v[156:159], v[44:47]
	v_mfma_f32_16x16x32_bf16 v[40:43], v[140:143], v[156:159], v[40:43]
	v_mfma_f32_16x16x32_bf16 v[28:31], v[132:135], v[164:167], v[28:31]
	v_mfma_f32_16x16x32_bf16 v[24:27], v[140:143], v[164:167], v[24:27]
	v_mfma_f32_16x16x32_bf16 v[12:15], v[132:135], v[172:175], v[12:15]
	v_mfma_f32_16x16x32_bf16 v[8:11], v[140:143], v[172:175], v[8:11]
	s_setprio 0
	s_barrier
; #define PG8_STAGE(bufoff, gbase, voff) do { _Pragma("unroll") for (int _i = 0; _i < 2; ++_i) \
;         __builtin_amdgcn_global_load_lds((const unsigned*)((const char*)(gbase) + (voff)[_i]), (LAS unsigned*)(lds + (bufoff) + ldsw + _i * 8192), 16, 0, 0); } while (0)
; #define PG8_LDA(dst, b, h) do { _Pragma("unroll") for (int m = 0; m < 4; ++m) _Pragma("unroll") for (int k = 0; k < 2; ++k) dst[m][k] = *(const LAS bf16x8*)(lds + PG8_SA(b, h) + aoff + m * 2048 + k * 1024); } while (0)
; #define PG8_LDB(dst, b, h) do { _Pragma("unroll") for (int n = 0; n < 2; ++n) _Pragma("unroll") for (int k = 0; k < 2; ++k) dst[n][k] = *(const LAS bf16x8*)(lds + PG8_SB(b, h) + boff + n * 2048 + k * 1024); } while (0)
; #define PG8_MMA(ai, bj, At, Bt) do { __builtin_amdgcn_s_setprio(1); _Pragma("unroll") for (int m = 0; m < 4; ++m) _Pragma("unroll") for (int n = 0; n < 2; ++n) _Pragma("unroll") for (int k = 0; k < 2; ++k) \
;         acc[ai][bj][m][n] = __builtin_amdgcn_mfma_f32_16x16x32_bf16(Bt[n][k], At[m][k], acc[ai][bj][m][n], 0, 0, 0); __builtin_amdgcn_s_setprio(0); } while (0)
; #define PG8_WAIT_V(n) asm volatile("s_waitcnt vmcnt(" #n ")" ::: "memory")
; #define PG8_WAIT_L(n) asm volatile("s_waitcnt lgkmcnt(" #n ")" ::: "memory")
; #define PG8_BAR __builtin_amdgcn_s_barrier()
; #define PG8_SCHED __builtin_amdgcn_sched_barrier(0)
; template <class Epi>
; __device__ __forceinline__ void gemm_phase(LAS unsigned char* lds, const GSched& S, const int K, const int lda, const int ldb, const Epi& E) {
;     ...
;             PG8_STAGE(PG8_SB(0, 1), b2 + hstepB, voffB);
;             PG8_WAIT_V(6); PG8_BAR; if constexpr (!Epi::NARROW) PG8_MMA(1, 1, At, B1); PG8_BAR;
;             PG8_LDB(B0, 1, 0); PG8_SCHED; PG8_LDA(At, 1, 0); PG8_STAGE(PG8_SA(0, 1), a2 + hstepA, voffA);
;             PG8_WAIT_L(8); PG8_BAR; PG8_WAIT_L(0); PG8_MMA(0, 0, At, B0); PG8_BAR; PG8_SCHED;
;             if constexpr (!Epi::NARROW) PG8_LDB(B1, 1, 1); PG8_STAGE(PG8_SB(1, 0), b3, voffB);
;             PG8_BAR; PG8_WAIT_L(0); if constexpr (!Epi::NARROW) PG8_MMA(0, 1, At, B1); PG8_BAR;
;             PG8_LDA(At, 1, 1); PG8_STAGE(PG8_SA(1, 0), a3, voffA);
;             PG8_BAR; PG8_WAIT_L(0); PG8_MMA(1, 0, At, B0); PG8_BAR; PG8_SCHED;
	s_add_u32 s80, s8, 0x20000
	s_addc_u32 s81, s9, 0
	s_add_i32 s3, s72, s59
	v_lshl_add_u64 v[128:129], s[80:81], 0, v[196:197]
	s_mov_b32 m0, s3
	s_nop 0
	global_load_lds_dwordx4 v[128:129], off
	v_lshl_add_u64 v[128:129], s[80:81], 0, v[192:193]
	s_add_i32 m0, s3, 0x2000
	s_nop 0
	global_load_lds_dwordx4 v[128:129], off
	s_waitcnt vmcnt(6)
	s_barrier
	s_setprio 1
	v_mfma_f32_16x16x32_bf16 v[52:55], v[176:179], v[144:147], v[52:55]
	v_mfma_f32_16x16x32_bf16 v[48:51], v[184:187], v[144:147], v[48:51]
	v_mfma_f32_16x16x32_bf16 v[36:39], v[176:179], v[152:155], v[36:39]
	v_mfma_f32_16x16x32_bf16 v[32:35], v[184:187], v[152:155], v[32:35]
	v_mfma_f32_16x16x32_bf16 v[20:23], v[176:179], v[160:163], v[20:23]
	v_mfma_f32_16x16x32_bf16 v[16:19], v[184:187], v[160:163], v[16:19]
	v_mfma_f32_16x16x32_bf16 v[4:7], v[176:179], v[168:171], v[4:7]
	v_mfma_f32_16x16x32_bf16 v[0:3], v[184:187], v[168:171], v[0:3]
	v_mfma_f32_16x16x32_bf16 v[52:55], v[180:183], v[148:151], v[52:55]
	v_mfma_f32_16x16x32_bf16 v[48:51], v[188:191], v[148:151], v[48:51]
	v_mfma_f32_16x16x32_bf16 v[36:39], v[180:183], v[156:159], v[36:39]
	v_mfma_f32_16x16x32_bf16 v[32:35], v[188:191], v[156:159], v[32:35]
	v_mfma_f32_16x16x32_bf16 v[20:23], v[180:183], v[164:167], v[20:23]
	v_mfma_f32_16x16x32_bf16 v[16:19], v[188:191], v[164:167], v[16:19]
	v_mfma_f32_16x16x32_bf16 v[4:7], v[180:183], v[172:175], v[4:7]
	v_mfma_f32_16x16x32_bf16 v[0:3], v[188:191], v[172:175], v[0:3]
	s_setprio 0
	s_add_i32 s3, 0, 0x18000
	v_add_u32_e32 v140, s3, v215
	s_barrier
	ds_read_b128 v[128:131], v140
	ds_read_b128 v[132:135], v140 offset:1024
	ds_read_b128 v[136:139], v140 offset:2048
	ds_read_b128 v[140:143], v140 offset:3072
	s_add_u32 s10, s10, 0x40000
	s_addc_u32 s11, s11, 0
	s_mov_b32 m0, s61
	v_lshl_add_u64 v[176:177], s[10:11], 0, v[198:199]
	ds_read_b128 v[144:147], v221 offset:32768
	ds_read_b128 v[148:151], v221 offset:33792
	ds_read_b128 v[152:155], v221 offset:34816
	ds_read_b128 v[156:159], v221 offset:35840
	ds_read_b128 v[160:163], v221 offset:36864
	ds_read_b128 v[164:167], v221 offset:37888
	ds_read_b128 v[168:171], v221 offset:38912
	ds_read_b128 v[172:175], v221 offset:39936
	global_load_lds_dwordx4 v[176:177], off
	v_lshl_add_u64 v[176:177], s[10:11], 0, v[194:195]
	s_mov_b32 m0, s62
	s_nop 0
	global_load_lds_dwordx4 v[176:177], off
	s_waitcnt lgkmcnt(8)
	s_barrier
	s_waitcnt lgkmcnt(0)
	s_setprio 1
	s_waitcnt lgkmcnt(0)
	v_mfma_f32_16x16x32_bf16 v[124:127], v[128:131], v[144:147], v[124:127]
	v_mfma_f32_16x16x32_bf16 v[120:123], v[136:139], v[144:147], v[120:123]
	v_mfma_f32_16x16x32_bf16 v[108:111], v[128:131], v[152:155], v[108:111]
	v_mfma_f32_16x16x32_bf16 v[104:107], v[136:139], v[152:155], v[104:107]
	v_mfma_f32_16x16x32_bf16 v[92:95], v[128:131], v[160:163], v[92:95]
	v_mfma_f32_16x16x32_bf16 v[88:91], v[136:139], v[160:163], v[88:91]
	v_mfma_f32_16x16x32_bf16 v[76:79], v[128:131], v[168:171], v[76:79]
	v_mfma_f32_16x16x32_bf16 v[72:75], v[136:139], v[168:171], v[72:75]
	v_mfma_f32_16x16x32_bf16 v[124:127], v[132:135], v[148:151], v[124:127]
	v_mfma_f32_16x16x32_bf16 v[120:123], v[140:143], v[148:151], v[120:123]
	v_mfma_f32_16x16x32_bf16 v[108:111], v[132:135], v[156:159], v[108:111]
	v_mfma_f32_16x16x32_bf16 v[104:107], v[140:143], v[156:159], v[104:107]
	v_mfma_f32_16x16x32_bf16 v[92:95], v[132:135], v[164:167], v[92:95]
	v_mfma_f32_16x16x32_bf16 v[88:91], v[140:143], v[164:167], v[88:91]
	v_mfma_f32_16x16x32_bf16 v[76:79], v[132:135], v[172:175], v[76:79]
	v_mfma_f32_16x16x32_bf16 v[72:75], v[140:143], v[172:175], v[72:75]
	s_setprio 0
	s_barrier
	s_add_i32 s10, 0, 0x1c000
	s_add_i32 s3, s3, s59
	v_add_u32_e32 v188, s10, v215
	v_lshl_add_u64 v[226:227], v[226:227], 0, s[36:37]
	s_mov_b32 m0, s3
	ds_read_b128 v[176:179], v188
	ds_read_b128 v[180:183], v188 offset:1024
	ds_read_b128 v[184:187], v188 offset:2048
	ds_read_b128 v[188:191], v188 offset:3072
	global_load_lds_dwordx4 v[226:227], off
	v_lshl_add_u64 v[226:227], v[228:229], 0, s[36:37]
	s_add_i32 m0, s3, 0x2000
	s_nop 0
	global_load_lds_dwordx4 v[226:227], off
	s_barrier
	s_waitcnt lgkmcnt(0)
	s_setprio 1
	s_waitcnt lgkmcnt(0)
	v_mfma_f32_16x16x32_bf16 v[116:119], v[176:179], v[144:147], v[116:119]
	v_mfma_f32_16x16x32_bf16 v[112:115], v[184:187], v[144:147], v[112:115]
	v_mfma_f32_16x16x32_bf16 v[100:103], v[176:179], v[152:155], v[100:103]
	v_mfma_f32_16x16x32_bf16 v[96:99], v[184:187], v[152:155], v[96:99]
	v_mfma_f32_16x16x32_bf16 v[84:87], v[176:179], v[160:163], v[84:87]
	v_mfma_f32_16x16x32_bf16 v[80:83], v[184:187], v[160:163], v[80:83]
	v_mfma_f32_16x16x32_bf16 v[68:71], v[176:179], v[168:171], v[68:71]
	v_mfma_f32_16x16x32_bf16 v[64:67], v[184:187], v[168:171], v[64:67]
	v_mfma_f32_16x16x32_bf16 v[116:119], v[180:183], v[148:151], v[116:119]
	v_mfma_f32_16x16x32_bf16 v[112:115], v[188:191], v[148:151], v[112:115]
	v_mfma_f32_16x16x32_bf16 v[100:103], v[180:183], v[156:159], v[100:103]
	v_mfma_f32_16x16x32_bf16 v[96:99], v[188:191], v[156:159], v[96:99]
	v_mfma_f32_16x16x32_bf16 v[84:87], v[180:183], v[164:167], v[84:87]
	v_mfma_f32_16x16x32_bf16 v[80:83], v[188:191], v[164:167], v[80:83]
	v_mfma_f32_16x16x32_bf16 v[68:71], v[180:183], v[172:175], v[68:71]
	v_mfma_f32_16x16x32_bf16 v[64:67], v[188:191], v[172:175], v[64:67]
	s_setprio 0
	s_mov_b32 m0, s66
	v_lshl_add_u64 v[226:227], v[234:235], 0, s[36:37]
	s_barrier
	ds_read_b128 v[144:147], v221 offset:49152
	ds_read_b128 v[148:151], v221 offset:50176
	ds_read_b128 v[152:155], v221 offset:51200
	ds_read_b128 v[156:159], v221 offset:52224
	ds_read_b128 v[160:163], v221 offset:53248
	ds_read_b128 v[164:167], v221 offset:54272
	ds_read_b128 v[168:171], v221 offset:55296
	ds_read_b128 v[172:175], v221 offset:56320
	global_load_lds_dwordx4 v[226:227], off
	v_lshl_add_u64 v[226:227], v[236:237], 0, s[36:37]
	s_mov_b32 m0, s67
	s_nop 0
	global_load_lds_dwordx4 v[226:227], off
	s_barrier
; #define PG8_STAGE(bufoff, gbase, voff) do { _Pragma("unroll") for (int _i = 0; _i < 2; ++_i) \
;         __builtin_amdgcn_global_load_lds((const unsigned*)((const char*)(gbase) + (voff)[_i]), (LAS unsigned*)(lds + (bufoff) + ldsw + _i * 8192), 16, 0, 0); } while (0)
; #define PG8_MMA(ai, bj, At, Bt) do { __builtin_amdgcn_s_setprio(1); _Pragma("unroll") for (int m = 0; m < 4; ++m) _Pragma("unroll") for (int n = 0; n < 2; ++n) _Pragma("unroll") for (int k = 0; k < 2; ++k) \
;         acc[ai][bj][m][n] = __builtin_amdgcn_mfma_f32_16x16x32_bf16(Bt[n][k], At[m][k], acc[ai][bj][m][n], 0, 0, 0); __builtin_amdgcn_s_setprio(0); } while (0)
; #define PG8_WAIT_V(n) asm volatile("s_waitcnt vmcnt(" #n ")" ::: "memory")
; #define PG8_WAIT_L(n) asm volatile("s_waitcnt lgkmcnt(" #n ")" ::: "memory")
; #define PG8_BAR __builtin_amdgcn_s_barrier()
; #define PG8_SCHED __builtin_amdgcn_sched_barrier(0)
; template <class Epi>
; __device__ __forceinline__ void gemm_phase(LAS unsigned char* lds, const GSched& S, const int K, const int lda, const int ldb, const Epi& E) {
;     ...
;             PG8_BAR; PG8_WAIT_L(0); PG8_MMA(1, 0, At, B0); PG8_BAR; PG8_SCHED;
;             PG8_STAGE(PG8_SB(1, 1), b3 + hstepB, voffB);
;             PG8_WAIT_V(6); PG8_BAR; if constexpr (!Epi::NARROW) PG8_MMA(1, 1, At, B1); PG8_BAR;
;             if constexpr (Epi::HAS_MID) { if (t + 2 == E.mid_t) { PG8_SCHED; E.mid(acc, cur, wr, wc, fr, fq); PG8_SCHED; } }
;         }
	s_waitcnt lgkmcnt(0)
	s_setprio 1
	v_mfma_f32_16x16x32_bf16 v[60:63], v[128:131], v[144:147], v[60:63]
	v_mfma_f32_16x16x32_bf16 v[56:59], v[136:139], v[144:147], v[56:59]
	v_mfma_f32_16x16x32_bf16 v[44:47], v[128:131], v[152:155], v[44:47]
	v_mfma_f32_16x16x32_bf16 v[40:43], v[136:139], v[152:155], v[40:43]
	v_mfma_f32_16x16x32_bf16 v[28:31], v[128:131], v[160:163], v[28:31]
	v_mfma_f32_16x16x32_bf16 v[24:27], v[136:139], v[160:163], v[24:27]
	v_mfma_f32_16x16x32_bf16 v[12:15], v[128:131], v[168:171], v[12:15]
	v_mfma_f32_16x16x32_bf16 v[8:11], v[136:139], v[168:171], v[8:11]
	v_mfma_f32_16x16x32_bf16 v[60:63], v[132:135], v[148:151], v[60:63]
	v_mfma_f32_16x16x32_bf16 v[56:59], v[140:143], v[148:151], v[56:59]
	v_mfma_f32_16x16x32_bf16 v[44:47], v[132:135], v[156:159], v[44:47]
	v_mfma_f32_16x16x32_bf16 v[40:43], v[140:143], v[156:159], v[40:43]
	v_mfma_f32_16x16x32_bf16 v[28:31], v[132:135], v[164:167], v[28:31]
	v_mfma_f32_16x16x32_bf16 v[24:27], v[140:143], v[164:167], v[24:27]
	v_mfma_f32_16x16x32_bf16 v[12:15], v[132:135], v[172:175], v[12:15]
	v_mfma_f32_16x16x32_bf16 v[8:11], v[140:143], v[172:175], v[8:11]
	s_setprio 0
	s_barrier
	s_add_u32 s8, s8, 0x20080
	s_addc_u32 s9, s9, 0
	s_add_i32 s3, s10, s59
	v_lshl_add_u64 v[128:129], s[8:9], 0, v[196:197]
	s_mov_b32 m0, s3
	s_nop 0
	global_load_lds_dwordx4 v[128:129], off
	v_lshl_add_u64 v[128:129], s[8:9], 0, v[192:193]
	s_add_i32 m0, s3, 0x2000
	s_nop 0
	global_load_lds_dwordx4 v[128:129], off
	s_waitcnt vmcnt(6)
	s_barrier
	s_setprio 1
	v_mfma_f32_16x16x32_bf16 v[52:55], v[176:179], v[144:147], v[52:55]
	v_mfma_f32_16x16x32_bf16 v[48:51], v[184:187], v[144:147], v[48:51]
	v_mfma_f32_16x16x32_bf16 v[36:39], v[176:179], v[152:155], v[36:39]
	v_mfma_f32_16x16x32_bf16 v[32:35], v[184:187], v[152:155], v[32:35]
	v_mfma_f32_16x16x32_bf16 v[20:23], v[176:179], v[160:163], v[20:23]
	v_mfma_f32_16x16x32_bf16 v[16:19], v[184:187], v[160:163], v[16:19]
	v_mfma_f32_16x16x32_bf16 v[4:7], v[176:179], v[168:171], v[4:7]
	v_mfma_f32_16x16x32_bf16 v[0:3], v[184:187], v[168:171], v[0:3]
	v_mfma_f32_16x16x32_bf16 v[52:55], v[180:183], v[148:151], v[52:55]
	v_mfma_f32_16x16x32_bf16 v[48:51], v[188:191], v[148:151], v[48:51]
	v_mfma_f32_16x16x32_bf16 v[36:39], v[180:183], v[156:159], v[36:39]
	v_mfma_f32_16x16x32_bf16 v[32:35], v[188:191], v[156:159], v[32:35]
	v_mfma_f32_16x16x32_bf16 v[20:23], v[180:183], v[164:167], v[20:23]
	v_mfma_f32_16x16x32_bf16 v[16:19], v[188:191], v[164:167], v[16:19]
	v_mfma_f32_16x16x32_bf16 v[4:7], v[180:183], v[172:175], v[4:7]
	v_mfma_f32_16x16x32_bf16 v[0:3], v[188:191], v[172:175], v[0:3]
	s_setprio 0
	s_add_i32 s77, s77, 2
	s_add_u32 s43, s43, 0x100
	s_addc_u32 s45, s45, 0
	s_add_u32 s6, s6, 0x100
	s_addc_u32 s7, s7, 0
	s_cmp_gt_u32 s77, 5
	s_barrier
	s_cbranch_scc0 .LBB0_543
;     __device__ __forceinline__ void operator()(Acc& acc, const Unit& u, int wr, int wc, int fr, int fq, const float (&rsv)[8]) const {
;         const int row0 = u.pm * BM + wr * 64 + fr, col0 = u.pn * BM + wc * 32 + 8 * fq;
;         const int off0 = col0 % 192, off1 = (col0 + HALF) % 192;
;         const int ropebj = (u.z == 0) ? (off0 >= 128 ? 0 : (off1 >= 128 ? 1 : -1)) : -1;
;         const int kk = ((ropebj == 0 ? off0 : off1) - 128) >> 3;
;         f32x4 cs[8], sn[8];
;         if (ropebj >= 0) {
; #pragma unroll
;             for (int g = 0; g < 8; ++g) { const int pos = (row0 + (g >> 2) * HALF + (g & 3) * 16) & (SEQ - 1); cs[g] = *(const f32x4*)(rc + pos * 32 + 4 * kk); sn[g] = *(const f32x4*)(rsn + pos * 32 + 4 * kk); }
;         } else {
; #pragma unroll
;             for (int g = 0; g < 8; ++g) { cs[g] = (f32x4){1.f, 1.f, 1.f, 1.f}; sn[g] = (f32x4){0.f, 0.f, 0.f, 0.f}; }
;         }
	v_lshl_or_b32 v228, s0, 8, v217
	v_mul_hi_i32 v128, v228, s73
	v_lshrrev_b32_e32 v129, 31, v128
	v_lshrrev_b32_e32 v128, 5, v128
	v_add_u32_e32 v128, v128, v129
	v_mul_lo_u32 v128, v128, s64
	v_sub_u32_e32 v200, v228, v128
	v_or_b32_e32 v128, 0x80, v228
	v_mul_hi_i32 v129, v128, s73
	v_lshrrev_b32_e32 v130, 31, v129
	v_lshrrev_b32_e32 v129, 5, v129
	v_add_u32_e32 v129, v129, v130
	v_mul_lo_u32 v129, v129, s64
	v_sub_u32_e32 v227, v128, v129
	v_cmp_lt_i32_e32 vcc, s74, v227
	v_cmp_lt_i32_e64 s[8:9], s74, v200
	v_mov_b32_e32 v132, 0
	v_cndmask_b32_e64 v128, -1, 1, vcc
	v_cndmask_b32_e64 v128, v128, 0, s[8:9]
	v_cmp_eq_u32_e32 vcc, 0, v230
	v_lshl_add_u32 v226, s28, 8, v213
	s_and_b64 s[8:9], vcc, s[8:9]
	v_cndmask_b32_e32 v231, -1, v128, vcc
	v_mov_b32_e32 v128, 1.0
	v_cmp_lt_i32_e64 s[10:11], -1, v231
	v_mov_b32_e32 v133, v132
	v_mov_b32_e32 v134, v132
	v_mov_b32_e32 v135, v132
	v_mov_b32_e32 v136, v132
	v_mov_b32_e32 v137, v132
	v_mov_b32_e32 v138, v132
	v_mov_b32_e32 v139, v132
	v_mov_b32_e32 v144, v132
	v_mov_b32_e32 v145, v132
	v_mov_b32_e32 v146, v132
	v_mov_b32_e32 v147, v132
	v_mov_b32_e32 v152, v132
	v_mov_b32_e32 v153, v132
	v_mov_b32_e32 v154, v132
	v_mov_b32_e32 v155, v132
	v_mov_b32_e32 v160, v132
	v_mov_b32_e32 v161, v132
	v_mov_b32_e32 v162, v132
	v_mov_b32_e32 v163, v132
	v_mov_b32_e32 v168, v132
	v_mov_b32_e32 v169, v132
	v_mov_b32_e32 v170, v132
	v_mov_b32_e32 v171, v132
	v_mov_b32_e32 v176, v132
	v_mov_b32_e32 v177, v132
	v_mov_b32_e32 v178, v132
	v_mov_b32_e32 v179, v132
	v_mov_b32_e32 v184, v132
	v_mov_b32_e32 v185, v132
	v_mov_b32_e32 v186, v132
	v_mov_b32_e32 v187, v132
	v_mov_b32_e32 v129, v128
	v_mov_b32_e32 v130, v128
	v_mov_b32_e32 v131, v128
	v_mov_b32_e32 v188, v128
	v_mov_b32_e32 v189, v128
	v_mov_b32_e32 v190, v128
	v_mov_b32_e32 v191, v128
	v_mov_b32_e32 v180, v128
	v_mov_b32_e32 v181, v128
	v_mov_b32_e32 v182, v128
	v_mov_b32_e32 v183, v128
	v_mov_b32_e32 v172, v128
	v_mov_b32_e32 v173, v128
	v_mov_b32_e32 v174, v128
	v_mov_b32_e32 v175, v128
	v_mov_b32_e32 v164, v128
	v_mov_b32_e32 v165, v128
	v_mov_b32_e32 v166, v128
	v_mov_b32_e32 v167, v128
	v_mov_b32_e32 v156, v128
	v_mov_b32_e32 v157, v128
	v_mov_b32_e32 v158, v128
	v_mov_b32_e32 v159, v128
	v_mov_b32_e32 v148, v128
	v_mov_b32_e32 v149, v128
	v_mov_b32_e32 v150, v128
	v_mov_b32_e32 v151, v128
	v_mov_b32_e32 v140, v128
	v_mov_b32_e32 v141, v128
	v_mov_b32_e32 v142, v128
	v_mov_b32_e32 v143, v128
	s_and_saveexec_b64 s[6:7], s[10:11]
	s_cbranch_execz .LBB0_546
	v_cndmask_b32_e64 v128, v227, v200, s[8:9]
	v_add_u32_e32 v128, 0xffffff80, v128
	v_ashrrev_i32_e32 v128, 1, v128
	v_and_b32_e32 v128, -4, v128
	v_ashrrev_i32_e32 v129, 31, v128
	v_lshlrev_b64 v[128:129], 2, v[128:129]
	v_lshlrev_b32_e32 v132, 7, v226
	v_lshl_add_u64 v[130:131], s[14:15], 0, v[128:129]
	v_and_b32_e32 v200, 0x3e780, v132
	v_lshl_add_u64 v[128:129], s[16:17], 0, v[128:129]
	v_lshl_add_u64 v[132:133], v[130:131], 0, v[200:201]
	v_lshl_add_u64 v[134:135], v[128:129], 0, v[200:201]
	global_load_dwordx4 v[188:191], v[132:133], off
	global_load_dwordx4 v[180:183], v[132:133], off offset:2048
	global_load_dwordx4 v[184:187], v[134:135], off
	global_load_dwordx4 v[176:179], v[134:135], off offset:2048
	v_or_b32_e32 v132, 0x1000, v200
	v_mov_b32_e32 v133, v201
	v_lshl_add_u64 v[134:135], v[130:131], 0, v[132:133]
	v_lshl_add_u64 v[132:133], v[128:129], 0, v[132:133]
	v_or_b32_e32 v200, 0x1800, v200
	global_load_dwordx4 v[172:175], v[134:135], off
	global_load_dwordx4 v[168:171], v[132:133], off
	v_lshl_add_u64 v[132:133], v[130:131], 0, v[200:201]
	v_lshl_add_u64 v[134:135], v[128:129], 0, v[200:201]
	global_load_dwordx4 v[164:167], v[132:133], off
	global_load_dwordx4 v[160:163], v[134:135], off
	v_lshl_add_u32 v132, v226, 5, v225
	v_and_b32_e32 v132, 0xf9e0, v132
	v_lshlrev_b32_e32 v200, 2, v132
	v_lshl_add_u64 v[132:133], v[130:131], 0, v[200:201]
	v_lshl_add_u64 v[134:135], v[128:129], 0, v[200:201]
	global_load_dwordx4 v[156:159], v[132:133], off
	global_load_dwordx4 v[148:151], v[132:133], off offset:2048
	global_load_dwordx4 v[152:155], v[134:135], off
	global_load_dwordx4 v[144:147], v[134:135], off offset:2048
	v_or_b32_e32 v132, 0x1000, v200
	v_mov_b32_e32 v133, v201
	v_lshl_add_u64 v[134:135], v[130:131], 0, v[132:133]
	v_lshl_add_u64 v[132:133], v[128:129], 0, v[132:133]
	v_or_b32_e32 v200, 0x1800, v200
	global_load_dwordx4 v[140:143], v[134:135], off
	global_load_dwordx4 v[136:139], v[132:133], off
	v_lshl_add_u64 v[130:131], v[130:131], 0, v[200:201]
	v_lshl_add_u64 v[132:133], v[128:129], 0, v[200:201]
	global_load_dwordx4 v[128:131], v[130:131], off
	s_nop 0
	global_load_dwordx4 v[132:135], v[132:133], off

; #define PG8_STAGE(bufoff, gbase, voff) do { _Pragma("unroll") for (int _i = 0; _i < 2; ++_i) \
;         __builtin_amdgcn_global_load_lds((const unsigned*)((const char*)(gbase) + (voff)[_i]), (LAS unsigned*)(lds + (bufoff) + ldsw + _i * 8192), 16, 0, 0); } while (0)
; #define PG8_LDA(dst, b, h) do { _Pragma("unroll") for (int m = 0; m < 4; ++m) _Pragma("unroll") for (int k = 0; k < 2; ++k) dst[m][k] = *(const LAS bf16x8*)(lds + PG8_SA(b, h) + aoff + m * 2048 + k * 1024); } while (0)
; #define PG8_LDB(dst, b, h) do { _Pragma("unroll") for (int n = 0; n < 2; ++n) _Pragma("unroll") for (int k = 0; k < 2; ++k) dst[n][k] = *(const LAS bf16x8*)(lds + PG8_SB(b, h) + boff + n * 2048 + k * 1024); } while (0)
; #define PG8_MMA(ai, bj, At, Bt) do { __builtin_amdgcn_s_setprio(1); _Pragma("unroll") for (int m = 0; m < 4; ++m) _Pragma("unroll") for (int n = 0; n < 2; ++n) _Pragma("unroll") for (int k = 0; k < 2; ++k) \
;         acc[ai][bj][m][n] = __builtin_amdgcn_mfma_f32_16x16x32_bf16(Bt[n][k], At[m][k], acc[ai][bj][m][n], 0, 0, 0); __builtin_amdgcn_s_setprio(0); } while (0)
; #define PG8_WAIT_V(n) asm volatile("s_waitcnt vmcnt(" #n ")" ::: "memory")
; #define PG8_BAR __builtin_amdgcn_s_barrier()
; template <class Epi>
; __device__ __forceinline__ void gemm_phase(LAS unsigned char* lds, const GSched& S, const int K, const int lda, const int ldb, const Epi& E) {
;     ...
;             PG8_LDB(B0, 0, 0); PG8_SCHED; PG8_LDA(At, 0, 0); PG8_STAGE(PG8_SA(1, 1), a1 + hstepA, voffA);
;             PG8_WAIT_L(8); PG8_BAR; PG8_WAIT_L(0); PG8_MMA(0, 0, At, B0); PG8_BAR; PG8_SCHED;
;             if constexpr (!Epi::NARROW) PG8_LDB(B1, 0, 1); PG8_STAGE(PG8_SB(0, 0), b2, voffB);
;             PG8_BAR; PG8_WAIT_L(0); if constexpr (!Epi::NARROW) PG8_MMA(0, 1, At, B1); PG8_BAR;
;             PG8_LDA(At, 0, 1); PG8_STAGE(PG8_SA(0, 0), a2, voffA);
;             PG8_BAR; PG8_WAIT_L(0); PG8_MMA(1, 0, At, B0); PG8_BAR; PG8_SCHED;
;             PG8_STAGE(PG8_SB(0, 1), b2 + hstepB, voffB);
;             PG8_WAIT_V(6); PG8_BAR; if constexpr (!Epi::NARROW) PG8_MMA(1, 1, At, B1); PG8_BAR;
;             PG8_LDB(B0, 1, 0); PG8_SCHED; PG8_LDA(At, 1, 0); PG8_STAGE(PG8_SA(0, 1), a2 + hstepA, voffA);
;             PG8_WAIT_L(8); PG8_BAR; PG8_WAIT_L(0); PG8_MMA(0, 0, At, B0); PG8_BAR; PG8_SCHED;
;             if constexpr (!Epi::NARROW) PG8_LDB(B1, 1, 1); PG8_STAGE(PG8_SB(1, 0), b3, voffB);
.LBB0_573:
	ds_read_b128 v[102:105], v97
	ds_read_b128 v[106:109], v97 offset:1024
	ds_read_b128 v[110:113], v97 offset:2048
	ds_read_b128 v[114:117], v97 offset:3072
	s_add_u32 s8, s6, 0x100
	s_addc_u32 s9, s7, 0
	s_cmp_eq_u32 s63, 28
	s_cselect_b32 s41, s15, s9
	s_cselect_b32 s40, s14, s8
	s_cselect_b32 s39, s17, s62
	s_cselect_b32 s38, s16, s3
	v_lshl_add_u64 v[150:151], s[6:7], 0, v[84:85]
	s_add_i32 m0, s43, 0xc000
	ds_read_b128 v[118:121], v99
	ds_read_b128 v[122:125], v99 offset:1024
	ds_read_b128 v[126:129], v99 offset:2048
	ds_read_b128 v[130:133], v99 offset:3072
	ds_read_b128 v[134:137], v99 offset:4096
	ds_read_b128 v[138:141], v99 offset:5120
	ds_read_b128 v[142:145], v99 offset:6144
	ds_read_b128 v[146:149], v99 offset:7168
	global_load_lds_dwordx4 v[150:151], off
	v_lshl_add_u64 v[150:151], s[6:7], 0, v[82:83]
	s_add_i32 m0, s43, 0xe000
	s_nop 0
	global_load_lds_dwordx4 v[150:151], off
	s_waitcnt lgkmcnt(8)
	s_barrier
	s_waitcnt lgkmcnt(0)
	s_setprio 1
	s_waitcnt lgkmcnt(0)
	v_mfma_f32_16x16x32_bf16 v[60:63], v[102:105], v[118:121], v[60:63]
	v_mfma_f32_16x16x32_bf16 v[56:59], v[110:113], v[118:121], v[56:59]
	v_mfma_f32_16x16x32_bf16 v[52:55], v[102:105], v[126:129], v[52:55]
	v_mfma_f32_16x16x32_bf16 v[48:51], v[110:113], v[126:129], v[48:51]
	v_mfma_f32_16x16x32_bf16 v[44:47], v[102:105], v[134:137], v[44:47]
	v_mfma_f32_16x16x32_bf16 v[40:43], v[110:113], v[134:137], v[40:43]
	v_mfma_f32_16x16x32_bf16 v[36:39], v[102:105], v[142:145], v[36:39]
	v_mfma_f32_16x16x32_bf16 v[32:35], v[110:113], v[142:145], v[32:35]
	v_mfma_f32_16x16x32_bf16 v[60:63], v[106:109], v[122:125], v[60:63]
	v_mfma_f32_16x16x32_bf16 v[56:59], v[114:117], v[122:125], v[56:59]
	v_mfma_f32_16x16x32_bf16 v[52:55], v[106:109], v[130:133], v[52:55]
	v_mfma_f32_16x16x32_bf16 v[48:51], v[114:117], v[130:133], v[48:51]
	v_mfma_f32_16x16x32_bf16 v[44:47], v[106:109], v[138:141], v[44:47]
	v_mfma_f32_16x16x32_bf16 v[40:43], v[114:117], v[138:141], v[40:43]
	v_mfma_f32_16x16x32_bf16 v[36:39], v[106:109], v[146:149], v[36:39]
	v_mfma_f32_16x16x32_bf16 v[32:35], v[114:117], v[146:149], v[32:35]
	s_setprio 0
	s_barrier
	s_add_i32 s6, s59, s42
	v_lshl_add_u64 v[150:151], s[38:39], 0, v[66:67]
	s_mov_b32 m0, s6
	v_lshl_add_u64 v[152:153], s[38:39], 0, v[70:71]
	global_load_lds_dwordx4 v[150:151], off
	s_add_i32 m0, s6, 0x2000
	v_lshl_add_u64 v[154:155], s[40:41], 0, v[64:65]
	global_load_lds_dwordx4 v[152:153], off
	s_mov_b32 m0, s43
	s_barrier
	s_waitcnt lgkmcnt(0)
	s_barrier
	ds_read_b128 v[118:121], v99 offset:16384
	ds_read_b128 v[122:125], v99 offset:17408
	ds_read_b128 v[126:129], v99 offset:18432
	ds_read_b128 v[130:133], v99 offset:19456
	ds_read_b128 v[134:137], v99 offset:20480
	ds_read_b128 v[138:141], v99 offset:21504
	ds_read_b128 v[142:145], v99 offset:22528
	ds_read_b128 v[146:149], v99 offset:23552
	global_load_lds_dwordx4 v[154:155], off
	v_lshl_add_u64 v[156:157], s[40:41], 0, v[68:69]
	s_mov_b32 m0, s44
	s_nop 0
	global_load_lds_dwordx4 v[156:157], off
	s_barrier
	s_waitcnt lgkmcnt(0)
	s_setprio 1
	s_waitcnt lgkmcnt(0)
	v_mfma_f32_16x16x32_bf16 v[28:31], v[102:105], v[118:121], v[28:31]
	v_mfma_f32_16x16x32_bf16 v[24:27], v[110:113], v[118:121], v[24:27]
	v_mfma_f32_16x16x32_bf16 v[20:23], v[102:105], v[126:129], v[20:23]
	v_mfma_f32_16x16x32_bf16 v[16:19], v[110:113], v[126:129], v[16:19]
	v_mfma_f32_16x16x32_bf16 v[12:15], v[102:105], v[134:137], v[12:15]
	v_mfma_f32_16x16x32_bf16 v[8:11], v[110:113], v[134:137], v[8:11]
	v_mfma_f32_16x16x32_bf16 v[4:7], v[102:105], v[142:145], v[4:7]
	v_mfma_f32_16x16x32_bf16 v[0:3], v[110:113], v[142:145], v[0:3]
	v_mfma_f32_16x16x32_bf16 v[28:31], v[106:109], v[122:125], v[28:31]
	v_mfma_f32_16x16x32_bf16 v[24:27], v[114:117], v[122:125], v[24:27]
	v_mfma_f32_16x16x32_bf16 v[20:23], v[106:109], v[130:133], v[20:23]
	v_mfma_f32_16x16x32_bf16 v[16:19], v[114:117], v[130:133], v[16:19]
	v_mfma_f32_16x16x32_bf16 v[12:15], v[106:109], v[138:141], v[12:15]
	v_mfma_f32_16x16x32_bf16 v[8:11], v[114:117], v[138:141], v[8:11]
	v_mfma_f32_16x16x32_bf16 v[4:7], v[106:109], v[146:149], v[4:7]
	v_mfma_f32_16x16x32_bf16 v[0:3], v[114:117], v[146:149], v[0:3]
	s_setprio 0
	s_barrier
	s_add_u32 s6, s38, 0x84000
	s_addc_u32 s7, s39, 0
	s_mov_b32 m0, s45
	v_lshl_add_u64 v[102:103], s[6:7], 0, v[66:67]
	global_load_lds_dwordx4 v[102:103], off
	v_lshl_add_u64 v[102:103], s[6:7], 0, v[70:71]
	s_mov_b32 m0, s46
	s_add_i32 s64, 0, 0x18000
	global_load_lds_dwordx4 v[102:103], off
	v_add_u32_e32 v72, s64, v95
	s_waitcnt vmcnt(6)
	s_barrier
	s_barrier
	ds_read_b128 v[102:105], v72
	ds_read_b128 v[106:109], v72 offset:1024
	ds_read_b128 v[110:113], v72 offset:2048
	ds_read_b128 v[114:117], v72 offset:3072
	s_add_u32 s6, s40, 0x94000
	s_addc_u32 s7, s41, 0
	s_mov_b32 m0, s47
	v_lshl_add_u64 v[158:159], s[6:7], 0, v[64:65]
	ds_read_b128 v[118:121], v99 offset:32768
	ds_read_b128 v[122:125], v99 offset:33792
	ds_read_b128 v[126:129], v99 offset:34816
	ds_read_b128 v[130:133], v99 offset:35840
	ds_read_b128 v[134:137], v99 offset:36864
	ds_read_b128 v[138:141], v99 offset:37888
	ds_read_b128 v[142:145], v99 offset:38912
	ds_read_b128 v[146:149], v99 offset:39936
	global_load_lds_dwordx4 v[158:159], off
	v_lshl_add_u64 v[158:159], s[6:7], 0, v[68:69]
	s_mov_b32 m0, s48
	s_nop 0
	global_load_lds_dwordx4 v[158:159], off
	s_waitcnt lgkmcnt(8)
	s_barrier
; #define PG8_STAGE(bufoff, gbase, voff) do { _Pragma("unroll") for (int _i = 0; _i < 2; ++_i) \
;         __builtin_amdgcn_global_load_lds((const unsigned*)((const char*)(gbase) + (voff)[_i]), (LAS unsigned*)(lds + (bufoff) + ldsw + _i * 8192), 16, 0, 0); } while (0)
; #define PG8_LDA(dst, b, h) do { _Pragma("unroll") for (int m = 0; m < 4; ++m) _Pragma("unroll") for (int k = 0; k < 2; ++k) dst[m][k] = *(const LAS bf16x8*)(lds + PG8_SA(b, h) + aoff + m * 2048 + k * 1024); } while (0)
; #define PG8_MMA(ai, bj, At, Bt) do { __builtin_amdgcn_s_setprio(1); _Pragma("unroll") for (int m = 0; m < 4; ++m) _Pragma("unroll") for (int n = 0; n < 2; ++n) _Pragma("unroll") for (int k = 0; k < 2; ++k) \
;         acc[ai][bj][m][n] = __builtin_amdgcn_mfma_f32_16x16x32_bf16(Bt[n][k], At[m][k], acc[ai][bj][m][n], 0, 0, 0); __builtin_amdgcn_s_setprio(0); } while (0)
; #define PG8_BAR __builtin_amdgcn_s_barrier()
;     __device__ __forceinline__ void operator()(Acc& acc, const Unit& u, int wr, int wc, int fr, int fq, const float (&rsv)[8]) const {
;         if (wc >= 2) return;
;         const int row0 = u.pm * BM + wr * 64 + fr, k = wc * 4 + fq;
; #pragma unroll
;         for (int ai = 0; ai < 2; ++ai)
; #pragma unroll
;             for (int m = 0; m < 4; ++m) {
;                 const int row = row0 + ai * HALF + m * 16; const float rs = rsv[ai * 4 + m]; const int pos = row & (SEQ - 1);
;                 const f32x4 c = *(const f32x4*)(rc + pos * 32 + 4 * k), s = *(const f32x4*)(rsn + pos * 32 + 4 * k);
;                 const f32x4 x1 = acc[ai][0][m][0] * rs, x2 = acc[ai][0][m][1] * rs;
;                 const f32x4 o1 = x1 * c - x2 * s, o2 = x2 * c + x1 * s;
; template <class Epi>
; __device__ __forceinline__ void gemm_phase(LAS unsigned char* lds, const GSched& S, const int K, const int lda, const int ldb, const Epi& E) {
;     ...
;             PG8_BAR; PG8_WAIT_L(0); if constexpr (!Epi::NARROW) PG8_MMA(0, 1, At, B1); PG8_BAR;
;             PG8_LDA(At, 1, 1); PG8_STAGE(PG8_SA(1, 0), a3, voffA);
;             PG8_BAR; PG8_WAIT_L(0); PG8_MMA(1, 0, At, B0); PG8_BAR; PG8_SCHED;
;             PG8_STAGE(PG8_SB(1, 1), b3 + hstepB, voffB);
;             PG8_WAIT_V(6); PG8_BAR; if constexpr (!Epi::NARROW) PG8_MMA(1, 1, At, B1); PG8_BAR;
;             if constexpr (Epi::HAS_MID) { if (t + 2 == E.mid_t) { PG8_SCHED; E.mid(acc, cur, wr, wc, fr, fq); PG8_SCHED; } }
;         }
	s_waitcnt lgkmcnt(0)
	s_setprio 1
	s_waitcnt lgkmcnt(0)
	v_mfma_f32_16x16x32_bf16 v[60:63], v[102:105], v[118:121], v[60:63]
	v_mfma_f32_16x16x32_bf16 v[56:59], v[110:113], v[118:121], v[56:59]
	v_mfma_f32_16x16x32_bf16 v[52:55], v[102:105], v[126:129], v[52:55]
	v_mfma_f32_16x16x32_bf16 v[48:51], v[110:113], v[126:129], v[48:51]
	v_mfma_f32_16x16x32_bf16 v[44:47], v[102:105], v[134:137], v[44:47]
	v_mfma_f32_16x16x32_bf16 v[40:43], v[110:113], v[134:137], v[40:43]
	v_mfma_f32_16x16x32_bf16 v[36:39], v[102:105], v[142:145], v[36:39]
	v_mfma_f32_16x16x32_bf16 v[32:35], v[110:113], v[142:145], v[32:35]
	v_mfma_f32_16x16x32_bf16 v[60:63], v[106:109], v[122:125], v[60:63]
	v_mfma_f32_16x16x32_bf16 v[56:59], v[114:117], v[122:125], v[56:59]
	v_mfma_f32_16x16x32_bf16 v[52:55], v[106:109], v[130:133], v[52:55]
	v_mfma_f32_16x16x32_bf16 v[48:51], v[114:117], v[130:133], v[48:51]
	v_mfma_f32_16x16x32_bf16 v[44:47], v[106:109], v[138:141], v[44:47]
	v_mfma_f32_16x16x32_bf16 v[40:43], v[114:117], v[138:141], v[40:43]
	v_mfma_f32_16x16x32_bf16 v[36:39], v[106:109], v[146:149], v[36:39]
	v_mfma_f32_16x16x32_bf16 v[32:35], v[114:117], v[146:149], v[32:35]
	s_setprio 0
	s_barrier
	s_add_i32 s6, s64, s42
	v_lshl_add_u64 v[118:119], v[150:151], 0, s[30:31]
	s_mov_b32 m0, s6
	v_lshl_add_u64 v[150:151], v[154:155], 0, s[30:31]
	global_load_lds_dwordx4 v[118:119], off
	v_lshl_add_u64 v[118:119], v[152:153], 0, s[30:31]
	s_add_i32 m0, s6, 0x2000
	s_nop 0
	global_load_lds_dwordx4 v[118:119], off
	s_mov_b32 m0, s53
	s_barrier
	s_waitcnt lgkmcnt(0)
	s_barrier
	ds_read_b128 v[118:121], v99 offset:49152
	ds_read_b128 v[122:125], v99 offset:50176
	ds_read_b128 v[126:129], v99 offset:51200
	ds_read_b128 v[130:133], v99 offset:52224
	ds_read_b128 v[134:137], v99 offset:53248
	ds_read_b128 v[138:141], v99 offset:54272
	ds_read_b128 v[142:145], v99 offset:55296
	ds_read_b128 v[146:149], v99 offset:56320
	global_load_lds_dwordx4 v[150:151], off
	v_lshl_add_u64 v[150:151], v[156:157], 0, s[30:31]
	s_mov_b32 m0, s54
	s_nop 0
	global_load_lds_dwordx4 v[150:151], off
	s_barrier
	s_waitcnt lgkmcnt(0)
	s_setprio 1
	v_mfma_f32_16x16x32_bf16 v[28:31], v[102:105], v[118:121], v[28:31]
	v_mfma_f32_16x16x32_bf16 v[24:27], v[110:113], v[118:121], v[24:27]
	v_mfma_f32_16x16x32_bf16 v[20:23], v[102:105], v[126:129], v[20:23]
	v_mfma_f32_16x16x32_bf16 v[16:19], v[110:113], v[126:129], v[16:19]
	v_mfma_f32_16x16x32_bf16 v[12:15], v[102:105], v[134:137], v[12:15]
	v_mfma_f32_16x16x32_bf16 v[8:11], v[110:113], v[134:137], v[8:11]
	v_mfma_f32_16x16x32_bf16 v[4:7], v[102:105], v[142:145], v[4:7]
	v_mfma_f32_16x16x32_bf16 v[0:3], v[110:113], v[142:145], v[0:3]
	v_mfma_f32_16x16x32_bf16 v[28:31], v[106:109], v[122:125], v[28:31]
	v_mfma_f32_16x16x32_bf16 v[24:27], v[114:117], v[122:125], v[24:27]
	v_mfma_f32_16x16x32_bf16 v[20:23], v[106:109], v[130:133], v[20:23]
	v_mfma_f32_16x16x32_bf16 v[16:19], v[114:117], v[130:133], v[16:19]
	v_mfma_f32_16x16x32_bf16 v[12:15], v[106:109], v[138:141], v[12:15]
	v_mfma_f32_16x16x32_bf16 v[8:11], v[114:117], v[138:141], v[8:11]
	v_mfma_f32_16x16x32_bf16 v[4:7], v[106:109], v[146:149], v[4:7]
	v_mfma_f32_16x16x32_bf16 v[0:3], v[114:117], v[146:149], v[0:3]
	s_setprio 0
	s_barrier
	s_add_u32 s6, s38, 0x84080
	s_addc_u32 s7, s39, 0
	s_mov_b32 m0, s55
	v_lshl_add_u64 v[102:103], s[6:7], 0, v[66:67]
	global_load_lds_dwordx4 v[102:103], off
	v_lshl_add_u64 v[102:103], s[6:7], 0, v[70:71]
	s_mov_b32 m0, s56
	s_add_i32 s63, s63, 2
	global_load_lds_dwordx4 v[102:103], off
	s_waitcnt vmcnt(6)
	s_add_u32 s3, s3, 0x100
	s_addc_u32 s62, s62, 0
	s_cmp_gt_u32 s63, 29
	s_mov_b64 s[6:7], s[8:9]
	s_barrier
	s_barrier
	s_cbranch_scc0 .LBB0_573
	s_andn2_b64 vcc, exec, s[34:35]
	s_cbranch_vccnz .LBB0_576
	v_lshl_add_u32 v102, s52, 8, v93
	v_lshlrev_b32_e32 v72, 7, v102
	v_and_b32_e32 v72, 0x3e780, v72
	v_lshl_add_u64 v[104:105], v[76:77], 0, v[72:73]
	global_load_dwordx4 v[104:107], v[104:105], off
	v_lshl_add_u64 v[108:109], v[74:75], 0, v[72:73]
	global_load_dwordx4 v[108:111], v[108:109], off
	v_pk_mul_f32 v[62:63], v[86:87], v[62:63] op_sel_hi:[0,1]
	v_pk_mul_f32 v[60:61], v[86:87], v[60:61] op_sel_hi:[0,1]
	v_pk_mul_f32 v[58:59], v[86:87], v[58:59] op_sel_hi:[0,1]
	v_pk_mul_f32 v[56:57], v[86:87], v[56:57] op_sel_hi:[0,1]
	v_ashrrev_i32_e32 v103, 31, v102
	v_or_b32_e32 v112, 16, v102
	v_lshlrev_b64 v[114:115], 7, v[102:103]
	v_lshlrev_b32_e32 v72, 7, v112
	v_lshl_add_u64 v[114:115], v[78:79], 0, v[114:115]
	v_and_b32_e32 v72, 0x3ef80, v72
	v_lshl_add_u64 v[116:117], v[76:77], 0, v[72:73]
	v_pk_mul_f32 v[54:55], v[88:89], v[54:55] op_sel_hi:[0,1]
	v_pk_mul_f32 v[52:53], v[88:89], v[52:53] op_sel_hi:[0,1]
	v_pk_mul_f32 v[50:51], v[88:89], v[50:51] op_sel_hi:[0,1]
	v_pk_mul_f32 v[48:49], v[88:89], v[48:49] op_sel_hi:[0,1]
	v_ashrrev_i32_e32 v113, 31, v112
	v_pk_mul_f32 v[46:47], v[90:91], v[46:47] op_sel_hi:[0,1]
	v_pk_mul_f32 v[44:45], v[90:91], v[44:45] op_sel_hi:[0,1]
	v_pk_mul_f32 v[42:43], v[90:91], v[42:43] op_sel_hi:[0,1]
	v_pk_mul_f32 v[40:41], v[90:91], v[40:41] op_sel_hi:[0,1]
	v_pk_mul_f32 v[38:39], v[92:93], v[38:39] op_sel_hi:[0,1]
	v_pk_mul_f32 v[36:37], v[92:93], v[36:37] op_sel_hi:[0,1]
	v_pk_mul_f32 v[34:35], v[92:93], v[34:35] op_sel_hi:[0,1]
	v_pk_mul_f32 v[32:33], v[92:93], v[32:33] op_sel_hi:[0,1]
	v_pk_mul_f32 v[30:31], v[94:95], v[30:31] op_sel_hi:[0,1]
	v_pk_mul_f32 v[28:29], v[94:95], v[28:29] op_sel_hi:[0,1]
	v_pk_mul_f32 v[26:27], v[94:95], v[26:27] op_sel_hi:[0,1]
	v_pk_mul_f32 v[24:25], v[94:95], v[24:25] op_sel_hi:[0,1]
	v_pk_mul_f32 v[22:23], v[96:97], v[22:23] op_sel_hi:[0,1]
	v_pk_mul_f32 v[20:21], v[96:97], v[20:21] op_sel_hi:[0,1]
	v_pk_mul_f32 v[18:19], v[96:97], v[18:19] op_sel_hi:[0,1]
	v_pk_mul_f32 v[16:17], v[96:97], v[16:17] op_sel_hi:[0,1]
	v_pk_mul_f32 v[14:15], v[98:99], v[14:15] op_sel_hi:[0,1]
	v_pk_mul_f32 v[12:13], v[98:99], v[12:13] op_sel_hi:[0,1]
	v_pk_mul_f32 v[10:11], v[98:99], v[10:11] op_sel_hi:[0,1]
	v_pk_mul_f32 v[8:9], v[98:99], v[8:9] op_sel_hi:[0,1]
	v_pk_mul_f32 v[6:7], v[100:101], v[6:7] op_sel_hi:[0,1]
	v_pk_mul_f32 v[4:5], v[100:101], v[4:5] op_sel_hi:[0,1]
	v_pk_mul_f32 v[2:3], v[100:101], v[2:3] op_sel_hi:[0,1]
	v_pk_mul_f32 v[0:1], v[100:101], v[0:1] op_sel_hi:[0,1]
	s_waitcnt vmcnt(0)
; __device__ __forceinline__ u32x4 pack8(const f32x4 a, const f32x4 b) { u32x4 w; w.x = cvt_pk_bf16(a[0], a[1]); w.y = cvt_pk_bf16(a[2], a[3]); w.z = cvt_pk_bf16(b[0], b[1]); w.w = cvt_pk_bf16(b[2], b[3]); return w; }
;     __device__ __forceinline__ void operator()(Acc& acc, const Unit& u, int wr, int wc, int fr, int fq, const float (&rsv)[8]) const {
;     ...
;         for (int ai = 0; ai < 2; ++ai)
; #pragma unroll
;             for (int m = 0; m < 4; ++m) {
;                 const int row = row0 + ai * HALF + m * 16; const float rs = rsv[ai * 4 + m]; const int pos = row & (SEQ - 1);
;                 const f32x4 c = *(const f32x4*)(rc + pos * 32 + 4 * k), s = *(const f32x4*)(rsn + pos * 32 + 4 * k);
;                 const f32x4 x1 = acc[ai][0][m][0] * rs, x2 = acc[ai][0][m][1] * rs;
;                 const f32x4 o1 = x1 * c - x2 * s, o2 = x2 * c + x1 * s;
;                 *(u32x4*)(krope + (size_t)row * 64 + wc * 32 + 8 * fq) = pack8(o1, o2);
;             }
	v_pk_mul_f32 v[118:119], v[58:59], v[106:107]
	v_pk_mul_f32 v[120:121], v[56:57], v[104:105]
	v_pk_mul_f32 v[106:107], v[62:63], v[106:107]
	v_pk_mul_f32 v[104:105], v[60:61], v[104:105]
	v_pk_fma_f32 v[62:63], v[62:63], v[110:111], v[118:119] neg_lo:[0,0,1] neg_hi:[0,0,1]
	v_pk_fma_f32 v[60:61], v[60:61], v[108:109], v[120:121] neg_lo:[0,0,1] neg_hi:[0,0,1]
	v_pk_fma_f32 v[106:107], v[58:59], v[110:111], v[106:107]
	v_pk_fma_f32 v[58:59], v[56:57], v[108:109], v[104:105]
	v_cvt_pk_bf16_f32 v56, v60, v61
	v_cvt_pk_bf16_f32 v57, v62, v63
	v_cvt_pk_bf16_f32 v58, v58, v59
	v_cvt_pk_bf16_f32 v59, v106, v107
	global_store_dwordx4 v[114:115], v[56:59], off
	global_load_dwordx4 v[56:59], v[116:117], off
	v_lshl_add_u64 v[60:61], v[74:75], 0, v[72:73]
	global_load_dwordx4 v[60:63], v[60:61], off
	v_or_b32_e32 v104, 32, v102
	v_lshlrev_b64 v[106:107], 7, v[112:113]
	v_lshlrev_b32_e32 v72, 7, v104
	v_lshl_add_u64 v[106:107], v[78:79], 0, v[106:107]
	v_and_b32_e32 v72, 0x3f780, v72
	v_lshl_add_u64 v[108:109], v[76:77], 0, v[72:73]
	v_ashrrev_i32_e32 v105, 31, v104
	s_waitcnt vmcnt(0)
	v_pk_mul_f32 v[110:111], v[50:51], v[58:59]
	v_pk_mul_f32 v[112:113], v[48:49], v[56:57]
	v_pk_mul_f32 v[58:59], v[54:55], v[58:59]
	v_pk_mul_f32 v[56:57], v[52:53], v[56:57]
	v_pk_fma_f32 v[54:55], v[54:55], v[62:63], v[110:111] neg_lo:[0,0,1] neg_hi:[0,0,1]
	v_pk_fma_f32 v[52:53], v[52:53], v[60:61], v[112:113] neg_lo:[0,0,1] neg_hi:[0,0,1]
	v_pk_fma_f32 v[58:59], v[50:51], v[62:63], v[58:59]
	v_pk_fma_f32 v[50:51], v[48:49], v[60:61], v[56:57]
	v_cvt_pk_bf16_f32 v48, v52, v53
	v_cvt_pk_bf16_f32 v49, v54, v55
	v_cvt_pk_bf16_f32 v50, v50, v51
	v_cvt_pk_bf16_f32 v51, v58, v59
	global_store_dwordx4 v[106:107], v[48:51], off
	global_load_dwordx4 v[48:51], v[108:109], off
	v_lshl_add_u64 v[52:53], v[74:75], 0, v[72:73]
	global_load_dwordx4 v[52:55], v[52:53], off
	v_or_b32_e32 v56, 48, v102
	v_lshlrev_b64 v[58:59], 7, v[104:105]
	v_lshlrev_b32_e32 v57, 7, v56
	v_lshl_add_u64 v[58:59], v[78:79], 0, v[58:59]
	v_and_b32_e32 v72, 0x3ff80, v57
	v_lshl_add_u64 v[60:61], v[76:77], 0, v[72:73]
	v_ashrrev_i32_e32 v57, 31, v56
	s_waitcnt vmcnt(0)
	v_pk_mul_f32 v[62:63], v[42:43], v[50:51]
	v_pk_mul_f32 v[104:105], v[40:41], v[48:49]
	v_pk_mul_f32 v[50:51], v[46:47], v[50:51]
	v_pk_mul_f32 v[48:49], v[44:45], v[48:49]
	v_pk_fma_f32 v[46:47], v[46:47], v[54:55], v[62:63] neg_lo:[0,0,1] neg_hi:[0,0,1]
	v_pk_fma_f32 v[44:45], v[44:45], v[52:53], v[104:105] neg_lo:[0,0,1] neg_hi:[0,0,1]
	v_pk_fma_f32 v[50:51], v[42:43], v[54:55], v[50:51]
	v_pk_fma_f32 v[42:43], v[40:41], v[52:53], v[48:49]
	v_cvt_pk_bf16_f32 v40, v44, v45
	v_cvt_pk_bf16_f32 v41, v46, v47
	v_cvt_pk_bf16_f32 v42, v42, v43
	v_cvt_pk_bf16_f32 v43, v50, v51
	global_store_dwordx4 v[58:59], v[40:43], off
	global_load_dwordx4 v[40:43], v[60:61], off
	v_lshl_add_u64 v[44:45], v[74:75], 0, v[72:73]
	global_load_dwordx4 v[44:47], v[44:45], off
	v_add_u32_e32 v48, 0x80, v102
	v_lshlrev_b64 v[50:51], 7, v[56:57]
	v_lshlrev_b32_e32 v49, 7, v48
	v_lshl_add_u64 v[50:51], v[78:79], 0, v[50:51]
	v_and_b32_e32 v72, 0x3e780, v49
	v_lshl_add_u64 v[52:53], v[76:77], 0, v[72:73]
	v_ashrrev_i32_e32 v49, 31, v48
	s_waitcnt vmcnt(0)
	v_pk_mul_f32 v[54:55], v[34:35], v[42:43]
	v_pk_mul_f32 v[56:57], v[32:33], v[40:41]
	v_pk_mul_f32 v[42:43], v[38:39], v[42:43]
	v_pk_mul_f32 v[40:41], v[36:37], v[40:41]
	v_pk_fma_f32 v[38:39], v[38:39], v[46:47], v[54:55] neg_lo:[0,0,1] neg_hi:[0,0,1]
	v_pk_fma_f32 v[36:37], v[36:37], v[44:45], v[56:57] neg_lo:[0,0,1] neg_hi:[0,0,1]
	v_pk_fma_f32 v[42:43], v[34:35], v[46:47], v[42:43]
	v_pk_fma_f32 v[34:35], v[32:33], v[44:45], v[40:41]
	v_cvt_pk_bf16_f32 v32, v36, v37
	v_cvt_pk_bf16_f32 v33, v38, v39
	v_cvt_pk_bf16_f32 v34, v34, v35
	v_cvt_pk_bf16_f32 v35, v42, v43
	global_store_dwordx4 v[50:51], v[32:35], off
	global_load_dwordx4 v[32:35], v[52:53], off
	v_lshl_add_u64 v[36:37], v[74:75], 0, v[72:73]
	global_load_dwordx4 v[36:39], v[36:37], off
	v_add_u32_e32 v40, 0x90, v102
	v_lshlrev_b64 v[42:43], 7, v[48:49]
	v_lshlrev_b32_e32 v41, 7, v40
	v_lshl_add_u64 v[42:43], v[78:79], 0, v[42:43]
	v_and_b32_e32 v72, 0x3ef80, v41
	v_lshl_add_u64 v[44:45], v[76:77], 0, v[72:73]
	v_ashrrev_i32_e32 v41, 31, v40
	s_waitcnt vmcnt(0)
; __device__ __forceinline__ u32x4 pack8(const f32x4 a, const f32x4 b) { u32x4 w; w.x = cvt_pk_bf16(a[0], a[1]); w.y = cvt_pk_bf16(a[2], a[3]); w.z = cvt_pk_bf16(b[0], b[1]); w.w = cvt_pk_bf16(b[2], b[3]); return w; }
;     __device__ __forceinline__ void operator()(Acc& acc, const Unit& u, int wr, int wc, int fr, int fq, const float (&rsv)[8]) const {
;     ...
;         for (int ai = 0; ai < 2; ++ai)
; #pragma unroll
;             for (int m = 0; m < 4; ++m) {
;                 const int row = row0 + ai * HALF + m * 16; const float rs = rsv[ai * 4 + m]; const int pos = row & (SEQ - 1);
;                 const f32x4 c = *(const f32x4*)(rc + pos * 32 + 4 * k), s = *(const f32x4*)(rsn + pos * 32 + 4 * k);
;                 const f32x4 x1 = acc[ai][0][m][0] * rs, x2 = acc[ai][0][m][1] * rs;
;                 const f32x4 o1 = x1 * c - x2 * s, o2 = x2 * c + x1 * s;
;                 *(u32x4*)(krope + (size_t)row * 64 + wc * 32 + 8 * fq) = pack8(o1, o2);
;             }
	v_pk_mul_f32 v[46:47], v[26:27], v[34:35]
	v_pk_mul_f32 v[48:49], v[24:25], v[32:33]
	v_pk_mul_f32 v[34:35], v[30:31], v[34:35]
	v_pk_mul_f32 v[32:33], v[28:29], v[32:33]
	v_pk_fma_f32 v[30:31], v[30:31], v[38:39], v[46:47] neg_lo:[0,0,1] neg_hi:[0,0,1]
	v_pk_fma_f32 v[28:29], v[28:29], v[36:37], v[48:49] neg_lo:[0,0,1] neg_hi:[0,0,1]
	v_pk_fma_f32 v[34:35], v[26:27], v[38:39], v[34:35]
	v_pk_fma_f32 v[26:27], v[24:25], v[36:37], v[32:33]
	v_cvt_pk_bf16_f32 v24, v28, v29
	v_cvt_pk_bf16_f32 v25, v30, v31
	v_cvt_pk_bf16_f32 v26, v26, v27
	v_cvt_pk_bf16_f32 v27, v34, v35
	global_store_dwordx4 v[42:43], v[24:27], off
	global_load_dwordx4 v[24:27], v[44:45], off
	v_lshl_add_u64 v[28:29], v[74:75], 0, v[72:73]
	global_load_dwordx4 v[28:31], v[28:29], off
	v_add_u32_e32 v32, 0xa0, v102
	v_lshlrev_b64 v[34:35], 7, v[40:41]
	v_lshlrev_b32_e32 v33, 7, v32
	v_lshl_add_u64 v[34:35], v[78:79], 0, v[34:35]
	v_and_b32_e32 v72, 0x3f780, v33
	v_lshl_add_u64 v[36:37], v[76:77], 0, v[72:73]
	v_ashrrev_i32_e32 v33, 31, v32
	s_waitcnt vmcnt(0)
	v_pk_mul_f32 v[38:39], v[18:19], v[26:27]
	v_pk_mul_f32 v[40:41], v[16:17], v[24:25]
	v_pk_mul_f32 v[26:27], v[22:23], v[26:27]
	v_pk_mul_f32 v[24:25], v[20:21], v[24:25]
	v_pk_fma_f32 v[22:23], v[22:23], v[30:31], v[38:39] neg_lo:[0,0,1] neg_hi:[0,0,1]
	v_pk_fma_f32 v[20:21], v[20:21], v[28:29], v[40:41] neg_lo:[0,0,1] neg_hi:[0,0,1]
	v_pk_fma_f32 v[26:27], v[18:19], v[30:31], v[26:27]
	v_pk_fma_f32 v[18:19], v[16:17], v[28:29], v[24:25]
	v_cvt_pk_bf16_f32 v16, v20, v21
	v_cvt_pk_bf16_f32 v17, v22, v23
	v_cvt_pk_bf16_f32 v18, v18, v19
	v_cvt_pk_bf16_f32 v19, v26, v27
	global_store_dwordx4 v[34:35], v[16:19], off
	global_load_dwordx4 v[16:19], v[36:37], off
	v_lshl_add_u64 v[20:21], v[74:75], 0, v[72:73]
	global_load_dwordx4 v[20:23], v[20:21], off
	v_add_u32_e32 v24, 0xb0, v102
	v_lshlrev_b64 v[26:27], 7, v[32:33]
	v_lshlrev_b32_e32 v25, 7, v24
	v_lshl_add_u64 v[26:27], v[78:79], 0, v[26:27]
	v_and_b32_e32 v72, 0x3ff80, v25
	v_lshl_add_u64 v[28:29], v[76:77], 0, v[72:73]
	v_ashrrev_i32_e32 v25, 31, v24
	s_waitcnt vmcnt(0)
	v_pk_mul_f32 v[30:31], v[10:11], v[18:19]
	v_pk_mul_f32 v[32:33], v[8:9], v[16:17]
	v_pk_mul_f32 v[18:19], v[14:15], v[18:19]
	v_pk_mul_f32 v[16:17], v[12:13], v[16:17]
	v_pk_fma_f32 v[14:15], v[14:15], v[22:23], v[30:31] neg_lo:[0,0,1] neg_hi:[0,0,1]
	v_pk_fma_f32 v[12:13], v[12:13], v[20:21], v[32:33] neg_lo:[0,0,1] neg_hi:[0,0,1]
	v_pk_fma_f32 v[18:19], v[10:11], v[22:23], v[18:19]
	v_pk_fma_f32 v[10:11], v[8:9], v[20:21], v[16:17]
	v_cvt_pk_bf16_f32 v8, v12, v13
	v_cvt_pk_bf16_f32 v9, v14, v15
	v_cvt_pk_bf16_f32 v10, v10, v11
	v_cvt_pk_bf16_f32 v11, v18, v19
	global_store_dwordx4 v[26:27], v[8:11], off
	global_load_dwordx4 v[8:11], v[28:29], off
	v_lshl_add_u64 v[12:13], v[74:75], 0, v[72:73]
	global_load_dwordx4 v[12:15], v[12:13], off
	v_lshlrev_b64 v[16:17], 7, v[24:25]
	s_waitcnt vmcnt(0)
	v_pk_mul_f32 v[18:19], v[2:3], v[10:11]
	v_pk_mul_f32 v[20:21], v[0:1], v[8:9]
	v_pk_mul_f32 v[10:11], v[6:7], v[10:11]
	v_pk_mul_f32 v[8:9], v[4:5], v[8:9]
	v_pk_fma_f32 v[6:7], v[6:7], v[14:15], v[18:19] neg_lo:[0,0,1] neg_hi:[0,0,1]
	v_pk_fma_f32 v[4:5], v[4:5], v[12:13], v[20:21] neg_lo:[0,0,1] neg_hi:[0,0,1]
	v_pk_fma_f32 v[10:11], v[2:3], v[14:15], v[10:11]
	v_pk_fma_f32 v[2:3], v[0:1], v[12:13], v[8:9]
	v_cvt_pk_bf16_f32 v0, v4, v5
	v_cvt_pk_bf16_f32 v1, v6, v7
	v_cvt_pk_bf16_f32 v2, v2, v3
	v_cvt_pk_bf16_f32 v3, v10, v11
	v_lshl_add_u64 v[4:5], v[78:79], 0, v[16:17]
	global_store_dwordx4 v[4:5], v[0:3], off

; #define PG8_STAGE(bufoff, gbase, voff) do { _Pragma("unroll") for (int _i = 0; _i < 2; ++_i) \
;         __builtin_amdgcn_global_load_lds((const unsigned*)((const char*)(gbase) + (voff)[_i]), (LAS unsigned*)(lds + (bufoff) + ldsw + _i * 8192), 16, 0, 0); } while (0)
; #define PG8_LDA(dst, b, h) do { _Pragma("unroll") for (int m = 0; m < 4; ++m) _Pragma("unroll") for (int k = 0; k < 2; ++k) dst[m][k] = *(const LAS bf16x8*)(lds + PG8_SA(b, h) + aoff + m * 2048 + k * 1024); } while (0)
; #define PG8_LDB(dst, b, h) do { _Pragma("unroll") for (int n = 0; n < 2; ++n) _Pragma("unroll") for (int k = 0; k < 2; ++k) dst[n][k] = *(const LAS bf16x8*)(lds + PG8_SB(b, h) + boff + n * 2048 + k * 1024); } while (0)
; #define PG8_MMA(ai, bj, At, Bt) do { __builtin_amdgcn_s_setprio(1); _Pragma("unroll") for (int m = 0; m < 4; ++m) _Pragma("unroll") for (int n = 0; n < 2; ++n) _Pragma("unroll") for (int k = 0; k < 2; ++k) \
;         acc[ai][bj][m][n] = __builtin_amdgcn_mfma_f32_16x16x32_bf16(Bt[n][k], At[m][k], acc[ai][bj][m][n], 0, 0, 0); __builtin_amdgcn_s_setprio(0); } while (0)
; #define PG8_WAIT_V(n) asm volatile("s_waitcnt vmcnt(" #n ")" ::: "memory")
; #define PG8_WAIT_L(n) asm volatile("s_waitcnt lgkmcnt(" #n ")" ::: "memory")
; #define PG8_BAR __builtin_amdgcn_s_barrier()
; #define PG8_SCHED __builtin_amdgcn_sched_barrier(0)
; template <class Epi>
; __device__ __forceinline__ void gemm_phase(LAS unsigned char* lds, const GSched& S, const int K, const int lda, const int ldb, const Epi& E) {
;     ...
;             PG8_LDB(B0, 0, 0); PG8_SCHED; PG8_LDA(At, 0, 0); PG8_STAGE(PG8_SA(1, 1), a1 + hstepA, voffA);
;             PG8_WAIT_L(8); PG8_BAR; PG8_WAIT_L(0); PG8_MMA(0, 0, At, B0); PG8_BAR; PG8_SCHED;
;             if constexpr (!Epi::NARROW) PG8_LDB(B1, 0, 1); PG8_STAGE(PG8_SB(0, 0), b2, voffB);
;             PG8_BAR; PG8_WAIT_L(0); if constexpr (!Epi::NARROW) PG8_MMA(0, 1, At, B1); PG8_BAR;
;             PG8_LDA(At, 0, 1); PG8_STAGE(PG8_SA(0, 0), a2, voffA);
;             PG8_BAR; PG8_WAIT_L(0); PG8_MMA(1, 0, At, B0); PG8_BAR; PG8_SCHED;
;             PG8_STAGE(PG8_SB(0, 1), b2 + hstepB, voffB);
;             PG8_WAIT_V(6); PG8_BAR; if constexpr (!Epi::NARROW) PG8_MMA(1, 1, At, B1); PG8_BAR;
.LBB0_769:
	ds_read_b128 v[166:169], v154
	ds_read_b128 v[170:173], v154 offset:1024
	ds_read_b128 v[174:177], v154 offset:2048
	ds_read_b128 v[178:181], v154 offset:3072
	s_add_u32 s34, s30, 0x100
	s_addc_u32 s35, s31, 0
	s_cmp_eq_u32 s64, 28
	s_cselect_b32 s39, s29, s35
	s_cselect_b32 s38, s28, s34
	s_cselect_b32 s37, s9, s5
	s_cselect_b32 s36, s8, s4
	v_lshl_add_u64 v[146:147], s[30:31], 0, v[140:141]
	s_add_i32 m0, s45, 0xc000
	ds_read_b128 v[182:185], v155
	ds_read_b128 v[186:189], v155 offset:1024
	ds_read_b128 v[190:193], v155 offset:2048
	ds_read_b128 v[194:197], v155 offset:3072
	ds_read_b128 v[198:201], v155 offset:4096
	ds_read_b128 v[202:205], v155 offset:5120
	ds_read_b128 v[206:209], v155 offset:6144
	ds_read_b128 v[210:213], v155 offset:7168
	global_load_lds_dwordx4 v[146:147], off
	v_lshl_add_u64 v[146:147], s[30:31], 0, v[138:139]
	s_add_i32 m0, s45, 0xe000
	s_nop 0
	global_load_lds_dwordx4 v[146:147], off
	s_waitcnt lgkmcnt(8)
	s_barrier
	s_waitcnt lgkmcnt(0)
	s_setprio 1
	s_waitcnt lgkmcnt(0)
	v_mfma_f32_16x16x32_bf16 v[124:127], v[166:169], v[182:185], v[124:127]
	v_mfma_f32_16x16x32_bf16 v[120:123], v[174:177], v[182:185], v[120:123]
	v_mfma_f32_16x16x32_bf16 v[108:111], v[166:169], v[190:193], v[108:111]
	v_mfma_f32_16x16x32_bf16 v[104:107], v[174:177], v[190:193], v[104:107]
	v_mfma_f32_16x16x32_bf16 v[92:95], v[166:169], v[198:201], v[92:95]
	v_mfma_f32_16x16x32_bf16 v[88:91], v[174:177], v[198:201], v[88:91]
	v_mfma_f32_16x16x32_bf16 v[76:79], v[166:169], v[206:209], v[76:79]
	v_mfma_f32_16x16x32_bf16 v[72:75], v[174:177], v[206:209], v[72:75]
	v_mfma_f32_16x16x32_bf16 v[124:127], v[170:173], v[186:189], v[124:127]
	v_mfma_f32_16x16x32_bf16 v[120:123], v[178:181], v[186:189], v[120:123]
	v_mfma_f32_16x16x32_bf16 v[108:111], v[170:173], v[194:197], v[108:111]
	v_mfma_f32_16x16x32_bf16 v[104:107], v[178:181], v[194:197], v[104:107]
	v_mfma_f32_16x16x32_bf16 v[92:95], v[170:173], v[202:205], v[92:95]
	v_mfma_f32_16x16x32_bf16 v[88:91], v[178:181], v[202:205], v[88:91]
	v_mfma_f32_16x16x32_bf16 v[76:79], v[170:173], v[210:213], v[76:79]
	v_mfma_f32_16x16x32_bf16 v[72:75], v[178:181], v[210:213], v[72:75]
	s_setprio 0
	s_barrier
	s_add_i32 s30, s58, s44
	v_lshl_add_u64 v[146:147], s[36:37], 0, v[130:131]
	s_mov_b32 m0, s30
	ds_read_b128 v[214:217], v156
	ds_read_b128 v[218:221], v156 offset:1024
	ds_read_b128 v[222:225], v156 offset:2048
	ds_read_b128 v[226:229], v156 offset:3072
	global_load_lds_dwordx4 v[146:147], off
	v_lshl_add_u64 v[230:231], s[36:37], 0, v[134:135]
	s_add_i32 m0, s30, 0x2000
	s_nop 0
	global_load_lds_dwordx4 v[230:231], off
	s_barrier
	s_waitcnt lgkmcnt(0)
	s_setprio 1
	v_mfma_f32_16x16x32_bf16 v[116:119], v[214:217], v[182:185], v[116:119]
	v_mfma_f32_16x16x32_bf16 v[112:115], v[222:225], v[182:185], v[112:115]
	v_mfma_f32_16x16x32_bf16 v[100:103], v[214:217], v[190:193], v[100:103]
	v_mfma_f32_16x16x32_bf16 v[96:99], v[222:225], v[190:193], v[96:99]
	v_mfma_f32_16x16x32_bf16 v[84:87], v[214:217], v[198:201], v[84:87]
	v_mfma_f32_16x16x32_bf16 v[80:83], v[222:225], v[198:201], v[80:83]
	v_mfma_f32_16x16x32_bf16 v[68:71], v[214:217], v[206:209], v[68:71]
	v_mfma_f32_16x16x32_bf16 v[64:67], v[222:225], v[206:209], v[64:67]
	v_mfma_f32_16x16x32_bf16 v[116:119], v[218:221], v[186:189], v[116:119]
	v_mfma_f32_16x16x32_bf16 v[112:115], v[226:229], v[186:189], v[112:115]
	v_mfma_f32_16x16x32_bf16 v[100:103], v[218:221], v[194:197], v[100:103]
	v_mfma_f32_16x16x32_bf16 v[96:99], v[226:229], v[194:197], v[96:99]
	v_mfma_f32_16x16x32_bf16 v[84:87], v[218:221], v[202:205], v[84:87]
	v_mfma_f32_16x16x32_bf16 v[80:83], v[226:229], v[202:205], v[80:83]
	v_mfma_f32_16x16x32_bf16 v[68:71], v[218:221], v[210:213], v[68:71]
	v_mfma_f32_16x16x32_bf16 v[64:67], v[226:229], v[210:213], v[64:67]
	s_setprio 0
	s_mov_b32 m0, s45
	v_lshl_add_u64 v[234:235], s[38:39], 0, v[128:129]
	s_barrier
	ds_read_b128 v[182:185], v155 offset:16384
	ds_read_b128 v[186:189], v155 offset:17408
	ds_read_b128 v[190:193], v155 offset:18432
	ds_read_b128 v[194:197], v155 offset:19456
	ds_read_b128 v[198:201], v155 offset:20480
	ds_read_b128 v[202:205], v155 offset:21504
	ds_read_b128 v[206:209], v155 offset:22528
	ds_read_b128 v[210:213], v155 offset:23552
	global_load_lds_dwordx4 v[234:235], off
	v_lshl_add_u64 v[236:237], s[38:39], 0, v[132:133]
	s_mov_b32 m0, s46
	s_nop 0
	global_load_lds_dwordx4 v[236:237], off
	s_barrier
	s_waitcnt lgkmcnt(0)
	s_setprio 1
	v_mfma_f32_16x16x32_bf16 v[60:63], v[166:169], v[182:185], v[60:63]
	v_mfma_f32_16x16x32_bf16 v[56:59], v[174:177], v[182:185], v[56:59]
	v_mfma_f32_16x16x32_bf16 v[44:47], v[166:169], v[190:193], v[44:47]
	v_mfma_f32_16x16x32_bf16 v[40:43], v[174:177], v[190:193], v[40:43]
	v_mfma_f32_16x16x32_bf16 v[28:31], v[166:169], v[198:201], v[28:31]
	v_mfma_f32_16x16x32_bf16 v[24:27], v[174:177], v[198:201], v[24:27]
	v_mfma_f32_16x16x32_bf16 v[12:15], v[166:169], v[206:209], v[12:15]
	v_mfma_f32_16x16x32_bf16 v[8:11], v[174:177], v[206:209], v[8:11]
	v_mfma_f32_16x16x32_bf16 v[60:63], v[170:173], v[186:189], v[60:63]
	v_mfma_f32_16x16x32_bf16 v[56:59], v[178:181], v[186:189], v[56:59]
	v_mfma_f32_16x16x32_bf16 v[44:47], v[170:173], v[194:197], v[44:47]
	v_mfma_f32_16x16x32_bf16 v[40:43], v[178:181], v[194:197], v[40:43]
	v_mfma_f32_16x16x32_bf16 v[28:31], v[170:173], v[202:205], v[28:31]
	v_mfma_f32_16x16x32_bf16 v[24:27], v[178:181], v[202:205], v[24:27]
	v_mfma_f32_16x16x32_bf16 v[12:15], v[170:173], v[210:213], v[12:15]
	v_mfma_f32_16x16x32_bf16 v[8:11], v[178:181], v[210:213], v[8:11]
	s_setprio 0
	s_barrier
; #define PG8_STAGE(bufoff, gbase, voff) do { _Pragma("unroll") for (int _i = 0; _i < 2; ++_i) \
;         __builtin_amdgcn_global_load_lds((const unsigned*)((const char*)(gbase) + (voff)[_i]), (LAS unsigned*)(lds + (bufoff) + ldsw + _i * 8192), 16, 0, 0); } while (0)
; #define PG8_LDA(dst, b, h) do { _Pragma("unroll") for (int m = 0; m < 4; ++m) _Pragma("unroll") for (int k = 0; k < 2; ++k) dst[m][k] = *(const LAS bf16x8*)(lds + PG8_SA(b, h) + aoff + m * 2048 + k * 1024); } while (0)
; #define PG8_LDB(dst, b, h) do { _Pragma("unroll") for (int n = 0; n < 2; ++n) _Pragma("unroll") for (int k = 0; k < 2; ++k) dst[n][k] = *(const LAS bf16x8*)(lds + PG8_SB(b, h) + boff + n * 2048 + k * 1024); } while (0)
; #define PG8_MMA(ai, bj, At, Bt) do { __builtin_amdgcn_s_setprio(1); _Pragma("unroll") for (int m = 0; m < 4; ++m) _Pragma("unroll") for (int n = 0; n < 2; ++n) _Pragma("unroll") for (int k = 0; k < 2; ++k) \
;         acc[ai][bj][m][n] = __builtin_amdgcn_mfma_f32_16x16x32_bf16(Bt[n][k], At[m][k], acc[ai][bj][m][n], 0, 0, 0); __builtin_amdgcn_s_setprio(0); } while (0)
; #define PG8_WAIT_V(n) asm volatile("s_waitcnt vmcnt(" #n ")" ::: "memory")
; #define PG8_WAIT_L(n) asm volatile("s_waitcnt lgkmcnt(" #n ")" ::: "memory")
; #define PG8_BAR __builtin_amdgcn_s_barrier()
; #define PG8_SCHED __builtin_amdgcn_sched_barrier(0)
; template <class Epi>
; __device__ __forceinline__ void gemm_phase(LAS unsigned char* lds, const GSched& S, const int K, const int lda, const int ldb, const Epi& E) {
;     ...
;             PG8_STAGE(PG8_SB(0, 1), b2 + hstepB, voffB);
;             PG8_WAIT_V(6); PG8_BAR; if constexpr (!Epi::NARROW) PG8_MMA(1, 1, At, B1); PG8_BAR;
;             PG8_LDB(B0, 1, 0); PG8_SCHED; PG8_LDA(At, 1, 0); PG8_STAGE(PG8_SA(0, 1), a2 + hstepA, voffA);
;             PG8_WAIT_L(8); PG8_BAR; PG8_WAIT_L(0); PG8_MMA(0, 0, At, B0); PG8_BAR; PG8_SCHED;
;             if constexpr (!Epi::NARROW) PG8_LDB(B1, 1, 1); PG8_STAGE(PG8_SB(1, 0), b3, voffB);
;             PG8_BAR; PG8_WAIT_L(0); if constexpr (!Epi::NARROW) PG8_MMA(0, 1, At, B1); PG8_BAR;
;             PG8_LDA(At, 1, 1); PG8_STAGE(PG8_SA(1, 0), a3, voffA);
;             PG8_BAR; PG8_WAIT_L(0); PG8_MMA(1, 0, At, B0); PG8_BAR; PG8_SCHED;
	s_add_u32 s30, s36, 0x84000
	s_addc_u32 s31, s37, 0
	s_add_i32 s65, s59, s44
	v_lshl_add_u64 v[166:167], s[30:31], 0, v[130:131]
	s_mov_b32 m0, s65
	s_nop 0
	global_load_lds_dwordx4 v[166:167], off
	v_lshl_add_u64 v[166:167], s[30:31], 0, v[134:135]
	s_add_i32 m0, s65, 0x2000
	s_nop 0
	global_load_lds_dwordx4 v[166:167], off
	s_waitcnt vmcnt(6)
	s_barrier
	s_setprio 1
	v_mfma_f32_16x16x32_bf16 v[52:55], v[214:217], v[182:185], v[52:55]
	v_mfma_f32_16x16x32_bf16 v[48:51], v[222:225], v[182:185], v[48:51]
	v_mfma_f32_16x16x32_bf16 v[36:39], v[214:217], v[190:193], v[36:39]
	v_mfma_f32_16x16x32_bf16 v[32:35], v[222:225], v[190:193], v[32:35]
	v_mfma_f32_16x16x32_bf16 v[20:23], v[214:217], v[198:201], v[20:23]
	v_mfma_f32_16x16x32_bf16 v[16:19], v[222:225], v[198:201], v[16:19]
	v_mfma_f32_16x16x32_bf16 v[4:7], v[214:217], v[206:209], v[4:7]
	v_mfma_f32_16x16x32_bf16 v[0:3], v[222:225], v[206:209], v[0:3]
	v_mfma_f32_16x16x32_bf16 v[52:55], v[218:221], v[186:189], v[52:55]
	v_mfma_f32_16x16x32_bf16 v[48:51], v[226:229], v[186:189], v[48:51]
	v_mfma_f32_16x16x32_bf16 v[36:39], v[218:221], v[194:197], v[36:39]
	v_mfma_f32_16x16x32_bf16 v[32:35], v[226:229], v[194:197], v[32:35]
	v_mfma_f32_16x16x32_bf16 v[20:23], v[218:221], v[202:205], v[20:23]
	v_mfma_f32_16x16x32_bf16 v[16:19], v[226:229], v[202:205], v[16:19]
	v_mfma_f32_16x16x32_bf16 v[4:7], v[218:221], v[210:213], v[4:7]
	v_mfma_f32_16x16x32_bf16 v[0:3], v[226:229], v[210:213], v[0:3]
	s_setprio 0
	s_add_i32 s65, 0, 0x18000
	v_add_u32_e32 v165, s65, v152
	s_barrier
	ds_read_b128 v[166:169], v165
	ds_read_b128 v[170:173], v165 offset:1024
	ds_read_b128 v[174:177], v165 offset:2048
	ds_read_b128 v[178:181], v165 offset:3072
	s_add_u32 s30, s38, 0x94000
	s_addc_u32 s31, s39, 0
	s_mov_b32 m0, s47
	v_lshl_add_u64 v[214:215], s[30:31], 0, v[128:129]
	ds_read_b128 v[182:185], v155 offset:32768
	ds_read_b128 v[186:189], v155 offset:33792
	ds_read_b128 v[190:193], v155 offset:34816
	ds_read_b128 v[194:197], v155 offset:35840
	ds_read_b128 v[198:201], v155 offset:36864
	ds_read_b128 v[202:205], v155 offset:37888
	ds_read_b128 v[206:209], v155 offset:38912
	ds_read_b128 v[210:213], v155 offset:39936
	global_load_lds_dwordx4 v[214:215], off
	v_lshl_add_u64 v[214:215], s[30:31], 0, v[132:133]
	s_mov_b32 m0, s48
	s_nop 0
	global_load_lds_dwordx4 v[214:215], off
	s_waitcnt lgkmcnt(8)
	s_barrier
	s_waitcnt lgkmcnt(0)
	s_setprio 1
	s_waitcnt lgkmcnt(0)
	v_mfma_f32_16x16x32_bf16 v[124:127], v[166:169], v[182:185], v[124:127]
	v_mfma_f32_16x16x32_bf16 v[120:123], v[174:177], v[182:185], v[120:123]
	v_mfma_f32_16x16x32_bf16 v[108:111], v[166:169], v[190:193], v[108:111]
	v_mfma_f32_16x16x32_bf16 v[104:107], v[174:177], v[190:193], v[104:107]
	v_mfma_f32_16x16x32_bf16 v[92:95], v[166:169], v[198:201], v[92:95]
	v_mfma_f32_16x16x32_bf16 v[88:91], v[174:177], v[198:201], v[88:91]
	v_mfma_f32_16x16x32_bf16 v[76:79], v[166:169], v[206:209], v[76:79]
	v_mfma_f32_16x16x32_bf16 v[72:75], v[174:177], v[206:209], v[72:75]
	v_mfma_f32_16x16x32_bf16 v[124:127], v[170:173], v[186:189], v[124:127]
	v_mfma_f32_16x16x32_bf16 v[120:123], v[178:181], v[186:189], v[120:123]
	v_mfma_f32_16x16x32_bf16 v[108:111], v[170:173], v[194:197], v[108:111]
	v_mfma_f32_16x16x32_bf16 v[104:107], v[178:181], v[194:197], v[104:107]
	v_mfma_f32_16x16x32_bf16 v[92:95], v[170:173], v[202:205], v[92:95]
	v_mfma_f32_16x16x32_bf16 v[88:91], v[178:181], v[202:205], v[88:91]
	v_mfma_f32_16x16x32_bf16 v[76:79], v[170:173], v[210:213], v[76:79]
	v_mfma_f32_16x16x32_bf16 v[72:75], v[178:181], v[210:213], v[72:75]
	s_setprio 0
	s_barrier
	s_add_i32 s38, 0, 0x1c000
	s_add_i32 s30, s65, s44
	v_add_u32_e32 v165, s38, v152
	v_lshl_add_u64 v[146:147], v[146:147], 0, s[26:27]
	s_mov_b32 m0, s30
	ds_read_b128 v[214:217], v165
	ds_read_b128 v[218:221], v165 offset:1024
	ds_read_b128 v[222:225], v165 offset:2048
	ds_read_b128 v[226:229], v165 offset:3072
	global_load_lds_dwordx4 v[146:147], off
	v_lshl_add_u64 v[146:147], v[230:231], 0, s[26:27]
	s_add_i32 m0, s30, 0x2000
	s_nop 0
	global_load_lds_dwordx4 v[146:147], off
	s_barrier
	s_waitcnt lgkmcnt(0)
	s_setprio 1
	s_waitcnt lgkmcnt(0)
	v_mfma_f32_16x16x32_bf16 v[116:119], v[214:217], v[182:185], v[116:119]
	v_mfma_f32_16x16x32_bf16 v[112:115], v[222:225], v[182:185], v[112:115]
	v_mfma_f32_16x16x32_bf16 v[100:103], v[214:217], v[190:193], v[100:103]
	v_mfma_f32_16x16x32_bf16 v[96:99], v[222:225], v[190:193], v[96:99]
	v_mfma_f32_16x16x32_bf16 v[84:87], v[214:217], v[198:201], v[84:87]
	v_mfma_f32_16x16x32_bf16 v[80:83], v[222:225], v[198:201], v[80:83]
	v_mfma_f32_16x16x32_bf16 v[68:71], v[214:217], v[206:209], v[68:71]
	v_mfma_f32_16x16x32_bf16 v[64:67], v[222:225], v[206:209], v[64:67]
	v_mfma_f32_16x16x32_bf16 v[116:119], v[218:221], v[186:189], v[116:119]
	v_mfma_f32_16x16x32_bf16 v[112:115], v[226:229], v[186:189], v[112:115]
	v_mfma_f32_16x16x32_bf16 v[100:103], v[218:221], v[194:197], v[100:103]
	v_mfma_f32_16x16x32_bf16 v[96:99], v[226:229], v[194:197], v[96:99]
	v_mfma_f32_16x16x32_bf16 v[84:87], v[218:221], v[202:205], v[84:87]
	v_mfma_f32_16x16x32_bf16 v[80:83], v[226:229], v[202:205], v[80:83]
	v_mfma_f32_16x16x32_bf16 v[68:71], v[218:221], v[210:213], v[68:71]
	v_mfma_f32_16x16x32_bf16 v[64:67], v[226:229], v[210:213], v[64:67]
	s_setprio 0
	s_mov_b32 m0, s53
	v_lshl_add_u64 v[146:147], v[234:235], 0, s[26:27]
	s_barrier
	ds_read_b128 v[182:185], v155 offset:49152
	ds_read_b128 v[186:189], v155 offset:50176
	ds_read_b128 v[190:193], v155 offset:51200
	ds_read_b128 v[194:197], v155 offset:52224
	ds_read_b128 v[198:201], v155 offset:53248
	ds_read_b128 v[202:205], v155 offset:54272
	ds_read_b128 v[206:209], v155 offset:55296
	ds_read_b128 v[210:213], v155 offset:56320
	global_load_lds_dwordx4 v[146:147], off
	v_lshl_add_u64 v[146:147], v[236:237], 0, s[26:27]
	s_mov_b32 m0, s54
	s_nop 0
	global_load_lds_dwordx4 v[146:147], off
	s_barrier
; __device__ __forceinline__ void st_nt(float* p, f32x4 v) { __builtin_nontemporal_store(v, (f32x4*)p); }
;     __device__ __forceinline__ void operator()(Acc& acc, const Unit& u, int wr, int wc, int fr, int fq, const float (&rsv)[8]) const {
;         const int row0 = u.pm * BM + wr * 64 + fr, col = u.pn * HALF + wc * 32 + 8 * fq;
; #pragma unroll
;         for (int ai = 0; ai < 2; ++ai)
; #pragma unroll
;             for (int m = 0; m < 4; ++m) {
;                 const int row = row0 + ai * HALF + m * 16; const float rs = rsv[ai * 4 + m];
;                 f32x4 r0, r1, b0, b1;
; #pragma unroll
;                 for (int jj = 0; jj < 4; ++jj) {
;                     const float rsn = rs * -1.4426950408889634f;
;                     const float da0 = 1.0f + __builtin_amdgcn_exp2f(acc[ai][0][m][0][jj] * rsn), da1 = 1.0f + __builtin_amdgcn_exp2f(acc[ai][0][m][1][jj] * rsn);
;                     const float db0 = 1.0f + __builtin_amdgcn_exp2f(acc[ai][1][m][0][jj] * rsn), db1 = 1.0f + __builtin_amdgcn_exp2f(acc[ai][1][m][1][jj] * rsn);
;                     b0[jj] = __builtin_amdgcn_rcpf(db0); b1[jj] = __builtin_amdgcn_rcpf(db1);
;                     r0[jj] = db0 * __builtin_amdgcn_rcpf(da0); r1[jj] = db1 * __builtin_amdgcn_rcpf(da1); }
;                 st_nt(gates + (size_t)row * 4096 + col, pack8(r0, r1));
;                 st_nt(gates + (size_t)row * 4096 + 2048 + col, pack8(b0, b1));
; template <class Epi>
; __device__ __forceinline__ void gemm_phase(LAS unsigned char* lds, const GSched& S, const int K, const int lda, const int ldb, const Epi& E) {
;     ...
;             PG8_WAIT_V(6); PG8_BAR; if constexpr (!Epi::NARROW) PG8_MMA(1, 1, At, B1); PG8_BAR;
;             PG8_LDB(B0, 1, 0); PG8_SCHED; PG8_LDA(At, 1, 0); PG8_STAGE(PG8_SA(0, 1), a2 + hstepA, voffA);
;             PG8_WAIT_L(8); PG8_BAR; PG8_WAIT_L(0); PG8_MMA(0, 0, At, B0); PG8_BAR; PG8_SCHED;
;             if constexpr (!Epi::NARROW) PG8_LDB(B1, 1, 1); PG8_STAGE(PG8_SB(1, 0), b3, voffB);
;             PG8_BAR; PG8_WAIT_L(0); if constexpr (!Epi::NARROW) PG8_MMA(0, 1, At, B1); PG8_BAR;
;             PG8_LDA(At, 1, 1); PG8_STAGE(PG8_SA(1, 0), a3, voffA);
;             PG8_BAR; PG8_WAIT_L(0); PG8_MMA(1, 0, At, B0); PG8_BAR; PG8_SCHED;
;             PG8_STAGE(PG8_SB(1, 1), b3 + hstepB, voffB);
;             PG8_WAIT_V(6); PG8_BAR; if constexpr (!Epi::NARROW) PG8_MMA(1, 1, At, B1); PG8_BAR;
	s_waitcnt lgkmcnt(0)
	s_setprio 1
	v_mfma_f32_16x16x32_bf16 v[60:63], v[166:169], v[182:185], v[60:63]
	v_mfma_f32_16x16x32_bf16 v[56:59], v[174:177], v[182:185], v[56:59]
	v_mfma_f32_16x16x32_bf16 v[44:47], v[166:169], v[190:193], v[44:47]
	v_mfma_f32_16x16x32_bf16 v[40:43], v[174:177], v[190:193], v[40:43]
	v_mfma_f32_16x16x32_bf16 v[28:31], v[166:169], v[198:201], v[28:31]
	v_mfma_f32_16x16x32_bf16 v[24:27], v[174:177], v[198:201], v[24:27]
	v_mfma_f32_16x16x32_bf16 v[12:15], v[166:169], v[206:209], v[12:15]
	v_mfma_f32_16x16x32_bf16 v[8:11], v[174:177], v[206:209], v[8:11]
	v_mfma_f32_16x16x32_bf16 v[60:63], v[170:173], v[186:189], v[60:63]
	v_mfma_f32_16x16x32_bf16 v[56:59], v[178:181], v[186:189], v[56:59]
	v_mfma_f32_16x16x32_bf16 v[44:47], v[170:173], v[194:197], v[44:47]
	v_mfma_f32_16x16x32_bf16 v[40:43], v[178:181], v[194:197], v[40:43]
	v_mfma_f32_16x16x32_bf16 v[28:31], v[170:173], v[202:205], v[28:31]
	v_mfma_f32_16x16x32_bf16 v[24:27], v[178:181], v[202:205], v[24:27]
	v_mfma_f32_16x16x32_bf16 v[12:15], v[170:173], v[210:213], v[12:15]
	v_mfma_f32_16x16x32_bf16 v[8:11], v[178:181], v[210:213], v[8:11]
	s_setprio 0
	s_barrier
	s_add_u32 s30, s36, 0x84080
	s_addc_u32 s31, s37, 0
	s_add_i32 s36, s38, s44
	v_lshl_add_u64 v[146:147], s[30:31], 0, v[130:131]
	s_mov_b32 m0, s36
	s_nop 0
	global_load_lds_dwordx4 v[146:147], off
	v_lshl_add_u64 v[146:147], s[30:31], 0, v[134:135]
	s_add_i32 m0, s36, 0x2000
	s_nop 0
	global_load_lds_dwordx4 v[146:147], off
	s_waitcnt vmcnt(6)
	s_barrier
	s_setprio 1
	v_mfma_f32_16x16x32_bf16 v[52:55], v[214:217], v[182:185], v[52:55]
	v_mfma_f32_16x16x32_bf16 v[48:51], v[222:225], v[182:185], v[48:51]
	v_mfma_f32_16x16x32_bf16 v[36:39], v[214:217], v[190:193], v[36:39]
	v_mfma_f32_16x16x32_bf16 v[32:35], v[222:225], v[190:193], v[32:35]
	v_mfma_f32_16x16x32_bf16 v[20:23], v[214:217], v[198:201], v[20:23]
	v_mfma_f32_16x16x32_bf16 v[16:19], v[222:225], v[198:201], v[16:19]
	v_mfma_f32_16x16x32_bf16 v[4:7], v[214:217], v[206:209], v[4:7]
	v_mfma_f32_16x16x32_bf16 v[0:3], v[222:225], v[206:209], v[0:3]
	v_mfma_f32_16x16x32_bf16 v[52:55], v[218:221], v[186:189], v[52:55]
	v_mfma_f32_16x16x32_bf16 v[48:51], v[226:229], v[186:189], v[48:51]
	v_mfma_f32_16x16x32_bf16 v[36:39], v[218:221], v[194:197], v[36:39]
	v_mfma_f32_16x16x32_bf16 v[32:35], v[226:229], v[194:197], v[32:35]
	v_mfma_f32_16x16x32_bf16 v[20:23], v[218:221], v[202:205], v[20:23]
	v_mfma_f32_16x16x32_bf16 v[16:19], v[226:229], v[202:205], v[16:19]
	v_mfma_f32_16x16x32_bf16 v[4:7], v[218:221], v[210:213], v[4:7]
	v_mfma_f32_16x16x32_bf16 v[0:3], v[226:229], v[210:213], v[0:3]
	s_setprio 0
	s_add_i32 s64, s64, 2
	s_add_u32 s4, s4, 0x100
	s_addc_u32 s5, s5, 0
	s_cmp_gt_u32 s64, 29
	s_mov_b64 s[30:31], s[34:35]
	s_barrier
	s_cbranch_scc0 .LBB0_769
	v_mul_f32_e32 v147, 0xbfb8aa3b, v157
	v_mul_f32_e32 v120, v147, v120
	v_exp_f32_e32 v120, v120
	v_mul_f32_e32 v124, v147, v124
	v_exp_f32_e32 v124, v124
	v_mul_f32_e32 v116, v147, v116
	v_add_f32_e32 v165, 1.0, v120
	v_mul_f32_e32 v120, v147, v125
	v_exp_f32_e32 v125, v120
	v_mul_f32_e32 v120, v147, v121
	v_exp_f32_e32 v121, v120
	v_mul_f32_e32 v117, v147, v117
	v_add_f32_e32 v124, 1.0, v124
	v_exp_f32_e32 v116, v116
	v_add_f32_e32 v125, 1.0, v125
	v_exp_f32_e32 v117, v117
	v_rcp_f32_e32 v120, v124
	v_rcp_f32_e32 v124, v165
	v_add_f32_e32 v165, 1.0, v121
	v_rcp_f32_e32 v121, v125
	v_mul_f32_e32 v112, v147, v112
	v_mul_f32_e32 v113, v147, v113
	v_pk_add_f32 v[116:117], v[116:117], 1.0 op_sel_hi:[1,0]
	v_exp_f32_e32 v112, v112
	v_exp_f32_e32 v113, v113
	v_rcp_f32_e32 v168, v116
	v_pk_mul_f32 v[120:121], v[120:121], v[116:117]
	v_mul_f32_e32 v116, v147, v126
	v_rcp_f32_e32 v125, v165
	v_exp_f32_e32 v116, v116
	v_rcp_f32_e32 v169, v117
	v_pk_add_f32 v[112:113], v[112:113], 1.0 op_sel_hi:[1,0]
	v_mul_f32_e32 v117, v147, v122
	v_exp_f32_e32 v117, v117
	v_pk_mul_f32 v[124:125], v[124:125], v[112:113]
	v_rcp_f32_e32 v170, v113
	v_add_f32_e32 v113, 1.0, v116
	v_mul_f32_e32 v116, v147, v127
	v_exp_f32_e32 v122, v116
	v_mul_f32_e32 v116, v147, v123
	v_exp_f32_e32 v123, v116
	v_rcp_f32_e32 v165, v112
	v_add_f32_e32 v117, 1.0, v117
	v_mul_f32_e32 v112, v147, v118
	v_rcp_f32_e32 v116, v113
	v_mul_f32_e32 v113, v147, v119
	v_exp_f32_e32 v112, v112
	v_rcp_f32_e32 v118, v117
	v_add_f32_e32 v117, 1.0, v122
	v_exp_f32_e32 v113, v113
	v_mul_f32_e32 v114, v147, v114
	v_mul_f32_e32 v115, v147, v115
	v_rcp_f32_e32 v117, v117
	v_exp_f32_e32 v114, v114
	v_add_f32_e32 v126, 1.0, v123
	v_exp_f32_e32 v115, v115
	v_rcp_f32_e32 v119, v126
	v_pk_add_f32 v[112:113], v[112:113], 1.0 op_sel_hi:[1,0]
	v_lshl_add_u32 v146, s55, 8, v151
	v_pk_mul_f32 v[122:123], v[116:117], v[112:113]
	v_lshl_or_b32 v166, s2, 7, v153
	v_rcp_f32_e32 v171, v112
	v_rcp_f32_e32 v172, v113
	v_pk_add_f32 v[112:113], v[114:115], 1.0 op_sel_hi:[1,0]
	v_ashrrev_i32_e32 v147, 31, v146
	v_cvt_pk_bf16_f32 v117, v122, v123
	v_mul_f32_e32 v122, 0xbfb8aa3b, v158
	v_ashrrev_i32_e32 v167, 31, v166
	v_rcp_f32_e32 v173, v112
	v_pk_mul_f32 v[126:127], v[118:119], v[112:113]
	v_rcp_f32_e32 v174, v113
	v_lshlrev_b64 v[112:113], 13, v[146:147]
	v_mul_f32_e32 v104, v122, v104
	v_lshl_add_u64 v[112:113], s[24:25], 0, v[112:113]
	v_lshlrev_b64 v[114:115], 1, v[166:167]
	v_exp_f32_e32 v104, v104
	v_lshl_add_u64 v[112:113], v[112:113], 0, v[114:115]
	v_cvt_pk_bf16_f32 v116, v120, v121
	v_cvt_pk_bf16_f32 v118, v124, v125
	v_cvt_pk_bf16_f32 v119, v126, v127
	v_add_co_u32_e32 v120, vcc, s50, v112
	global_store_dwordx4 v[112:113], v[116:119], off nt
	s_nop 0
	v_addc_co_u32_e32 v121, vcc, 0, v113, vcc
	v_cvt_pk_bf16_f32 v116, v168, v169
	v_cvt_pk_bf16_f32 v117, v171, v172
; __device__ __forceinline__ void st_nt(float* p, f32x4 v) { __builtin_nontemporal_store(v, (f32x4*)p); }
; __device__ __forceinline__ void st_nt(bf16_t* p, u32x4 v) { __builtin_nontemporal_store(v, (u32x4*)p); }
; __device__ __forceinline__ u32x4 pack8(const f32x4 a, const f32x4 b) { u32x4 w; w.x = cvt_pk_bf16(a[0], a[1]); w.y = cvt_pk_bf16(a[2], a[3]); w.z = cvt_pk_bf16(b[0], b[1]); w.w = cvt_pk_bf16(b[2], b[3]); return w; }
;     __device__ __forceinline__ void operator()(Acc& acc, const Unit& u, int wr, int wc, int fr, int fq, const float (&rsv)[8]) const {
;         const int row0 = u.pm * BM + wr * 64 + fr, col = u.pn * HALF + wc * 32 + 8 * fq;
; #pragma unroll
;         for (int ai = 0; ai < 2; ++ai)
; #pragma unroll
;             for (int m = 0; m < 4; ++m) {
;                 const int row = row0 + ai * HALF + m * 16; const float rs = rsv[ai * 4 + m];
;                 f32x4 r0, r1, b0, b1;
; #pragma unroll
;                 for (int jj = 0; jj < 4; ++jj) {
;                     const float rsn = rs * -1.4426950408889634f;
;                     const float da0 = 1.0f + __builtin_amdgcn_exp2f(acc[ai][0][m][0][jj] * rsn), da1 = 1.0f + __builtin_amdgcn_exp2f(acc[ai][0][m][1][jj] * rsn);
;                     const float db0 = 1.0f + __builtin_amdgcn_exp2f(acc[ai][1][m][0][jj] * rsn), db1 = 1.0f + __builtin_amdgcn_exp2f(acc[ai][1][m][1][jj] * rsn);
;                     b0[jj] = __builtin_amdgcn_rcpf(db0); b1[jj] = __builtin_amdgcn_rcpf(db1);
;                     r0[jj] = db0 * __builtin_amdgcn_rcpf(da0); r1[jj] = db1 * __builtin_amdgcn_rcpf(da1); }
;                 st_nt(gates + (size_t)row * 4096 + col, pack8(r0, r1));
;                 st_nt(gates + (size_t)row * 4096 + 2048 + col, pack8(b0, b1));
	v_cvt_pk_bf16_f32 v118, v165, v170
	v_cvt_pk_bf16_f32 v119, v173, v174
	v_mul_f32_e32 v108, v122, v108
	global_store_dwordx4 v[120:121], v[116:119], off nt
	v_exp_f32_e32 v108, v108
	v_mul_f32_e32 v100, v122, v100
	v_add_f32_e32 v116, 1.0, v104
	v_mul_f32_e32 v104, v122, v109
	v_exp_f32_e32 v109, v104
	v_mul_f32_e32 v104, v122, v105
	v_exp_f32_e32 v105, v104
	v_mul_f32_e32 v101, v122, v101
	v_add_f32_e32 v108, 1.0, v108
	v_exp_f32_e32 v100, v100
	v_add_f32_e32 v109, 1.0, v109
	v_exp_f32_e32 v101, v101
	v_mul_f32_e32 v96, v122, v96
	v_rcp_f32_e32 v104, v108
	v_rcp_f32_e32 v108, v116
	v_add_f32_e32 v116, 1.0, v105
	v_mul_f32_e32 v97, v122, v97
	v_rcp_f32_e32 v105, v109
	v_exp_f32_e32 v96, v96
	v_exp_f32_e32 v97, v97
	v_rcp_f32_e32 v109, v116
	v_pk_add_f32 v[100:101], v[100:101], 1.0 op_sel_hi:[1,0]
	v_mul_f32_e32 v98, v122, v98
	v_rcp_f32_e32 v117, v100
	v_pk_mul_f32 v[104:105], v[104:105], v[100:101]
	v_mul_f32_e32 v100, v122, v110
	v_pk_add_f32 v[96:97], v[96:97], 1.0 op_sel_hi:[1,0]
	v_exp_f32_e32 v110, v100
	v_mul_f32_e32 v100, v122, v106
	v_rcp_f32_e32 v118, v101
	v_rcp_f32_e32 v116, v96
	v_exp_f32_e32 v106, v100
	v_pk_mul_f32 v[100:101], v[108:109], v[96:97]
	v_mul_f32_e32 v96, v122, v102
	v_mul_f32_e32 v102, v122, v111
	v_exp_f32_e32 v108, v102
	v_mul_f32_e32 v102, v122, v107
	v_exp_f32_e32 v107, v102
	v_rcp_f32_e32 v119, v97
	v_add_f32_e32 v97, 1.0, v110
	v_rcp_f32_e32 v102, v97
	v_mul_f32_e32 v97, v122, v103
	v_exp_f32_e32 v96, v96
	v_add_f32_e32 v108, 1.0, v108
	v_exp_f32_e32 v97, v97
	v_mul_f32_e32 v99, v122, v99
	v_add_f32_e32 v106, 1.0, v106
	v_exp_f32_e32 v98, v98
	v_add_f32_e32 v107, 1.0, v107
	v_rcp_f32_e32 v103, v108
	v_exp_f32_e32 v99, v99
	v_rcp_f32_e32 v106, v106
	v_rcp_f32_e32 v107, v107
	v_pk_add_f32 v[96:97], v[96:97], 1.0 op_sel_hi:[1,0]
	s_mov_b64 s[30:31], -1
	v_rcp_f32_e32 v110, v96
	v_pk_mul_f32 v[102:103], v[102:103], v[96:97]
	v_rcp_f32_e32 v111, v97
	v_pk_add_f32 v[96:97], v[98:99], 1.0 op_sel_hi:[1,0]
	v_cvt_pk_bf16_f32 v98, v100, v101
	v_rcp_f32_e32 v120, v96
	v_pk_mul_f32 v[106:107], v[106:107], v[96:97]
	v_or_b32_e32 v96, 16, v146
	v_rcp_f32_e32 v121, v97
	v_ashrrev_i32_e32 v97, 31, v96
	v_lshlrev_b64 v[96:97], 13, v[96:97]
	v_lshl_add_u64 v[96:97], s[24:25], 0, v[96:97]
	v_lshl_add_u64 v[108:109], v[96:97], 0, v[114:115]
	v_cvt_pk_bf16_f32 v97, v102, v103
	v_mul_f32_e32 v102, 0xbfb8aa3b, v159
	v_mul_f32_e32 v88, v102, v88
	v_exp_f32_e32 v88, v88
	v_cvt_pk_bf16_f32 v96, v104, v105
	v_cvt_pk_bf16_f32 v99, v106, v107
	v_add_co_u32_e32 v100, vcc, s50, v108
	global_store_dwordx4 v[108:109], v[96:99], off nt
	s_nop 0
	v_addc_co_u32_e32 v101, vcc, 0, v109, vcc
	v_cvt_pk_bf16_f32 v96, v117, v118
	v_cvt_pk_bf16_f32 v97, v110, v111
	v_cvt_pk_bf16_f32 v98, v116, v119
	v_cvt_pk_bf16_f32 v99, v120, v121
	v_mul_f32_e32 v92, v102, v92
	global_store_dwordx4 v[100:101], v[96:99], off nt
	v_exp_f32_e32 v92, v92
	v_mul_f32_e32 v84, v102, v84
	v_add_f32_e32 v96, 1.0, v88
	v_mul_f32_e32 v88, v102, v93
	v_exp_f32_e32 v93, v88
	v_mul_f32_e32 v88, v102, v89
	v_exp_f32_e32 v89, v88
	v_mul_f32_e32 v85, v102, v85
	v_add_f32_e32 v92, 1.0, v92
	v_exp_f32_e32 v84, v84
	v_add_f32_e32 v93, 1.0, v93
	v_exp_f32_e32 v85, v85
	v_mul_f32_e32 v80, v102, v80
	v_rcp_f32_e32 v88, v92
	v_rcp_f32_e32 v92, v96
	v_add_f32_e32 v96, 1.0, v89
	v_mul_f32_e32 v81, v102, v81
	v_rcp_f32_e32 v89, v93
	v_exp_f32_e32 v80, v80
	v_exp_f32_e32 v81, v81
	v_rcp_f32_e32 v93, v96
	v_pk_add_f32 v[84:85], v[84:85], 1.0 op_sel_hi:[1,0]
	v_mul_f32_e32 v82, v102, v82
	v_rcp_f32_e32 v97, v84
	v_pk_mul_f32 v[88:89], v[88:89], v[84:85]
	v_mul_f32_e32 v84, v102, v94
	v_pk_add_f32 v[80:81], v[80:81], 1.0 op_sel_hi:[1,0]
	v_exp_f32_e32 v94, v84
	v_mul_f32_e32 v84, v102, v90
	v_rcp_f32_e32 v98, v85
	v_rcp_f32_e32 v96, v80
	v_exp_f32_e32 v90, v84
	v_pk_mul_f32 v[84:85], v[92:93], v[80:81]
	v_mul_f32_e32 v80, v102, v86
	v_mul_f32_e32 v86, v102, v95
	v_exp_f32_e32 v92, v86
	v_mul_f32_e32 v86, v102, v91
	v_exp_f32_e32 v91, v86
	v_rcp_f32_e32 v99, v81
	v_add_f32_e32 v81, 1.0, v94
	v_rcp_f32_e32 v86, v81
	v_mul_f32_e32 v81, v102, v87
	v_exp_f32_e32 v80, v80
	v_add_f32_e32 v92, 1.0, v92
	v_exp_f32_e32 v81, v81
	v_mul_f32_e32 v83, v102, v83
	v_add_f32_e32 v90, 1.0, v90
	v_exp_f32_e32 v82, v82
	v_add_f32_e32 v91, 1.0, v91
	v_rcp_f32_e32 v87, v92
	v_exp_f32_e32 v83, v83
	v_rcp_f32_e32 v90, v90
	v_rcp_f32_e32 v91, v91
	v_pk_add_f32 v[80:81], v[80:81], 1.0 op_sel_hi:[1,0]
	s_nop 0
	v_rcp_f32_e32 v94, v80
	v_pk_mul_f32 v[86:87], v[86:87], v[80:81]
	v_rcp_f32_e32 v95, v81
	v_pk_add_f32 v[80:81], v[82:83], 1.0 op_sel_hi:[1,0]
	v_cvt_pk_bf16_f32 v82, v84, v85
	v_rcp_f32_e32 v100, v80
	v_pk_mul_f32 v[90:91], v[90:91], v[80:81]
	v_or_b32_e32 v80, 32, v146
	v_rcp_f32_e32 v101, v81
	v_ashrrev_i32_e32 v81, 31, v80
	v_lshlrev_b64 v[80:81], 13, v[80:81]
	v_lshl_add_u64 v[80:81], s[24:25], 0, v[80:81]
	v_lshl_add_u64 v[92:93], v[80:81], 0, v[114:115]
	v_cvt_pk_bf16_f32 v81, v86, v87
	v_mul_f32_e32 v86, 0xbfb8aa3b, v160
	v_mul_f32_e32 v72, v86, v72
	v_exp_f32_e32 v72, v72
	v_cvt_pk_bf16_f32 v80, v88, v89
	v_cvt_pk_bf16_f32 v83, v90, v91
	v_add_co_u32_e32 v84, vcc, s50, v92
	global_store_dwordx4 v[92:93], v[80:83], off nt
	s_nop 0
	v_addc_co_u32_e32 v85, vcc, 0, v93, vcc
	v_cvt_pk_bf16_f32 v80, v97, v98
	v_cvt_pk_bf16_f32 v81, v94, v95
	v_cvt_pk_bf16_f32 v82, v96, v99
	v_cvt_pk_bf16_f32 v83, v100, v101
	v_mul_f32_e32 v76, v86, v76
	global_store_dwordx4 v[84:85], v[80:83], off nt
	v_exp_f32_e32 v76, v76
	v_mul_f32_e32 v68, v86, v68
	v_add_f32_e32 v80, 1.0, v72
	v_mul_f32_e32 v72, v86, v77
	v_exp_f32_e32 v77, v72
	v_mul_f32_e32 v72, v86, v73
	v_exp_f32_e32 v73, v72
	v_mul_f32_e32 v69, v86, v69
; __device__ __forceinline__ void st_nt(float* p, f32x4 v) { __builtin_nontemporal_store(v, (f32x4*)p); }
; __device__ __forceinline__ void st_nt(bf16_t* p, u32x4 v) { __builtin_nontemporal_store(v, (u32x4*)p); }
; __device__ __forceinline__ u32x4 pack8(const f32x4 a, const f32x4 b) { u32x4 w; w.x = cvt_pk_bf16(a[0], a[1]); w.y = cvt_pk_bf16(a[2], a[3]); w.z = cvt_pk_bf16(b[0], b[1]); w.w = cvt_pk_bf16(b[2], b[3]); return w; }
;     __device__ __forceinline__ void operator()(Acc& acc, const Unit& u, int wr, int wc, int fr, int fq, const float (&rsv)[8]) const {
;         const int row0 = u.pm * BM + wr * 64 + fr, col = u.pn * HALF + wc * 32 + 8 * fq;
; #pragma unroll
;         for (int ai = 0; ai < 2; ++ai)
; #pragma unroll
;             for (int m = 0; m < 4; ++m) {
;                 const int row = row0 + ai * HALF + m * 16; const float rs = rsv[ai * 4 + m];
;                 f32x4 r0, r1, b0, b1;
; #pragma unroll
;                 for (int jj = 0; jj < 4; ++jj) {
;                     const float rsn = rs * -1.4426950408889634f;
;                     const float da0 = 1.0f + __builtin_amdgcn_exp2f(acc[ai][0][m][0][jj] * rsn), da1 = 1.0f + __builtin_amdgcn_exp2f(acc[ai][0][m][1][jj] * rsn);
;                     const float db0 = 1.0f + __builtin_amdgcn_exp2f(acc[ai][1][m][0][jj] * rsn), db1 = 1.0f + __builtin_amdgcn_exp2f(acc[ai][1][m][1][jj] * rsn);
;                     b0[jj] = __builtin_amdgcn_rcpf(db0); b1[jj] = __builtin_amdgcn_rcpf(db1);
;                     r0[jj] = db0 * __builtin_amdgcn_rcpf(da0); r1[jj] = db1 * __builtin_amdgcn_rcpf(da1); }
;                 st_nt(gates + (size_t)row * 4096 + col, pack8(r0, r1));
;                 st_nt(gates + (size_t)row * 4096 + 2048 + col, pack8(b0, b1));
	v_add_f32_e32 v76, 1.0, v76
	v_exp_f32_e32 v68, v68
	v_add_f32_e32 v77, 1.0, v77
	v_exp_f32_e32 v69, v69
	v_mul_f32_e32 v64, v86, v64
	v_rcp_f32_e32 v72, v76
	v_rcp_f32_e32 v76, v80
	v_add_f32_e32 v80, 1.0, v73
	v_mul_f32_e32 v65, v86, v65
	v_rcp_f32_e32 v73, v77
	v_exp_f32_e32 v64, v64
	v_exp_f32_e32 v65, v65
	v_rcp_f32_e32 v77, v80
	v_pk_add_f32 v[68:69], v[68:69], 1.0 op_sel_hi:[1,0]
	v_mul_f32_e32 v66, v86, v66
	v_rcp_f32_e32 v81, v68
	v_pk_mul_f32 v[72:73], v[72:73], v[68:69]
	v_mul_f32_e32 v68, v86, v78
	v_pk_add_f32 v[64:65], v[64:65], 1.0 op_sel_hi:[1,0]
	v_exp_f32_e32 v78, v68
	v_mul_f32_e32 v68, v86, v74
	v_rcp_f32_e32 v82, v69
	v_rcp_f32_e32 v80, v64
	v_exp_f32_e32 v74, v68
	v_pk_mul_f32 v[68:69], v[76:77], v[64:65]
	v_mul_f32_e32 v64, v86, v70
	v_mul_f32_e32 v70, v86, v79
	v_exp_f32_e32 v76, v70
	v_mul_f32_e32 v70, v86, v75
	v_exp_f32_e32 v75, v70
	v_rcp_f32_e32 v83, v65
	v_add_f32_e32 v65, 1.0, v78
	v_rcp_f32_e32 v70, v65
	v_mul_f32_e32 v65, v86, v71
	v_exp_f32_e32 v64, v64
	v_add_f32_e32 v76, 1.0, v76
	v_exp_f32_e32 v65, v65
	v_mul_f32_e32 v67, v86, v67
	v_add_f32_e32 v74, 1.0, v74
	v_exp_f32_e32 v66, v66
	v_add_f32_e32 v75, 1.0, v75
	v_rcp_f32_e32 v71, v76
	v_exp_f32_e32 v67, v67
	v_rcp_f32_e32 v74, v74
	v_rcp_f32_e32 v75, v75
	v_pk_add_f32 v[64:65], v[64:65], 1.0 op_sel_hi:[1,0]
	s_nop 0
	v_rcp_f32_e32 v78, v64
	v_pk_mul_f32 v[70:71], v[70:71], v[64:65]
	v_rcp_f32_e32 v79, v65
	v_pk_add_f32 v[64:65], v[66:67], 1.0 op_sel_hi:[1,0]
	v_cvt_pk_bf16_f32 v66, v68, v69
	v_rcp_f32_e32 v84, v64
	v_pk_mul_f32 v[74:75], v[74:75], v[64:65]
	v_or_b32_e32 v64, 48, v146
	v_rcp_f32_e32 v85, v65
	v_ashrrev_i32_e32 v65, 31, v64
	v_lshlrev_b64 v[64:65], 13, v[64:65]
	v_lshl_add_u64 v[64:65], s[24:25], 0, v[64:65]
	v_lshl_add_u64 v[76:77], v[64:65], 0, v[114:115]
	v_cvt_pk_bf16_f32 v65, v70, v71
	v_mul_f32_e32 v70, 0xbfb8aa3b, v161
	v_mul_f32_e32 v56, v70, v56
	v_exp_f32_e32 v56, v56
	v_cvt_pk_bf16_f32 v64, v72, v73
	v_cvt_pk_bf16_f32 v67, v74, v75
	v_add_co_u32_e32 v68, vcc, s50, v76
	global_store_dwordx4 v[76:77], v[64:67], off nt
	s_nop 0
	v_addc_co_u32_e32 v69, vcc, 0, v77, vcc
	v_cvt_pk_bf16_f32 v64, v81, v82
	v_cvt_pk_bf16_f32 v65, v78, v79
	v_cvt_pk_bf16_f32 v66, v80, v83
	v_cvt_pk_bf16_f32 v67, v84, v85
	v_mul_f32_e32 v60, v70, v60
	global_store_dwordx4 v[68:69], v[64:67], off nt
	v_exp_f32_e32 v60, v60
	v_mul_f32_e32 v52, v70, v52
	v_add_f32_e32 v64, 1.0, v56
	v_mul_f32_e32 v56, v70, v61
	v_exp_f32_e32 v61, v56
	v_mul_f32_e32 v56, v70, v57
	v_exp_f32_e32 v57, v56
	v_mul_f32_e32 v53, v70, v53
	v_add_f32_e32 v60, 1.0, v60
	v_exp_f32_e32 v52, v52
	v_add_f32_e32 v61, 1.0, v61
	v_exp_f32_e32 v53, v53
	v_mul_f32_e32 v48, v70, v48
	v_rcp_f32_e32 v56, v60
	v_rcp_f32_e32 v60, v64
	v_add_f32_e32 v64, 1.0, v57
	v_mul_f32_e32 v49, v70, v49
	v_rcp_f32_e32 v57, v61
	v_exp_f32_e32 v48, v48
	v_exp_f32_e32 v49, v49
	v_rcp_f32_e32 v61, v64
	v_pk_add_f32 v[52:53], v[52:53], 1.0 op_sel_hi:[1,0]
	v_mul_f32_e32 v50, v70, v50
	v_rcp_f32_e32 v65, v52
	v_pk_mul_f32 v[56:57], v[56:57], v[52:53]
	v_mul_f32_e32 v52, v70, v62
	v_pk_add_f32 v[48:49], v[48:49], 1.0 op_sel_hi:[1,0]
	v_exp_f32_e32 v62, v52
	v_mul_f32_e32 v52, v70, v58
	v_rcp_f32_e32 v66, v53
	v_rcp_f32_e32 v64, v48
	v_exp_f32_e32 v58, v52
	v_pk_mul_f32 v[52:53], v[60:61], v[48:49]
	v_mul_f32_e32 v48, v70, v54
	v_mul_f32_e32 v54, v70, v63
	v_exp_f32_e32 v61, v54
	v_mul_f32_e32 v54, v70, v59
	v_exp_f32_e32 v59, v54
	v_rcp_f32_e32 v60, v49
	v_add_f32_e32 v49, 1.0, v62
	v_rcp_f32_e32 v54, v49
	v_mul_f32_e32 v49, v70, v55
	v_exp_f32_e32 v48, v48
	v_add_f32_e32 v61, 1.0, v61
	v_exp_f32_e32 v49, v49
	v_mul_f32_e32 v51, v70, v51
	v_add_f32_e32 v58, 1.0, v58
	v_exp_f32_e32 v50, v50
	v_add_f32_e32 v59, 1.0, v59
	v_rcp_f32_e32 v55, v61
	v_exp_f32_e32 v51, v51
	v_rcp_f32_e32 v58, v58
	v_rcp_f32_e32 v59, v59
	v_pk_add_f32 v[48:49], v[48:49], 1.0 op_sel_hi:[1,0]
	s_nop 0
	v_rcp_f32_e32 v61, v48
	v_pk_mul_f32 v[54:55], v[54:55], v[48:49]
	v_rcp_f32_e32 v62, v49
	v_pk_add_f32 v[48:49], v[50:51], 1.0 op_sel_hi:[1,0]
	v_cvt_pk_bf16_f32 v50, v52, v53
	v_pk_mul_f32 v[58:59], v[58:59], v[48:49]
	v_rcp_f32_e32 v67, v49
	v_cvt_pk_bf16_f32 v49, v54, v55
	v_mul_f32_e32 v54, 0xbfb8aa3b, v162
	v_rcp_f32_e32 v63, v48
	v_mul_f32_e32 v40, v54, v40
	v_exp_f32_e32 v40, v40
	v_add_co_u32_e32 v52, vcc, s60, v112
	v_cvt_pk_bf16_f32 v48, v56, v57
	v_cvt_pk_bf16_f32 v51, v58, v59
	v_addc_co_u32_e32 v53, vcc, 0, v113, vcc
	global_store_dwordx4 v[52:53], v[48:51], off offset:-4096 nt
	v_mul_f32_e32 v44, v54, v44
	v_exp_f32_e32 v44, v44
	v_cvt_pk_bf16_f32 v48, v65, v66
	v_cvt_pk_bf16_f32 v49, v61, v62
	v_cvt_pk_bf16_f32 v50, v64, v60
	v_cvt_pk_bf16_f32 v51, v63, v67
	global_store_dwordx4 v[52:53], v[48:51], off nt
	v_mul_f32_e32 v36, v54, v36
	v_mul_f32_e32 v37, v54, v37
	v_add_f32_e32 v48, 1.0, v40
	v_mul_f32_e32 v40, v54, v45
	v_exp_f32_e32 v45, v40
	v_mul_f32_e32 v40, v54, v41
	v_exp_f32_e32 v41, v40
	v_add_f32_e32 v44, 1.0, v44
	v_exp_f32_e32 v36, v36
	v_add_f32_e32 v45, 1.0, v45
	v_exp_f32_e32 v37, v37
	v_mul_f32_e32 v32, v54, v32
	v_rcp_f32_e32 v40, v44
	v_rcp_f32_e32 v44, v48
	v_add_f32_e32 v48, 1.0, v41
	v_mul_f32_e32 v33, v54, v33
	v_rcp_f32_e32 v41, v45
	v_exp_f32_e32 v32, v32
	v_exp_f32_e32 v33, v33
	v_rcp_f32_e32 v45, v48
	v_pk_add_f32 v[36:37], v[36:37], 1.0 op_sel_hi:[1,0]
	v_mul_f32_e32 v34, v54, v34
	v_rcp_f32_e32 v49, v36
	v_pk_mul_f32 v[40:41], v[40:41], v[36:37]
	v_mul_f32_e32 v36, v54, v46
	v_pk_add_f32 v[32:33], v[32:33], 1.0 op_sel_hi:[1,0]
	v_exp_f32_e32 v46, v36
	v_mul_f32_e32 v36, v54, v42
	v_rcp_f32_e32 v50, v37
	v_rcp_f32_e32 v48, v32
	v_exp_f32_e32 v42, v36
	v_pk_mul_f32 v[36:37], v[44:45], v[32:33]
; __device__ __forceinline__ void st_nt(float* p, f32x4 v) { __builtin_nontemporal_store(v, (f32x4*)p); }
; __device__ __forceinline__ void st_nt(bf16_t* p, u32x4 v) { __builtin_nontemporal_store(v, (u32x4*)p); }
; __device__ __forceinline__ u32x4 pack8(const f32x4 a, const f32x4 b) { u32x4 w; w.x = cvt_pk_bf16(a[0], a[1]); w.y = cvt_pk_bf16(a[2], a[3]); w.z = cvt_pk_bf16(b[0], b[1]); w.w = cvt_pk_bf16(b[2], b[3]); return w; }
;     __device__ __forceinline__ void operator()(Acc& acc, const Unit& u, int wr, int wc, int fr, int fq, const float (&rsv)[8]) const {
;         const int row0 = u.pm * BM + wr * 64 + fr, col = u.pn * HALF + wc * 32 + 8 * fq;
; #pragma unroll
;         for (int ai = 0; ai < 2; ++ai)
; #pragma unroll
;             for (int m = 0; m < 4; ++m) {
;                 const int row = row0 + ai * HALF + m * 16; const float rs = rsv[ai * 4 + m];
;                 f32x4 r0, r1, b0, b1;
; #pragma unroll
;                 for (int jj = 0; jj < 4; ++jj) {
;                     const float rsn = rs * -1.4426950408889634f;
;                     const float da0 = 1.0f + __builtin_amdgcn_exp2f(acc[ai][0][m][0][jj] * rsn), da1 = 1.0f + __builtin_amdgcn_exp2f(acc[ai][0][m][1][jj] * rsn);
;                     const float db0 = 1.0f + __builtin_amdgcn_exp2f(acc[ai][1][m][0][jj] * rsn), db1 = 1.0f + __builtin_amdgcn_exp2f(acc[ai][1][m][1][jj] * rsn);
;                     b0[jj] = __builtin_amdgcn_rcpf(db0); b1[jj] = __builtin_amdgcn_rcpf(db1);
;                     r0[jj] = db0 * __builtin_amdgcn_rcpf(da0); r1[jj] = db1 * __builtin_amdgcn_rcpf(da1); }
;                 st_nt(gates + (size_t)row * 4096 + col, pack8(r0, r1));
;                 st_nt(gates + (size_t)row * 4096 + 2048 + col, pack8(b0, b1));
; template <class Epi>
; __device__ __forceinline__ void gemm_phase(LAS unsigned char* lds, const GSched& S, const int K, const int lda, const int ldb, const Epi& E) {
;     ...
;         if (!has_next) break;
	v_mul_f32_e32 v32, v54, v38
	v_mul_f32_e32 v38, v54, v47
	v_exp_f32_e32 v45, v38
	v_mul_f32_e32 v38, v54, v43
	v_exp_f32_e32 v43, v38
	v_rcp_f32_e32 v44, v33
	v_add_f32_e32 v33, 1.0, v46
	v_rcp_f32_e32 v38, v33
	v_mul_f32_e32 v33, v54, v39
	v_exp_f32_e32 v32, v32
	v_add_f32_e32 v45, 1.0, v45
	v_exp_f32_e32 v33, v33
	v_mul_f32_e32 v35, v54, v35
	v_add_f32_e32 v42, 1.0, v42
	v_exp_f32_e32 v34, v34
	v_add_f32_e32 v43, 1.0, v43
	v_rcp_f32_e32 v39, v45
	v_exp_f32_e32 v35, v35
	v_rcp_f32_e32 v42, v42
	v_rcp_f32_e32 v43, v43
	v_pk_add_f32 v[32:33], v[32:33], 1.0 op_sel_hi:[1,0]
	s_nop 0
	v_rcp_f32_e32 v45, v32
	v_pk_mul_f32 v[38:39], v[38:39], v[32:33]
	v_rcp_f32_e32 v46, v33
	v_pk_add_f32 v[32:33], v[34:35], 1.0 op_sel_hi:[1,0]
	v_cvt_pk_bf16_f32 v34, v36, v37
	v_pk_mul_f32 v[42:43], v[42:43], v[32:33]
	v_rcp_f32_e32 v51, v33
	v_cvt_pk_bf16_f32 v33, v38, v39
	v_mul_f32_e32 v38, 0xbfb8aa3b, v163
	v_rcp_f32_e32 v47, v32
	v_mul_f32_e32 v24, v38, v24
	v_exp_f32_e32 v24, v24
	v_add_co_u32_e32 v36, vcc, s61, v112
	v_cvt_pk_bf16_f32 v32, v40, v41
	v_cvt_pk_bf16_f32 v35, v42, v43
	v_addc_co_u32_e32 v37, vcc, 0, v113, vcc
	global_store_dwordx4 v[36:37], v[32:35], off offset:-4096 nt
	v_mul_f32_e32 v28, v38, v28
	v_exp_f32_e32 v28, v28
	v_cvt_pk_bf16_f32 v32, v49, v50
	v_cvt_pk_bf16_f32 v33, v45, v46
	v_cvt_pk_bf16_f32 v34, v48, v44
	v_cvt_pk_bf16_f32 v35, v47, v51
	global_store_dwordx4 v[36:37], v[32:35], off nt
	v_mul_f32_e32 v20, v38, v20
	v_mul_f32_e32 v21, v38, v21
	v_add_f32_e32 v32, 1.0, v24
	v_mul_f32_e32 v24, v38, v29
	v_exp_f32_e32 v29, v24
	v_mul_f32_e32 v24, v38, v25
	v_exp_f32_e32 v25, v24
	v_add_f32_e32 v28, 1.0, v28
	v_exp_f32_e32 v20, v20
	v_add_f32_e32 v29, 1.0, v29
	v_exp_f32_e32 v21, v21
	v_mul_f32_e32 v16, v38, v16
	v_rcp_f32_e32 v24, v28
	v_rcp_f32_e32 v28, v32
	v_add_f32_e32 v32, 1.0, v25
	v_mul_f32_e32 v17, v38, v17
	v_rcp_f32_e32 v25, v29
	v_exp_f32_e32 v16, v16
	v_exp_f32_e32 v17, v17
	v_rcp_f32_e32 v29, v32
	v_pk_add_f32 v[20:21], v[20:21], 1.0 op_sel_hi:[1,0]
	v_mul_f32_e32 v18, v38, v18
	v_rcp_f32_e32 v33, v20
	v_pk_mul_f32 v[24:25], v[24:25], v[20:21]
	v_mul_f32_e32 v20, v38, v30
	v_pk_add_f32 v[16:17], v[16:17], 1.0 op_sel_hi:[1,0]
	v_exp_f32_e32 v30, v20
	v_mul_f32_e32 v20, v38, v26
	v_rcp_f32_e32 v34, v21
	v_rcp_f32_e32 v32, v16
	v_exp_f32_e32 v26, v20
	v_pk_mul_f32 v[20:21], v[28:29], v[16:17]
	v_mul_f32_e32 v16, v38, v22
	v_mul_f32_e32 v22, v38, v31
	v_exp_f32_e32 v29, v22
	v_mul_f32_e32 v22, v38, v27
	v_exp_f32_e32 v27, v22
	v_rcp_f32_e32 v28, v17
	v_add_f32_e32 v17, 1.0, v30
	v_rcp_f32_e32 v22, v17
	v_mul_f32_e32 v17, v38, v23
	v_exp_f32_e32 v16, v16
	v_add_f32_e32 v29, 1.0, v29
	v_exp_f32_e32 v17, v17
	v_mul_f32_e32 v19, v38, v19
	v_add_f32_e32 v26, 1.0, v26
	v_exp_f32_e32 v18, v18
	v_add_f32_e32 v27, 1.0, v27
	v_rcp_f32_e32 v23, v29
	v_exp_f32_e32 v19, v19
	v_rcp_f32_e32 v26, v26
	v_rcp_f32_e32 v27, v27
	v_pk_add_f32 v[16:17], v[16:17], 1.0 op_sel_hi:[1,0]
	s_nop 0
	v_rcp_f32_e32 v29, v16
	v_pk_mul_f32 v[22:23], v[22:23], v[16:17]
	v_rcp_f32_e32 v30, v17
	v_pk_add_f32 v[16:17], v[18:19], 1.0 op_sel_hi:[1,0]
	v_cvt_pk_bf16_f32 v18, v20, v21
	v_pk_mul_f32 v[26:27], v[26:27], v[16:17]
	v_rcp_f32_e32 v35, v17
	v_cvt_pk_bf16_f32 v17, v22, v23
	v_mul_f32_e32 v22, 0xbfb8aa3b, v164
	v_rcp_f32_e32 v31, v16
	v_mul_f32_e32 v8, v22, v8
	v_exp_f32_e32 v8, v8
	v_add_co_u32_e32 v20, vcc, s62, v112
	v_cvt_pk_bf16_f32 v16, v24, v25
	v_cvt_pk_bf16_f32 v19, v26, v27
	v_addc_co_u32_e32 v21, vcc, 0, v113, vcc
	global_store_dwordx4 v[20:21], v[16:19], off offset:-4096 nt
	v_mul_f32_e32 v12, v22, v12
	v_exp_f32_e32 v12, v12
	v_cvt_pk_bf16_f32 v16, v33, v34
	v_cvt_pk_bf16_f32 v17, v29, v30
	v_cvt_pk_bf16_f32 v18, v32, v28
	v_cvt_pk_bf16_f32 v19, v31, v35
	global_store_dwordx4 v[20:21], v[16:19], off nt
	v_mul_f32_e32 v4, v22, v4
	v_mul_f32_e32 v5, v22, v5
	v_add_f32_e32 v16, 1.0, v8
	v_mul_f32_e32 v8, v22, v13
	v_exp_f32_e32 v13, v8
	v_mul_f32_e32 v8, v22, v9
	v_exp_f32_e32 v9, v8
	v_add_f32_e32 v12, 1.0, v12
	v_exp_f32_e32 v4, v4
	v_add_f32_e32 v13, 1.0, v13
	v_exp_f32_e32 v5, v5
	v_mul_f32_e32 v0, v22, v0
	v_rcp_f32_e32 v8, v12
	v_rcp_f32_e32 v12, v16
	v_add_f32_e32 v16, 1.0, v9
	v_mul_f32_e32 v1, v22, v1
	v_rcp_f32_e32 v9, v13
	v_exp_f32_e32 v0, v0
	v_exp_f32_e32 v1, v1
	v_rcp_f32_e32 v13, v16
	v_pk_add_f32 v[4:5], v[4:5], 1.0 op_sel_hi:[1,0]
	v_mul_f32_e32 v2, v22, v2
	v_rcp_f32_e32 v17, v4
	v_pk_mul_f32 v[8:9], v[8:9], v[4:5]
	v_mul_f32_e32 v4, v22, v14
	v_pk_add_f32 v[0:1], v[0:1], 1.0 op_sel_hi:[1,0]
	v_exp_f32_e32 v14, v4
	v_mul_f32_e32 v4, v22, v10
	v_rcp_f32_e32 v18, v5
	v_rcp_f32_e32 v16, v0
	v_exp_f32_e32 v10, v4
	v_pk_mul_f32 v[4:5], v[12:13], v[0:1]
	v_mul_f32_e32 v0, v22, v6
	v_mul_f32_e32 v6, v22, v15
	v_exp_f32_e32 v13, v6
	v_mul_f32_e32 v6, v22, v11
	v_exp_f32_e32 v11, v6
	v_rcp_f32_e32 v12, v1
	v_add_f32_e32 v1, 1.0, v14
	v_rcp_f32_e32 v6, v1
	v_mul_f32_e32 v1, v22, v7
	v_exp_f32_e32 v0, v0
	v_add_f32_e32 v13, 1.0, v13
	v_exp_f32_e32 v1, v1
	v_mul_f32_e32 v3, v22, v3
	v_add_f32_e32 v10, 1.0, v10
	v_exp_f32_e32 v2, v2
	v_add_f32_e32 v11, 1.0, v11
	v_rcp_f32_e32 v7, v13
	v_exp_f32_e32 v3, v3
	v_rcp_f32_e32 v10, v10
	v_rcp_f32_e32 v11, v11
	v_pk_add_f32 v[0:1], v[0:1], 1.0 op_sel_hi:[1,0]
	s_nop 0
	v_rcp_f32_e32 v13, v0
	v_pk_mul_f32 v[6:7], v[6:7], v[0:1]
	v_rcp_f32_e32 v14, v1
	v_pk_add_f32 v[0:1], v[2:3], 1.0 op_sel_hi:[1,0]
	v_cvt_pk_bf16_f32 v2, v4, v5
	v_rcp_f32_e32 v15, v0
	v_pk_mul_f32 v[10:11], v[10:11], v[0:1]
	v_rcp_f32_e32 v19, v1
	v_add_co_u32_e32 v4, vcc, s63, v112
	v_cvt_pk_bf16_f32 v0, v8, v9
	v_cvt_pk_bf16_f32 v1, v6, v7
	v_cvt_pk_bf16_f32 v3, v10, v11
	v_addc_co_u32_e32 v5, vcc, 0, v113, vcc
	global_store_dwordx4 v[4:5], v[0:3], off nt
	v_add_co_u32_e32 v4, vcc, 0x161000, v112
	s_nop 0
	v_cvt_pk_bf16_f32 v0, v17, v18
	v_addc_co_u32_e32 v5, vcc, 0, v113, vcc
	v_cvt_pk_bf16_f32 v1, v13, v14
	v_cvt_pk_bf16_f32 v2, v16, v12
	v_cvt_pk_bf16_f32 v3, v15, v19
	s_and_b64 vcc, exec, s[6:7]
	global_store_dwordx4 v[4:5], v[0:3], off nt
	s_cbranch_vccz .LBB0_757
;     __device__ __forceinline__ void rstd_fill(float (&rsv)[8], const Unit& u, int wr, int fr, int fq) const { rstd_regs32(rsv, part, u.pm * BM + wr * 64 + fr, fq); }
;     __device__ __forceinline__ void rstd_fill(float (&rsv)[8], const Unit& u, int wr, int fr, int fq) const { rstd_regs32(rsv, part, u.pm * BM + wr * 64 + fr, fq); }
;     __device__ __forceinline__ void rstd_fill(float (&rsv)[8], const Unit& u, int wr, int fr, int fq) const { rstd_regs32(rsv, part, u.pm * BM + wr * 64 + fr, fq); }
;     __device__ __forceinline__ void rstd_fill(float (&rsv)[8], const Unit& u, int wr, int fr, int fq) const { rstd_regs32(rsv, part, u.pm * BM + wr * 64 + fr, fq); }
;     __device__ __forceinline__ void rstd_fill(float (&rsv)[8], const Unit& u, int wr, int fr, int fq) const { rstd_regs_lat(rsv, latpart, u.pm * BM + wr * 64 + fr, u.z); }
;     __device__ __forceinline__ void rstd_fill(float (&rsv)[8], const Unit& u, int wr, int fr, int fq) const { rstd_regs32(rsv, part_in, u.pm * BM + wr * 64 + fr, fq); }
; #define PG8_SCHED __builtin_amdgcn_sched_barrier(0)
; __device__ __forceinline__ void rstd_regs32(float (&rsv)[8], const float* part, int row0, int fq) {
;     int r0 = row0; asm volatile("" : "+v"(r0));
;     const float* q = part + (size_t)r0 * 32 + fq * 8;
;     f32x4 a[8], b[8];
; #pragma unroll
;     for (int g = 0; g < 8; ++g) { const float* p = q + (size_t)((g >> 2) * HALF + (g & 3) * 16) * 32; a[g] = *(const f32x4*)p; b[g] = *(const f32x4*)(p + 4); }
; #pragma unroll
;     for (int g = 0; g < 8; ++g) { float s = ((a[g][0] + a[g][1]) + (a[g][2] + a[g][3])) + ((b[g][0] + b[g][1]) + (b[g][2] + b[g][3]));
;         s += __shfl_xor(s, 16); s += __shfl_xor(s, 32); rsv[g] = __builtin_amdgcn_rsqf(s * (1.0f / 2048.0f) + EPS); }
; }
; template <class Epi>
; __device__ __forceinline__ void gemm_phase(LAS unsigned char* lds, const GSched& S, const int K, const int lda, const int ldb, const Epi& E) {
;     ...
;         if constexpr (Epi::RSTD) { if (nxt.pm != cur.pm || nxt.z != cur.z) { PG8_SCHED; E.rstd_fill(rsv, nxt, wr, fr, fq); PG8_SCHED; } }
	s_cmp_eq_u32 s1, s55
	s_cbranch_scc1 .LBB0_756
	v_lshl_add_u32 v0, s1, 8, v151
	s_nop 0
	v_ashrrev_i32_e32 v1, 31, v0
	v_lshlrev_b64 v[0:1], 7, v[0:1]
	v_lshl_add_u64 v[48:49], v[136:137], 0, v[0:1]
	global_load_dwordx4 v[0:3], v[48:49], off
	global_load_dwordx4 v[4:7], v[48:49], off offset:16
	global_load_dwordx4 v[8:11], v[48:49], off offset:2048
	global_load_dwordx4 v[12:15], v[48:49], off offset:2064
	v_add_co_u32_e32 v28, vcc, 0x1000, v48
	v_lshl_add_u64 v[24:25], v[48:49], 0, s[12:13]
	v_lshl_add_u64 v[16:17], v[48:49], 0, s[16:17]
	v_addc_co_u32_e32 v29, vcc, 0, v49, vcc
	v_lshl_add_u64 v[32:33], v[48:49], 0, s[14:15]
	global_load_dwordx4 v[16:19], v[16:17], off offset:16
	s_nop 0
	global_load_dwordx4 v[20:23], v[28:29], off
	s_nop 0
	global_load_dwordx4 v[24:27], v[24:25], off offset:16
	s_nop 0
	global_load_dwordx4 v[28:31], v[28:29], off offset:2048
	s_nop 0
	global_load_dwordx4 v[32:35], v[32:33], off offset:16
	v_add_co_u32_e32 v50, vcc, s49, v48
	s_mov_b64 s[6:7], vcc
	v_add_co_u32_e32 v56, vcc, s51, v48
	v_lshl_add_u64 v[40:41], v[48:49], 0, s[18:19]
	s_nop 0
	v_addc_co_u32_e32 v57, vcc, 0, v49, vcc
	global_load_dwordx4 v[36:39], v[56:57], off offset:-4096
	v_lshl_add_u64 v[44:45], v[48:49], 0, s[20:21]
	global_load_dwordx4 v[40:43], v[40:41], off offset:16
	s_nop 0
	global_load_dwordx4 v[44:47], v[44:45], off offset:16
	v_lshl_add_u64 v[60:61], v[48:49], 0, s[22:23]
	v_addc_co_u32_e64 v51, vcc, 0, v49, s[6:7]
	global_load_dwordx4 v[48:51], v[50:51], off offset:2048
	s_nop 0
	global_load_dwordx4 v[52:55], v[56:57], off
	s_nop 0
	global_load_dwordx4 v[56:59], v[56:57], off offset:2048
	s_nop 0
	global_load_dwordx4 v[60:63], v[60:61], off offset:16
	s_waitcnt vmcnt(0)
	v_mov_b32_e32 v64, v0
	v_mov_b32_e32 v65, v4
	v_mov_b32_e32 v4, v1
	v_mov_b32_e32 v0, v2
	v_mov_b32_e32 v1, v6
	v_mov_b32_e32 v6, v3
	v_mov_b32_e32 v2, v8
	v_mov_b32_e32 v3, v12
	v_mov_b32_e32 v12, v9
	v_mov_b32_e32 v8, v10
	v_mov_b32_e32 v9, v14
	v_mov_b32_e32 v14, v11
	v_pk_add_f32 v[4:5], v[64:65], v[4:5]
	v_pk_add_f32 v[0:1], v[0:1], v[6:7]
	v_pk_add_f32 v[2:3], v[2:3], v[12:13]
	v_pk_add_f32 v[6:7], v[8:9], v[14:15]
	v_pk_add_f32 v[0:1], v[4:5], v[0:1]
	v_pk_add_f32 v[2:3], v[2:3], v[6:7]
	v_mov_b32_e32 v4, v20
	v_mov_b32_e32 v5, v24
	v_mov_b32_e32 v24, v21
	v_mov_b32_e32 v6, v22
	v_mov_b32_e32 v7, v26
	v_mov_b32_e32 v26, v23
	v_mov_b32_e32 v10, v28
	v_mov_b32_e32 v11, v32
	v_mov_b32_e32 v32, v29
	v_add_f32_e32 v14, v0, v1
	v_add_f32_e32 v15, v2, v3
	v_mov_b32_e32 v12, v30
	v_mov_b32_e32 v13, v34
	v_mov_b32_e32 v34, v31
	v_pk_add_f32 v[0:1], v[4:5], v[24:25]
	v_pk_add_f32 v[2:3], v[6:7], v[26:27]
	v_pk_add_f32 v[4:5], v[10:11], v[32:33]
	ds_bpermute_b32 v10, v148, v14
	ds_bpermute_b32 v11, v148, v15
	v_pk_add_f32 v[6:7], v[12:13], v[34:35]
	v_pk_add_f32 v[0:1], v[0:1], v[2:3]
	v_pk_add_f32 v[2:3], v[4:5], v[6:7]
	v_add_f32_e32 v0, v0, v1
	v_add_f32_e32 v1, v2, v3
	ds_bpermute_b32 v2, v148, v0
	ds_bpermute_b32 v3, v148, v1
	s_waitcnt lgkmcnt(0)
	v_add_f32_e32 v4, v14, v10
	v_add_f32_e32 v5, v15, v11
	ds_bpermute_b32 v6, v149, v4
	ds_bpermute_b32 v7, v149, v5
	v_add_f32_e32 v0, v0, v2
	v_add_f32_e32 v10, v1, v3
	ds_bpermute_b32 v1, v149, v0
	s_waitcnt lgkmcnt(2)
	v_add_f32_e32 v2, v4, v6
	s_waitcnt lgkmcnt(1)
	v_add_f32_e32 v3, v5, v7
	v_fmamk_f32 v2, v2, 0x3a000000, v150
	v_fmamk_f32 v3, v3, 0x3a000000, v150
	v_mov_b32_e32 v9, v16
	v_mov_b32_e32 v8, v36
	v_rsq_f32_e32 v157, v2
	v_rsq_f32_e32 v158, v3
	v_mov_b32_e32 v16, v37
	v_mov_b32_e32 v2, v38
	v_mov_b32_e32 v3, v18
	v_mov_b32_e32 v18, v39
	s_waitcnt lgkmcnt(0)
	v_add_f32_e32 v4, v0, v1
	v_pk_add_f32 v[0:1], v[8:9], v[16:17]
	v_pk_add_f32 v[2:3], v[2:3], v[18:19]
	ds_bpermute_b32 v11, v149, v10
	v_pk_add_f32 v[0:1], v[0:1], v[2:3]
	v_fmamk_f32 v2, v4, 0x3a000000, v150
	v_add_f32_e32 v0, v0, v1
	ds_bpermute_b32 v1, v148, v0
	v_rsq_f32_e32 v159, v2
	s_waitcnt lgkmcnt(1)
	v_add_f32_e32 v2, v10, v11
	v_fmamk_f32 v4, v2, 0x3a000000, v150
	v_mov_b32_e32 v2, v50
	s_waitcnt lgkmcnt(0)
	v_add_f32_e32 v5, v0, v1
	v_mov_b32_e32 v0, v48
	v_mov_b32_e32 v1, v40
	v_mov_b32_e32 v40, v49
	v_mov_b32_e32 v3, v42
	v_mov_b32_e32 v42, v51
	v_pk_add_f32 v[0:1], v[0:1], v[40:41]
	v_pk_add_f32 v[2:3], v[2:3], v[42:43]
	ds_bpermute_b32 v6, v149, v5
	v_pk_add_f32 v[0:1], v[0:1], v[2:3]
	v_rsq_f32_e32 v160, v4
	v_add_f32_e32 v0, v0, v1
	ds_bpermute_b32 v1, v148, v0
	s_waitcnt lgkmcnt(1)
	v_add_f32_e32 v2, v5, v6
	v_fmamk_f32 v2, v2, 0x3a000000, v150
	v_rsq_f32_e32 v161, v2
	v_mov_b32_e32 v2, v54
	s_waitcnt lgkmcnt(0)
	v_add_f32_e32 v4, v0, v1
	v_mov_b32_e32 v0, v52
	v_mov_b32_e32 v1, v44
	v_mov_b32_e32 v44, v53
	v_mov_b32_e32 v3, v46
	v_mov_b32_e32 v46, v55
	v_pk_add_f32 v[0:1], v[0:1], v[44:45]
	v_pk_add_f32 v[2:3], v[2:3], v[46:47]
	ds_bpermute_b32 v5, v149, v4
	v_pk_add_f32 v[0:1], v[0:1], v[2:3]
	v_mov_b32_e32 v2, v58
	v_add_f32_e32 v6, v0, v1
	v_mov_b32_e32 v0, v56
	v_mov_b32_e32 v1, v60
	v_mov_b32_e32 v60, v57
	v_mov_b32_e32 v3, v62
	v_mov_b32_e32 v62, v59
	v_pk_add_f32 v[0:1], v[0:1], v[60:61]
	v_pk_add_f32 v[2:3], v[2:3], v[62:63]
	ds_bpermute_b32 v7, v148, v6
	v_pk_add_f32 v[0:1], v[0:1], v[2:3]
	s_waitcnt lgkmcnt(1)
	v_add_f32_e32 v2, v4, v5
	v_add_f32_e32 v0, v0, v1
	ds_bpermute_b32 v1, v148, v0
	s_waitcnt lgkmcnt(1)
	v_add_f32_e32 v3, v6, v7
	ds_bpermute_b32 v4, v149, v3
	v_fmamk_f32 v2, v2, 0x3a000000, v150
	v_rsq_f32_e32 v162, v2
	s_waitcnt lgkmcnt(1)
	v_add_f32_e32 v0, v0, v1
	ds_bpermute_b32 v1, v149, v0
	s_waitcnt lgkmcnt(1)
	v_add_f32_e32 v2, v3, v4
	v_fmamk_f32 v2, v2, 0x3a000000, v150
	v_rsq_f32_e32 v163, v2
	s_waitcnt lgkmcnt(0)
	v_add_f32_e32 v0, v0, v1
	v_fmamk_f32 v0, v0, 0x3a000000, v150
	v_rsq_f32_e32 v164, v0
	s_branch .LBB0_756

; #define PG8_STAGE(bufoff, gbase, voff) do { _Pragma("unroll") for (int _i = 0; _i < 2; ++_i) \
;         __builtin_amdgcn_global_load_lds((const unsigned*)((const char*)(gbase) + (voff)[_i]), (LAS unsigned*)(lds + (bufoff) + ldsw + _i * 8192), 16, 0, 0); } while (0)
; #define PG8_LDA(dst, b, h) do { _Pragma("unroll") for (int m = 0; m < 4; ++m) _Pragma("unroll") for (int k = 0; k < 2; ++k) dst[m][k] = *(const LAS bf16x8*)(lds + PG8_SA(b, h) + aoff + m * 2048 + k * 1024); } while (0)
; #define PG8_LDB(dst, b, h) do { _Pragma("unroll") for (int n = 0; n < 2; ++n) _Pragma("unroll") for (int k = 0; k < 2; ++k) dst[n][k] = *(const LAS bf16x8*)(lds + PG8_SB(b, h) + boff + n * 2048 + k * 1024); } while (0)
; #define PG8_MMA(ai, bj, At, Bt) do { __builtin_amdgcn_s_setprio(1); _Pragma("unroll") for (int m = 0; m < 4; ++m) _Pragma("unroll") for (int n = 0; n < 2; ++n) _Pragma("unroll") for (int k = 0; k < 2; ++k) \
;         acc[ai][bj][m][n] = __builtin_amdgcn_mfma_f32_16x16x32_bf16(Bt[n][k], At[m][k], acc[ai][bj][m][n], 0, 0, 0); __builtin_amdgcn_s_setprio(0); } while (0)
; #define PG8_WAIT_V(n) asm volatile("s_waitcnt vmcnt(" #n ")" ::: "memory")
; #define PG8_WAIT_L(n) asm volatile("s_waitcnt lgkmcnt(" #n ")" ::: "memory")
; #define PG8_BAR __builtin_amdgcn_s_barrier()
; template <class Epi>
; __device__ __forceinline__ void gemm_phase(LAS unsigned char* lds, const GSched& S, const int K, const int lda, const int ldb, const Epi& E) {
;     ...
;             PG8_LDB(B0, 0, 0); PG8_SCHED; PG8_LDA(At, 0, 0); PG8_STAGE(PG8_SA(1, 1), a1 + hstepA, voffA);
;             PG8_WAIT_L(8); PG8_BAR; PG8_WAIT_L(0); PG8_MMA(0, 0, At, B0); PG8_BAR; PG8_SCHED;
;             if constexpr (!Epi::NARROW) PG8_LDB(B1, 0, 1); PG8_STAGE(PG8_SB(0, 0), b2, voffB);
;             PG8_BAR; PG8_WAIT_L(0); if constexpr (!Epi::NARROW) PG8_MMA(0, 1, At, B1); PG8_BAR;
;             PG8_LDA(At, 0, 1); PG8_STAGE(PG8_SA(0, 0), a2, voffA);
;             PG8_BAR; PG8_WAIT_L(0); PG8_MMA(1, 0, At, B0); PG8_BAR; PG8_SCHED;
;             PG8_STAGE(PG8_SB(0, 1), b2 + hstepB, voffB);
;             PG8_WAIT_V(6); PG8_BAR; if constexpr (!Epi::NARROW) PG8_MMA(1, 1, At, B1); PG8_BAR;
;             PG8_LDB(B0, 1, 0); PG8_SCHED; PG8_LDA(At, 1, 0); PG8_STAGE(PG8_SA(0, 1), a2 + hstepA, voffA);
;             PG8_WAIT_L(8); PG8_BAR; PG8_WAIT_L(0); PG8_MMA(0, 0, At, B0); PG8_BAR; PG8_SCHED;
.LBB0_862:
	ds_read_b128 v[128:131], v207
	ds_read_b128 v[132:135], v207 offset:1024
	ds_read_b128 v[136:139], v207 offset:2048
	ds_read_b128 v[146:149], v207 offset:3072
	s_add_u32 s26, s5, s24
	s_addc_u32 s27, s9, s25
	s_add_u32 s56, s2, s24
	s_addc_u32 s57, s4, s25
	s_cmpk_eq_i32 s24, 0xf00
	s_cselect_b32 s28, s1, s26
	s_cselect_b32 s26, s20, s56
	s_cselect_b32 s29, s0, s27
	s_cselect_b32 s27, s21, s57
	v_lshl_add_u64 v[170:171], v[144:145], 0, s[24:25]
	s_add_i32 m0, s37, 0xc000
	ds_read_b128 v[150:153], v208
	ds_read_b128 v[154:157], v208 offset:1024
	ds_read_b128 v[158:161], v208 offset:2048
	ds_read_b128 v[162:165], v208 offset:3072
	ds_read_b128 v[166:169], v208 offset:4096
	ds_read_b128 v[192:195], v208 offset:5120
	ds_read_b128 v[196:199], v208 offset:6144
	ds_read_b128 v[200:203], v208 offset:7168
	global_load_lds_dwordx4 v[170:171], off
	v_lshl_add_u64 v[170:171], v[142:143], 0, s[24:25]
	s_add_i32 m0, s37, 0xe000
	s_nop 0
	global_load_lds_dwordx4 v[170:171], off
	s_waitcnt lgkmcnt(8)
	s_barrier
	s_waitcnt lgkmcnt(0)
	s_setprio 1
	s_waitcnt lgkmcnt(0)
	v_mfma_f32_16x16x32_bf16 v[124:127], v[128:131], v[150:153], v[124:127]
	v_mfma_f32_16x16x32_bf16 v[120:123], v[136:139], v[150:153], v[120:123]
	v_mfma_f32_16x16x32_bf16 v[108:111], v[128:131], v[158:161], v[108:111]
	v_mfma_f32_16x16x32_bf16 v[104:107], v[136:139], v[158:161], v[104:107]
	v_mfma_f32_16x16x32_bf16 v[92:95], v[128:131], v[166:169], v[92:95]
	v_mfma_f32_16x16x32_bf16 v[88:91], v[136:139], v[166:169], v[88:91]
	v_mfma_f32_16x16x32_bf16 v[76:79], v[128:131], v[196:199], v[76:79]
	v_mfma_f32_16x16x32_bf16 v[72:75], v[136:139], v[196:199], v[72:75]
	v_mfma_f32_16x16x32_bf16 v[124:127], v[132:135], v[154:157], v[124:127]
	v_mfma_f32_16x16x32_bf16 v[120:123], v[146:149], v[154:157], v[120:123]
	v_mfma_f32_16x16x32_bf16 v[108:111], v[132:135], v[162:165], v[108:111]
	v_mfma_f32_16x16x32_bf16 v[104:107], v[146:149], v[162:165], v[104:107]
	v_mfma_f32_16x16x32_bf16 v[92:95], v[132:135], v[192:195], v[92:95]
	v_mfma_f32_16x16x32_bf16 v[88:91], v[146:149], v[192:195], v[88:91]
	v_mfma_f32_16x16x32_bf16 v[76:79], v[132:135], v[200:203], v[76:79]
	v_mfma_f32_16x16x32_bf16 v[72:75], v[146:149], v[200:203], v[72:75]
	s_setprio 0
	s_barrier
	s_add_i32 s56, s46, s36
	v_lshl_add_u64 v[170:171], s[26:27], 0, v[174:175]
	s_mov_b32 m0, s56
	ds_read_b128 v[210:213], v209
	ds_read_b128 v[214:217], v209 offset:1024
	ds_read_b128 v[218:221], v209 offset:2048
	ds_read_b128 v[222:225], v209 offset:3072
	global_load_lds_dwordx4 v[170:171], off
	v_lshl_add_u64 v[226:227], s[26:27], 0, v[178:179]
	s_add_i32 m0, s56, 0x2000
	s_nop 0
	global_load_lds_dwordx4 v[226:227], off
	s_barrier
	s_waitcnt lgkmcnt(0)
	s_setprio 1
	v_mfma_f32_16x16x32_bf16 v[116:119], v[210:213], v[150:153], v[116:119]
	v_mfma_f32_16x16x32_bf16 v[112:115], v[218:221], v[150:153], v[112:115]
	v_mfma_f32_16x16x32_bf16 v[100:103], v[210:213], v[158:161], v[100:103]
	v_mfma_f32_16x16x32_bf16 v[96:99], v[218:221], v[158:161], v[96:99]
	v_mfma_f32_16x16x32_bf16 v[84:87], v[210:213], v[166:169], v[84:87]
	v_mfma_f32_16x16x32_bf16 v[80:83], v[218:221], v[166:169], v[80:83]
	v_mfma_f32_16x16x32_bf16 v[68:71], v[210:213], v[196:199], v[68:71]
	v_mfma_f32_16x16x32_bf16 v[64:67], v[218:221], v[196:199], v[64:67]
	v_mfma_f32_16x16x32_bf16 v[116:119], v[214:217], v[154:157], v[116:119]
	v_mfma_f32_16x16x32_bf16 v[112:115], v[222:225], v[154:157], v[112:115]
	v_mfma_f32_16x16x32_bf16 v[100:103], v[214:217], v[162:165], v[100:103]
	v_mfma_f32_16x16x32_bf16 v[96:99], v[222:225], v[162:165], v[96:99]
	v_mfma_f32_16x16x32_bf16 v[84:87], v[214:217], v[192:195], v[84:87]
	v_mfma_f32_16x16x32_bf16 v[80:83], v[222:225], v[192:195], v[80:83]
	v_mfma_f32_16x16x32_bf16 v[68:71], v[214:217], v[200:203], v[68:71]
	v_mfma_f32_16x16x32_bf16 v[64:67], v[222:225], v[200:203], v[64:67]
	s_setprio 0
	s_mov_b32 m0, s37
	v_lshl_add_u64 v[228:229], s[28:29], 0, v[172:173]
	s_barrier
	ds_read_b128 v[150:153], v208 offset:16384
	ds_read_b128 v[154:157], v208 offset:17408
	ds_read_b128 v[158:161], v208 offset:18432
	ds_read_b128 v[162:165], v208 offset:19456
	ds_read_b128 v[166:169], v208 offset:20480
	ds_read_b128 v[192:195], v208 offset:21504
	ds_read_b128 v[196:199], v208 offset:22528
	ds_read_b128 v[200:203], v208 offset:23552
	global_load_lds_dwordx4 v[228:229], off
	v_lshl_add_u64 v[230:231], s[28:29], 0, v[176:177]
	s_mov_b32 m0, s38
	s_nop 0
	global_load_lds_dwordx4 v[230:231], off
	s_barrier
	s_waitcnt lgkmcnt(0)
	s_setprio 1
	v_mfma_f32_16x16x32_bf16 v[60:63], v[128:131], v[150:153], v[60:63]
	v_mfma_f32_16x16x32_bf16 v[56:59], v[136:139], v[150:153], v[56:59]
	v_mfma_f32_16x16x32_bf16 v[44:47], v[128:131], v[158:161], v[44:47]
	v_mfma_f32_16x16x32_bf16 v[40:43], v[136:139], v[158:161], v[40:43]
	v_mfma_f32_16x16x32_bf16 v[28:31], v[128:131], v[166:169], v[28:31]
	v_mfma_f32_16x16x32_bf16 v[24:27], v[136:139], v[166:169], v[24:27]
	v_mfma_f32_16x16x32_bf16 v[12:15], v[128:131], v[196:199], v[12:15]
	v_mfma_f32_16x16x32_bf16 v[8:11], v[136:139], v[196:199], v[8:11]
	v_mfma_f32_16x16x32_bf16 v[60:63], v[132:135], v[154:157], v[60:63]
	v_mfma_f32_16x16x32_bf16 v[56:59], v[146:149], v[154:157], v[56:59]
	v_mfma_f32_16x16x32_bf16 v[44:47], v[132:135], v[162:165], v[44:47]
	v_mfma_f32_16x16x32_bf16 v[40:43], v[146:149], v[162:165], v[40:43]
	v_mfma_f32_16x16x32_bf16 v[28:31], v[132:135], v[192:195], v[28:31]
	v_mfma_f32_16x16x32_bf16 v[24:27], v[146:149], v[192:195], v[24:27]
	v_mfma_f32_16x16x32_bf16 v[12:15], v[132:135], v[200:203], v[12:15]
	v_mfma_f32_16x16x32_bf16 v[8:11], v[146:149], v[200:203], v[8:11]
	s_setprio 0
	s_barrier
; #define PG8_STAGE(bufoff, gbase, voff) do { _Pragma("unroll") for (int _i = 0; _i < 2; ++_i) \
;         __builtin_amdgcn_global_load_lds((const unsigned*)((const char*)(gbase) + (voff)[_i]), (LAS unsigned*)(lds + (bufoff) + ldsw + _i * 8192), 16, 0, 0); } while (0)
; #define PG8_LDA(dst, b, h) do { _Pragma("unroll") for (int m = 0; m < 4; ++m) _Pragma("unroll") for (int k = 0; k < 2; ++k) dst[m][k] = *(const LAS bf16x8*)(lds + PG8_SA(b, h) + aoff + m * 2048 + k * 1024); } while (0)
; #define PG8_LDB(dst, b, h) do { _Pragma("unroll") for (int n = 0; n < 2; ++n) _Pragma("unroll") for (int k = 0; k < 2; ++k) dst[n][k] = *(const LAS bf16x8*)(lds + PG8_SB(b, h) + boff + n * 2048 + k * 1024); } while (0)
; #define PG8_MMA(ai, bj, At, Bt) do { __builtin_amdgcn_s_setprio(1); _Pragma("unroll") for (int m = 0; m < 4; ++m) _Pragma("unroll") for (int n = 0; n < 2; ++n) _Pragma("unroll") for (int k = 0; k < 2; ++k) \
;         acc[ai][bj][m][n] = __builtin_amdgcn_mfma_f32_16x16x32_bf16(Bt[n][k], At[m][k], acc[ai][bj][m][n], 0, 0, 0); __builtin_amdgcn_s_setprio(0); } while (0)
; #define PG8_WAIT_V(n) asm volatile("s_waitcnt vmcnt(" #n ")" ::: "memory")
; #define PG8_WAIT_L(n) asm volatile("s_waitcnt lgkmcnt(" #n ")" ::: "memory")
; #define PG8_BAR __builtin_amdgcn_s_barrier()
; #define PG8_SCHED __builtin_amdgcn_sched_barrier(0)
; template <class Epi>
; __device__ __forceinline__ void gemm_phase(LAS unsigned char* lds, const GSched& S, const int K, const int lda, const int ldb, const Epi& E) {
;     ...
;             PG8_STAGE(PG8_SB(0, 1), b2 + hstepB, voffB);
;             PG8_WAIT_V(6); PG8_BAR; if constexpr (!Epi::NARROW) PG8_MMA(1, 1, At, B1); PG8_BAR;
;             PG8_LDB(B0, 1, 0); PG8_SCHED; PG8_LDA(At, 1, 0); PG8_STAGE(PG8_SA(0, 1), a2 + hstepA, voffA);
;             PG8_WAIT_L(8); PG8_BAR; PG8_WAIT_L(0); PG8_MMA(0, 0, At, B0); PG8_BAR; PG8_SCHED;
;             if constexpr (!Epi::NARROW) PG8_LDB(B1, 1, 1); PG8_STAGE(PG8_SB(1, 0), b3, voffB);
;             PG8_BAR; PG8_WAIT_L(0); if constexpr (!Epi::NARROW) PG8_MMA(0, 1, At, B1); PG8_BAR;
;             PG8_LDA(At, 1, 1); PG8_STAGE(PG8_SA(1, 0), a3, voffA);
;             PG8_BAR; PG8_WAIT_L(0); PG8_MMA(1, 0, At, B0); PG8_BAR; PG8_SCHED;
	s_add_u32 s56, s26, 0x84000
	s_addc_u32 s57, s27, 0
	s_add_i32 s58, s47, s36
	v_lshl_add_u64 v[128:129], s[56:57], 0, v[174:175]
	s_mov_b32 m0, s58
	s_nop 0
	global_load_lds_dwordx4 v[128:129], off
	v_lshl_add_u64 v[128:129], s[56:57], 0, v[178:179]
	s_add_i32 m0, s58, 0x2000
	s_nop 0
	global_load_lds_dwordx4 v[128:129], off
	s_waitcnt vmcnt(6)
	s_barrier
	s_setprio 1
	v_mfma_f32_16x16x32_bf16 v[52:55], v[210:213], v[150:153], v[52:55]
	v_mfma_f32_16x16x32_bf16 v[48:51], v[218:221], v[150:153], v[48:51]
	v_mfma_f32_16x16x32_bf16 v[36:39], v[210:213], v[158:161], v[36:39]
	v_mfma_f32_16x16x32_bf16 v[32:35], v[218:221], v[158:161], v[32:35]
	v_mfma_f32_16x16x32_bf16 v[20:23], v[210:213], v[166:169], v[20:23]
	v_mfma_f32_16x16x32_bf16 v[16:19], v[218:221], v[166:169], v[16:19]
	v_mfma_f32_16x16x32_bf16 v[4:7], v[210:213], v[196:199], v[4:7]
	v_mfma_f32_16x16x32_bf16 v[0:3], v[218:221], v[196:199], v[0:3]
	v_mfma_f32_16x16x32_bf16 v[52:55], v[214:217], v[154:157], v[52:55]
	v_mfma_f32_16x16x32_bf16 v[48:51], v[222:225], v[154:157], v[48:51]
	v_mfma_f32_16x16x32_bf16 v[36:39], v[214:217], v[162:165], v[36:39]
	v_mfma_f32_16x16x32_bf16 v[32:35], v[222:225], v[162:165], v[32:35]
	v_mfma_f32_16x16x32_bf16 v[20:23], v[214:217], v[192:195], v[20:23]
	v_mfma_f32_16x16x32_bf16 v[16:19], v[222:225], v[192:195], v[16:19]
	v_mfma_f32_16x16x32_bf16 v[4:7], v[214:217], v[200:203], v[4:7]
	v_mfma_f32_16x16x32_bf16 v[0:3], v[222:225], v[200:203], v[0:3]
	s_setprio 0
	s_add_i32 s56, 0, 0x18000
	v_add_u32_e32 v146, s56, v205
	s_barrier
	ds_read_b128 v[128:131], v146
	ds_read_b128 v[132:135], v146 offset:1024
	ds_read_b128 v[136:139], v146 offset:2048
	ds_read_b128 v[146:149], v146 offset:3072
	s_add_u32 s28, s28, 0x80000
	s_addc_u32 s29, s29, 0
	s_mov_b32 m0, s39
	v_lshl_add_u64 v[210:211], s[28:29], 0, v[172:173]
	ds_read_b128 v[150:153], v208 offset:32768
	ds_read_b128 v[154:157], v208 offset:33792
	ds_read_b128 v[158:161], v208 offset:34816
	ds_read_b128 v[162:165], v208 offset:35840
	ds_read_b128 v[166:169], v208 offset:36864
	ds_read_b128 v[192:195], v208 offset:37888
	ds_read_b128 v[196:199], v208 offset:38912
	ds_read_b128 v[200:203], v208 offset:39936
	global_load_lds_dwordx4 v[210:211], off
	v_lshl_add_u64 v[210:211], s[28:29], 0, v[176:177]
	s_mov_b32 m0, s40
	s_nop 0
	global_load_lds_dwordx4 v[210:211], off
	s_waitcnt lgkmcnt(8)
	s_barrier
	s_waitcnt lgkmcnt(0)
	s_setprio 1
	s_waitcnt lgkmcnt(0)
	v_mfma_f32_16x16x32_bf16 v[124:127], v[128:131], v[150:153], v[124:127]
	v_mfma_f32_16x16x32_bf16 v[120:123], v[136:139], v[150:153], v[120:123]
	v_mfma_f32_16x16x32_bf16 v[108:111], v[128:131], v[158:161], v[108:111]
	v_mfma_f32_16x16x32_bf16 v[104:107], v[136:139], v[158:161], v[104:107]
	v_mfma_f32_16x16x32_bf16 v[92:95], v[128:131], v[166:169], v[92:95]
	v_mfma_f32_16x16x32_bf16 v[88:91], v[136:139], v[166:169], v[88:91]
	v_mfma_f32_16x16x32_bf16 v[76:79], v[128:131], v[196:199], v[76:79]
	v_mfma_f32_16x16x32_bf16 v[72:75], v[136:139], v[196:199], v[72:75]
	v_mfma_f32_16x16x32_bf16 v[124:127], v[132:135], v[154:157], v[124:127]
	v_mfma_f32_16x16x32_bf16 v[120:123], v[146:149], v[154:157], v[120:123]
	v_mfma_f32_16x16x32_bf16 v[108:111], v[132:135], v[162:165], v[108:111]
	v_mfma_f32_16x16x32_bf16 v[104:107], v[146:149], v[162:165], v[104:107]
	v_mfma_f32_16x16x32_bf16 v[92:95], v[132:135], v[192:195], v[92:95]
	v_mfma_f32_16x16x32_bf16 v[88:91], v[146:149], v[192:195], v[88:91]
	v_mfma_f32_16x16x32_bf16 v[76:79], v[132:135], v[200:203], v[76:79]
	v_mfma_f32_16x16x32_bf16 v[72:75], v[146:149], v[200:203], v[72:75]
	s_setprio 0
	s_barrier
	s_add_i32 s28, 0, 0x1c000
	s_add_i32 s29, s56, s36
	v_add_u32_e32 v191, s28, v205
	v_lshl_add_u64 v[170:171], v[170:171], 0, s[14:15]
	s_mov_b32 m0, s29
	ds_read_b128 v[210:213], v191
	ds_read_b128 v[214:217], v191 offset:1024
	ds_read_b128 v[218:221], v191 offset:2048
	ds_read_b128 v[222:225], v191 offset:3072
	global_load_lds_dwordx4 v[170:171], off
	v_lshl_add_u64 v[170:171], v[226:227], 0, s[14:15]
	s_add_i32 m0, s29, 0x2000
	s_nop 0
	global_load_lds_dwordx4 v[170:171], off
	s_barrier
	s_waitcnt lgkmcnt(0)
	s_setprio 1
	s_waitcnt lgkmcnt(0)
	v_mfma_f32_16x16x32_bf16 v[116:119], v[210:213], v[150:153], v[116:119]
	v_mfma_f32_16x16x32_bf16 v[112:115], v[218:221], v[150:153], v[112:115]
	v_mfma_f32_16x16x32_bf16 v[100:103], v[210:213], v[158:161], v[100:103]
	v_mfma_f32_16x16x32_bf16 v[96:99], v[218:221], v[158:161], v[96:99]
	v_mfma_f32_16x16x32_bf16 v[84:87], v[210:213], v[166:169], v[84:87]
	v_mfma_f32_16x16x32_bf16 v[80:83], v[218:221], v[166:169], v[80:83]
	v_mfma_f32_16x16x32_bf16 v[68:71], v[210:213], v[196:199], v[68:71]
	v_mfma_f32_16x16x32_bf16 v[64:67], v[218:221], v[196:199], v[64:67]
	v_mfma_f32_16x16x32_bf16 v[116:119], v[214:217], v[154:157], v[116:119]
	v_mfma_f32_16x16x32_bf16 v[112:115], v[222:225], v[154:157], v[112:115]
	v_mfma_f32_16x16x32_bf16 v[100:103], v[214:217], v[162:165], v[100:103]
	v_mfma_f32_16x16x32_bf16 v[96:99], v[222:225], v[162:165], v[96:99]
	v_mfma_f32_16x16x32_bf16 v[84:87], v[214:217], v[192:195], v[84:87]
	v_mfma_f32_16x16x32_bf16 v[80:83], v[222:225], v[192:195], v[80:83]
	v_mfma_f32_16x16x32_bf16 v[68:71], v[214:217], v[200:203], v[68:71]
	v_mfma_f32_16x16x32_bf16 v[64:67], v[222:225], v[200:203], v[64:67]
	s_setprio 0
	s_mov_b32 m0, s42
	v_lshl_add_u64 v[170:171], v[228:229], 0, s[14:15]
	s_barrier
	ds_read_b128 v[150:153], v208 offset:49152
	ds_read_b128 v[154:157], v208 offset:50176
	ds_read_b128 v[158:161], v208 offset:51200
	ds_read_b128 v[162:165], v208 offset:52224
	ds_read_b128 v[166:169], v208 offset:53248
	ds_read_b128 v[192:195], v208 offset:54272
	ds_read_b128 v[196:199], v208 offset:55296
	ds_read_b128 v[200:203], v208 offset:56320
	global_load_lds_dwordx4 v[170:171], off
	v_lshl_add_u64 v[170:171], v[230:231], 0, s[14:15]
	s_mov_b32 m0, s43
	s_nop 0
	global_load_lds_dwordx4 v[170:171], off
	s_barrier
; __device__ __forceinline__ f32x4 ld_nt(const float* p) { return __builtin_nontemporal_load((const f32x4*)p); }
; __device__ __forceinline__ u32x4 ld_nt(const bf16_t* p) { return __builtin_nontemporal_load((const u32x4*)p); }
; __device__ __forceinline__ void unpack8(const u32x4 w, f32x4& a, f32x4& b) { a = (f32x4){bf_lo(w.x), bf_hi(w.x), bf_lo(w.y), bf_hi(w.y)}; b = (f32x4){bf_lo(w.z), bf_hi(w.z), bf_lo(w.w), bf_hi(w.w)}; }
; #define PG8_STAGE(bufoff, gbase, voff) do { _Pragma("unroll") for (int _i = 0; _i < 2; ++_i) \
;         __builtin_amdgcn_global_load_lds((const unsigned*)((const char*)(gbase) + (voff)[_i]), (LAS unsigned*)(lds + (bufoff) + ldsw + _i * 8192), 16, 0, 0); } while (0)
;     __device__ __forceinline__ void mid(Acc& acc, const Unit& u, int wr, int wc, int fr, int fq) const {
;         int row0 = u.pm * BM + wr * 64 + fr; asm volatile("" : "+v"(row0));
;         const bf16_t* gb = gates + (size_t)row0 * 4096 + u.pn * BM + wc * 32 + 8 * fq;
; #pragma unroll
;         for (int ai = 0; ai < 2; ++ai)
; #pragma unroll
;             for (int mp = 0; mp < 1; ++mp) {
;                 u32x4 ga[4][2];
; #pragma unroll
;                 for (int mm = 0; mm < 4; ++mm)
; #pragma unroll
;                     for (int bj = 0; bj < 2; ++bj) { const bf16_t* g = gb + (size_t)(ai * HALF + mm * 16) * 4096 + bj * HALF; ga[mm][bj] = ld_nt(g); }
; #pragma unroll
;                 for (int mm = 0; mm < 4; ++mm)
; #pragma unroll
;                     for (int bj = 0; bj < 2; ++bj) { const int m = mm; f32x4 a0, a1; unpack8(ga[mm][bj], a0, a1);
; #pragma unroll
;                         for (int j = 0; j < 4; ++j) { acc[ai][bj][m][0][j] *= a0[j]; acc[ai][bj][m][1][j] *= a1[j]; } }
;                 asm volatile("" ::: "memory"); }
; template <class Epi>
; __device__ __forceinline__ void gemm_phase(LAS unsigned char* lds, const GSched& S, const int K, const int lda, const int ldb, const Epi& E) {
;     ...
;             PG8_LDA(At, 1, 1); PG8_STAGE(PG8_SA(1, 0), a3, voffA);
;             PG8_BAR; PG8_WAIT_L(0); PG8_MMA(1, 0, At, B0); PG8_BAR; PG8_SCHED;
;             PG8_STAGE(PG8_SB(1, 1), b3 + hstepB, voffB);
;             PG8_WAIT_V(6); PG8_BAR; if constexpr (!Epi::NARROW) PG8_MMA(1, 1, At, B1); PG8_BAR;
;             if constexpr (Epi::HAS_MID) { if (t + 2 == E.mid_t) { PG8_SCHED; E.mid(acc, cur, wr, wc, fr, fq); PG8_SCHED; } }
	s_waitcnt lgkmcnt(0)
	s_setprio 1
	v_mfma_f32_16x16x32_bf16 v[60:63], v[128:131], v[150:153], v[60:63]
	v_mfma_f32_16x16x32_bf16 v[56:59], v[136:139], v[150:153], v[56:59]
	v_mfma_f32_16x16x32_bf16 v[44:47], v[128:131], v[158:161], v[44:47]
	v_mfma_f32_16x16x32_bf16 v[40:43], v[136:139], v[158:161], v[40:43]
	v_mfma_f32_16x16x32_bf16 v[28:31], v[128:131], v[166:169], v[28:31]
	v_mfma_f32_16x16x32_bf16 v[24:27], v[136:139], v[166:169], v[24:27]
	v_mfma_f32_16x16x32_bf16 v[12:15], v[128:131], v[196:199], v[12:15]
	v_mfma_f32_16x16x32_bf16 v[8:11], v[136:139], v[196:199], v[8:11]
	v_mfma_f32_16x16x32_bf16 v[60:63], v[132:135], v[154:157], v[60:63]
	v_mfma_f32_16x16x32_bf16 v[56:59], v[146:149], v[154:157], v[56:59]
	v_mfma_f32_16x16x32_bf16 v[44:47], v[132:135], v[162:165], v[44:47]
	v_mfma_f32_16x16x32_bf16 v[40:43], v[146:149], v[162:165], v[40:43]
	v_mfma_f32_16x16x32_bf16 v[28:31], v[132:135], v[192:195], v[28:31]
	v_mfma_f32_16x16x32_bf16 v[24:27], v[146:149], v[192:195], v[24:27]
	v_mfma_f32_16x16x32_bf16 v[12:15], v[132:135], v[200:203], v[12:15]
	v_mfma_f32_16x16x32_bf16 v[8:11], v[146:149], v[200:203], v[8:11]
	s_setprio 0
	s_barrier
	s_add_u32 s26, s26, 0x84080
	s_addc_u32 s27, s27, 0
	s_add_i32 s28, s28, s36
	v_lshl_add_u64 v[128:129], s[26:27], 0, v[174:175]
	s_mov_b32 m0, s28
	s_nop 0
	global_load_lds_dwordx4 v[128:129], off
	v_lshl_add_u64 v[128:129], s[26:27], 0, v[178:179]
	s_add_i32 m0, s28, 0x2000
	s_nop 0
	global_load_lds_dwordx4 v[128:129], off
	s_waitcnt vmcnt(6)
	s_barrier
	s_setprio 1
	v_mfma_f32_16x16x32_bf16 v[52:55], v[210:213], v[150:153], v[52:55]
	v_mfma_f32_16x16x32_bf16 v[48:51], v[218:221], v[150:153], v[48:51]
	v_mfma_f32_16x16x32_bf16 v[36:39], v[210:213], v[158:161], v[36:39]
	v_mfma_f32_16x16x32_bf16 v[32:35], v[218:221], v[158:161], v[32:35]
	v_mfma_f32_16x16x32_bf16 v[20:23], v[210:213], v[166:169], v[20:23]
	v_mfma_f32_16x16x32_bf16 v[16:19], v[218:221], v[166:169], v[16:19]
	v_mfma_f32_16x16x32_bf16 v[4:7], v[210:213], v[196:199], v[4:7]
	v_mfma_f32_16x16x32_bf16 v[0:3], v[218:221], v[196:199], v[0:3]
	v_mfma_f32_16x16x32_bf16 v[52:55], v[214:217], v[154:157], v[52:55]
	v_mfma_f32_16x16x32_bf16 v[48:51], v[222:225], v[154:157], v[48:51]
	v_mfma_f32_16x16x32_bf16 v[36:39], v[214:217], v[162:165], v[36:39]
	v_mfma_f32_16x16x32_bf16 v[32:35], v[222:225], v[162:165], v[32:35]
	v_mfma_f32_16x16x32_bf16 v[20:23], v[214:217], v[192:195], v[20:23]
	v_mfma_f32_16x16x32_bf16 v[16:19], v[222:225], v[192:195], v[16:19]
	v_mfma_f32_16x16x32_bf16 v[4:7], v[214:217], v[200:203], v[4:7]
	v_mfma_f32_16x16x32_bf16 v[0:3], v[222:225], v[200:203], v[0:3]
	s_setprio 0
	s_add_i32 s26, s19, 2
	s_cmp_lg_u32 s26, 16
	s_barrier
	s_cbranch_scc1 .LBB0_864
	v_mov_b32_e32 v128, v190
	s_nop 0
	v_ashrrev_i32_e32 v129, 31, v128
	v_lshlrev_b64 v[128:129], 13, v[128:129]
	v_lshl_add_u64 v[146:147], v[140:141], 0, v[128:129]
	v_add_co_u32_e32 v128, vcc, s48, v146
	global_load_dwordx4 v[148:151], v[146:147], off nt
	global_load_dwordx4 v[152:155], v[146:147], off offset:256 nt
	v_addc_co_u32_e32 v129, vcc, 0, v147, vcc
	global_load_dwordx4 v[156:159], v[128:129], off nt
	global_load_dwordx4 v[136:139], v[128:129], off offset:256 nt
	v_add_co_u32_e32 v128, vcc, s49, v146
	s_waitcnt vmcnt(0)
	v_lshlrev_b32_e32 v196, 16, v148
	v_addc_co_u32_e32 v129, vcc, 0, v147, vcc
	global_load_dwordx4 v[132:135], v[128:129], off nt
	s_nop 0
	global_load_dwordx4 v[128:131], v[128:129], off offset:256 nt
	v_add_co_u32_e32 v192, vcc, s51, v146
	v_and_b32_e32 v197, 0xffff0000, v148
	s_nop 0
	v_addc_co_u32_e32 v193, vcc, 0, v147, vcc
	v_add_co_u32_e32 v164, vcc, s50, v146
	v_lshlrev_b32_e32 v148, 16, v149
	s_nop 0
	v_addc_co_u32_e32 v165, vcc, 0, v147, vcc
	global_load_dwordx4 v[160:163], v[164:165], off nt
	s_nop 0
	global_load_dwordx4 v[164:167], v[164:165], off offset:256 nt
	global_load_dwordx4 v[168:171], v[192:193], off nt
	s_nop 0
	global_load_dwordx4 v[192:195], v[192:193], off offset:256 nt
	v_and_b32_e32 v149, 0xffff0000, v149
	v_lshlrev_b32_e32 v198, 16, v150
	v_and_b32_e32 v199, 0xffff0000, v150
	v_lshlrev_b32_e32 v150, 16, v151
	v_and_b32_e32 v151, 0xffff0000, v151
	v_lshlrev_b32_e32 v200, 16, v152
	v_and_b32_e32 v201, 0xffff0000, v152
	v_lshlrev_b32_e32 v202, 16, v154
	v_and_b32_e32 v203, 0xffff0000, v154
	v_lshlrev_b32_e32 v152, 16, v153
	v_and_b32_e32 v153, 0xffff0000, v153
	v_lshlrev_b32_e32 v154, 16, v155
	v_and_b32_e32 v155, 0xffff0000, v155
	v_pk_mul_f32 v[126:127], v[126:127], v[148:149]
	v_lshlrev_b32_e32 v148, 16, v156
	v_and_b32_e32 v149, 0xffff0000, v156
	v_pk_mul_f32 v[122:123], v[122:123], v[150:151]
	v_pk_mul_f32 v[118:119], v[118:119], v[152:153]
	v_pk_mul_f32 v[114:115], v[114:115], v[154:155]
	v_lshlrev_b32_e32 v150, 16, v158
	v_and_b32_e32 v151, 0xffff0000, v158
	v_lshlrev_b32_e32 v152, 16, v157
	v_and_b32_e32 v153, 0xffff0000, v157
	v_lshlrev_b32_e32 v154, 16, v159
	v_and_b32_e32 v155, 0xffff0000, v159
	v_lshlrev_b32_e32 v156, 16, v136
	v_and_b32_e32 v157, 0xffff0000, v136
	v_lshlrev_b32_e32 v158, 16, v138
	v_and_b32_e32 v159, 0xffff0000, v138
	v_lshlrev_b32_e32 v136, 16, v137
	v_and_b32_e32 v137, 0xffff0000, v137
	v_lshlrev_b32_e32 v138, 16, v139
	v_and_b32_e32 v139, 0xffff0000, v139
	v_pk_mul_f32 v[108:109], v[108:109], v[148:149]
	v_add_co_u32_e32 v148, vcc, s52, v146
	v_pk_mul_f32 v[102:103], v[102:103], v[136:137]
	v_pk_mul_f32 v[98:99], v[98:99], v[138:139]
	v_addc_co_u32_e32 v149, vcc, 0, v147, vcc
	v_pk_mul_f32 v[104:105], v[104:105], v[150:151]
	v_pk_mul_f32 v[110:111], v[110:111], v[152:153]
	v_pk_mul_f32 v[106:107], v[106:107], v[154:155]
	v_pk_mul_f32 v[100:101], v[100:101], v[156:157]
	v_pk_mul_f32 v[96:97], v[96:97], v[158:159]
	v_pk_mul_f32 v[124:125], v[124:125], v[196:197]
	v_pk_mul_f32 v[120:121], v[120:121], v[198:199]
	v_pk_mul_f32 v[116:117], v[116:117], v[200:201]
	v_pk_mul_f32 v[112:113], v[112:113], v[202:203]
	s_waitcnt vmcnt(0)
; __device__ __forceinline__ f32x4 ld_nt(const float* p) { return __builtin_nontemporal_load((const f32x4*)p); }
; __device__ __forceinline__ u32x4 ld_nt(const bf16_t* p) { return __builtin_nontemporal_load((const u32x4*)p); }
; __device__ __forceinline__ void unpack8(const u32x4 w, f32x4& a, f32x4& b) { a = (f32x4){bf_lo(w.x), bf_hi(w.x), bf_lo(w.y), bf_hi(w.y)}; b = (f32x4){bf_lo(w.z), bf_hi(w.z), bf_lo(w.w), bf_hi(w.w)}; }
;     __device__ __forceinline__ void mid(Acc& acc, const Unit& u, int wr, int wc, int fr, int fq) const {
;     ...
;                 u32x4 ga[4][2];
; #pragma unroll
;                 for (int mm = 0; mm < 4; ++mm)
; #pragma unroll
;                     for (int bj = 0; bj < 2; ++bj) { const bf16_t* g = gb + (size_t)(ai * HALF + mm * 16) * 4096 + bj * HALF; ga[mm][bj] = ld_nt(g); }
; #pragma unroll
;                 for (int mm = 0; mm < 4; ++mm)
; #pragma unroll
;                     for (int bj = 0; bj < 2; ++bj) { const int m = mm; f32x4 a0, a1; unpack8(ga[mm][bj], a0, a1);
; #pragma unroll
;                         for (int j = 0; j < 4; ++j) { acc[ai][bj][m][0][j] *= a0[j]; acc[ai][bj][m][1][j] *= a1[j]; } }
;                 asm volatile("" ::: "memory"); }
	v_lshlrev_b32_e32 v136, 16, v132
	v_and_b32_e32 v137, 0xffff0000, v132
	v_lshlrev_b32_e32 v138, 16, v134
	v_and_b32_e32 v139, 0xffff0000, v134
	v_lshlrev_b32_e32 v132, 16, v133
	v_and_b32_e32 v133, 0xffff0000, v133
	v_pk_mul_f32 v[92:93], v[92:93], v[136:137]
	v_pk_mul_f32 v[88:89], v[88:89], v[138:139]
	global_load_dwordx4 v[136:139], v[148:149], off nt
	v_pk_mul_f32 v[94:95], v[94:95], v[132:133]
	v_lshlrev_b32_e32 v132, 16, v135
	v_and_b32_e32 v133, 0xffff0000, v135
	v_pk_mul_f32 v[90:91], v[90:91], v[132:133]
	v_lshlrev_b32_e32 v132, 16, v128
	v_and_b32_e32 v133, 0xffff0000, v128
	v_pk_mul_f32 v[84:85], v[84:85], v[132:133]
	v_lshlrev_b32_e32 v150, 16, v130
	v_and_b32_e32 v151, 0xffff0000, v130
	global_load_dwordx4 v[132:135], v[148:149], off offset:256 nt
	v_lshlrev_b32_e32 v128, 16, v129
	v_and_b32_e32 v129, 0xffff0000, v129
	v_add_co_u32_e32 v148, vcc, s53, v146
	v_pk_mul_f32 v[80:81], v[80:81], v[150:151]
	v_pk_mul_f32 v[86:87], v[86:87], v[128:129]
	v_lshlrev_b32_e32 v128, 16, v131
	v_and_b32_e32 v129, 0xffff0000, v131
	v_addc_co_u32_e32 v149, vcc, 0, v147, vcc
	v_lshlrev_b32_e32 v150, 16, v160
	v_and_b32_e32 v151, 0xffff0000, v160
	v_pk_mul_f32 v[82:83], v[82:83], v[128:129]
	global_load_dwordx4 v[128:131], v[148:149], off nt
	v_pk_mul_f32 v[76:77], v[76:77], v[150:151]
	v_lshlrev_b32_e32 v150, 16, v162
	v_and_b32_e32 v151, 0xffff0000, v162
	v_pk_mul_f32 v[72:73], v[72:73], v[150:151]
	v_lshlrev_b32_e32 v150, 16, v161
	v_and_b32_e32 v151, 0xffff0000, v161
	v_pk_mul_f32 v[78:79], v[78:79], v[150:151]
	global_load_dwordx4 v[148:151], v[148:149], off offset:256 nt
	v_lshlrev_b32_e32 v152, 16, v163
	v_and_b32_e32 v153, 0xffff0000, v163
	v_pk_mul_f32 v[74:75], v[74:75], v[152:153]
	v_lshlrev_b32_e32 v152, 16, v164
	v_and_b32_e32 v153, 0xffff0000, v164
	v_add_co_u32_e32 v146, vcc, s54, v146
	v_pk_mul_f32 v[68:69], v[68:69], v[152:153]
	v_lshlrev_b32_e32 v152, 16, v166
	v_and_b32_e32 v153, 0xffff0000, v166
	v_addc_co_u32_e32 v147, vcc, 0, v147, vcc
	v_pk_mul_f32 v[64:65], v[64:65], v[152:153]
	global_load_dwordx4 v[152:155], v[146:147], off nt
	v_lshlrev_b32_e32 v156, 16, v165
	v_and_b32_e32 v157, 0xffff0000, v165
	v_pk_mul_f32 v[70:71], v[70:71], v[156:157]
	v_lshlrev_b32_e32 v156, 16, v167
	v_and_b32_e32 v157, 0xffff0000, v167
	v_pk_mul_f32 v[66:67], v[66:67], v[156:157]
	global_load_dwordx4 v[156:159], v[146:147], off offset:256 nt
	v_lshlrev_b32_e32 v146, 16, v168
	v_and_b32_e32 v147, 0xffff0000, v168
	v_pk_mul_f32 v[60:61], v[60:61], v[146:147]
	v_lshlrev_b32_e32 v146, 16, v170
	v_and_b32_e32 v147, 0xffff0000, v170
	v_pk_mul_f32 v[56:57], v[56:57], v[146:147]
	v_lshlrev_b32_e32 v146, 16, v169
	v_and_b32_e32 v147, 0xffff0000, v169
	v_pk_mul_f32 v[62:63], v[62:63], v[146:147]
	v_lshlrev_b32_e32 v146, 16, v171
	v_and_b32_e32 v147, 0xffff0000, v171
	v_pk_mul_f32 v[58:59], v[58:59], v[146:147]
	v_lshlrev_b32_e32 v146, 16, v192
	v_and_b32_e32 v147, 0xffff0000, v192
	v_pk_mul_f32 v[52:53], v[52:53], v[146:147]
	v_lshlrev_b32_e32 v146, 16, v194
	v_and_b32_e32 v147, 0xffff0000, v194
	v_pk_mul_f32 v[48:49], v[48:49], v[146:147]
	v_lshlrev_b32_e32 v146, 16, v193
	v_and_b32_e32 v147, 0xffff0000, v193
	v_pk_mul_f32 v[54:55], v[54:55], v[146:147]
	v_lshlrev_b32_e32 v146, 16, v195
	v_and_b32_e32 v147, 0xffff0000, v195
	v_pk_mul_f32 v[50:51], v[50:51], v[146:147]
	s_waitcnt vmcnt(0)
	v_lshlrev_b32_e32 v146, 16, v136
	v_and_b32_e32 v147, 0xffff0000, v136
	v_lshlrev_b32_e32 v136, 16, v137
	v_and_b32_e32 v137, 0xffff0000, v137
	v_pk_mul_f32 v[46:47], v[46:47], v[136:137]
	v_lshlrev_b32_e32 v136, 16, v139
	v_and_b32_e32 v137, 0xffff0000, v139
	v_pk_mul_f32 v[42:43], v[42:43], v[136:137]
	v_pk_mul_f32 v[44:45], v[44:45], v[146:147]
	v_lshlrev_b32_e32 v146, 16, v138
	v_lshlrev_b32_e32 v136, 16, v132
	v_and_b32_e32 v137, 0xffff0000, v132
	v_lshlrev_b32_e32 v132, 16, v133
	v_and_b32_e32 v133, 0xffff0000, v133
	v_pk_mul_f32 v[38:39], v[38:39], v[132:133]
	v_lshlrev_b32_e32 v132, 16, v135
	v_and_b32_e32 v133, 0xffff0000, v135
	v_pk_mul_f32 v[34:35], v[34:35], v[132:133]
	v_and_b32_e32 v147, 0xffff0000, v138
	v_pk_mul_f32 v[36:37], v[36:37], v[136:137]
	v_lshlrev_b32_e32 v136, 16, v134
	v_and_b32_e32 v137, 0xffff0000, v134
	v_pk_mul_f32 v[40:41], v[40:41], v[146:147]
	v_pk_mul_f32 v[32:33], v[32:33], v[136:137]
	v_lshlrev_b32_e32 v132, 16, v128
	v_and_b32_e32 v133, 0xffff0000, v128
	v_lshlrev_b32_e32 v128, 16, v129
	v_and_b32_e32 v129, 0xffff0000, v129
	v_pk_mul_f32 v[30:31], v[30:31], v[128:129]
	v_lshlrev_b32_e32 v128, 16, v131
	v_and_b32_e32 v129, 0xffff0000, v131
	v_pk_mul_f32 v[26:27], v[26:27], v[128:129]
	v_lshlrev_b32_e32 v128, 16, v148
	v_and_b32_e32 v129, 0xffff0000, v148
	v_pk_mul_f32 v[20:21], v[20:21], v[128:129]
	v_lshlrev_b32_e32 v128, 16, v150
	v_and_b32_e32 v129, 0xffff0000, v150
	v_pk_mul_f32 v[16:17], v[16:17], v[128:129]
	v_lshlrev_b32_e32 v128, 16, v149
	v_and_b32_e32 v129, 0xffff0000, v149
	v_pk_mul_f32 v[22:23], v[22:23], v[128:129]
	v_lshlrev_b32_e32 v128, 16, v151
	v_and_b32_e32 v129, 0xffff0000, v151
	v_pk_mul_f32 v[18:19], v[18:19], v[128:129]
	v_pk_mul_f32 v[28:29], v[28:29], v[132:133]
	v_lshlrev_b32_e32 v132, 16, v130
	v_lshlrev_b32_e32 v128, 16, v152
	v_and_b32_e32 v129, 0xffff0000, v152
	v_pk_mul_f32 v[12:13], v[12:13], v[128:129]
	v_lshlrev_b32_e32 v128, 16, v154
	v_and_b32_e32 v129, 0xffff0000, v154
	v_pk_mul_f32 v[8:9], v[8:9], v[128:129]
	v_lshlrev_b32_e32 v128, 16, v153
	v_and_b32_e32 v129, 0xffff0000, v153
	v_pk_mul_f32 v[14:15], v[14:15], v[128:129]
	v_lshlrev_b32_e32 v128, 16, v155
	v_and_b32_e32 v129, 0xffff0000, v155
	v_pk_mul_f32 v[10:11], v[10:11], v[128:129]
	v_lshlrev_b32_e32 v128, 16, v156
	v_and_b32_e32 v129, 0xffff0000, v156
	v_pk_mul_f32 v[4:5], v[4:5], v[128:129]
	v_lshlrev_b32_e32 v128, 16, v158
	v_and_b32_e32 v129, 0xffff0000, v158
	v_pk_mul_f32 v[0:1], v[0:1], v[128:129]
	v_lshlrev_b32_e32 v128, 16, v157
	v_and_b32_e32 v129, 0xffff0000, v157
	v_and_b32_e32 v133, 0xffff0000, v130
	v_pk_mul_f32 v[6:7], v[6:7], v[128:129]
	v_lshlrev_b32_e32 v128, 16, v159
	v_and_b32_e32 v129, 0xffff0000, v159
	v_pk_mul_f32 v[24:25], v[24:25], v[132:133]
	v_pk_mul_f32 v[2:3], v[2:3], v[128:129]

; #define PG8_STAGE(bufoff, gbase, voff) do { _Pragma("unroll") for (int _i = 0; _i < 2; ++_i) \
;         __builtin_amdgcn_global_load_lds((const unsigned*)((const char*)(gbase) + (voff)[_i]), (LAS unsigned*)(lds + (bufoff) + ldsw + _i * 8192), 16, 0, 0); } while (0)
; #define PG8_LDA(dst, b, h) do { _Pragma("unroll") for (int m = 0; m < 4; ++m) _Pragma("unroll") for (int k = 0; k < 2; ++k) dst[m][k] = *(const LAS bf16x8*)(lds + PG8_SA(b, h) + aoff + m * 2048 + k * 1024); } while (0)
; #define PG8_LDB(dst, b, h) do { _Pragma("unroll") for (int n = 0; n < 2; ++n) _Pragma("unroll") for (int k = 0; k < 2; ++k) dst[n][k] = *(const LAS bf16x8*)(lds + PG8_SB(b, h) + boff + n * 2048 + k * 1024); } while (0)
; #define PG8_MMA(ai, bj, At, Bt) do { __builtin_amdgcn_s_setprio(1); _Pragma("unroll") for (int m = 0; m < 4; ++m) _Pragma("unroll") for (int n = 0; n < 2; ++n) _Pragma("unroll") for (int k = 0; k < 2; ++k) \
;         acc[ai][bj][m][n] = __builtin_amdgcn_mfma_f32_16x16x32_bf16(Bt[n][k], At[m][k], acc[ai][bj][m][n], 0, 0, 0); __builtin_amdgcn_s_setprio(0); } while (0)
; #define PG8_WAIT_V(n) asm volatile("s_waitcnt vmcnt(" #n ")" ::: "memory")
; #define PG8_WAIT_L(n) asm volatile("s_waitcnt lgkmcnt(" #n ")" ::: "memory")
; #define PG8_BAR __builtin_amdgcn_s_barrier()
; template <class Epi>
; __device__ __forceinline__ void gemm_phase(LAS unsigned char* lds, const GSched& S, const int K, const int lda, const int ldb, const Epi& E) {
;     ...
;             PG8_LDB(B0, 0, 0); PG8_SCHED; PG8_LDA(At, 0, 0); PG8_STAGE(PG8_SA(1, 1), a1 + hstepA, voffA);
;             PG8_WAIT_L(8); PG8_BAR; PG8_WAIT_L(0); PG8_MMA(0, 0, At, B0); PG8_BAR; PG8_SCHED;
;             if constexpr (!Epi::NARROW) PG8_LDB(B1, 0, 1); PG8_STAGE(PG8_SB(0, 0), b2, voffB);
;             PG8_BAR; PG8_WAIT_L(0); if constexpr (!Epi::NARROW) PG8_MMA(0, 1, At, B1); PG8_BAR;
;             PG8_LDA(At, 0, 1); PG8_STAGE(PG8_SA(0, 0), a2, voffA);
;             PG8_BAR; PG8_WAIT_L(0); PG8_MMA(1, 0, At, B0); PG8_BAR; PG8_SCHED;
;             PG8_STAGE(PG8_SB(0, 1), b2 + hstepB, voffB);
;             PG8_WAIT_V(6); PG8_BAR; if constexpr (!Epi::NARROW) PG8_MMA(1, 1, At, B1); PG8_BAR;
;             PG8_LDB(B0, 1, 0); PG8_SCHED; PG8_LDA(At, 1, 0); PG8_STAGE(PG8_SA(0, 1), a2 + hstepA, voffA);
;             PG8_WAIT_L(8); PG8_BAR; PG8_WAIT_L(0); PG8_MMA(0, 0, At, B0); PG8_BAR; PG8_SCHED;
.LBB0_941:
	ds_read_b128 v[104:107], v235
	ds_read_b128 v[116:119], v235 offset:1024
	ds_read_b128 v[128:131], v235 offset:2048
	ds_read_b128 v[140:143], v235 offset:3072
	s_add_u32 s26, s10, 0xfff80080
	s_addc_u32 s27, s11, -1
	s_cmp_eq_u32 s50, 28
	s_cselect_b32 s29, s21, s27
	s_cselect_b32 s28, s47, s26
	s_cselect_b32 s27, s23, s49
	s_cselect_b32 s26, s22, s48
	v_lshl_add_u64 v[176:177], s[10:11], 0, v[194:195]
	s_add_i32 m0, s0, 0xc000
	ds_read_b128 v[144:147], v236
	ds_read_b128 v[148:151], v236 offset:1024
	ds_read_b128 v[152:155], v236 offset:2048
	ds_read_b128 v[156:159], v236 offset:3072
	ds_read_b128 v[160:163], v236 offset:4096
	ds_read_b128 v[164:167], v236 offset:5120
	ds_read_b128 v[168:171], v236 offset:6144
	ds_read_b128 v[172:175], v236 offset:7168
	global_load_lds_dwordx4 v[176:177], off
	v_lshl_add_u64 v[176:177], s[10:11], 0, v[192:193]
	s_add_i32 m0, s0, 0xe000
	s_nop 0
	global_load_lds_dwordx4 v[176:177], off
	s_waitcnt lgkmcnt(8)
	s_barrier
	s_waitcnt lgkmcnt(0)
	s_setprio 1
	s_waitcnt lgkmcnt(0)
	v_mfma_f32_16x16x32_bf16 v[136:139], v[104:107], v[144:147], v[136:139]
	v_mfma_f32_16x16x32_bf16 v[132:135], v[128:131], v[144:147], v[132:135]
	v_mfma_f32_16x16x32_bf16 v[112:115], v[104:107], v[152:155], v[112:115]
	v_mfma_f32_16x16x32_bf16 v[108:111], v[128:131], v[152:155], v[108:111]
	v_mfma_f32_16x16x32_bf16 v[92:95], v[104:107], v[160:163], v[92:95]
	v_mfma_f32_16x16x32_bf16 v[88:91], v[128:131], v[160:163], v[88:91]
	v_mfma_f32_16x16x32_bf16 v[76:79], v[104:107], v[168:171], v[76:79]
	v_mfma_f32_16x16x32_bf16 v[72:75], v[128:131], v[168:171], v[72:75]
	v_mfma_f32_16x16x32_bf16 v[136:139], v[116:119], v[148:151], v[136:139]
	v_mfma_f32_16x16x32_bf16 v[132:135], v[140:143], v[148:151], v[132:135]
	v_mfma_f32_16x16x32_bf16 v[112:115], v[116:119], v[156:159], v[112:115]
	v_mfma_f32_16x16x32_bf16 v[108:111], v[140:143], v[156:159], v[108:111]
	v_mfma_f32_16x16x32_bf16 v[92:95], v[116:119], v[164:167], v[92:95]
	v_mfma_f32_16x16x32_bf16 v[88:91], v[140:143], v[164:167], v[88:91]
	v_mfma_f32_16x16x32_bf16 v[76:79], v[116:119], v[172:175], v[76:79]
	v_mfma_f32_16x16x32_bf16 v[72:75], v[140:143], v[172:175], v[72:75]
	s_setprio 0
	s_barrier
	s_add_i32 s51, s41, s4
	v_lshl_add_u64 v[208:209], s[26:27], 0, v[186:187]
	s_mov_b32 m0, s51
	ds_read_b128 v[176:179], v237
	ds_read_b128 v[180:183], v237 offset:1024
	ds_read_b128 v[200:203], v237 offset:2048
	ds_read_b128 v[204:207], v237 offset:3072
	global_load_lds_dwordx4 v[208:209], off
	v_lshl_add_u64 v[210:211], s[26:27], 0, v[190:191]
	s_add_i32 m0, s51, 0x2000
	s_nop 0
	global_load_lds_dwordx4 v[210:211], off
	s_barrier
	s_waitcnt lgkmcnt(0)
	s_setprio 1
	v_mfma_f32_16x16x32_bf16 v[124:127], v[176:179], v[144:147], v[124:127]
	v_mfma_f32_16x16x32_bf16 v[120:123], v[200:203], v[144:147], v[120:123]
	v_mfma_f32_16x16x32_bf16 v[100:103], v[176:179], v[152:155], v[100:103]
	v_mfma_f32_16x16x32_bf16 v[96:99], v[200:203], v[152:155], v[96:99]
	v_mfma_f32_16x16x32_bf16 v[84:87], v[176:179], v[160:163], v[84:87]
	v_mfma_f32_16x16x32_bf16 v[80:83], v[200:203], v[160:163], v[80:83]
	v_mfma_f32_16x16x32_bf16 v[68:71], v[176:179], v[168:171], v[68:71]
	v_mfma_f32_16x16x32_bf16 v[64:67], v[200:203], v[168:171], v[64:67]
	v_mfma_f32_16x16x32_bf16 v[124:127], v[180:183], v[148:151], v[124:127]
	v_mfma_f32_16x16x32_bf16 v[120:123], v[204:207], v[148:151], v[120:123]
	v_mfma_f32_16x16x32_bf16 v[100:103], v[180:183], v[156:159], v[100:103]
	v_mfma_f32_16x16x32_bf16 v[96:99], v[204:207], v[156:159], v[96:99]
	v_mfma_f32_16x16x32_bf16 v[84:87], v[180:183], v[164:167], v[84:87]
	v_mfma_f32_16x16x32_bf16 v[80:83], v[204:207], v[164:167], v[80:83]
	v_mfma_f32_16x16x32_bf16 v[68:71], v[180:183], v[172:175], v[68:71]
	v_mfma_f32_16x16x32_bf16 v[64:67], v[204:207], v[172:175], v[64:67]
	s_setprio 0
	s_mov_b32 m0, s0
	v_lshl_add_u64 v[212:213], s[28:29], 0, v[184:185]
	s_barrier
	ds_read_b128 v[144:147], v236 offset:16384
	ds_read_b128 v[148:151], v236 offset:17408
	ds_read_b128 v[152:155], v236 offset:18432
	ds_read_b128 v[156:159], v236 offset:19456
	ds_read_b128 v[160:163], v236 offset:20480
	ds_read_b128 v[164:167], v236 offset:21504
	ds_read_b128 v[168:171], v236 offset:22528
	ds_read_b128 v[172:175], v236 offset:23552
	global_load_lds_dwordx4 v[212:213], off
	v_lshl_add_u64 v[214:215], s[28:29], 0, v[188:189]
	s_mov_b32 m0, s1
	s_nop 0
	global_load_lds_dwordx4 v[214:215], off
	s_barrier
	s_waitcnt lgkmcnt(0)
	s_setprio 1
	v_mfma_f32_16x16x32_bf16 v[60:63], v[104:107], v[144:147], v[60:63]
	v_mfma_f32_16x16x32_bf16 v[56:59], v[128:131], v[144:147], v[56:59]
	v_mfma_f32_16x16x32_bf16 v[44:47], v[104:107], v[152:155], v[44:47]
	v_mfma_f32_16x16x32_bf16 v[40:43], v[128:131], v[152:155], v[40:43]
	v_mfma_f32_16x16x32_bf16 v[28:31], v[104:107], v[160:163], v[28:31]
	v_mfma_f32_16x16x32_bf16 v[24:27], v[128:131], v[160:163], v[24:27]
	v_mfma_f32_16x16x32_bf16 v[12:15], v[104:107], v[168:171], v[12:15]
	v_mfma_f32_16x16x32_bf16 v[8:11], v[128:131], v[168:171], v[8:11]
	v_mfma_f32_16x16x32_bf16 v[60:63], v[116:119], v[148:151], v[60:63]
	v_mfma_f32_16x16x32_bf16 v[56:59], v[140:143], v[148:151], v[56:59]
	v_mfma_f32_16x16x32_bf16 v[44:47], v[116:119], v[156:159], v[44:47]
	v_mfma_f32_16x16x32_bf16 v[40:43], v[140:143], v[156:159], v[40:43]
	v_mfma_f32_16x16x32_bf16 v[28:31], v[116:119], v[164:167], v[28:31]
	v_mfma_f32_16x16x32_bf16 v[24:27], v[140:143], v[164:167], v[24:27]
	v_mfma_f32_16x16x32_bf16 v[12:15], v[116:119], v[172:175], v[12:15]
	v_mfma_f32_16x16x32_bf16 v[8:11], v[140:143], v[172:175], v[8:11]
	s_setprio 0
	s_barrier
; #define PG8_STAGE(bufoff, gbase, voff) do { _Pragma("unroll") for (int _i = 0; _i < 2; ++_i) \
;         __builtin_amdgcn_global_load_lds((const unsigned*)((const char*)(gbase) + (voff)[_i]), (LAS unsigned*)(lds + (bufoff) + ldsw + _i * 8192), 16, 0, 0); } while (0)
; #define PG8_LDA(dst, b, h) do { _Pragma("unroll") for (int m = 0; m < 4; ++m) _Pragma("unroll") for (int k = 0; k < 2; ++k) dst[m][k] = *(const LAS bf16x8*)(lds + PG8_SA(b, h) + aoff + m * 2048 + k * 1024); } while (0)
; #define PG8_LDB(dst, b, h) do { _Pragma("unroll") for (int n = 0; n < 2; ++n) _Pragma("unroll") for (int k = 0; k < 2; ++k) dst[n][k] = *(const LAS bf16x8*)(lds + PG8_SB(b, h) + boff + n * 2048 + k * 1024); } while (0)
; #define PG8_MMA(ai, bj, At, Bt) do { __builtin_amdgcn_s_setprio(1); _Pragma("unroll") for (int m = 0; m < 4; ++m) _Pragma("unroll") for (int n = 0; n < 2; ++n) _Pragma("unroll") for (int k = 0; k < 2; ++k) \
;         acc[ai][bj][m][n] = __builtin_amdgcn_mfma_f32_16x16x32_bf16(Bt[n][k], At[m][k], acc[ai][bj][m][n], 0, 0, 0); __builtin_amdgcn_s_setprio(0); } while (0)
; #define PG8_WAIT_V(n) asm volatile("s_waitcnt vmcnt(" #n ")" ::: "memory")
; #define PG8_WAIT_L(n) asm volatile("s_waitcnt lgkmcnt(" #n ")" ::: "memory")
; #define PG8_BAR __builtin_amdgcn_s_barrier()
; #define PG8_SCHED __builtin_amdgcn_sched_barrier(0)
; template <class Epi>
; __device__ __forceinline__ void gemm_phase(LAS unsigned char* lds, const GSched& S, const int K, const int lda, const int ldb, const Epi& E) {
;     ...
;             PG8_STAGE(PG8_SB(0, 1), b2 + hstepB, voffB);
;             PG8_WAIT_V(6); PG8_BAR; if constexpr (!Epi::NARROW) PG8_MMA(1, 1, At, B1); PG8_BAR;
;             PG8_LDB(B0, 1, 0); PG8_SCHED; PG8_LDA(At, 1, 0); PG8_STAGE(PG8_SA(0, 1), a2 + hstepA, voffA);
;             PG8_WAIT_L(8); PG8_BAR; PG8_WAIT_L(0); PG8_MMA(0, 0, At, B0); PG8_BAR; PG8_SCHED;
;             if constexpr (!Epi::NARROW) PG8_LDB(B1, 1, 1); PG8_STAGE(PG8_SB(1, 0), b3, voffB);
;             PG8_BAR; PG8_WAIT_L(0); if constexpr (!Epi::NARROW) PG8_MMA(0, 1, At, B1); PG8_BAR;
;             PG8_LDA(At, 1, 1); PG8_STAGE(PG8_SA(1, 0), a3, voffA);
;             PG8_BAR; PG8_WAIT_L(0); PG8_MMA(1, 0, At, B0); PG8_BAR; PG8_SCHED;
	s_add_u32 s52, s26, 0x84000
	s_addc_u32 s53, s27, 0
	s_add_i32 s51, s42, s4
	v_lshl_add_u64 v[104:105], s[52:53], 0, v[186:187]
	s_mov_b32 m0, s51
	s_nop 0
	global_load_lds_dwordx4 v[104:105], off
	v_lshl_add_u64 v[104:105], s[52:53], 0, v[190:191]
	s_add_i32 m0, s51, 0x2000
	s_nop 0
	global_load_lds_dwordx4 v[104:105], off
	s_waitcnt vmcnt(6)
	s_barrier
	s_setprio 1
	v_mfma_f32_16x16x32_bf16 v[52:55], v[176:179], v[144:147], v[52:55]
	v_mfma_f32_16x16x32_bf16 v[48:51], v[200:203], v[144:147], v[48:51]
	v_mfma_f32_16x16x32_bf16 v[36:39], v[176:179], v[152:155], v[36:39]
	v_mfma_f32_16x16x32_bf16 v[32:35], v[200:203], v[152:155], v[32:35]
	v_mfma_f32_16x16x32_bf16 v[20:23], v[176:179], v[160:163], v[20:23]
	v_mfma_f32_16x16x32_bf16 v[16:19], v[200:203], v[160:163], v[16:19]
	v_mfma_f32_16x16x32_bf16 v[4:7], v[176:179], v[168:171], v[4:7]
	v_mfma_f32_16x16x32_bf16 v[0:3], v[200:203], v[168:171], v[0:3]
	v_mfma_f32_16x16x32_bf16 v[52:55], v[180:183], v[148:151], v[52:55]
	v_mfma_f32_16x16x32_bf16 v[48:51], v[204:207], v[148:151], v[48:51]
	v_mfma_f32_16x16x32_bf16 v[36:39], v[180:183], v[156:159], v[36:39]
	v_mfma_f32_16x16x32_bf16 v[32:35], v[204:207], v[156:159], v[32:35]
	v_mfma_f32_16x16x32_bf16 v[20:23], v[180:183], v[164:167], v[20:23]
	v_mfma_f32_16x16x32_bf16 v[16:19], v[204:207], v[164:167], v[16:19]
	v_mfma_f32_16x16x32_bf16 v[4:7], v[180:183], v[172:175], v[4:7]
	v_mfma_f32_16x16x32_bf16 v[0:3], v[204:207], v[172:175], v[0:3]
	s_setprio 0
	s_add_i32 s51, 0, 0x18000
	v_add_u32_e32 v140, s51, v231
	s_barrier
	ds_read_b128 v[104:107], v140
	ds_read_b128 v[116:119], v140 offset:1024
	ds_read_b128 v[128:131], v140 offset:2048
	ds_read_b128 v[140:143], v140 offset:3072
	s_add_u32 s28, s28, 0x80000
	s_addc_u32 s29, s29, 0
	s_mov_b32 m0, s2
	v_lshl_add_u64 v[176:177], s[28:29], 0, v[184:185]
	ds_read_b128 v[144:147], v236 offset:32768
	ds_read_b128 v[148:151], v236 offset:33792
	ds_read_b128 v[152:155], v236 offset:34816
	ds_read_b128 v[156:159], v236 offset:35840
	ds_read_b128 v[160:163], v236 offset:36864
	ds_read_b128 v[164:167], v236 offset:37888
	ds_read_b128 v[168:171], v236 offset:38912
	ds_read_b128 v[172:175], v236 offset:39936
	global_load_lds_dwordx4 v[176:177], off
	v_lshl_add_u64 v[176:177], s[28:29], 0, v[188:189]
	s_mov_b32 m0, s5
	s_nop 0
	global_load_lds_dwordx4 v[176:177], off
	s_waitcnt lgkmcnt(8)
	s_barrier
	s_waitcnt lgkmcnt(0)
	s_setprio 1
	s_waitcnt lgkmcnt(0)
	v_mfma_f32_16x16x32_bf16 v[136:139], v[104:107], v[144:147], v[136:139]
	v_mfma_f32_16x16x32_bf16 v[132:135], v[128:131], v[144:147], v[132:135]
	v_mfma_f32_16x16x32_bf16 v[112:115], v[104:107], v[152:155], v[112:115]
	v_mfma_f32_16x16x32_bf16 v[108:111], v[128:131], v[152:155], v[108:111]
	v_mfma_f32_16x16x32_bf16 v[92:95], v[104:107], v[160:163], v[92:95]
	v_mfma_f32_16x16x32_bf16 v[88:91], v[128:131], v[160:163], v[88:91]
	v_mfma_f32_16x16x32_bf16 v[76:79], v[104:107], v[168:171], v[76:79]
	v_mfma_f32_16x16x32_bf16 v[72:75], v[128:131], v[168:171], v[72:75]
	v_mfma_f32_16x16x32_bf16 v[136:139], v[116:119], v[148:151], v[136:139]
	v_mfma_f32_16x16x32_bf16 v[132:135], v[140:143], v[148:151], v[132:135]
	v_mfma_f32_16x16x32_bf16 v[112:115], v[116:119], v[156:159], v[112:115]
	v_mfma_f32_16x16x32_bf16 v[108:111], v[140:143], v[156:159], v[108:111]
	v_mfma_f32_16x16x32_bf16 v[92:95], v[116:119], v[164:167], v[92:95]
	v_mfma_f32_16x16x32_bf16 v[88:91], v[140:143], v[164:167], v[88:91]
	v_mfma_f32_16x16x32_bf16 v[76:79], v[116:119], v[172:175], v[76:79]
	v_mfma_f32_16x16x32_bf16 v[72:75], v[140:143], v[172:175], v[72:75]
	s_setprio 0
	s_barrier
	s_add_i32 s28, 0, 0x1c000
	s_add_i32 s29, s51, s4
	v_add_u32_e32 v204, s28, v231
	v_lshl_add_u64 v[208:209], v[208:209], 0, s[18:19]
	s_mov_b32 m0, s29
	ds_read_b128 v[176:179], v204
	ds_read_b128 v[180:183], v204 offset:1024
	ds_read_b128 v[200:203], v204 offset:2048
	ds_read_b128 v[204:207], v204 offset:3072
	global_load_lds_dwordx4 v[208:209], off
	v_lshl_add_u64 v[208:209], v[210:211], 0, s[18:19]
	s_add_i32 m0, s29, 0x2000
	s_nop 0
	global_load_lds_dwordx4 v[208:209], off
	s_barrier
	s_waitcnt lgkmcnt(0)
	s_setprio 1
	s_waitcnt lgkmcnt(0)
	v_mfma_f32_16x16x32_bf16 v[124:127], v[176:179], v[144:147], v[124:127]
	v_mfma_f32_16x16x32_bf16 v[120:123], v[200:203], v[144:147], v[120:123]
	v_mfma_f32_16x16x32_bf16 v[100:103], v[176:179], v[152:155], v[100:103]
	v_mfma_f32_16x16x32_bf16 v[96:99], v[200:203], v[152:155], v[96:99]
	v_mfma_f32_16x16x32_bf16 v[84:87], v[176:179], v[160:163], v[84:87]
	v_mfma_f32_16x16x32_bf16 v[80:83], v[200:203], v[160:163], v[80:83]
	v_mfma_f32_16x16x32_bf16 v[68:71], v[176:179], v[168:171], v[68:71]
	v_mfma_f32_16x16x32_bf16 v[64:67], v[200:203], v[168:171], v[64:67]
	v_mfma_f32_16x16x32_bf16 v[124:127], v[180:183], v[148:151], v[124:127]
	v_mfma_f32_16x16x32_bf16 v[120:123], v[204:207], v[148:151], v[120:123]
	v_mfma_f32_16x16x32_bf16 v[100:103], v[180:183], v[156:159], v[100:103]
	v_mfma_f32_16x16x32_bf16 v[96:99], v[204:207], v[156:159], v[96:99]
	v_mfma_f32_16x16x32_bf16 v[84:87], v[180:183], v[164:167], v[84:87]
	v_mfma_f32_16x16x32_bf16 v[80:83], v[204:207], v[164:167], v[80:83]
	v_mfma_f32_16x16x32_bf16 v[68:71], v[180:183], v[172:175], v[68:71]
	v_mfma_f32_16x16x32_bf16 v[64:67], v[204:207], v[172:175], v[64:67]
	s_setprio 0
	s_mov_b32 m0, s36
	v_lshl_add_u64 v[208:209], v[212:213], 0, s[18:19]
	s_barrier
	ds_read_b128 v[144:147], v236 offset:49152
	ds_read_b128 v[148:151], v236 offset:50176
	ds_read_b128 v[152:155], v236 offset:51200
	ds_read_b128 v[156:159], v236 offset:52224
	ds_read_b128 v[160:163], v236 offset:53248
	ds_read_b128 v[164:167], v236 offset:54272
	ds_read_b128 v[168:171], v236 offset:55296
	ds_read_b128 v[172:175], v236 offset:56320
	global_load_lds_dwordx4 v[208:209], off
	v_lshl_add_u64 v[208:209], v[214:215], 0, s[18:19]
	s_mov_b32 m0, s37
	s_nop 0
	global_load_lds_dwordx4 v[208:209], off
	s_barrier
; #define PG8_STAGE(bufoff, gbase, voff) do { _Pragma("unroll") for (int _i = 0; _i < 2; ++_i) \
;         __builtin_amdgcn_global_load_lds((const unsigned*)((const char*)(gbase) + (voff)[_i]), (LAS unsigned*)(lds + (bufoff) + ldsw + _i * 8192), 16, 0, 0); } while (0)
; #define PG8_LDA(dst, b, h) do { _Pragma("unroll") for (int m = 0; m < 4; ++m) _Pragma("unroll") for (int k = 0; k < 2; ++k) dst[m][k] = *(const LAS bf16x8*)(lds + PG8_SA(b, h) + aoff + m * 2048 + k * 1024); } while (0)
; #define PG8_MMA(ai, bj, At, Bt) do { __builtin_amdgcn_s_setprio(1); _Pragma("unroll") for (int m = 0; m < 4; ++m) _Pragma("unroll") for (int n = 0; n < 2; ++n) _Pragma("unroll") for (int k = 0; k < 2; ++k) \
;         acc[ai][bj][m][n] = __builtin_amdgcn_mfma_f32_16x16x32_bf16(Bt[n][k], At[m][k], acc[ai][bj][m][n], 0, 0, 0); __builtin_amdgcn_s_setprio(0); } while (0)
; #define PG8_WAIT_V(n) asm volatile("s_waitcnt vmcnt(" #n ")" ::: "memory")
; #define PG8_WAIT_L(n) asm volatile("s_waitcnt lgkmcnt(" #n ")" ::: "memory")
; #define PG8_BAR __builtin_amdgcn_s_barrier()
; #define PG8_SCHED __builtin_amdgcn_sched_barrier(0)
; template <class Epi>
; __device__ __forceinline__ void gemm_phase(LAS unsigned char* lds, const GSched& S, const int K, const int lda, const int ldb, const Epi& E) {
;     ...
;             PG8_LDA(At, 1, 1); PG8_STAGE(PG8_SA(1, 0), a3, voffA);
;             PG8_BAR; PG8_WAIT_L(0); PG8_MMA(1, 0, At, B0); PG8_BAR; PG8_SCHED;
;             PG8_STAGE(PG8_SB(1, 1), b3 + hstepB, voffB);
;             PG8_WAIT_V(6); PG8_BAR; if constexpr (!Epi::NARROW) PG8_MMA(1, 1, At, B1); PG8_BAR;
	s_waitcnt lgkmcnt(0)
	s_setprio 1
	v_mfma_f32_16x16x32_bf16 v[60:63], v[104:107], v[144:147], v[60:63]
	v_mfma_f32_16x16x32_bf16 v[56:59], v[128:131], v[144:147], v[56:59]
	v_mfma_f32_16x16x32_bf16 v[44:47], v[104:107], v[152:155], v[44:47]
	v_mfma_f32_16x16x32_bf16 v[40:43], v[128:131], v[152:155], v[40:43]
	v_mfma_f32_16x16x32_bf16 v[28:31], v[104:107], v[160:163], v[28:31]
	v_mfma_f32_16x16x32_bf16 v[24:27], v[128:131], v[160:163], v[24:27]
	v_mfma_f32_16x16x32_bf16 v[12:15], v[104:107], v[168:171], v[12:15]
	v_mfma_f32_16x16x32_bf16 v[8:11], v[128:131], v[168:171], v[8:11]
	v_mfma_f32_16x16x32_bf16 v[60:63], v[116:119], v[148:151], v[60:63]
	v_mfma_f32_16x16x32_bf16 v[56:59], v[140:143], v[148:151], v[56:59]
	v_mfma_f32_16x16x32_bf16 v[44:47], v[116:119], v[156:159], v[44:47]
	v_mfma_f32_16x16x32_bf16 v[40:43], v[140:143], v[156:159], v[40:43]
	v_mfma_f32_16x16x32_bf16 v[28:31], v[116:119], v[164:167], v[28:31]
	v_mfma_f32_16x16x32_bf16 v[24:27], v[140:143], v[164:167], v[24:27]
	v_mfma_f32_16x16x32_bf16 v[12:15], v[116:119], v[172:175], v[12:15]
	v_mfma_f32_16x16x32_bf16 v[8:11], v[140:143], v[172:175], v[8:11]
	s_setprio 0
	s_barrier
	s_add_u32 s26, s26, 0x84080
	s_addc_u32 s27, s27, 0
	s_add_i32 s28, s28, s4
	v_lshl_add_u64 v[104:105], s[26:27], 0, v[186:187]
	s_mov_b32 m0, s28
	s_nop 0
	global_load_lds_dwordx4 v[104:105], off
	v_lshl_add_u64 v[104:105], s[26:27], 0, v[190:191]
	s_add_i32 m0, s28, 0x2000
	s_nop 0
	global_load_lds_dwordx4 v[104:105], off
	s_waitcnt vmcnt(6)
	s_barrier
	s_setprio 1
	v_mfma_f32_16x16x32_bf16 v[52:55], v[176:179], v[144:147], v[52:55]
	v_mfma_f32_16x16x32_bf16 v[48:51], v[200:203], v[144:147], v[48:51]
	v_mfma_f32_16x16x32_bf16 v[36:39], v[176:179], v[152:155], v[36:39]
	v_mfma_f32_16x16x32_bf16 v[32:35], v[200:203], v[152:155], v[32:35]
	v_mfma_f32_16x16x32_bf16 v[20:23], v[176:179], v[160:163], v[20:23]
	v_mfma_f32_16x16x32_bf16 v[16:19], v[200:203], v[160:163], v[16:19]
	v_mfma_f32_16x16x32_bf16 v[4:7], v[176:179], v[168:171], v[4:7]
	v_mfma_f32_16x16x32_bf16 v[0:3], v[200:203], v[168:171], v[0:3]
	v_mfma_f32_16x16x32_bf16 v[52:55], v[180:183], v[148:151], v[52:55]
	v_mfma_f32_16x16x32_bf16 v[48:51], v[204:207], v[148:151], v[48:51]
	v_mfma_f32_16x16x32_bf16 v[36:39], v[180:183], v[156:159], v[36:39]
	v_mfma_f32_16x16x32_bf16 v[32:35], v[204:207], v[156:159], v[32:35]
	v_mfma_f32_16x16x32_bf16 v[20:23], v[180:183], v[164:167], v[20:23]
	v_mfma_f32_16x16x32_bf16 v[16:19], v[204:207], v[164:167], v[16:19]
	v_mfma_f32_16x16x32_bf16 v[4:7], v[180:183], v[172:175], v[4:7]
	v_mfma_f32_16x16x32_bf16 v[0:3], v[204:207], v[172:175], v[0:3]
	s_setprio 0
	s_add_i32 s50, s50, 2
	s_add_u32 s48, s48, 0x100
	s_addc_u32 s49, s49, 0
	s_add_u32 s10, s10, 0x100
	s_addc_u32 s11, s11, 0
	s_cmp_gt_u32 s50, 29
	s_barrier
	s_cbranch_scc0 .LBB0_941
; __device__ __forceinline__ float sumsq4(const f32x4 v) { return (v[0] * v[0] + v[1] * v[1]) + (v[2] * v[2] + v[3] * v[3]); }
; __device__ __forceinline__ u32x4 pack8(const f32x4 a, const f32x4 b) { u32x4 w; w.x = cvt_pk_bf16(a[0], a[1]); w.y = cvt_pk_bf16(a[2], a[3]); w.z = cvt_pk_bf16(b[0], b[1]); w.w = cvt_pk_bf16(b[2], b[3]); return w; }
; __device__ __forceinline__ void unpack8(const u32x4 w, f32x4& a, f32x4& b) { a = (f32x4){bf_lo(w.x), bf_hi(w.x), bf_lo(w.y), bf_hi(w.y)}; b = (f32x4){bf_lo(w.z), bf_hi(w.z), bf_lo(w.w), bf_hi(w.w)}; }
;     __device__ __forceinline__ void operator()(Acc& acc, const Unit& u, int wr, int wc, int fr, int fq, const float (&rsv)[8]) const {
;     ...
;         } else {
;             u32x4 w[8][2];
; #pragma unroll
;             for (int g = 0; g < 8; ++g)
; #pragma unroll
;                 for (int bj = 0; bj < 2; ++bj) w[g][bj] = *(const u32x4*)(hb + (size_t)(row0 + (g >> 2) * HALF + (g & 3) * 16) * LDHB + 256 + col0 + bj * HALF);
; #pragma unroll
;             for (int g = 0; g < 8; ++g) {
;                 const int ai = g >> 2, m = g & 3;
;                 const int row = row0 + ai * HALF + m * 16;
;                 float ss = 0.f;
; #pragma unroll
;                 for (int bj = 0; bj < 2; ++bj) { f32x4 h0, h1; unpack8(w[g][bj], h0, h1);
;                     const f32x4 v0 = h0 + acc[ai][bj][m][0] * scale, v1 = h1 + acc[ai][bj][m][1] * scale;
;                     ss += sumsq4(v0) + sumsq4(v1);
;                     *(u32x4*)(hb + (size_t)row * LDHB + 256 + col0 + bj * HALF) = pack8(v0, v1); }
;                 ss += __shfl_xor(ss, 16); ss += __shfl_xor(ss, 32);
;                 if (fq == 0) part[(size_t)row * 32 + u.pn * 4 + wc] = ss;
;             }
	v_lshl_or_b32 v104, s46, 8, v234
	v_lshl_add_u32 v228, s12, 8, v230
	v_ashrrev_i32_e32 v105, 31, v104
	v_mov_b64_e32 v[106:107], s[14:15]
	v_mad_i64_i32 v[116:117], s[10:11], v228, s43, v[106:107]
	v_lshlrev_b64 v[104:105], 1, v[104:105]
	v_lshl_add_u64 v[248:249], v[116:117], 0, v[104:105]
	global_load_dwordx4 v[240:243], v[248:249], off offset:512
	global_load_dwordx4 v[244:247], v[248:249], off offset:768
	v_or_b32_e32 v224, 16, v228
	v_or_b32_e32 v220, 32, v228
	v_or_b32_e32 v216, 48, v228
	v_add_u32_e32 v212, 0x80, v228
	v_add_u32_e32 v208, 0x90, v228
	v_add_u32_e32 v204, 0xa0, v228
	v_add_u32_e32 v200, 0xb0, v228
	v_mad_i64_i32 v[116:117], s[10:11], v224, s43, v[106:107]
	v_mad_i64_i32 v[118:119], s[10:11], v220, s43, v[106:107]
	v_mad_i64_i32 v[128:129], s[10:11], v216, s43, v[106:107]
	v_mad_i64_i32 v[130:131], s[10:11], v212, s43, v[106:107]
	v_mad_i64_i32 v[140:141], s[10:11], v208, s43, v[106:107]
	v_mad_i64_i32 v[142:143], s[10:11], v204, s43, v[106:107]
	v_mad_i64_i32 v[106:107], s[10:11], v200, s43, v[106:107]
	v_lshl_add_u64 v[226:227], v[116:117], 0, v[104:105]
	v_lshl_add_u64 v[222:223], v[118:119], 0, v[104:105]
	v_lshl_add_u64 v[218:219], v[128:129], 0, v[104:105]
	v_lshl_add_u64 v[214:215], v[130:131], 0, v[104:105]
	v_lshl_add_u64 v[210:211], v[140:141], 0, v[104:105]
	v_lshl_add_u64 v[206:207], v[142:143], 0, v[104:105]
	v_lshl_add_u64 v[202:203], v[106:107], 0, v[104:105]
	global_load_dwordx4 v[180:183], v[226:227], off offset:512
	global_load_dwordx4 v[176:179], v[226:227], off offset:768
	global_load_dwordx4 v[172:175], v[222:223], off offset:512
	global_load_dwordx4 v[168:171], v[222:223], off offset:768
	global_load_dwordx4 v[164:167], v[218:219], off offset:512
	global_load_dwordx4 v[160:163], v[218:219], off offset:768
	global_load_dwordx4 v[156:159], v[214:215], off offset:512
	global_load_dwordx4 v[152:155], v[214:215], off offset:768
	global_load_dwordx4 v[148:151], v[210:211], off offset:512
	global_load_dwordx4 v[144:147], v[210:211], off offset:768
	global_load_dwordx4 v[140:143], v[206:207], off offset:512
	global_load_dwordx4 v[128:131], v[206:207], off offset:768
	global_load_dwordx4 v[116:119], v[202:203], off offset:512
	global_load_dwordx4 v[104:107], v[202:203], off offset:768
	v_and_b32_e32 v205, 64, v238
	v_xor_b32_e32 v201, 16, v238
	v_add_u32_e32 v205, 64, v205
	v_xor_b32_e32 v209, 32, v238
	v_cmp_lt_i32_e32 vcc, v201, v205
	s_lshl_b32 s10, s46, 2
	s_ashr_i32 s11, s10, 31
	v_cndmask_b32_e32 v201, v238, v201, vcc
	v_cmp_lt_i32_e32 vcc, v209, v205
	v_lshlrev_b32_e32 v239, 2, v201
	s_waitcnt vmcnt(0)
	v_lshlrev_b32_e32 v250, 16, v240
	v_and_b32_e32 v251, 0xffff0000, v240
	v_lshlrev_b32_e32 v240, 16, v241
	v_and_b32_e32 v241, 0xffff0000, v241
	v_lshlrev_b32_e32 v252, 16, v242
	v_and_b32_e32 v253, 0xffff0000, v242
	v_lshlrev_b32_e32 v242, 16, v243
	v_and_b32_e32 v243, 0xffff0000, v243
	v_cndmask_b32_e32 v205, v238, v209, vcc
	v_pk_add_f32 v[138:139], v[138:139], v[240:241]
	v_pk_add_f32 v[136:137], v[136:137], v[250:251]
	v_pk_add_f32 v[240:241], v[134:135], v[242:243]
	v_pk_add_f32 v[134:135], v[132:133], v[252:253]
	v_lshlrev_b32_e32 v201, 2, v205
	v_mul_f32_e32 v205, v137, v137
	v_mul_f32_e32 v209, v139, v139
	v_mul_f32_e32 v213, v135, v135
	v_mul_f32_e32 v217, v241, v241
	v_fmac_f32_e32 v205, v136, v136
	v_fmac_f32_e32 v209, v138, v138
	v_fmac_f32_e32 v213, v134, v134
	v_fmac_f32_e32 v217, v240, v240
	v_cvt_pk_bf16_f32 v132, v136, v137
	v_add_f32_e32 v136, v205, v209
	v_add_f32_e32 v137, v213, v217
	v_lshlrev_b32_e32 v232, 16, v244
	v_add_f32_e32 v205, v136, v137
	v_and_b32_e32 v233, 0xffff0000, v244
	v_lshlrev_b32_e32 v136, 16, v245
	v_and_b32_e32 v137, 0xffff0000, v245
	v_cvt_pk_bf16_f32 v133, v138, v139
	v_lshlrev_b32_e32 v138, 16, v246
	v_and_b32_e32 v139, 0xffff0000, v246
	v_pk_add_f32 v[126:127], v[126:127], v[136:137]
	v_pk_add_f32 v[124:125], v[124:125], v[232:233]
	v_lshlrev_b32_e32 v242, 16, v247
	v_and_b32_e32 v243, 0xffff0000, v247
	v_pk_add_f32 v[138:139], v[120:121], v[138:139]
	v_mul_f32_e32 v120, v125, v125
	v_mul_f32_e32 v121, v127, v127
	v_pk_add_f32 v[136:137], v[122:123], v[242:243]
	v_fmac_f32_e32 v120, v124, v124
	v_fmac_f32_e32 v121, v126, v126
	v_add_f32_e32 v120, v120, v121
	v_mul_f32_e32 v121, v139, v139
	v_mul_f32_e32 v122, v137, v137
	v_fmac_f32_e32 v121, v138, v138
	v_fmac_f32_e32 v122, v136, v136
	v_add_f32_e32 v121, v121, v122
	v_add_f32_e32 v120, v120, v121
	v_add_f32_e32 v120, v205, v120
	ds_bpermute_b32 v121, v239, v120
	v_cvt_pk_bf16_f32 v134, v134, v135
	v_cvt_pk_bf16_f32 v135, v240, v241
	v_cvt_pk_bf16_f32 v122, v124, v125
	v_cvt_pk_bf16_f32 v123, v126, v127
	s_waitcnt lgkmcnt(0)
	v_add_f32_e32 v120, v120, v121
	ds_bpermute_b32 v121, v201, v120
	v_cvt_pk_bf16_f32 v124, v138, v139
	v_cvt_pk_bf16_f32 v125, v136, v137
	global_store_dwordx4 v[248:249], v[132:135], off offset:512
	global_store_dwordx4 v[248:249], v[122:125], off offset:768
	s_and_saveexec_b64 s[26:27], s[6:7]
	s_cbranch_execz .LBB0_944
	v_ashrrev_i32_e32 v229, 31, v228
	v_lshlrev_b64 v[122:123], 7, v[228:229]
	v_lshl_add_u64 v[122:123], s[16:17], 0, v[122:123]
	v_lshl_add_u64 v[122:123], s[10:11], 2, v[122:123]
	s_lshl_b32 s12, s35, 2
	v_lshl_add_u64 v[122:123], v[122:123], 0, s[12:13]
	s_waitcnt lgkmcnt(0)
	v_add_f32_e32 v120, v120, v121
	global_store_dword v[122:123], v120, off

; #define PG8_STAGE(bufoff, gbase, voff) do { _Pragma("unroll") for (int _i = 0; _i < 2; ++_i) \
;         __builtin_amdgcn_global_load_lds((const unsigned*)((const char*)(gbase) + (voff)[_i]), (LAS unsigned*)(lds + (bufoff) + ldsw + _i * 8192), 16, 0, 0); } while (0)
; #define PG8_LDA(dst, b, h) do { _Pragma("unroll") for (int m = 0; m < 4; ++m) _Pragma("unroll") for (int k = 0; k < 2; ++k) dst[m][k] = *(const LAS bf16x8*)(lds + PG8_SA(b, h) + aoff + m * 2048 + k * 1024); } while (0)
; #define PG8_LDB(dst, b, h) do { _Pragma("unroll") for (int n = 0; n < 2; ++n) _Pragma("unroll") for (int k = 0; k < 2; ++k) dst[n][k] = *(const LAS bf16x8*)(lds + PG8_SB(b, h) + boff + n * 2048 + k * 1024); } while (0)
; #define PG8_MMA(ai, bj, At, Bt) do { __builtin_amdgcn_s_setprio(1); _Pragma("unroll") for (int m = 0; m < 4; ++m) _Pragma("unroll") for (int n = 0; n < 2; ++n) _Pragma("unroll") for (int k = 0; k < 2; ++k) \
;         acc[ai][bj][m][n] = __builtin_amdgcn_mfma_f32_16x16x32_bf16(Bt[n][k], At[m][k], acc[ai][bj][m][n], 0, 0, 0); __builtin_amdgcn_s_setprio(0); } while (0)
; #define PG8_WAIT_V(n) asm volatile("s_waitcnt vmcnt(" #n ")" ::: "memory")
; #define PG8_WAIT_L(n) asm volatile("s_waitcnt lgkmcnt(" #n ")" ::: "memory")
; #define PG8_BAR __builtin_amdgcn_s_barrier()
; template <class Epi>
; __device__ __forceinline__ void gemm_phase(LAS unsigned char* lds, const GSched& S, const int K, const int lda, const int ldb, const Epi& E) {
;     ...
;             PG8_LDB(B0, 0, 0); PG8_SCHED; PG8_LDA(At, 0, 0); PG8_STAGE(PG8_SA(1, 1), a1 + hstepA, voffA);
;             PG8_WAIT_L(8); PG8_BAR; PG8_WAIT_L(0); PG8_MMA(0, 0, At, B0); PG8_BAR; PG8_SCHED;
;             if constexpr (!Epi::NARROW) PG8_LDB(B1, 0, 1); PG8_STAGE(PG8_SB(0, 0), b2, voffB);
;             PG8_BAR; PG8_WAIT_L(0); if constexpr (!Epi::NARROW) PG8_MMA(0, 1, At, B1); PG8_BAR;
;             PG8_LDA(At, 0, 1); PG8_STAGE(PG8_SA(0, 0), a2, voffA);
;             PG8_BAR; PG8_WAIT_L(0); PG8_MMA(1, 0, At, B0); PG8_BAR; PG8_SCHED;
;             PG8_STAGE(PG8_SB(0, 1), b2 + hstepB, voffB);
;             PG8_WAIT_V(6); PG8_BAR; if constexpr (!Epi::NARROW) PG8_MMA(1, 1, At, B1); PG8_BAR;
;             PG8_LDB(B0, 1, 0); PG8_SCHED; PG8_LDA(At, 1, 0); PG8_STAGE(PG8_SA(0, 1), a2 + hstepA, voffA);
;             PG8_WAIT_L(8); PG8_BAR; PG8_WAIT_L(0); PG8_MMA(0, 0, At, B0); PG8_BAR; PG8_SCHED;
.LBB0_1026:
	ds_read_b128 v[164:167], v152
	ds_read_b128 v[168:171], v152 offset:1024
	ds_read_b128 v[172:175], v152 offset:2048
	ds_read_b128 v[176:179], v152 offset:3072
	s_add_u32 s30, s28, 0x100
	s_addc_u32 s31, s29, 0
	s_cmp_eq_u32 s59, 28
	s_cselect_b32 s37, s27, s31
	s_cselect_b32 s36, s26, s30
	s_cselect_b32 s35, s9, s58
	s_cselect_b32 s34, s8, s57
	v_lshl_add_u64 v[212:213], s[28:29], 0, v[140:141]
	s_add_i32 m0, s44, 0xc000
	ds_read_b128 v[180:183], v153
	ds_read_b128 v[184:187], v153 offset:1024
	ds_read_b128 v[188:191], v153 offset:2048
	ds_read_b128 v[192:195], v153 offset:3072
	ds_read_b128 v[196:199], v153 offset:4096
	ds_read_b128 v[200:203], v153 offset:5120
	ds_read_b128 v[204:207], v153 offset:6144
	ds_read_b128 v[208:211], v153 offset:7168
	global_load_lds_dwordx4 v[212:213], off
	v_lshl_add_u64 v[212:213], s[28:29], 0, v[138:139]
	s_add_i32 m0, s44, 0xe000
	s_nop 0
	global_load_lds_dwordx4 v[212:213], off
	s_waitcnt lgkmcnt(8)
	s_barrier
	s_waitcnt lgkmcnt(0)
	s_setprio 1
	v_mfma_f32_16x16x32_bf16 v[124:127], v[164:167], v[180:183], v[124:127]
	v_mfma_f32_16x16x32_bf16 v[116:119], v[172:175], v[180:183], v[116:119]
	v_mfma_f32_16x16x32_bf16 v[108:111], v[164:167], v[188:191], v[108:111]
	v_mfma_f32_16x16x32_bf16 v[100:103], v[172:175], v[188:191], v[100:103]
	v_mfma_f32_16x16x32_bf16 v[92:95], v[164:167], v[196:199], v[92:95]
	v_mfma_f32_16x16x32_bf16 v[84:87], v[172:175], v[196:199], v[84:87]
	v_mfma_f32_16x16x32_bf16 v[76:79], v[164:167], v[204:207], v[76:79]
	v_mfma_f32_16x16x32_bf16 v[68:71], v[172:175], v[204:207], v[68:71]
	v_mfma_f32_16x16x32_bf16 v[124:127], v[168:171], v[184:187], v[124:127]
	v_mfma_f32_16x16x32_bf16 v[116:119], v[176:179], v[184:187], v[116:119]
	v_mfma_f32_16x16x32_bf16 v[108:111], v[168:171], v[192:195], v[108:111]
	v_mfma_f32_16x16x32_bf16 v[100:103], v[176:179], v[192:195], v[100:103]
	v_mfma_f32_16x16x32_bf16 v[92:95], v[168:171], v[200:203], v[92:95]
	v_mfma_f32_16x16x32_bf16 v[84:87], v[176:179], v[200:203], v[84:87]
	v_mfma_f32_16x16x32_bf16 v[76:79], v[168:171], v[208:211], v[76:79]
	v_mfma_f32_16x16x32_bf16 v[68:71], v[176:179], v[208:211], v[68:71]
	s_setprio 0
	s_barrier
	s_add_i32 s28, s51, s41
	v_lshl_add_u64 v[228:229], s[34:35], 0, v[132:133]
	s_mov_b32 m0, s28
	ds_read_b128 v[212:215], v154
	ds_read_b128 v[216:219], v154 offset:1024
	ds_read_b128 v[220:223], v154 offset:2048
	ds_read_b128 v[224:227], v154 offset:3072
	global_load_lds_dwordx4 v[228:229], off
	v_lshl_add_u64 v[230:231], s[34:35], 0, v[128:129]
	s_add_i32 m0, s28, 0x2000
	s_nop 0
	global_load_lds_dwordx4 v[230:231], off
	s_barrier
	s_waitcnt lgkmcnt(0)
	s_setprio 1
	v_mfma_f32_16x16x32_bf16 v[120:123], v[212:215], v[180:183], v[120:123]
	v_mfma_f32_16x16x32_bf16 v[112:115], v[220:223], v[180:183], v[112:115]
	v_mfma_f32_16x16x32_bf16 v[104:107], v[212:215], v[188:191], v[104:107]
	v_mfma_f32_16x16x32_bf16 v[96:99], v[220:223], v[188:191], v[96:99]
	v_mfma_f32_16x16x32_bf16 v[88:91], v[212:215], v[196:199], v[88:91]
	v_mfma_f32_16x16x32_bf16 v[80:83], v[220:223], v[196:199], v[80:83]
	v_mfma_f32_16x16x32_bf16 v[72:75], v[212:215], v[204:207], v[72:75]
	v_mfma_f32_16x16x32_bf16 v[64:67], v[220:223], v[204:207], v[64:67]
	v_mfma_f32_16x16x32_bf16 v[120:123], v[216:219], v[184:187], v[120:123]
	v_mfma_f32_16x16x32_bf16 v[112:115], v[224:227], v[184:187], v[112:115]
	v_mfma_f32_16x16x32_bf16 v[104:107], v[216:219], v[192:195], v[104:107]
	v_mfma_f32_16x16x32_bf16 v[96:99], v[224:227], v[192:195], v[96:99]
	v_mfma_f32_16x16x32_bf16 v[88:91], v[216:219], v[200:203], v[88:91]
	v_mfma_f32_16x16x32_bf16 v[80:83], v[224:227], v[200:203], v[80:83]
	v_mfma_f32_16x16x32_bf16 v[72:75], v[216:219], v[208:211], v[72:75]
	v_mfma_f32_16x16x32_bf16 v[64:67], v[224:227], v[208:211], v[64:67]
	s_setprio 0
	s_mov_b32 m0, s44
	v_lshl_add_u64 v[232:233], s[36:37], 0, v[134:135]
	s_barrier
	ds_read_b128 v[180:183], v153 offset:16384
	ds_read_b128 v[184:187], v153 offset:17408
	ds_read_b128 v[188:191], v153 offset:18432
	ds_read_b128 v[192:195], v153 offset:19456
	ds_read_b128 v[196:199], v153 offset:20480
	ds_read_b128 v[200:203], v153 offset:21504
	ds_read_b128 v[204:207], v153 offset:22528
	ds_read_b128 v[208:211], v153 offset:23552
	global_load_lds_dwordx4 v[232:233], off
	v_lshl_add_u64 v[234:235], s[36:37], 0, v[130:131]
	s_mov_b32 m0, s45
	s_nop 0
	global_load_lds_dwordx4 v[234:235], off
	s_barrier
	s_waitcnt lgkmcnt(0)
	s_setprio 1
	v_mfma_f32_16x16x32_bf16 v[60:63], v[164:167], v[180:183], v[60:63]
	v_mfma_f32_16x16x32_bf16 v[52:55], v[172:175], v[180:183], v[52:55]
	v_mfma_f32_16x16x32_bf16 v[44:47], v[164:167], v[188:191], v[44:47]
	v_mfma_f32_16x16x32_bf16 v[36:39], v[172:175], v[188:191], v[36:39]
	v_mfma_f32_16x16x32_bf16 v[28:31], v[164:167], v[196:199], v[28:31]
	v_mfma_f32_16x16x32_bf16 v[20:23], v[172:175], v[196:199], v[20:23]
	v_mfma_f32_16x16x32_bf16 v[12:15], v[164:167], v[204:207], v[12:15]
	v_mfma_f32_16x16x32_bf16 v[4:7], v[172:175], v[204:207], v[4:7]
	v_mfma_f32_16x16x32_bf16 v[60:63], v[168:171], v[184:187], v[60:63]
	v_mfma_f32_16x16x32_bf16 v[52:55], v[176:179], v[184:187], v[52:55]
	v_mfma_f32_16x16x32_bf16 v[44:47], v[168:171], v[192:195], v[44:47]
	v_mfma_f32_16x16x32_bf16 v[36:39], v[176:179], v[192:195], v[36:39]
	v_mfma_f32_16x16x32_bf16 v[28:31], v[168:171], v[200:203], v[28:31]
	v_mfma_f32_16x16x32_bf16 v[20:23], v[176:179], v[200:203], v[20:23]
	v_mfma_f32_16x16x32_bf16 v[12:15], v[168:171], v[208:211], v[12:15]
	v_mfma_f32_16x16x32_bf16 v[4:7], v[176:179], v[208:211], v[4:7]
	s_setprio 0
	s_barrier
; #define PG8_STAGE(bufoff, gbase, voff) do { _Pragma("unroll") for (int _i = 0; _i < 2; ++_i) \
;         __builtin_amdgcn_global_load_lds((const unsigned*)((const char*)(gbase) + (voff)[_i]), (LAS unsigned*)(lds + (bufoff) + ldsw + _i * 8192), 16, 0, 0); } while (0)
; #define PG8_LDA(dst, b, h) do { _Pragma("unroll") for (int m = 0; m < 4; ++m) _Pragma("unroll") for (int k = 0; k < 2; ++k) dst[m][k] = *(const LAS bf16x8*)(lds + PG8_SA(b, h) + aoff + m * 2048 + k * 1024); } while (0)
; #define PG8_LDB(dst, b, h) do { _Pragma("unroll") for (int n = 0; n < 2; ++n) _Pragma("unroll") for (int k = 0; k < 2; ++k) dst[n][k] = *(const LAS bf16x8*)(lds + PG8_SB(b, h) + boff + n * 2048 + k * 1024); } while (0)
; #define PG8_MMA(ai, bj, At, Bt) do { __builtin_amdgcn_s_setprio(1); _Pragma("unroll") for (int m = 0; m < 4; ++m) _Pragma("unroll") for (int n = 0; n < 2; ++n) _Pragma("unroll") for (int k = 0; k < 2; ++k) \
;         acc[ai][bj][m][n] = __builtin_amdgcn_mfma_f32_16x16x32_bf16(Bt[n][k], At[m][k], acc[ai][bj][m][n], 0, 0, 0); __builtin_amdgcn_s_setprio(0); } while (0)
; #define PG8_WAIT_V(n) asm volatile("s_waitcnt vmcnt(" #n ")" ::: "memory")
; #define PG8_WAIT_L(n) asm volatile("s_waitcnt lgkmcnt(" #n ")" ::: "memory")
; #define PG8_BAR __builtin_amdgcn_s_barrier()
; #define PG8_SCHED __builtin_amdgcn_sched_barrier(0)
; template <class Epi>
; __device__ __forceinline__ void gemm_phase(LAS unsigned char* lds, const GSched& S, const int K, const int lda, const int ldb, const Epi& E) {
;     ...
;             PG8_STAGE(PG8_SB(0, 1), b2 + hstepB, voffB);
;             PG8_WAIT_V(6); PG8_BAR; if constexpr (!Epi::NARROW) PG8_MMA(1, 1, At, B1); PG8_BAR;
;             PG8_LDB(B0, 1, 0); PG8_SCHED; PG8_LDA(At, 1, 0); PG8_STAGE(PG8_SA(0, 1), a2 + hstepA, voffA);
;             PG8_WAIT_L(8); PG8_BAR; PG8_WAIT_L(0); PG8_MMA(0, 0, At, B0); PG8_BAR; PG8_SCHED;
;             if constexpr (!Epi::NARROW) PG8_LDB(B1, 1, 1); PG8_STAGE(PG8_SB(1, 0), b3, voffB);
;             PG8_BAR; PG8_WAIT_L(0); if constexpr (!Epi::NARROW) PG8_MMA(0, 1, At, B1); PG8_BAR;
;             PG8_LDA(At, 1, 1); PG8_STAGE(PG8_SA(1, 0), a3, voffA);
;             PG8_BAR; PG8_WAIT_L(0); PG8_MMA(1, 0, At, B0); PG8_BAR; PG8_SCHED;
	s_add_u32 s28, s34, 0x84000
	s_addc_u32 s29, s35, 0
	s_add_i32 s60, s52, s41
	v_lshl_add_u64 v[164:165], s[28:29], 0, v[132:133]
	s_mov_b32 m0, s60
	s_nop 0
	global_load_lds_dwordx4 v[164:165], off
	v_lshl_add_u64 v[164:165], s[28:29], 0, v[128:129]
	s_add_i32 m0, s60, 0x2000
	s_nop 0
	global_load_lds_dwordx4 v[164:165], off
	s_waitcnt vmcnt(6)
	s_barrier
	s_setprio 1
	v_mfma_f32_16x16x32_bf16 v[56:59], v[212:215], v[180:183], v[56:59]
	v_mfma_f32_16x16x32_bf16 v[48:51], v[220:223], v[180:183], v[48:51]
	v_mfma_f32_16x16x32_bf16 v[40:43], v[212:215], v[188:191], v[40:43]
	v_mfma_f32_16x16x32_bf16 v[32:35], v[220:223], v[188:191], v[32:35]
	v_mfma_f32_16x16x32_bf16 v[24:27], v[212:215], v[196:199], v[24:27]
	v_mfma_f32_16x16x32_bf16 v[16:19], v[220:223], v[196:199], v[16:19]
	v_mfma_f32_16x16x32_bf16 v[8:11], v[212:215], v[204:207], v[8:11]
	v_mfma_f32_16x16x32_bf16 v[0:3], v[220:223], v[204:207], v[0:3]
	v_mfma_f32_16x16x32_bf16 v[56:59], v[216:219], v[184:187], v[56:59]
	v_mfma_f32_16x16x32_bf16 v[48:51], v[224:227], v[184:187], v[48:51]
	v_mfma_f32_16x16x32_bf16 v[40:43], v[216:219], v[192:195], v[40:43]
	v_mfma_f32_16x16x32_bf16 v[32:35], v[224:227], v[192:195], v[32:35]
	v_mfma_f32_16x16x32_bf16 v[24:27], v[216:219], v[200:203], v[24:27]
	v_mfma_f32_16x16x32_bf16 v[16:19], v[224:227], v[200:203], v[16:19]
	v_mfma_f32_16x16x32_bf16 v[8:11], v[216:219], v[208:211], v[8:11]
	v_mfma_f32_16x16x32_bf16 v[0:3], v[224:227], v[208:211], v[0:3]
	s_setprio 0
	s_add_i32 s60, 0, 0x18000
	v_add_u32_e32 v163, s60, v150
	s_barrier
	ds_read_b128 v[164:167], v163
	ds_read_b128 v[168:171], v163 offset:1024
	ds_read_b128 v[172:175], v163 offset:2048
	ds_read_b128 v[176:179], v163 offset:3072
	s_add_u32 s28, s36, 0x94000
	s_addc_u32 s29, s37, 0
	s_mov_b32 m0, s46
	v_lshl_add_u64 v[212:213], s[28:29], 0, v[134:135]
	ds_read_b128 v[180:183], v153 offset:32768
	ds_read_b128 v[184:187], v153 offset:33792
	ds_read_b128 v[188:191], v153 offset:34816
	ds_read_b128 v[192:195], v153 offset:35840
	ds_read_b128 v[196:199], v153 offset:36864
	ds_read_b128 v[200:203], v153 offset:37888
	ds_read_b128 v[204:207], v153 offset:38912
	ds_read_b128 v[208:211], v153 offset:39936
	global_load_lds_dwordx4 v[212:213], off
	v_lshl_add_u64 v[212:213], s[28:29], 0, v[130:131]
	s_mov_b32 m0, s47
	s_nop 0
	global_load_lds_dwordx4 v[212:213], off
	s_waitcnt lgkmcnt(8)
	s_barrier
	s_waitcnt lgkmcnt(0)
	s_setprio 1
	s_waitcnt lgkmcnt(0)
	v_mfma_f32_16x16x32_bf16 v[124:127], v[164:167], v[180:183], v[124:127]
	v_mfma_f32_16x16x32_bf16 v[116:119], v[172:175], v[180:183], v[116:119]
	v_mfma_f32_16x16x32_bf16 v[108:111], v[164:167], v[188:191], v[108:111]
	v_mfma_f32_16x16x32_bf16 v[100:103], v[172:175], v[188:191], v[100:103]
	v_mfma_f32_16x16x32_bf16 v[92:95], v[164:167], v[196:199], v[92:95]
	v_mfma_f32_16x16x32_bf16 v[84:87], v[172:175], v[196:199], v[84:87]
	v_mfma_f32_16x16x32_bf16 v[76:79], v[164:167], v[204:207], v[76:79]
	v_mfma_f32_16x16x32_bf16 v[68:71], v[172:175], v[204:207], v[68:71]
	v_mfma_f32_16x16x32_bf16 v[124:127], v[168:171], v[184:187], v[124:127]
	v_mfma_f32_16x16x32_bf16 v[116:119], v[176:179], v[184:187], v[116:119]
	v_mfma_f32_16x16x32_bf16 v[108:111], v[168:171], v[192:195], v[108:111]
	v_mfma_f32_16x16x32_bf16 v[100:103], v[176:179], v[192:195], v[100:103]
	v_mfma_f32_16x16x32_bf16 v[92:95], v[168:171], v[200:203], v[92:95]
	v_mfma_f32_16x16x32_bf16 v[84:87], v[176:179], v[200:203], v[84:87]
	v_mfma_f32_16x16x32_bf16 v[76:79], v[168:171], v[208:211], v[76:79]
	v_mfma_f32_16x16x32_bf16 v[68:71], v[176:179], v[208:211], v[68:71]
	s_setprio 0
	s_barrier
	s_add_i32 s36, 0, 0x1c000
	s_add_i32 s28, s60, s41
	v_add_u32_e32 v163, s36, v150
	v_lshl_add_u64 v[228:229], v[228:229], 0, s[24:25]
	s_mov_b32 m0, s28
	ds_read_b128 v[212:215], v163
	ds_read_b128 v[216:219], v163 offset:1024
	ds_read_b128 v[220:223], v163 offset:2048
	ds_read_b128 v[224:227], v163 offset:3072
	global_load_lds_dwordx4 v[228:229], off
	v_lshl_add_u64 v[228:229], v[230:231], 0, s[24:25]
	s_add_i32 m0, s28, 0x2000
	s_nop 0
	global_load_lds_dwordx4 v[228:229], off
	s_barrier
	s_waitcnt lgkmcnt(0)
	s_setprio 1
	s_waitcnt lgkmcnt(0)
	v_mfma_f32_16x16x32_bf16 v[120:123], v[212:215], v[180:183], v[120:123]
	v_mfma_f32_16x16x32_bf16 v[112:115], v[220:223], v[180:183], v[112:115]
	v_mfma_f32_16x16x32_bf16 v[104:107], v[212:215], v[188:191], v[104:107]
	v_mfma_f32_16x16x32_bf16 v[96:99], v[220:223], v[188:191], v[96:99]
	v_mfma_f32_16x16x32_bf16 v[88:91], v[212:215], v[196:199], v[88:91]
	v_mfma_f32_16x16x32_bf16 v[80:83], v[220:223], v[196:199], v[80:83]
	v_mfma_f32_16x16x32_bf16 v[72:75], v[212:215], v[204:207], v[72:75]
	v_mfma_f32_16x16x32_bf16 v[64:67], v[220:223], v[204:207], v[64:67]
	v_mfma_f32_16x16x32_bf16 v[120:123], v[216:219], v[184:187], v[120:123]
	v_mfma_f32_16x16x32_bf16 v[112:115], v[224:227], v[184:187], v[112:115]
	v_mfma_f32_16x16x32_bf16 v[104:107], v[216:219], v[192:195], v[104:107]
	v_mfma_f32_16x16x32_bf16 v[96:99], v[224:227], v[192:195], v[96:99]
	v_mfma_f32_16x16x32_bf16 v[88:91], v[216:219], v[200:203], v[88:91]
	v_mfma_f32_16x16x32_bf16 v[80:83], v[224:227], v[200:203], v[80:83]
	v_mfma_f32_16x16x32_bf16 v[72:75], v[216:219], v[208:211], v[72:75]
	v_mfma_f32_16x16x32_bf16 v[64:67], v[224:227], v[208:211], v[64:67]
	s_setprio 0
	s_mov_b32 m0, s0
	v_lshl_add_u64 v[228:229], v[232:233], 0, s[24:25]
	s_barrier
	ds_read_b128 v[180:183], v153 offset:49152
	ds_read_b128 v[184:187], v153 offset:50176
	ds_read_b128 v[188:191], v153 offset:51200
	ds_read_b128 v[192:195], v153 offset:52224
	ds_read_b128 v[196:199], v153 offset:53248
	ds_read_b128 v[200:203], v153 offset:54272
	ds_read_b128 v[204:207], v153 offset:55296
	ds_read_b128 v[208:211], v153 offset:56320
	global_load_lds_dwordx4 v[228:229], off
	v_lshl_add_u64 v[228:229], v[234:235], 0, s[24:25]
	s_mov_b32 m0, s1
	s_nop 0
	global_load_lds_dwordx4 v[228:229], off
	s_barrier
; __device__ __forceinline__ void st_nt(float* p, f32x4 v) { __builtin_nontemporal_store(v, (f32x4*)p); }
; __device__ __forceinline__ void st_nt(bf16_t* p, u32x4 v) { __builtin_nontemporal_store(v, (u32x4*)p); }
; __device__ __forceinline__ u32x4 pack8(const f32x4 a, const f32x4 b) { u32x4 w; w.x = cvt_pk_bf16(a[0], a[1]); w.y = cvt_pk_bf16(a[2], a[3]); w.z = cvt_pk_bf16(b[0], b[1]); w.w = cvt_pk_bf16(b[2], b[3]); return w; }
; #define PG8_STAGE(bufoff, gbase, voff) do { _Pragma("unroll") for (int _i = 0; _i < 2; ++_i) \
;         __builtin_amdgcn_global_load_lds((const unsigned*)((const char*)(gbase) + (voff)[_i]), (LAS unsigned*)(lds + (bufoff) + ldsw + _i * 8192), 16, 0, 0); } while (0)
; #define PG8_LDA(dst, b, h) do { _Pragma("unroll") for (int m = 0; m < 4; ++m) _Pragma("unroll") for (int k = 0; k < 2; ++k) dst[m][k] = *(const LAS bf16x8*)(lds + PG8_SA(b, h) + aoff + m * 2048 + k * 1024); } while (0)
; #define PG8_BAR __builtin_amdgcn_s_barrier()
;     __device__ __forceinline__ void operator()(Acc& acc, const Unit& u, int wr, int wc, int fr, int fq, const float (&rsv)[8]) const {
;         const int row0 = u.pm * BM + wr * 64 + fr, col = u.pn * 128 + wc * 32 + 8 * fq;
; #pragma unroll
;         for (int ai = 0; ai < 2; ++ai)
; #pragma unroll
;             for (int m = 0; m < 4; ++m) {
;                 const int row = row0 + ai * HALF + m * 16; const float rs = rsv[ai * 4 + m];
;                 f32x4 o[2];
;                 const float rsn = rs * -1.4426950408889634f, rs2 = rs * rs;
; #pragma unroll
;                 for (int n = 0; n < 2; ++n) { const f32x4 g = acc[ai][0][m][n], uu = acc[ai][1][m][n]; const f32x4 t = g * rsn, w = (g * uu) * rs2;
; #pragma unroll
;                     for (int j = 0; j < 4; ++j) o[n][j] = w[j] * __builtin_amdgcn_rcpf(1.0f + __builtin_amdgcn_exp2f(t[j])); }
;                 st_nt(act + (size_t)row * LDACT + col, pack8(o[0], o[1]));
;             }
; template <class Epi>
; __device__ __forceinline__ void gemm_phase(LAS unsigned char* lds, const GSched& S, const int K, const int lda, const int ldb, const Epi& E) {
;     ...
;             PG8_LDA(At, 1, 1); PG8_STAGE(PG8_SA(1, 0), a3, voffA);
;             PG8_BAR; PG8_WAIT_L(0); PG8_MMA(1, 0, At, B0); PG8_BAR; PG8_SCHED;
;             PG8_STAGE(PG8_SB(1, 1), b3 + hstepB, voffB);
;             PG8_WAIT_V(6); PG8_BAR; if constexpr (!Epi::NARROW) PG8_MMA(1, 1, At, B1); PG8_BAR;
	s_waitcnt lgkmcnt(0)
	s_setprio 1
	v_mfma_f32_16x16x32_bf16 v[60:63], v[164:167], v[180:183], v[60:63]
	v_mfma_f32_16x16x32_bf16 v[52:55], v[172:175], v[180:183], v[52:55]
	v_mfma_f32_16x16x32_bf16 v[44:47], v[164:167], v[188:191], v[44:47]
	v_mfma_f32_16x16x32_bf16 v[36:39], v[172:175], v[188:191], v[36:39]
	v_mfma_f32_16x16x32_bf16 v[28:31], v[164:167], v[196:199], v[28:31]
	v_mfma_f32_16x16x32_bf16 v[20:23], v[172:175], v[196:199], v[20:23]
	v_mfma_f32_16x16x32_bf16 v[12:15], v[164:167], v[204:207], v[12:15]
	v_mfma_f32_16x16x32_bf16 v[4:7], v[172:175], v[204:207], v[4:7]
	v_mfma_f32_16x16x32_bf16 v[60:63], v[168:171], v[184:187], v[60:63]
	v_mfma_f32_16x16x32_bf16 v[52:55], v[176:179], v[184:187], v[52:55]
	v_mfma_f32_16x16x32_bf16 v[44:47], v[168:171], v[192:195], v[44:47]
	v_mfma_f32_16x16x32_bf16 v[36:39], v[176:179], v[192:195], v[36:39]
	v_mfma_f32_16x16x32_bf16 v[28:31], v[168:171], v[200:203], v[28:31]
	v_mfma_f32_16x16x32_bf16 v[20:23], v[176:179], v[200:203], v[20:23]
	v_mfma_f32_16x16x32_bf16 v[12:15], v[168:171], v[208:211], v[12:15]
	v_mfma_f32_16x16x32_bf16 v[4:7], v[176:179], v[208:211], v[4:7]
	s_setprio 0
	s_barrier
	s_add_u32 s28, s34, 0x84080
	s_addc_u32 s29, s35, 0
	s_add_i32 s34, s36, s41
	v_lshl_add_u64 v[164:165], s[28:29], 0, v[132:133]
	s_mov_b32 m0, s34
	s_nop 0
	global_load_lds_dwordx4 v[164:165], off
	v_lshl_add_u64 v[164:165], s[28:29], 0, v[128:129]
	s_add_i32 m0, s34, 0x2000
	s_nop 0
	global_load_lds_dwordx4 v[164:165], off
	s_waitcnt vmcnt(6)
	s_barrier
	s_setprio 1
	v_mfma_f32_16x16x32_bf16 v[56:59], v[212:215], v[180:183], v[56:59]
	v_mfma_f32_16x16x32_bf16 v[48:51], v[220:223], v[180:183], v[48:51]
	v_mfma_f32_16x16x32_bf16 v[40:43], v[212:215], v[188:191], v[40:43]
	v_mfma_f32_16x16x32_bf16 v[32:35], v[220:223], v[188:191], v[32:35]
	v_mfma_f32_16x16x32_bf16 v[24:27], v[212:215], v[196:199], v[24:27]
	v_mfma_f32_16x16x32_bf16 v[16:19], v[220:223], v[196:199], v[16:19]
	v_mfma_f32_16x16x32_bf16 v[8:11], v[212:215], v[204:207], v[8:11]
	v_mfma_f32_16x16x32_bf16 v[0:3], v[220:223], v[204:207], v[0:3]
	v_mfma_f32_16x16x32_bf16 v[56:59], v[216:219], v[184:187], v[56:59]
	v_mfma_f32_16x16x32_bf16 v[48:51], v[224:227], v[184:187], v[48:51]
	v_mfma_f32_16x16x32_bf16 v[40:43], v[216:219], v[192:195], v[40:43]
	v_mfma_f32_16x16x32_bf16 v[32:35], v[224:227], v[192:195], v[32:35]
	v_mfma_f32_16x16x32_bf16 v[24:27], v[216:219], v[200:203], v[24:27]
	v_mfma_f32_16x16x32_bf16 v[16:19], v[224:227], v[200:203], v[16:19]
	v_mfma_f32_16x16x32_bf16 v[8:11], v[216:219], v[208:211], v[8:11]
	v_mfma_f32_16x16x32_bf16 v[0:3], v[224:227], v[208:211], v[0:3]
	s_setprio 0
	s_add_i32 s59, s59, 2
	s_add_u32 s57, s57, 0x100
	s_addc_u32 s58, s58, 0
	s_cmp_gt_u32 s59, 29
	s_mov_b64 s[28:29], s[30:31]
	s_barrier
	s_cbranch_scc0 .LBB0_1026
	v_mul_f32_e32 v166, 0xbfb8aa3b, v155
	v_pk_mul_f32 v[168:169], v[166:167], v[124:125] op_sel_hi:[0,1]
	v_exp_f32_e32 v167, v168
	v_pk_mul_f32 v[120:121], v[124:125], v[120:121]
	v_exp_f32_e32 v169, v169
	v_mul_f32_e32 v168, v155, v155
	v_pk_mul_f32 v[170:171], v[166:167], v[126:127] op_sel_hi:[0,1]
	v_exp_f32_e32 v124, v170
	v_exp_f32_e32 v125, v171
	v_add_f32_e32 v167, 1.0, v167
	v_rcp_f32_e32 v172, v167
	v_add_f32_e32 v124, 1.0, v124
	v_add_f32_e32 v125, 1.0, v125
	v_rcp_f32_e32 v124, v124
	v_rcp_f32_e32 v125, v125
	v_add_f32_e32 v167, 1.0, v169
	v_pk_mul_f32 v[122:123], v[126:127], v[122:123]
	v_pk_mul_f32 v[126:127], v[166:167], v[116:117] op_sel_hi:[0,1]
	v_pk_mul_f32 v[122:123], v[168:169], v[122:123] op_sel_hi:[0,1]
	v_exp_f32_e32 v126, v126
	v_pk_mul_f32 v[122:123], v[124:125], v[122:123]
	v_exp_f32_e32 v127, v127
	v_pk_mul_f32 v[124:125], v[166:167], v[118:119] op_sel_hi:[0,1]
	v_exp_f32_e32 v124, v124
	v_pk_mul_f32 v[114:115], v[118:119], v[114:115]
	v_exp_f32_e32 v118, v125
	v_add_f32_e32 v126, 1.0, v126
	v_add_f32_e32 v127, 1.0, v127
	v_rcp_f32_e32 v126, v126
	v_rcp_f32_e32 v127, v127
	v_pk_mul_f32 v[112:113], v[116:117], v[112:113]
	v_add_f32_e32 v116, 1.0, v124
	v_add_f32_e32 v117, 1.0, v118
	v_rcp_f32_e32 v116, v116
	v_rcp_f32_e32 v117, v117
	v_rcp_f32_e32 v173, v167
	v_pk_mul_f32 v[112:113], v[168:169], v[112:113] op_sel_hi:[0,1]
	v_lshl_or_b32 v164, s56, 7, v151
	v_pk_mul_f32 v[118:119], v[126:127], v[112:113]
	v_pk_mul_f32 v[112:113], v[168:169], v[114:115] op_sel_hi:[0,1]
	v_lshl_add_u32 v163, s2, 8, v149
	v_ashrrev_i32_e32 v165, 31, v164
	v_pk_mul_f32 v[120:121], v[168:169], v[120:121] op_sel_hi:[0,1]
	v_pk_mul_f32 v[124:125], v[116:117], v[112:113]
	v_mov_b64_e32 v[112:113], s[22:23]
	v_pk_mul_f32 v[120:121], v[172:173], v[120:121]
	v_mad_i64_i32 v[116:117], s[28:29], v163, s53, v[112:113]
	v_lshlrev_b64 v[114:115], 1, v[164:165]
	v_lshl_add_u64 v[126:127], v[116:117], 0, v[114:115]
	v_cvt_pk_bf16_f32 v116, v120, v121
	v_cvt_pk_bf16_f32 v117, v122, v123
	v_cvt_pk_bf16_f32 v118, v118, v119
	v_cvt_pk_bf16_f32 v119, v124, v125
	global_store_dwordx4 v[126:127], v[116:119], off
	v_pk_mul_f32 v[104:105], v[108:109], v[104:105]
	v_pk_mul_f32 v[106:107], v[110:111], v[106:107]
	v_mul_f32_e32 v116, 0xbfb8aa3b, v156
	v_pk_mul_f32 v[118:119], v[116:117], v[108:109] op_sel_hi:[0,1]
	v_exp_f32_e32 v117, v118
	v_exp_f32_e32 v119, v119
	v_mul_f32_e32 v118, v156, v156
	v_pk_mul_f32 v[98:99], v[102:103], v[98:99]
	v_pk_mul_f32 v[120:121], v[116:117], v[110:111] op_sel_hi:[0,1]
	v_exp_f32_e32 v108, v120
	v_exp_f32_e32 v109, v121
	v_add_f32_e32 v117, 1.0, v117
	v_rcp_f32_e32 v122, v117
	v_add_f32_e32 v108, 1.0, v108
	v_add_f32_e32 v109, 1.0, v109
	v_rcp_f32_e32 v108, v108
	v_rcp_f32_e32 v109, v109
	v_add_f32_e32 v117, 1.0, v119
	v_pk_mul_f32 v[106:107], v[118:119], v[106:107] op_sel_hi:[0,1]
; __device__ __forceinline__ void st_nt(float* p, f32x4 v) { __builtin_nontemporal_store(v, (f32x4*)p); }
; __device__ __forceinline__ void st_nt(bf16_t* p, u32x4 v) { __builtin_nontemporal_store(v, (u32x4*)p); }
; __device__ __forceinline__ u32x4 pack8(const f32x4 a, const f32x4 b) { u32x4 w; w.x = cvt_pk_bf16(a[0], a[1]); w.y = cvt_pk_bf16(a[2], a[3]); w.z = cvt_pk_bf16(b[0], b[1]); w.w = cvt_pk_bf16(b[2], b[3]); return w; }
;     __device__ __forceinline__ void operator()(Acc& acc, const Unit& u, int wr, int wc, int fr, int fq, const float (&rsv)[8]) const {
;         const int row0 = u.pm * BM + wr * 64 + fr, col = u.pn * 128 + wc * 32 + 8 * fq;
; #pragma unroll
;         for (int ai = 0; ai < 2; ++ai)
; #pragma unroll
;             for (int m = 0; m < 4; ++m) {
;                 const int row = row0 + ai * HALF + m * 16; const float rs = rsv[ai * 4 + m];
;                 f32x4 o[2];
;                 const float rsn = rs * -1.4426950408889634f, rs2 = rs * rs;
; #pragma unroll
;                 for (int n = 0; n < 2; ++n) { const f32x4 g = acc[ai][0][m][n], uu = acc[ai][1][m][n]; const f32x4 t = g * rsn, w = (g * uu) * rs2;
; #pragma unroll
;                     for (int j = 0; j < 4; ++j) o[n][j] = w[j] * __builtin_amdgcn_rcpf(1.0f + __builtin_amdgcn_exp2f(t[j])); }
;                 st_nt(act + (size_t)row * LDACT + col, pack8(o[0], o[1]));
;             }
	v_pk_mul_f32 v[110:111], v[116:117], v[100:101] op_sel_hi:[0,1]
	v_exp_f32_e32 v110, v110
	v_pk_mul_f32 v[106:107], v[108:109], v[106:107]
	v_exp_f32_e32 v111, v111
	v_pk_mul_f32 v[108:109], v[116:117], v[102:103] op_sel_hi:[0,1]
	v_exp_f32_e32 v108, v108
	v_exp_f32_e32 v102, v109
	v_add_f32_e32 v110, 1.0, v110
	v_add_f32_e32 v111, 1.0, v111
	v_rcp_f32_e32 v110, v110
	v_rcp_f32_e32 v111, v111
	v_pk_mul_f32 v[96:97], v[100:101], v[96:97]
	v_add_f32_e32 v100, 1.0, v108
	v_add_f32_e32 v101, 1.0, v102
	v_rcp_f32_e32 v100, v100
	v_rcp_f32_e32 v101, v101
	v_rcp_f32_e32 v123, v117
	v_pk_mul_f32 v[96:97], v[118:119], v[96:97] op_sel_hi:[0,1]
	v_pk_mul_f32 v[102:103], v[110:111], v[96:97]
	v_pk_mul_f32 v[96:97], v[118:119], v[98:99] op_sel_hi:[0,1]
	v_pk_mul_f32 v[104:105], v[118:119], v[104:105] op_sel_hi:[0,1]
	v_pk_mul_f32 v[100:101], v[100:101], v[96:97]
	v_or_b32_e32 v96, 16, v163
	v_pk_mul_f32 v[104:105], v[122:123], v[104:105]
	v_mad_i64_i32 v[96:97], s[28:29], v96, s53, v[112:113]
	v_lshl_add_u64 v[108:109], v[96:97], 0, v[114:115]
	v_cvt_pk_bf16_f32 v96, v104, v105
	v_cvt_pk_bf16_f32 v97, v106, v107
	v_cvt_pk_bf16_f32 v98, v102, v103
	v_cvt_pk_bf16_f32 v99, v100, v101
	global_store_dwordx4 v[108:109], v[96:99], off
	v_pk_mul_f32 v[88:89], v[92:93], v[88:89]
	v_pk_mul_f32 v[90:91], v[94:95], v[90:91]
	v_mul_f32_e32 v96, 0xbfb8aa3b, v157
	v_pk_mul_f32 v[98:99], v[96:97], v[92:93] op_sel_hi:[0,1]
	v_exp_f32_e32 v97, v98
	v_exp_f32_e32 v99, v99
	v_mul_f32_e32 v98, v157, v157
	v_pk_mul_f32 v[82:83], v[86:87], v[82:83]
	v_pk_mul_f32 v[100:101], v[96:97], v[94:95] op_sel_hi:[0,1]
	v_exp_f32_e32 v92, v100
	v_exp_f32_e32 v93, v101
	v_add_f32_e32 v97, 1.0, v97
	v_rcp_f32_e32 v102, v97
	v_add_f32_e32 v92, 1.0, v92
	v_add_f32_e32 v93, 1.0, v93
	v_rcp_f32_e32 v92, v92
	v_rcp_f32_e32 v93, v93
	v_add_f32_e32 v97, 1.0, v99
	v_pk_mul_f32 v[90:91], v[98:99], v[90:91] op_sel_hi:[0,1]
	v_pk_mul_f32 v[94:95], v[96:97], v[84:85] op_sel_hi:[0,1]
	v_exp_f32_e32 v94, v94
	v_pk_mul_f32 v[90:91], v[92:93], v[90:91]
	v_exp_f32_e32 v95, v95
	v_pk_mul_f32 v[92:93], v[96:97], v[86:87] op_sel_hi:[0,1]
	v_exp_f32_e32 v92, v92
	v_exp_f32_e32 v86, v93
	v_add_f32_e32 v94, 1.0, v94
	v_add_f32_e32 v95, 1.0, v95
	v_rcp_f32_e32 v94, v94
	v_rcp_f32_e32 v95, v95
	v_pk_mul_f32 v[80:81], v[84:85], v[80:81]
	v_add_f32_e32 v84, 1.0, v92
	v_add_f32_e32 v85, 1.0, v86
	v_rcp_f32_e32 v84, v84
	v_rcp_f32_e32 v85, v85
	v_rcp_f32_e32 v103, v97
	v_pk_mul_f32 v[80:81], v[98:99], v[80:81] op_sel_hi:[0,1]
	v_pk_mul_f32 v[86:87], v[94:95], v[80:81]
	v_pk_mul_f32 v[80:81], v[98:99], v[82:83] op_sel_hi:[0,1]
	v_pk_mul_f32 v[88:89], v[98:99], v[88:89] op_sel_hi:[0,1]
	v_pk_mul_f32 v[84:85], v[84:85], v[80:81]
	v_or_b32_e32 v80, 32, v163
	v_pk_mul_f32 v[88:89], v[102:103], v[88:89]
	v_mad_i64_i32 v[80:81], s[28:29], v80, s53, v[112:113]
	v_lshl_add_u64 v[92:93], v[80:81], 0, v[114:115]
	v_cvt_pk_bf16_f32 v80, v88, v89
	v_cvt_pk_bf16_f32 v81, v90, v91
	v_cvt_pk_bf16_f32 v82, v86, v87
	v_cvt_pk_bf16_f32 v83, v84, v85
	global_store_dwordx4 v[92:93], v[80:83], off
	v_pk_mul_f32 v[72:73], v[76:77], v[72:73]
	v_pk_mul_f32 v[74:75], v[78:79], v[74:75]
	v_mul_f32_e32 v80, 0xbfb8aa3b, v158
	v_pk_mul_f32 v[82:83], v[80:81], v[76:77] op_sel_hi:[0,1]
	v_exp_f32_e32 v81, v82
	v_exp_f32_e32 v83, v83
	v_mul_f32_e32 v82, v158, v158
	v_pk_mul_f32 v[66:67], v[70:71], v[66:67]
	v_pk_mul_f32 v[84:85], v[80:81], v[78:79] op_sel_hi:[0,1]
	v_exp_f32_e32 v76, v84
	v_exp_f32_e32 v77, v85
	v_add_f32_e32 v81, 1.0, v81
	v_rcp_f32_e32 v86, v81
	v_add_f32_e32 v76, 1.0, v76
	v_add_f32_e32 v77, 1.0, v77
	v_rcp_f32_e32 v76, v76
	v_rcp_f32_e32 v77, v77
	v_add_f32_e32 v81, 1.0, v83
	v_pk_mul_f32 v[74:75], v[82:83], v[74:75] op_sel_hi:[0,1]
	v_pk_mul_f32 v[78:79], v[80:81], v[68:69] op_sel_hi:[0,1]
	v_exp_f32_e32 v78, v78
	v_pk_mul_f32 v[74:75], v[76:77], v[74:75]
	v_exp_f32_e32 v79, v79
	v_pk_mul_f32 v[76:77], v[80:81], v[70:71] op_sel_hi:[0,1]
	v_exp_f32_e32 v76, v76
	v_exp_f32_e32 v70, v77
	v_add_f32_e32 v78, 1.0, v78
	v_add_f32_e32 v79, 1.0, v79
	v_rcp_f32_e32 v78, v78
	v_rcp_f32_e32 v79, v79
	v_pk_mul_f32 v[64:65], v[68:69], v[64:65]
	v_add_f32_e32 v68, 1.0, v76
	v_add_f32_e32 v69, 1.0, v70
	v_rcp_f32_e32 v68, v68
	v_rcp_f32_e32 v69, v69
	v_rcp_f32_e32 v87, v81
	v_pk_mul_f32 v[64:65], v[82:83], v[64:65] op_sel_hi:[0,1]
	v_pk_mul_f32 v[70:71], v[78:79], v[64:65]
	v_pk_mul_f32 v[64:65], v[82:83], v[66:67] op_sel_hi:[0,1]
	v_pk_mul_f32 v[72:73], v[82:83], v[72:73] op_sel_hi:[0,1]
	v_pk_mul_f32 v[68:69], v[68:69], v[64:65]
	v_or_b32_e32 v64, 48, v163
	v_pk_mul_f32 v[72:73], v[86:87], v[72:73]
	v_mad_i64_i32 v[64:65], s[28:29], v64, s53, v[112:113]
	v_lshl_add_u64 v[76:77], v[64:65], 0, v[114:115]
	v_cvt_pk_bf16_f32 v64, v72, v73
	v_cvt_pk_bf16_f32 v65, v74, v75
	v_cvt_pk_bf16_f32 v66, v70, v71
	v_cvt_pk_bf16_f32 v67, v68, v69
	global_store_dwordx4 v[76:77], v[64:67], off
	v_pk_mul_f32 v[56:57], v[60:61], v[56:57]
	v_pk_mul_f32 v[58:59], v[62:63], v[58:59]
	v_add_u32_e32 v65, 0x80, v163
	v_mul_f32_e32 v64, 0xbfb8aa3b, v159
	v_pk_mul_f32 v[68:69], v[64:65], v[62:63] op_sel_hi:[0,1]
	v_pk_mul_f32 v[66:67], v[64:65], v[60:61] op_sel_hi:[0,1]
	v_exp_f32_e32 v60, v68
	v_exp_f32_e32 v61, v69
	v_exp_f32_e32 v67, v67
	v_exp_f32_e32 v70, v66
	v_add_f32_e32 v60, 1.0, v60
	v_add_f32_e32 v61, 1.0, v61
	v_rcp_f32_e32 v60, v60
	v_rcp_f32_e32 v61, v61
	v_mul_f32_e32 v66, v159, v159
	v_add_f32_e32 v67, 1.0, v67
	v_pk_mul_f32 v[58:59], v[66:67], v[58:59] op_sel_hi:[0,1]
	v_pk_mul_f32 v[62:63], v[64:65], v[52:53] op_sel_hi:[0,1]
	v_exp_f32_e32 v62, v62
	v_pk_mul_f32 v[58:59], v[60:61], v[58:59]
	v_exp_f32_e32 v63, v63
; __device__ __forceinline__ void st_nt(float* p, f32x4 v) { __builtin_nontemporal_store(v, (f32x4*)p); }
; __device__ __forceinline__ void st_nt(bf16_t* p, u32x4 v) { __builtin_nontemporal_store(v, (u32x4*)p); }
; __device__ __forceinline__ u32x4 pack8(const f32x4 a, const f32x4 b) { u32x4 w; w.x = cvt_pk_bf16(a[0], a[1]); w.y = cvt_pk_bf16(a[2], a[3]); w.z = cvt_pk_bf16(b[0], b[1]); w.w = cvt_pk_bf16(b[2], b[3]); return w; }
;     __device__ __forceinline__ void operator()(Acc& acc, const Unit& u, int wr, int wc, int fr, int fq, const float (&rsv)[8]) const {
;         const int row0 = u.pm * BM + wr * 64 + fr, col = u.pn * 128 + wc * 32 + 8 * fq;
; #pragma unroll
;         for (int ai = 0; ai < 2; ++ai)
; #pragma unroll
;             for (int m = 0; m < 4; ++m) {
;                 const int row = row0 + ai * HALF + m * 16; const float rs = rsv[ai * 4 + m];
;                 f32x4 o[2];
;                 const float rsn = rs * -1.4426950408889634f, rs2 = rs * rs;
; #pragma unroll
;                 for (int n = 0; n < 2; ++n) { const f32x4 g = acc[ai][0][m][n], uu = acc[ai][1][m][n]; const f32x4 t = g * rsn, w = (g * uu) * rs2;
; #pragma unroll
;                     for (int j = 0; j < 4; ++j) o[n][j] = w[j] * __builtin_amdgcn_rcpf(1.0f + __builtin_amdgcn_exp2f(t[j])); }
;                 st_nt(act + (size_t)row * LDACT + col, pack8(o[0], o[1]));
;             }
; template <class Epi>
; __device__ __forceinline__ void gemm_phase(LAS unsigned char* lds, const GSched& S, const int K, const int lda, const int ldb, const Epi& E) {
;     ...
;         if (!has_next) break;
	v_pk_mul_f32 v[60:61], v[64:65], v[54:55] op_sel_hi:[0,1]
	v_exp_f32_e32 v60, v60
	v_pk_mul_f32 v[50:51], v[54:55], v[50:51]
	v_exp_f32_e32 v54, v61
	v_add_f32_e32 v62, 1.0, v62
	v_add_f32_e32 v63, 1.0, v63
	v_add_f32_e32 v70, 1.0, v70
	v_rcp_f32_e32 v62, v62
	v_rcp_f32_e32 v63, v63
	v_pk_mul_f32 v[48:49], v[52:53], v[48:49]
	v_add_f32_e32 v52, 1.0, v60
	v_add_f32_e32 v53, 1.0, v54
	v_rcp_f32_e32 v70, v70
	v_rcp_f32_e32 v71, v67
	v_rcp_f32_e32 v52, v52
	v_rcp_f32_e32 v53, v53
	v_pk_mul_f32 v[48:49], v[66:67], v[48:49] op_sel_hi:[0,1]
	v_pk_mul_f32 v[56:57], v[66:67], v[56:57] op_sel_hi:[0,1]
	v_pk_mul_f32 v[54:55], v[62:63], v[48:49]
	v_pk_mul_f32 v[48:49], v[66:67], v[50:51] op_sel_hi:[0,1]
	v_pk_mul_f32 v[56:57], v[70:71], v[56:57]
	v_pk_mul_f32 v[52:53], v[52:53], v[48:49]
	v_mad_i64_i32 v[48:49], s[28:29], v65, s53, v[112:113]
	v_lshl_add_u64 v[60:61], v[48:49], 0, v[114:115]
	v_cvt_pk_bf16_f32 v48, v56, v57
	v_cvt_pk_bf16_f32 v49, v58, v59
	v_cvt_pk_bf16_f32 v50, v54, v55
	v_cvt_pk_bf16_f32 v51, v52, v53
	global_store_dwordx4 v[60:61], v[48:51], off
	v_pk_mul_f32 v[40:41], v[44:45], v[40:41]
	v_pk_mul_f32 v[42:43], v[46:47], v[42:43]
	v_mul_f32_e32 v48, 0xbfb8aa3b, v160
	v_pk_mul_f32 v[50:51], v[48:49], v[44:45] op_sel_hi:[0,1]
	v_exp_f32_e32 v49, v50
	v_exp_f32_e32 v51, v51
	v_mul_f32_e32 v50, v160, v160
	v_pk_mul_f32 v[34:35], v[38:39], v[34:35]
	v_pk_mul_f32 v[52:53], v[48:49], v[46:47] op_sel_hi:[0,1]
	v_exp_f32_e32 v44, v52
	v_exp_f32_e32 v45, v53
	v_add_f32_e32 v49, 1.0, v49
	v_rcp_f32_e32 v54, v49
	v_add_f32_e32 v44, 1.0, v44
	v_add_f32_e32 v45, 1.0, v45
	v_rcp_f32_e32 v44, v44
	v_rcp_f32_e32 v45, v45
	v_add_f32_e32 v49, 1.0, v51
	v_pk_mul_f32 v[42:43], v[50:51], v[42:43] op_sel_hi:[0,1]
	v_pk_mul_f32 v[46:47], v[48:49], v[36:37] op_sel_hi:[0,1]
	v_exp_f32_e32 v46, v46
	v_pk_mul_f32 v[42:43], v[44:45], v[42:43]
	v_exp_f32_e32 v47, v47
	v_pk_mul_f32 v[44:45], v[48:49], v[38:39] op_sel_hi:[0,1]
	v_exp_f32_e32 v44, v44
	v_exp_f32_e32 v38, v45
	v_add_f32_e32 v46, 1.0, v46
	v_add_f32_e32 v47, 1.0, v47
	v_rcp_f32_e32 v46, v46
	v_rcp_f32_e32 v47, v47
	v_pk_mul_f32 v[32:33], v[36:37], v[32:33]
	v_add_f32_e32 v36, 1.0, v44
	v_add_f32_e32 v37, 1.0, v38
	v_rcp_f32_e32 v36, v36
	v_rcp_f32_e32 v37, v37
	v_rcp_f32_e32 v55, v49
	v_pk_mul_f32 v[32:33], v[50:51], v[32:33] op_sel_hi:[0,1]
	v_pk_mul_f32 v[38:39], v[46:47], v[32:33]
	v_pk_mul_f32 v[32:33], v[50:51], v[34:35] op_sel_hi:[0,1]
	v_pk_mul_f32 v[40:41], v[50:51], v[40:41] op_sel_hi:[0,1]
	v_pk_mul_f32 v[36:37], v[36:37], v[32:33]
	v_add_u32_e32 v32, 0x90, v163
	v_pk_mul_f32 v[40:41], v[54:55], v[40:41]
	v_mad_i64_i32 v[32:33], s[28:29], v32, s53, v[112:113]
	v_lshl_add_u64 v[44:45], v[32:33], 0, v[114:115]
	v_cvt_pk_bf16_f32 v32, v40, v41
	v_cvt_pk_bf16_f32 v33, v42, v43
	v_cvt_pk_bf16_f32 v34, v38, v39
	v_cvt_pk_bf16_f32 v35, v36, v37
	global_store_dwordx4 v[44:45], v[32:35], off
	v_pk_mul_f32 v[24:25], v[28:29], v[24:25]
	v_pk_mul_f32 v[26:27], v[30:31], v[26:27]
	v_mul_f32_e32 v32, 0xbfb8aa3b, v161
	v_pk_mul_f32 v[34:35], v[32:33], v[28:29] op_sel_hi:[0,1]
	v_exp_f32_e32 v33, v34
	v_exp_f32_e32 v35, v35
	v_mul_f32_e32 v34, v161, v161
	v_pk_mul_f32 v[18:19], v[22:23], v[18:19]
	v_pk_mul_f32 v[36:37], v[32:33], v[30:31] op_sel_hi:[0,1]
	v_exp_f32_e32 v28, v36
	v_exp_f32_e32 v29, v37
	v_add_f32_e32 v33, 1.0, v33
	v_rcp_f32_e32 v38, v33
	v_add_f32_e32 v28, 1.0, v28
	v_add_f32_e32 v29, 1.0, v29
	v_rcp_f32_e32 v28, v28
	v_rcp_f32_e32 v29, v29
	v_add_f32_e32 v33, 1.0, v35
	v_pk_mul_f32 v[26:27], v[34:35], v[26:27] op_sel_hi:[0,1]
	v_pk_mul_f32 v[30:31], v[32:33], v[20:21] op_sel_hi:[0,1]
	v_exp_f32_e32 v30, v30
	v_pk_mul_f32 v[26:27], v[28:29], v[26:27]
	v_exp_f32_e32 v31, v31
	v_pk_mul_f32 v[28:29], v[32:33], v[22:23] op_sel_hi:[0,1]
	v_exp_f32_e32 v28, v28
	v_exp_f32_e32 v22, v29
	v_add_f32_e32 v30, 1.0, v30
	v_add_f32_e32 v31, 1.0, v31
	v_rcp_f32_e32 v30, v30
	v_rcp_f32_e32 v31, v31
	v_pk_mul_f32 v[16:17], v[20:21], v[16:17]
	v_add_f32_e32 v20, 1.0, v28
	v_add_f32_e32 v21, 1.0, v22
	v_rcp_f32_e32 v20, v20
	v_rcp_f32_e32 v21, v21
	v_rcp_f32_e32 v39, v33
	v_pk_mul_f32 v[16:17], v[34:35], v[16:17] op_sel_hi:[0,1]
	v_pk_mul_f32 v[22:23], v[30:31], v[16:17]
	v_pk_mul_f32 v[16:17], v[34:35], v[18:19] op_sel_hi:[0,1]
	v_pk_mul_f32 v[24:25], v[34:35], v[24:25] op_sel_hi:[0,1]
	v_pk_mul_f32 v[20:21], v[20:21], v[16:17]
	v_add_u32_e32 v16, 0xa0, v163
	v_pk_mul_f32 v[24:25], v[38:39], v[24:25]
	v_mad_i64_i32 v[16:17], s[28:29], v16, s53, v[112:113]
	v_lshl_add_u64 v[28:29], v[16:17], 0, v[114:115]
	v_cvt_pk_bf16_f32 v16, v24, v25
	v_cvt_pk_bf16_f32 v17, v26, v27
	v_cvt_pk_bf16_f32 v18, v22, v23
	v_cvt_pk_bf16_f32 v19, v20, v21
	global_store_dwordx4 v[28:29], v[16:19], off
	v_pk_mul_f32 v[8:9], v[12:13], v[8:9]
	v_pk_mul_f32 v[10:11], v[14:15], v[10:11]
	v_mul_f32_e32 v16, 0xbfb8aa3b, v162
	v_pk_mul_f32 v[18:19], v[16:17], v[12:13] op_sel_hi:[0,1]
	v_exp_f32_e32 v17, v18
	v_exp_f32_e32 v19, v19
	v_mul_f32_e32 v18, v162, v162
	v_pk_mul_f32 v[2:3], v[6:7], v[2:3]
	v_pk_mul_f32 v[20:21], v[16:17], v[14:15] op_sel_hi:[0,1]
	v_exp_f32_e32 v12, v20
	v_exp_f32_e32 v13, v21
	v_add_f32_e32 v17, 1.0, v17
	v_rcp_f32_e32 v22, v17
	v_add_f32_e32 v12, 1.0, v12
	v_add_f32_e32 v13, 1.0, v13
	v_rcp_f32_e32 v12, v12
	v_rcp_f32_e32 v13, v13
	v_add_f32_e32 v17, 1.0, v19
	v_pk_mul_f32 v[10:11], v[18:19], v[10:11] op_sel_hi:[0,1]
	v_pk_mul_f32 v[14:15], v[16:17], v[4:5] op_sel_hi:[0,1]
	v_exp_f32_e32 v14, v14
	v_pk_mul_f32 v[10:11], v[12:13], v[10:11]
	v_exp_f32_e32 v15, v15
	v_pk_mul_f32 v[12:13], v[16:17], v[6:7] op_sel_hi:[0,1]
	v_exp_f32_e32 v12, v12
	v_exp_f32_e32 v6, v13
	v_add_f32_e32 v14, 1.0, v14
	v_add_f32_e32 v15, 1.0, v15
	v_rcp_f32_e32 v14, v14
	v_rcp_f32_e32 v15, v15
	v_pk_mul_f32 v[0:1], v[4:5], v[0:1]
	v_add_f32_e32 v4, 1.0, v12
	v_add_f32_e32 v5, 1.0, v6
	v_rcp_f32_e32 v4, v4
	v_rcp_f32_e32 v5, v5
	v_rcp_f32_e32 v23, v17
	v_pk_mul_f32 v[0:1], v[18:19], v[0:1] op_sel_hi:[0,1]
	v_pk_mul_f32 v[6:7], v[14:15], v[0:1]
	v_pk_mul_f32 v[0:1], v[18:19], v[2:3] op_sel_hi:[0,1]
	v_pk_mul_f32 v[8:9], v[18:19], v[8:9] op_sel_hi:[0,1]
	v_pk_mul_f32 v[4:5], v[4:5], v[0:1]
	v_add_u32_e32 v0, 0xb0, v163
	v_pk_mul_f32 v[8:9], v[22:23], v[8:9]
	v_mad_i64_i32 v[0:1], s[28:29], v0, s53, v[112:113]
	v_lshl_add_u64 v[12:13], v[0:1], 0, v[114:115]
	v_cvt_pk_bf16_f32 v0, v8, v9
	v_cvt_pk_bf16_f32 v1, v10, v11
	v_cvt_pk_bf16_f32 v2, v6, v7
	v_cvt_pk_bf16_f32 v3, v4, v5
	s_mov_b64 s[28:29], -1
	s_and_b64 vcc, exec, s[6:7]
	global_store_dwordx4 v[12:13], v[0:3], off
	s_cbranch_vccz .LBB0_1018
;     __device__ __forceinline__ void rstd_fill(float (&rsv)[8], const Unit& u, int wr, int fr, int fq) const { rstd_regs32(rsv, part, u.pm * BM + wr * 64 + fr, fq); }
;     __device__ __forceinline__ void rstd_fill(float (&rsv)[8], const Unit& u, int wr, int fr, int fq) const { rstd_regs32(rsv, part, u.pm * BM + wr * 64 + fr, fq); }
;     __device__ __forceinline__ void rstd_fill(float (&rsv)[8], const Unit& u, int wr, int fr, int fq) const { rstd_regs32(rsv, part, u.pm * BM + wr * 64 + fr, fq); }
;     __device__ __forceinline__ void rstd_fill(float (&rsv)[8], const Unit& u, int wr, int fr, int fq) const { rstd_regs32(rsv, part, u.pm * BM + wr * 64 + fr, fq); }
;     __device__ __forceinline__ void rstd_fill(float (&rsv)[8], const Unit& u, int wr, int fr, int fq) const { rstd_regs_lat(rsv, latpart, u.pm * BM + wr * 64 + fr, u.z); }
;     __device__ __forceinline__ void rstd_fill(float (&rsv)[8], const Unit& u, int wr, int fr, int fq) const { rstd_regs32(rsv, part_in, u.pm * BM + wr * 64 + fr, fq); }
; #define PG8_SCHED __builtin_amdgcn_sched_barrier(0)
; __device__ __forceinline__ void rstd_regs32(float (&rsv)[8], const float* part, int row0, int fq) {
;     int r0 = row0; asm volatile("" : "+v"(r0));
;     const float* q = part + (size_t)r0 * 32 + fq * 8;
;     f32x4 a[8], b[8];
; #pragma unroll
;     for (int g = 0; g < 8; ++g) { const float* p = q + (size_t)((g >> 2) * HALF + (g & 3) * 16) * 32; a[g] = *(const f32x4*)p; b[g] = *(const f32x4*)(p + 4); }
; #pragma unroll
;     for (int g = 0; g < 8; ++g) { float s = ((a[g][0] + a[g][1]) + (a[g][2] + a[g][3])) + ((b[g][0] + b[g][1]) + (b[g][2] + b[g][3]));
;         s += __shfl_xor(s, 16); s += __shfl_xor(s, 32); rsv[g] = __builtin_amdgcn_rsqf(s * (1.0f / 2048.0f) + EPS); }
; }
; template <class Epi>
; __device__ __forceinline__ void gemm_phase(LAS unsigned char* lds, const GSched& S, const int K, const int lda, const int ldb, const Epi& E) {
;     ...
;         if constexpr (Epi::RSTD) { if (nxt.pm != cur.pm || nxt.z != cur.z) { PG8_SCHED; E.rstd_fill(rsv, nxt, wr, fr, fq); PG8_SCHED; } }
	s_cmp_eq_u32 s55, s2
	s_cbranch_scc1 .LBB0_1017
	v_lshl_add_u32 v0, s55, 8, v149
	s_nop 0
	v_ashrrev_i32_e32 v1, 31, v0
	v_lshlrev_b64 v[0:1], 7, v[0:1]
	v_lshl_add_u64 v[48:49], v[136:137], 0, v[0:1]
	global_load_dwordx4 v[0:3], v[48:49], off
	global_load_dwordx4 v[4:7], v[48:49], off offset:16
	global_load_dwordx4 v[8:11], v[48:49], off offset:2048
	global_load_dwordx4 v[12:15], v[48:49], off offset:2064
	v_add_co_u32_e32 v28, vcc, 0x1000, v48
	v_lshl_add_u64 v[24:25], v[48:49], 0, s[10:11]
	v_lshl_add_u64 v[16:17], v[48:49], 0, s[14:15]
	v_addc_co_u32_e32 v29, vcc, 0, v49, vcc
	v_lshl_add_u64 v[32:33], v[48:49], 0, s[12:13]
	global_load_dwordx4 v[16:19], v[16:17], off offset:16
	s_nop 0
	global_load_dwordx4 v[20:23], v[28:29], off
	s_nop 0
	global_load_dwordx4 v[24:27], v[24:25], off offset:16
	s_nop 0
	global_load_dwordx4 v[28:31], v[28:29], off offset:2048
	s_nop 0
	global_load_dwordx4 v[32:35], v[32:33], off offset:16
	v_add_co_u32_e32 v50, vcc, s49, v48
	s_mov_b64 s[6:7], vcc
	v_add_co_u32_e32 v56, vcc, s50, v48
	v_lshl_add_u64 v[40:41], v[48:49], 0, s[16:17]
	s_nop 0
	v_addc_co_u32_e32 v57, vcc, 0, v49, vcc
	global_load_dwordx4 v[36:39], v[56:57], off offset:-4096
	v_lshl_add_u64 v[44:45], v[48:49], 0, s[18:19]
	global_load_dwordx4 v[40:43], v[40:41], off offset:16
	s_nop 0
	global_load_dwordx4 v[44:47], v[44:45], off offset:16
	v_lshl_add_u64 v[60:61], v[48:49], 0, s[20:21]
	v_addc_co_u32_e64 v51, vcc, 0, v49, s[6:7]
	global_load_dwordx4 v[48:51], v[50:51], off offset:2048
	s_nop 0
	global_load_dwordx4 v[52:55], v[56:57], off
	s_nop 0
	global_load_dwordx4 v[56:59], v[56:57], off offset:2048
	s_nop 0
	global_load_dwordx4 v[60:63], v[60:61], off offset:16
	s_waitcnt vmcnt(0)
	v_mov_b32_e32 v64, v0
	v_mov_b32_e32 v65, v4
	v_mov_b32_e32 v4, v1
	v_mov_b32_e32 v0, v2
	v_mov_b32_e32 v1, v6
	v_mov_b32_e32 v6, v3
	v_mov_b32_e32 v2, v8
	v_mov_b32_e32 v3, v12
	v_mov_b32_e32 v12, v9
	v_mov_b32_e32 v8, v10
	v_mov_b32_e32 v9, v14
	v_mov_b32_e32 v14, v11
	v_pk_add_f32 v[4:5], v[64:65], v[4:5]
	v_pk_add_f32 v[0:1], v[0:1], v[6:7]
	v_pk_add_f32 v[2:3], v[2:3], v[12:13]
	v_pk_add_f32 v[6:7], v[8:9], v[14:15]
	v_pk_add_f32 v[0:1], v[4:5], v[0:1]
	v_pk_add_f32 v[2:3], v[2:3], v[6:7]
	v_mov_b32_e32 v4, v20
	v_mov_b32_e32 v5, v24
	v_mov_b32_e32 v24, v21
	v_mov_b32_e32 v6, v22
	v_mov_b32_e32 v7, v26
	v_mov_b32_e32 v26, v23
	v_mov_b32_e32 v10, v28
	v_mov_b32_e32 v11, v32
	v_mov_b32_e32 v32, v29
	v_add_f32_e32 v14, v0, v1
	v_add_f32_e32 v15, v2, v3
	v_mov_b32_e32 v12, v30
	v_mov_b32_e32 v13, v34
	v_mov_b32_e32 v34, v31
	v_pk_add_f32 v[0:1], v[4:5], v[24:25]
	v_pk_add_f32 v[2:3], v[6:7], v[26:27]
	v_pk_add_f32 v[4:5], v[10:11], v[32:33]
	ds_bpermute_b32 v10, v146, v14
	ds_bpermute_b32 v11, v146, v15
	v_pk_add_f32 v[6:7], v[12:13], v[34:35]
	v_pk_add_f32 v[0:1], v[0:1], v[2:3]
	v_pk_add_f32 v[2:3], v[4:5], v[6:7]
	v_add_f32_e32 v0, v0, v1
	v_add_f32_e32 v1, v2, v3
	ds_bpermute_b32 v2, v146, v0
	ds_bpermute_b32 v3, v146, v1
	s_waitcnt lgkmcnt(0)
	v_add_f32_e32 v4, v14, v10
	v_add_f32_e32 v5, v15, v11
	ds_bpermute_b32 v6, v147, v4
	ds_bpermute_b32 v7, v147, v5
	v_add_f32_e32 v0, v0, v2
	v_add_f32_e32 v10, v1, v3
	ds_bpermute_b32 v1, v147, v0
	s_waitcnt lgkmcnt(2)
	v_add_f32_e32 v2, v4, v6
	s_waitcnt lgkmcnt(1)
	v_add_f32_e32 v3, v5, v7
	v_fmamk_f32 v2, v2, 0x3a000000, v148
	v_fmamk_f32 v3, v3, 0x3a000000, v148
	v_mov_b32_e32 v9, v16
	v_mov_b32_e32 v8, v36
	v_rsq_f32_e32 v155, v2
	v_rsq_f32_e32 v156, v3
	v_mov_b32_e32 v16, v37
	v_mov_b32_e32 v2, v38
	v_mov_b32_e32 v3, v18
	v_mov_b32_e32 v18, v39
	s_waitcnt lgkmcnt(0)
	v_add_f32_e32 v4, v0, v1
	v_pk_add_f32 v[0:1], v[8:9], v[16:17]
	v_pk_add_f32 v[2:3], v[2:3], v[18:19]
	ds_bpermute_b32 v11, v147, v10
	v_pk_add_f32 v[0:1], v[0:1], v[2:3]
	v_fmamk_f32 v2, v4, 0x3a000000, v148
	v_add_f32_e32 v0, v0, v1
	ds_bpermute_b32 v1, v146, v0
	v_rsq_f32_e32 v157, v2
	s_waitcnt lgkmcnt(1)
	v_add_f32_e32 v2, v10, v11
	v_fmamk_f32 v4, v2, 0x3a000000, v148
	v_mov_b32_e32 v2, v50
	s_waitcnt lgkmcnt(0)
	v_add_f32_e32 v5, v0, v1
	v_mov_b32_e32 v0, v48
	v_mov_b32_e32 v1, v40
	v_mov_b32_e32 v40, v49
	v_mov_b32_e32 v3, v42
	v_mov_b32_e32 v42, v51
	v_pk_add_f32 v[0:1], v[0:1], v[40:41]
	v_pk_add_f32 v[2:3], v[2:3], v[42:43]
	ds_bpermute_b32 v6, v147, v5
	v_pk_add_f32 v[0:1], v[0:1], v[2:3]
	v_rsq_f32_e32 v158, v4
	v_add_f32_e32 v0, v0, v1
	ds_bpermute_b32 v1, v146, v0
	s_waitcnt lgkmcnt(1)
	v_add_f32_e32 v2, v5, v6
	v_fmamk_f32 v2, v2, 0x3a000000, v148
	v_rsq_f32_e32 v159, v2
	v_mov_b32_e32 v2, v54
	s_waitcnt lgkmcnt(0)
	v_add_f32_e32 v4, v0, v1
	v_mov_b32_e32 v0, v52
	v_mov_b32_e32 v1, v44
	v_mov_b32_e32 v44, v53
	v_mov_b32_e32 v3, v46
	v_mov_b32_e32 v46, v55
	v_pk_add_f32 v[0:1], v[0:1], v[44:45]
	v_pk_add_f32 v[2:3], v[2:3], v[46:47]
	ds_bpermute_b32 v5, v147, v4
	v_pk_add_f32 v[0:1], v[0:1], v[2:3]
	v_mov_b32_e32 v2, v58
	v_add_f32_e32 v6, v0, v1
	v_mov_b32_e32 v0, v56
	v_mov_b32_e32 v1, v60
	v_mov_b32_e32 v60, v57
	v_mov_b32_e32 v3, v62
	v_mov_b32_e32 v62, v59
	v_pk_add_f32 v[0:1], v[0:1], v[60:61]
	v_pk_add_f32 v[2:3], v[2:3], v[62:63]
	ds_bpermute_b32 v7, v146, v6
	v_pk_add_f32 v[0:1], v[0:1], v[2:3]
	s_waitcnt lgkmcnt(1)
	v_add_f32_e32 v2, v4, v5
	v_add_f32_e32 v0, v0, v1
	ds_bpermute_b32 v1, v146, v0
	s_waitcnt lgkmcnt(1)
	v_add_f32_e32 v3, v6, v7
	ds_bpermute_b32 v4, v147, v3
	v_fmamk_f32 v2, v2, 0x3a000000, v148
	v_rsq_f32_e32 v160, v2
	s_waitcnt lgkmcnt(1)
	v_add_f32_e32 v0, v0, v1
	ds_bpermute_b32 v1, v147, v0
	s_waitcnt lgkmcnt(1)
	v_add_f32_e32 v2, v3, v4
	v_fmamk_f32 v2, v2, 0x3a000000, v148
	v_rsq_f32_e32 v161, v2
	s_waitcnt lgkmcnt(0)
	v_add_f32_e32 v0, v0, v1
	v_fmamk_f32 v0, v0, 0x3a000000, v148
	v_rsq_f32_e32 v162, v0
	s_branch .LBB0_1017

; #define PG8_STAGE(bufoff, gbase, voff) do { _Pragma("unroll") for (int _i = 0; _i < 2; ++_i) \
;         __builtin_amdgcn_global_load_lds((const unsigned*)((const char*)(gbase) + (voff)[_i]), (LAS unsigned*)(lds + (bufoff) + ldsw + _i * 8192), 16, 0, 0); } while (0)
; #define PG8_LDA(dst, b, h) do { _Pragma("unroll") for (int m = 0; m < 4; ++m) _Pragma("unroll") for (int k = 0; k < 2; ++k) dst[m][k] = *(const LAS bf16x8*)(lds + PG8_SA(b, h) + aoff + m * 2048 + k * 1024); } while (0)
; #define PG8_LDB(dst, b, h) do { _Pragma("unroll") for (int n = 0; n < 2; ++n) _Pragma("unroll") for (int k = 0; k < 2; ++k) dst[n][k] = *(const LAS bf16x8*)(lds + PG8_SB(b, h) + boff + n * 2048 + k * 1024); } while (0)
; #define PG8_MMA(ai, bj, At, Bt) do { __builtin_amdgcn_s_setprio(1); _Pragma("unroll") for (int m = 0; m < 4; ++m) _Pragma("unroll") for (int n = 0; n < 2; ++n) _Pragma("unroll") for (int k = 0; k < 2; ++k) \
;         acc[ai][bj][m][n] = __builtin_amdgcn_mfma_f32_16x16x32_bf16(Bt[n][k], At[m][k], acc[ai][bj][m][n], 0, 0, 0); __builtin_amdgcn_s_setprio(0); } while (0)
; #define PG8_WAIT_V(n) asm volatile("s_waitcnt vmcnt(" #n ")" ::: "memory")
; #define PG8_WAIT_L(n) asm volatile("s_waitcnt lgkmcnt(" #n ")" ::: "memory")
; #define PG8_BAR __builtin_amdgcn_s_barrier()
; template <class Epi>
; __device__ __forceinline__ void gemm_phase(LAS unsigned char* lds, const GSched& S, const int K, const int lda, const int ldb, const Epi& E) {
;     ...
;             PG8_LDB(B0, 0, 0); PG8_SCHED; PG8_LDA(At, 0, 0); PG8_STAGE(PG8_SA(1, 1), a1 + hstepA, voffA);
;             PG8_WAIT_L(8); PG8_BAR; PG8_WAIT_L(0); PG8_MMA(0, 0, At, B0); PG8_BAR; PG8_SCHED;
;             if constexpr (!Epi::NARROW) PG8_LDB(B1, 0, 1); PG8_STAGE(PG8_SB(0, 0), b2, voffB);
;             PG8_BAR; PG8_WAIT_L(0); if constexpr (!Epi::NARROW) PG8_MMA(0, 1, At, B1); PG8_BAR;
;             PG8_LDA(At, 0, 1); PG8_STAGE(PG8_SA(0, 0), a2, voffA);
;             PG8_BAR; PG8_WAIT_L(0); PG8_MMA(1, 0, At, B0); PG8_BAR; PG8_SCHED;
;             PG8_STAGE(PG8_SB(0, 1), b2 + hstepB, voffB);
;             PG8_WAIT_V(6); PG8_BAR; if constexpr (!Epi::NARROW) PG8_MMA(1, 1, At, B1); PG8_BAR;
;             PG8_LDB(B0, 1, 0); PG8_SCHED; PG8_LDA(At, 1, 0); PG8_STAGE(PG8_SA(0, 1), a2 + hstepA, voffA);
;             PG8_WAIT_L(8); PG8_BAR; PG8_WAIT_L(0); PG8_MMA(0, 0, At, B0); PG8_BAR; PG8_SCHED;
.LBB0_1107:
	ds_read_b128 v[104:107], v235
	ds_read_b128 v[116:119], v235 offset:1024
	ds_read_b128 v[128:131], v235 offset:2048
	ds_read_b128 v[140:143], v235 offset:3072
	s_add_u32 s24, s22, 0x100
	s_addc_u32 s25, s23, 0
	s_cmpk_eq_i32 s50, 0x54
	s_cselect_b32 s29, s11, s25
	s_cselect_b32 s28, s10, s24
	s_cselect_b32 s27, s13, s49
	s_cselect_b32 s26, s12, s48
	v_lshl_add_u64 v[176:177], s[22:23], 0, v[194:195]
	s_add_i32 m0, s0, 0xc000
	ds_read_b128 v[144:147], v236
	ds_read_b128 v[148:151], v236 offset:1024
	ds_read_b128 v[152:155], v236 offset:2048
	ds_read_b128 v[156:159], v236 offset:3072
	ds_read_b128 v[160:163], v236 offset:4096
	ds_read_b128 v[164:167], v236 offset:5120
	ds_read_b128 v[168:171], v236 offset:6144
	ds_read_b128 v[172:175], v236 offset:7168
	global_load_lds_dwordx4 v[176:177], off
	v_lshl_add_u64 v[176:177], s[22:23], 0, v[192:193]
	s_add_i32 m0, s0, 0xe000
	s_nop 0
	global_load_lds_dwordx4 v[176:177], off
	s_waitcnt lgkmcnt(8)
	s_barrier
	s_waitcnt lgkmcnt(0)
	s_setprio 1
	s_waitcnt lgkmcnt(0)
	v_mfma_f32_16x16x32_bf16 v[136:139], v[104:107], v[144:147], v[136:139]
	v_mfma_f32_16x16x32_bf16 v[132:135], v[128:131], v[144:147], v[132:135]
	v_mfma_f32_16x16x32_bf16 v[112:115], v[104:107], v[152:155], v[112:115]
	v_mfma_f32_16x16x32_bf16 v[108:111], v[128:131], v[152:155], v[108:111]
	v_mfma_f32_16x16x32_bf16 v[92:95], v[104:107], v[160:163], v[92:95]
	v_mfma_f32_16x16x32_bf16 v[88:91], v[128:131], v[160:163], v[88:91]
	v_mfma_f32_16x16x32_bf16 v[76:79], v[104:107], v[168:171], v[76:79]
	v_mfma_f32_16x16x32_bf16 v[72:75], v[128:131], v[168:171], v[72:75]
	v_mfma_f32_16x16x32_bf16 v[136:139], v[116:119], v[148:151], v[136:139]
	v_mfma_f32_16x16x32_bf16 v[132:135], v[140:143], v[148:151], v[132:135]
	v_mfma_f32_16x16x32_bf16 v[112:115], v[116:119], v[156:159], v[112:115]
	v_mfma_f32_16x16x32_bf16 v[108:111], v[140:143], v[156:159], v[108:111]
	v_mfma_f32_16x16x32_bf16 v[92:95], v[116:119], v[164:167], v[92:95]
	v_mfma_f32_16x16x32_bf16 v[88:91], v[140:143], v[164:167], v[88:91]
	v_mfma_f32_16x16x32_bf16 v[76:79], v[116:119], v[172:175], v[76:79]
	v_mfma_f32_16x16x32_bf16 v[72:75], v[140:143], v[172:175], v[72:75]
	s_setprio 0
	s_barrier
	s_add_i32 s22, s41, s4
	v_lshl_add_u64 v[208:209], s[26:27], 0, v[186:187]
	s_mov_b32 m0, s22
	ds_read_b128 v[176:179], v237
	ds_read_b128 v[180:183], v237 offset:1024
	ds_read_b128 v[200:203], v237 offset:2048
	ds_read_b128 v[204:207], v237 offset:3072
	global_load_lds_dwordx4 v[208:209], off
	v_lshl_add_u64 v[210:211], s[26:27], 0, v[190:191]
	s_add_i32 m0, s22, 0x2000
	s_nop 0
	global_load_lds_dwordx4 v[210:211], off
	s_barrier
	s_waitcnt lgkmcnt(0)
	s_setprio 1
	v_mfma_f32_16x16x32_bf16 v[124:127], v[176:179], v[144:147], v[124:127]
	v_mfma_f32_16x16x32_bf16 v[120:123], v[200:203], v[144:147], v[120:123]
	v_mfma_f32_16x16x32_bf16 v[100:103], v[176:179], v[152:155], v[100:103]
	v_mfma_f32_16x16x32_bf16 v[96:99], v[200:203], v[152:155], v[96:99]
	v_mfma_f32_16x16x32_bf16 v[84:87], v[176:179], v[160:163], v[84:87]
	v_mfma_f32_16x16x32_bf16 v[80:83], v[200:203], v[160:163], v[80:83]
	v_mfma_f32_16x16x32_bf16 v[68:71], v[176:179], v[168:171], v[68:71]
	v_mfma_f32_16x16x32_bf16 v[64:67], v[200:203], v[168:171], v[64:67]
	v_mfma_f32_16x16x32_bf16 v[124:127], v[180:183], v[148:151], v[124:127]
	v_mfma_f32_16x16x32_bf16 v[120:123], v[204:207], v[148:151], v[120:123]
	v_mfma_f32_16x16x32_bf16 v[100:103], v[180:183], v[156:159], v[100:103]
	v_mfma_f32_16x16x32_bf16 v[96:99], v[204:207], v[156:159], v[96:99]
	v_mfma_f32_16x16x32_bf16 v[84:87], v[180:183], v[164:167], v[84:87]
	v_mfma_f32_16x16x32_bf16 v[80:83], v[204:207], v[164:167], v[80:83]
	v_mfma_f32_16x16x32_bf16 v[68:71], v[180:183], v[172:175], v[68:71]
	v_mfma_f32_16x16x32_bf16 v[64:67], v[204:207], v[172:175], v[64:67]
	s_setprio 0
	s_mov_b32 m0, s0
	v_lshl_add_u64 v[212:213], s[28:29], 0, v[184:185]
	s_barrier
	ds_read_b128 v[144:147], v236 offset:16384
	ds_read_b128 v[148:151], v236 offset:17408
	ds_read_b128 v[152:155], v236 offset:18432
	ds_read_b128 v[156:159], v236 offset:19456
	ds_read_b128 v[160:163], v236 offset:20480
	ds_read_b128 v[164:167], v236 offset:21504
	ds_read_b128 v[168:171], v236 offset:22528
	ds_read_b128 v[172:175], v236 offset:23552
	global_load_lds_dwordx4 v[212:213], off
	v_lshl_add_u64 v[214:215], s[28:29], 0, v[188:189]
	s_mov_b32 m0, s1
	s_nop 0
	global_load_lds_dwordx4 v[214:215], off
	s_barrier
	s_waitcnt lgkmcnt(0)
	s_setprio 1
	v_mfma_f32_16x16x32_bf16 v[60:63], v[104:107], v[144:147], v[60:63]
	v_mfma_f32_16x16x32_bf16 v[56:59], v[128:131], v[144:147], v[56:59]
	v_mfma_f32_16x16x32_bf16 v[44:47], v[104:107], v[152:155], v[44:47]
	v_mfma_f32_16x16x32_bf16 v[40:43], v[128:131], v[152:155], v[40:43]
	v_mfma_f32_16x16x32_bf16 v[28:31], v[104:107], v[160:163], v[28:31]
	v_mfma_f32_16x16x32_bf16 v[24:27], v[128:131], v[160:163], v[24:27]
	v_mfma_f32_16x16x32_bf16 v[12:15], v[104:107], v[168:171], v[12:15]
	v_mfma_f32_16x16x32_bf16 v[8:11], v[128:131], v[168:171], v[8:11]
	v_mfma_f32_16x16x32_bf16 v[60:63], v[116:119], v[148:151], v[60:63]
	v_mfma_f32_16x16x32_bf16 v[56:59], v[140:143], v[148:151], v[56:59]
	v_mfma_f32_16x16x32_bf16 v[44:47], v[116:119], v[156:159], v[44:47]
	v_mfma_f32_16x16x32_bf16 v[40:43], v[140:143], v[156:159], v[40:43]
	v_mfma_f32_16x16x32_bf16 v[28:31], v[116:119], v[164:167], v[28:31]
	v_mfma_f32_16x16x32_bf16 v[24:27], v[140:143], v[164:167], v[24:27]
	v_mfma_f32_16x16x32_bf16 v[12:15], v[116:119], v[172:175], v[12:15]
	v_mfma_f32_16x16x32_bf16 v[8:11], v[140:143], v[172:175], v[8:11]
	s_setprio 0
	s_barrier
; #define PG8_STAGE(bufoff, gbase, voff) do { _Pragma("unroll") for (int _i = 0; _i < 2; ++_i) \
;         __builtin_amdgcn_global_load_lds((const unsigned*)((const char*)(gbase) + (voff)[_i]), (LAS unsigned*)(lds + (bufoff) + ldsw + _i * 8192), 16, 0, 0); } while (0)
; #define PG8_LDA(dst, b, h) do { _Pragma("unroll") for (int m = 0; m < 4; ++m) _Pragma("unroll") for (int k = 0; k < 2; ++k) dst[m][k] = *(const LAS bf16x8*)(lds + PG8_SA(b, h) + aoff + m * 2048 + k * 1024); } while (0)
; #define PG8_LDB(dst, b, h) do { _Pragma("unroll") for (int n = 0; n < 2; ++n) _Pragma("unroll") for (int k = 0; k < 2; ++k) dst[n][k] = *(const LAS bf16x8*)(lds + PG8_SB(b, h) + boff + n * 2048 + k * 1024); } while (0)
; #define PG8_MMA(ai, bj, At, Bt) do { __builtin_amdgcn_s_setprio(1); _Pragma("unroll") for (int m = 0; m < 4; ++m) _Pragma("unroll") for (int n = 0; n < 2; ++n) _Pragma("unroll") for (int k = 0; k < 2; ++k) \
;         acc[ai][bj][m][n] = __builtin_amdgcn_mfma_f32_16x16x32_bf16(Bt[n][k], At[m][k], acc[ai][bj][m][n], 0, 0, 0); __builtin_amdgcn_s_setprio(0); } while (0)
; #define PG8_WAIT_V(n) asm volatile("s_waitcnt vmcnt(" #n ")" ::: "memory")
; #define PG8_WAIT_L(n) asm volatile("s_waitcnt lgkmcnt(" #n ")" ::: "memory")
; #define PG8_BAR __builtin_amdgcn_s_barrier()
; #define PG8_SCHED __builtin_amdgcn_sched_barrier(0)
; template <class Epi>
; __device__ __forceinline__ void gemm_phase(LAS unsigned char* lds, const GSched& S, const int K, const int lda, const int ldb, const Epi& E) {
;     ...
;             PG8_STAGE(PG8_SB(0, 1), b2 + hstepB, voffB);
;             PG8_WAIT_V(6); PG8_BAR; if constexpr (!Epi::NARROW) PG8_MMA(1, 1, At, B1); PG8_BAR;
;             PG8_LDB(B0, 1, 0); PG8_SCHED; PG8_LDA(At, 1, 0); PG8_STAGE(PG8_SA(0, 1), a2 + hstepA, voffA);
;             PG8_WAIT_L(8); PG8_BAR; PG8_WAIT_L(0); PG8_MMA(0, 0, At, B0); PG8_BAR; PG8_SCHED;
;             if constexpr (!Epi::NARROW) PG8_LDB(B1, 1, 1); PG8_STAGE(PG8_SB(1, 0), b3, voffB);
;             PG8_BAR; PG8_WAIT_L(0); if constexpr (!Epi::NARROW) PG8_MMA(0, 1, At, B1); PG8_BAR;
;             PG8_LDA(At, 1, 1); PG8_STAGE(PG8_SA(1, 0), a3, voffA);
;             PG8_BAR; PG8_WAIT_L(0); PG8_MMA(1, 0, At, B0); PG8_BAR; PG8_SCHED;
	s_add_u32 s22, s26, 0x164000
	s_addc_u32 s23, s27, 0
	s_add_i32 s51, s42, s4
	v_lshl_add_u64 v[104:105], s[22:23], 0, v[186:187]
	s_mov_b32 m0, s51
	s_nop 0
	global_load_lds_dwordx4 v[104:105], off
	v_lshl_add_u64 v[104:105], s[22:23], 0, v[190:191]
	s_add_i32 m0, s51, 0x2000
	s_nop 0
	global_load_lds_dwordx4 v[104:105], off
	s_waitcnt vmcnt(6)
	s_barrier
	s_setprio 1
	v_mfma_f32_16x16x32_bf16 v[52:55], v[176:179], v[144:147], v[52:55]
	v_mfma_f32_16x16x32_bf16 v[48:51], v[200:203], v[144:147], v[48:51]
	v_mfma_f32_16x16x32_bf16 v[36:39], v[176:179], v[152:155], v[36:39]
	v_mfma_f32_16x16x32_bf16 v[32:35], v[200:203], v[152:155], v[32:35]
	v_mfma_f32_16x16x32_bf16 v[20:23], v[176:179], v[160:163], v[20:23]
	v_mfma_f32_16x16x32_bf16 v[16:19], v[200:203], v[160:163], v[16:19]
	v_mfma_f32_16x16x32_bf16 v[4:7], v[176:179], v[168:171], v[4:7]
	v_mfma_f32_16x16x32_bf16 v[0:3], v[200:203], v[168:171], v[0:3]
	v_mfma_f32_16x16x32_bf16 v[52:55], v[180:183], v[148:151], v[52:55]
	v_mfma_f32_16x16x32_bf16 v[48:51], v[204:207], v[148:151], v[48:51]
	v_mfma_f32_16x16x32_bf16 v[36:39], v[180:183], v[156:159], v[36:39]
	v_mfma_f32_16x16x32_bf16 v[32:35], v[204:207], v[156:159], v[32:35]
	v_mfma_f32_16x16x32_bf16 v[20:23], v[180:183], v[164:167], v[20:23]
	v_mfma_f32_16x16x32_bf16 v[16:19], v[204:207], v[164:167], v[16:19]
	v_mfma_f32_16x16x32_bf16 v[4:7], v[180:183], v[172:175], v[4:7]
	v_mfma_f32_16x16x32_bf16 v[0:3], v[204:207], v[172:175], v[0:3]
	s_setprio 0
	s_add_i32 s51, 0, 0x18000
	v_add_u32_e32 v140, s51, v231
	s_barrier
	ds_read_b128 v[104:107], v140
	ds_read_b128 v[116:119], v140 offset:1024
	ds_read_b128 v[128:131], v140 offset:2048
	ds_read_b128 v[140:143], v140 offset:3072
	s_add_u32 s22, s28, 0x164000
	s_addc_u32 s23, s29, 0
	s_mov_b32 m0, s2
	v_lshl_add_u64 v[176:177], s[22:23], 0, v[184:185]
	ds_read_b128 v[144:147], v236 offset:32768
	ds_read_b128 v[148:151], v236 offset:33792
	ds_read_b128 v[152:155], v236 offset:34816
	ds_read_b128 v[156:159], v236 offset:35840
	ds_read_b128 v[160:163], v236 offset:36864
	ds_read_b128 v[164:167], v236 offset:37888
	ds_read_b128 v[168:171], v236 offset:38912
	ds_read_b128 v[172:175], v236 offset:39936
	global_load_lds_dwordx4 v[176:177], off
	v_lshl_add_u64 v[176:177], s[22:23], 0, v[188:189]
	s_mov_b32 m0, s5
	s_nop 0
	global_load_lds_dwordx4 v[176:177], off
	s_waitcnt lgkmcnt(8)
	s_barrier
	s_waitcnt lgkmcnt(0)
	s_setprio 1
	s_waitcnt lgkmcnt(0)
	v_mfma_f32_16x16x32_bf16 v[136:139], v[104:107], v[144:147], v[136:139]
	v_mfma_f32_16x16x32_bf16 v[132:135], v[128:131], v[144:147], v[132:135]
	v_mfma_f32_16x16x32_bf16 v[112:115], v[104:107], v[152:155], v[112:115]
	v_mfma_f32_16x16x32_bf16 v[108:111], v[128:131], v[152:155], v[108:111]
	v_mfma_f32_16x16x32_bf16 v[92:95], v[104:107], v[160:163], v[92:95]
	v_mfma_f32_16x16x32_bf16 v[88:91], v[128:131], v[160:163], v[88:91]
	v_mfma_f32_16x16x32_bf16 v[76:79], v[104:107], v[168:171], v[76:79]
	v_mfma_f32_16x16x32_bf16 v[72:75], v[128:131], v[168:171], v[72:75]
	v_mfma_f32_16x16x32_bf16 v[136:139], v[116:119], v[148:151], v[136:139]
	v_mfma_f32_16x16x32_bf16 v[132:135], v[140:143], v[148:151], v[132:135]
	v_mfma_f32_16x16x32_bf16 v[112:115], v[116:119], v[156:159], v[112:115]
	v_mfma_f32_16x16x32_bf16 v[108:111], v[140:143], v[156:159], v[108:111]
	v_mfma_f32_16x16x32_bf16 v[92:95], v[116:119], v[164:167], v[92:95]
	v_mfma_f32_16x16x32_bf16 v[88:91], v[140:143], v[164:167], v[88:91]
	v_mfma_f32_16x16x32_bf16 v[76:79], v[116:119], v[172:175], v[76:79]
	v_mfma_f32_16x16x32_bf16 v[72:75], v[140:143], v[172:175], v[72:75]
	s_setprio 0
	s_barrier
	s_add_i32 s28, 0, 0x1c000
	s_add_i32 s22, s51, s4
	v_add_u32_e32 v204, s28, v231
	v_lshl_add_u64 v[208:209], v[208:209], 0, s[20:21]
	s_mov_b32 m0, s22
	ds_read_b128 v[176:179], v204
	ds_read_b128 v[180:183], v204 offset:1024
	ds_read_b128 v[200:203], v204 offset:2048
	ds_read_b128 v[204:207], v204 offset:3072
	global_load_lds_dwordx4 v[208:209], off
	v_lshl_add_u64 v[208:209], v[210:211], 0, s[20:21]
	s_add_i32 m0, s22, 0x2000
	s_nop 0
	global_load_lds_dwordx4 v[208:209], off
	s_barrier
	s_waitcnt lgkmcnt(0)
	s_setprio 1
	s_waitcnt lgkmcnt(0)
	v_mfma_f32_16x16x32_bf16 v[124:127], v[176:179], v[144:147], v[124:127]
	v_mfma_f32_16x16x32_bf16 v[120:123], v[200:203], v[144:147], v[120:123]
	v_mfma_f32_16x16x32_bf16 v[100:103], v[176:179], v[152:155], v[100:103]
	v_mfma_f32_16x16x32_bf16 v[96:99], v[200:203], v[152:155], v[96:99]
	v_mfma_f32_16x16x32_bf16 v[84:87], v[176:179], v[160:163], v[84:87]
	v_mfma_f32_16x16x32_bf16 v[80:83], v[200:203], v[160:163], v[80:83]
	v_mfma_f32_16x16x32_bf16 v[68:71], v[176:179], v[168:171], v[68:71]
	v_mfma_f32_16x16x32_bf16 v[64:67], v[200:203], v[168:171], v[64:67]
	v_mfma_f32_16x16x32_bf16 v[124:127], v[180:183], v[148:151], v[124:127]
	v_mfma_f32_16x16x32_bf16 v[120:123], v[204:207], v[148:151], v[120:123]
	v_mfma_f32_16x16x32_bf16 v[100:103], v[180:183], v[156:159], v[100:103]
	v_mfma_f32_16x16x32_bf16 v[96:99], v[204:207], v[156:159], v[96:99]
	v_mfma_f32_16x16x32_bf16 v[84:87], v[180:183], v[164:167], v[84:87]
	v_mfma_f32_16x16x32_bf16 v[80:83], v[204:207], v[164:167], v[80:83]
	v_mfma_f32_16x16x32_bf16 v[68:71], v[180:183], v[172:175], v[68:71]
	v_mfma_f32_16x16x32_bf16 v[64:67], v[204:207], v[172:175], v[64:67]
	s_setprio 0
	s_mov_b32 m0, s36
	v_lshl_add_u64 v[208:209], v[212:213], 0, s[20:21]
	s_barrier
	ds_read_b128 v[144:147], v236 offset:49152
	ds_read_b128 v[148:151], v236 offset:50176
	ds_read_b128 v[152:155], v236 offset:51200
	ds_read_b128 v[156:159], v236 offset:52224
	ds_read_b128 v[160:163], v236 offset:53248
	ds_read_b128 v[164:167], v236 offset:54272
	ds_read_b128 v[168:171], v236 offset:55296
	ds_read_b128 v[172:175], v236 offset:56320
	global_load_lds_dwordx4 v[208:209], off
	v_lshl_add_u64 v[208:209], v[214:215], 0, s[20:21]
	s_mov_b32 m0, s37
	s_nop 0
	global_load_lds_dwordx4 v[208:209], off
	s_barrier
; #define PG8_STAGE(bufoff, gbase, voff) do { _Pragma("unroll") for (int _i = 0; _i < 2; ++_i) \
;         __builtin_amdgcn_global_load_lds((const unsigned*)((const char*)(gbase) + (voff)[_i]), (LAS unsigned*)(lds + (bufoff) + ldsw + _i * 8192), 16, 0, 0); } while (0)
; #define PG8_LDA(dst, b, h) do { _Pragma("unroll") for (int m = 0; m < 4; ++m) _Pragma("unroll") for (int k = 0; k < 2; ++k) dst[m][k] = *(const LAS bf16x8*)(lds + PG8_SA(b, h) + aoff + m * 2048 + k * 1024); } while (0)
; #define PG8_MMA(ai, bj, At, Bt) do { __builtin_amdgcn_s_setprio(1); _Pragma("unroll") for (int m = 0; m < 4; ++m) _Pragma("unroll") for (int n = 0; n < 2; ++n) _Pragma("unroll") for (int k = 0; k < 2; ++k) \
;         acc[ai][bj][m][n] = __builtin_amdgcn_mfma_f32_16x16x32_bf16(Bt[n][k], At[m][k], acc[ai][bj][m][n], 0, 0, 0); __builtin_amdgcn_s_setprio(0); } while (0)
; #define PG8_WAIT_V(n) asm volatile("s_waitcnt vmcnt(" #n ")" ::: "memory")
; #define PG8_WAIT_L(n) asm volatile("s_waitcnt lgkmcnt(" #n ")" ::: "memory")
; #define PG8_BAR __builtin_amdgcn_s_barrier()
; #define PG8_SCHED __builtin_amdgcn_sched_barrier(0)
; template <class Epi>
; __device__ __forceinline__ void gemm_phase(LAS unsigned char* lds, const GSched& S, const int K, const int lda, const int ldb, const Epi& E) {
;     ...
;             PG8_LDA(At, 1, 1); PG8_STAGE(PG8_SA(1, 0), a3, voffA);
;             PG8_BAR; PG8_WAIT_L(0); PG8_MMA(1, 0, At, B0); PG8_BAR; PG8_SCHED;
;             PG8_STAGE(PG8_SB(1, 1), b3 + hstepB, voffB);
;             PG8_WAIT_V(6); PG8_BAR; if constexpr (!Epi::NARROW) PG8_MMA(1, 1, At, B1); PG8_BAR;
	s_waitcnt lgkmcnt(0)
	s_setprio 1
	v_mfma_f32_16x16x32_bf16 v[60:63], v[104:107], v[144:147], v[60:63]
	v_mfma_f32_16x16x32_bf16 v[56:59], v[128:131], v[144:147], v[56:59]
	v_mfma_f32_16x16x32_bf16 v[44:47], v[104:107], v[152:155], v[44:47]
	v_mfma_f32_16x16x32_bf16 v[40:43], v[128:131], v[152:155], v[40:43]
	v_mfma_f32_16x16x32_bf16 v[28:31], v[104:107], v[160:163], v[28:31]
	v_mfma_f32_16x16x32_bf16 v[24:27], v[128:131], v[160:163], v[24:27]
	v_mfma_f32_16x16x32_bf16 v[12:15], v[104:107], v[168:171], v[12:15]
	v_mfma_f32_16x16x32_bf16 v[8:11], v[128:131], v[168:171], v[8:11]
	v_mfma_f32_16x16x32_bf16 v[60:63], v[116:119], v[148:151], v[60:63]
	v_mfma_f32_16x16x32_bf16 v[56:59], v[140:143], v[148:151], v[56:59]
	v_mfma_f32_16x16x32_bf16 v[44:47], v[116:119], v[156:159], v[44:47]
	v_mfma_f32_16x16x32_bf16 v[40:43], v[140:143], v[156:159], v[40:43]
	v_mfma_f32_16x16x32_bf16 v[28:31], v[116:119], v[164:167], v[28:31]
	v_mfma_f32_16x16x32_bf16 v[24:27], v[140:143], v[164:167], v[24:27]
	v_mfma_f32_16x16x32_bf16 v[12:15], v[116:119], v[172:175], v[12:15]
	v_mfma_f32_16x16x32_bf16 v[8:11], v[140:143], v[172:175], v[8:11]
	s_setprio 0
	s_barrier
	s_add_u32 s22, s26, 0x164080
	s_addc_u32 s23, s27, 0
	s_add_i32 s26, s28, s4
	v_lshl_add_u64 v[104:105], s[22:23], 0, v[186:187]
	s_mov_b32 m0, s26
	s_nop 0
	global_load_lds_dwordx4 v[104:105], off
	v_lshl_add_u64 v[104:105], s[22:23], 0, v[190:191]
	s_add_i32 m0, s26, 0x2000
	s_nop 0
	global_load_lds_dwordx4 v[104:105], off
	s_waitcnt vmcnt(6)
	s_barrier
	s_setprio 1
	v_mfma_f32_16x16x32_bf16 v[52:55], v[176:179], v[144:147], v[52:55]
	v_mfma_f32_16x16x32_bf16 v[48:51], v[200:203], v[144:147], v[48:51]
	v_mfma_f32_16x16x32_bf16 v[36:39], v[176:179], v[152:155], v[36:39]
	v_mfma_f32_16x16x32_bf16 v[32:35], v[200:203], v[152:155], v[32:35]
	v_mfma_f32_16x16x32_bf16 v[20:23], v[176:179], v[160:163], v[20:23]
	v_mfma_f32_16x16x32_bf16 v[16:19], v[200:203], v[160:163], v[16:19]
	v_mfma_f32_16x16x32_bf16 v[4:7], v[176:179], v[168:171], v[4:7]
	v_mfma_f32_16x16x32_bf16 v[0:3], v[200:203], v[168:171], v[0:3]
	v_mfma_f32_16x16x32_bf16 v[52:55], v[180:183], v[148:151], v[52:55]
	v_mfma_f32_16x16x32_bf16 v[48:51], v[204:207], v[148:151], v[48:51]
	v_mfma_f32_16x16x32_bf16 v[36:39], v[180:183], v[156:159], v[36:39]
	v_mfma_f32_16x16x32_bf16 v[32:35], v[204:207], v[156:159], v[32:35]
	v_mfma_f32_16x16x32_bf16 v[20:23], v[180:183], v[164:167], v[20:23]
	v_mfma_f32_16x16x32_bf16 v[16:19], v[204:207], v[164:167], v[16:19]
	v_mfma_f32_16x16x32_bf16 v[4:7], v[180:183], v[172:175], v[4:7]
	v_mfma_f32_16x16x32_bf16 v[0:3], v[204:207], v[172:175], v[0:3]
	s_setprio 0
	s_add_i32 s50, s50, 2
	s_add_u32 s48, s48, 0x100
	s_addc_u32 s49, s49, 0
	s_cmpk_gt_u32 s50, 0x55
	s_mov_b64 s[22:23], s[24:25]
	s_barrier
	s_cbranch_scc0 .LBB0_1107
; __device__ __forceinline__ float sumsq4(const f32x4 v) { return (v[0] * v[0] + v[1] * v[1]) + (v[2] * v[2] + v[3] * v[3]); }
; __device__ __forceinline__ u32x4 pack8(const f32x4 a, const f32x4 b) { u32x4 w; w.x = cvt_pk_bf16(a[0], a[1]); w.y = cvt_pk_bf16(a[2], a[3]); w.z = cvt_pk_bf16(b[0], b[1]); w.w = cvt_pk_bf16(b[2], b[3]); return w; }
; __device__ __forceinline__ void unpack8(const u32x4 w, f32x4& a, f32x4& b) { a = (f32x4){bf_lo(w.x), bf_hi(w.x), bf_lo(w.y), bf_hi(w.y)}; b = (f32x4){bf_lo(w.z), bf_hi(w.z), bf_lo(w.w), bf_hi(w.w)}; }
;     __device__ __forceinline__ void operator()(Acc& acc, const Unit& u, int wr, int wc, int fr, int fq, const float (&rsv)[8]) const {
;     ...
;             u32x4 w[8][2];
; #pragma unroll
;             for (int g = 0; g < 8; ++g)
; #pragma unroll
;                 for (int bj = 0; bj < 2; ++bj) w[g][bj] = *(const u32x4*)(hb + (size_t)(row0 + (g >> 2) * HALF + (g & 3) * 16) * LDHB + 256 + col0 + bj * HALF);
; #pragma unroll
;             for (int g = 0; g < 8; ++g) {
;                 const int ai = g >> 2, m = g & 3;
;                 const int row = row0 + ai * HALF + m * 16;
;                 float ss = 0.f;
; #pragma unroll
;                 for (int bj = 0; bj < 2; ++bj) { f32x4 h0, h1; unpack8(w[g][bj], h0, h1);
;                     const f32x4 v0 = h0 + acc[ai][bj][m][0] * scale, v1 = h1 + acc[ai][bj][m][1] * scale;
;                     ss += sumsq4(v0) + sumsq4(v1);
;                     *(u32x4*)(hb + (size_t)row * LDHB + 256 + col0 + bj * HALF) = pack8(v0, v1); }
;                 ss += __shfl_xor(ss, 16); ss += __shfl_xor(ss, 32);
;                 if (fq == 0) part[(size_t)row * 32 + u.pn * 4 + wc] = ss;
;             }
	v_lshl_or_b32 v104, s14, 8, v234
	v_lshl_add_u32 v228, s47, 8, v230
	v_ashrrev_i32_e32 v105, 31, v104
	v_mov_b64_e32 v[106:107], s[16:17]
	v_mad_i64_i32 v[116:117], s[22:23], v228, s43, v[106:107]
	v_lshlrev_b64 v[104:105], 1, v[104:105]
	v_lshl_add_u64 v[232:233], v[116:117], 0, v[104:105]
	global_load_dwordx4 v[240:243], v[232:233], off offset:512
	global_load_dwordx4 v[244:247], v[232:233], off offset:768
	v_or_b32_e32 v224, 16, v228
	v_or_b32_e32 v220, 32, v228
	v_or_b32_e32 v216, 48, v228
	v_add_u32_e32 v212, 0x80, v228
	v_add_u32_e32 v208, 0x90, v228
	v_add_u32_e32 v204, 0xa0, v228
	v_add_u32_e32 v200, 0xb0, v228
	v_mad_i64_i32 v[116:117], s[22:23], v224, s43, v[106:107]
	v_mad_i64_i32 v[118:119], s[22:23], v220, s43, v[106:107]
	v_mad_i64_i32 v[128:129], s[22:23], v216, s43, v[106:107]
	v_mad_i64_i32 v[130:131], s[22:23], v212, s43, v[106:107]
	v_mad_i64_i32 v[140:141], s[22:23], v208, s43, v[106:107]
	v_mad_i64_i32 v[142:143], s[22:23], v204, s43, v[106:107]
	v_mad_i64_i32 v[106:107], s[22:23], v200, s43, v[106:107]
	v_lshl_add_u64 v[226:227], v[116:117], 0, v[104:105]
	v_lshl_add_u64 v[222:223], v[118:119], 0, v[104:105]
	v_lshl_add_u64 v[218:219], v[128:129], 0, v[104:105]
	v_lshl_add_u64 v[214:215], v[130:131], 0, v[104:105]
	v_lshl_add_u64 v[210:211], v[140:141], 0, v[104:105]
	v_lshl_add_u64 v[206:207], v[142:143], 0, v[104:105]
	v_lshl_add_u64 v[202:203], v[106:107], 0, v[104:105]
	global_load_dwordx4 v[180:183], v[226:227], off offset:512
	global_load_dwordx4 v[176:179], v[226:227], off offset:768
	global_load_dwordx4 v[172:175], v[222:223], off offset:512
	global_load_dwordx4 v[168:171], v[222:223], off offset:768
	global_load_dwordx4 v[164:167], v[218:219], off offset:512
	global_load_dwordx4 v[160:163], v[218:219], off offset:768
	global_load_dwordx4 v[156:159], v[214:215], off offset:512
	global_load_dwordx4 v[152:155], v[214:215], off offset:768
	global_load_dwordx4 v[148:151], v[210:211], off offset:512
	global_load_dwordx4 v[144:147], v[210:211], off offset:768
	global_load_dwordx4 v[140:143], v[206:207], off offset:512
	global_load_dwordx4 v[128:131], v[206:207], off offset:768
	global_load_dwordx4 v[116:119], v[202:203], off offset:512
	global_load_dwordx4 v[104:107], v[202:203], off offset:768
	v_and_b32_e32 v205, 64, v238
	v_xor_b32_e32 v201, 16, v238
	v_add_u32_e32 v205, 64, v205
	v_xor_b32_e32 v209, 32, v238
	v_cmp_lt_i32_e32 vcc, v201, v205
	s_lshl_b32 s22, s14, 2
	s_ashr_i32 s23, s22, 31
	v_cndmask_b32_e32 v201, v238, v201, vcc
	v_cmp_lt_i32_e32 vcc, v209, v205
	v_lshlrev_b32_e32 v239, 2, v201
	s_waitcnt vmcnt(0)
	v_lshlrev_b32_e32 v248, 16, v240
	v_and_b32_e32 v249, 0xffff0000, v240
	v_lshlrev_b32_e32 v240, 16, v241
	v_and_b32_e32 v241, 0xffff0000, v241
	v_lshlrev_b32_e32 v250, 16, v242
	v_and_b32_e32 v251, 0xffff0000, v242
	v_lshlrev_b32_e32 v242, 16, v243
	v_and_b32_e32 v243, 0xffff0000, v243
	v_cndmask_b32_e32 v205, v238, v209, vcc
	v_pk_fma_f32 v[138:139], v[138:139], 0.5, v[240:241] op_sel_hi:[1,0,1]
	v_pk_fma_f32 v[136:137], v[136:137], 0.5, v[248:249] op_sel_hi:[1,0,1]
	v_pk_fma_f32 v[240:241], v[134:135], 0.5, v[242:243] op_sel_hi:[1,0,1]
	v_pk_fma_f32 v[134:135], v[132:133], 0.5, v[250:251] op_sel_hi:[1,0,1]
	v_lshlrev_b32_e32 v201, 2, v205
	v_mul_f32_e32 v205, v137, v137
	v_mul_f32_e32 v209, v139, v139
	v_mul_f32_e32 v213, v135, v135
	v_mul_f32_e32 v217, v241, v241
	v_fmac_f32_e32 v205, v136, v136
	v_fmac_f32_e32 v209, v138, v138
	v_fmac_f32_e32 v213, v134, v134
	v_fmac_f32_e32 v217, v240, v240
	v_cvt_pk_bf16_f32 v132, v136, v137
	v_add_f32_e32 v136, v205, v209
	v_add_f32_e32 v137, v213, v217
	v_lshlrev_b32_e32 v252, 16, v244
	v_add_f32_e32 v205, v136, v137
	v_and_b32_e32 v253, 0xffff0000, v244
	v_lshlrev_b32_e32 v136, 16, v245
	v_and_b32_e32 v137, 0xffff0000, v245
	v_cvt_pk_bf16_f32 v133, v138, v139
	v_lshlrev_b32_e32 v138, 16, v246
	v_and_b32_e32 v139, 0xffff0000, v246
	v_pk_fma_f32 v[126:127], v[126:127], 0.5, v[136:137] op_sel_hi:[1,0,1]
	v_pk_fma_f32 v[124:125], v[124:125], 0.5, v[252:253] op_sel_hi:[1,0,1]
	v_lshlrev_b32_e32 v242, 16, v247
	v_and_b32_e32 v243, 0xffff0000, v247
	v_pk_fma_f32 v[138:139], v[120:121], 0.5, v[138:139] op_sel_hi:[1,0,1]
	v_mul_f32_e32 v120, v125, v125
	v_mul_f32_e32 v121, v127, v127
	v_pk_fma_f32 v[136:137], v[122:123], 0.5, v[242:243] op_sel_hi:[1,0,1]
	v_fmac_f32_e32 v120, v124, v124
	v_fmac_f32_e32 v121, v126, v126
	v_add_f32_e32 v120, v120, v121
	v_mul_f32_e32 v121, v139, v139
	v_mul_f32_e32 v122, v137, v137
	v_fmac_f32_e32 v121, v138, v138
	v_fmac_f32_e32 v122, v136, v136
	v_add_f32_e32 v121, v121, v122
	v_add_f32_e32 v120, v120, v121
	v_add_f32_e32 v120, v205, v120
	ds_bpermute_b32 v121, v239, v120
	v_cvt_pk_bf16_f32 v134, v134, v135
	v_cvt_pk_bf16_f32 v135, v240, v241
	v_cvt_pk_bf16_f32 v122, v124, v125
	v_cvt_pk_bf16_f32 v123, v126, v127
	s_waitcnt lgkmcnt(0)
	v_add_f32_e32 v120, v120, v121
	ds_bpermute_b32 v121, v201, v120
	v_cvt_pk_bf16_f32 v124, v138, v139
	v_cvt_pk_bf16_f32 v125, v136, v137
	global_store_dwordx4 v[232:233], v[132:135], off offset:512
	global_store_dwordx4 v[232:233], v[122:125], off offset:768
	s_and_saveexec_b64 s[24:25], s[6:7]
	s_cbranch_execz .LBB0_1110
	v_ashrrev_i32_e32 v229, 31, v228
	v_lshlrev_b64 v[122:123], 7, v[228:229]
	v_lshl_add_u64 v[122:123], s[18:19], 0, v[122:123]
	v_lshl_add_u64 v[122:123], s[22:23], 2, v[122:123]
	s_lshl_b32 s14, s35, 2
	v_lshl_add_u64 v[122:123], v[122:123], 0, s[14:15]
	s_waitcnt lgkmcnt(0)
	v_add_f32_e32 v120, v120, v121
	global_store_dword v[122:123], v120, off

; #define PG8_STAGE(bufoff, gbase, voff) do { _Pragma("unroll") for (int _i = 0; _i < 2; ++_i) \
;         __builtin_amdgcn_global_load_lds((const unsigned*)((const char*)(gbase) + (voff)[_i]), (LAS unsigned*)(lds + (bufoff) + ldsw + _i * 8192), 16, 0, 0); } while (0)
; #define PG8_LDA(dst, b, h) do { _Pragma("unroll") for (int m = 0; m < 4; ++m) _Pragma("unroll") for (int k = 0; k < 2; ++k) dst[m][k] = *(const LAS bf16x8*)(lds + PG8_SA(b, h) + aoff + m * 2048 + k * 1024); } while (0)
; #define PG8_LDB(dst, b, h) do { _Pragma("unroll") for (int n = 0; n < 2; ++n) _Pragma("unroll") for (int k = 0; k < 2; ++k) dst[n][k] = *(const LAS bf16x8*)(lds + PG8_SB(b, h) + boff + n * 2048 + k * 1024); } while (0)
; #define PG8_MMA(ai, bj, At, Bt) do { __builtin_amdgcn_s_setprio(1); _Pragma("unroll") for (int m = 0; m < 4; ++m) _Pragma("unroll") for (int n = 0; n < 2; ++n) _Pragma("unroll") for (int k = 0; k < 2; ++k) \
;         acc[ai][bj][m][n] = __builtin_amdgcn_mfma_f32_16x16x32_bf16(Bt[n][k], At[m][k], acc[ai][bj][m][n], 0, 0, 0); __builtin_amdgcn_s_setprio(0); } while (0)
; template <class Epi>
; __device__ __forceinline__ void gemm_phase(LAS unsigned char* lds, const GSched& S, const int K, const int lda, const int ldb, const Epi& E) {
;     ...
;             PG8_LDB(B0, 0, 0); PG8_SCHED; PG8_LDA(At, 0, 0); PG8_STAGE(PG8_SA(1, 1), a1 + hstepA, voffA);
;             PG8_WAIT_L(8); PG8_BAR; PG8_WAIT_L(0); PG8_MMA(0, 0, At, B0); PG8_BAR; PG8_SCHED;
;             if constexpr (!Epi::NARROW) PG8_LDB(B1, 0, 1); PG8_STAGE(PG8_SB(0, 0), b2, voffB);
;             PG8_BAR; PG8_WAIT_L(0); if constexpr (!Epi::NARROW) PG8_MMA(0, 1, At, B1); PG8_BAR;
;             PG8_LDA(At, 0, 1); PG8_STAGE(PG8_SA(0, 0), a2, voffA);
;             PG8_BAR; PG8_WAIT_L(0); PG8_MMA(1, 0, At, B0); PG8_BAR; PG8_SCHED;
;             PG8_STAGE(PG8_SB(0, 1), b2 + hstepB, voffB);
;             PG8_WAIT_V(6); PG8_BAR; if constexpr (!Epi::NARROW) PG8_MMA(1, 1, At, B1); PG8_BAR;
;             PG8_LDB(B0, 1, 0); PG8_SCHED; PG8_LDA(At, 1, 0); PG8_STAGE(PG8_SA(0, 1), a2 + hstepA, voffA);
;             PG8_WAIT_L(8); PG8_BAR; PG8_WAIT_L(0); PG8_MMA(0, 0, At, B0); PG8_BAR; PG8_SCHED;
;             if constexpr (!Epi::NARROW) PG8_LDB(B1, 1, 1); PG8_STAGE(PG8_SB(1, 0), b3, voffB);
;             PG8_BAR; PG8_WAIT_L(0); if constexpr (!Epi::NARROW) PG8_MMA(0, 1, At, B1); PG8_BAR;
.LBB0_1202:
	ds_read_b128 v[132:135], v241
	ds_read_b128 v[136:139], v241 offset:1024
	ds_read_b128 v[140:143], v241 offset:2048
	ds_read_b128 v[144:147], v241 offset:3072
	s_add_u32 s42, s2, s40
	s_addc_u32 s43, s24, s41
	s_add_u32 s75, s0, s40
	s_addc_u32 s76, s1, s41
	s_cmpk_eq_i32 s40, 0x1100
	s_cselect_b32 s44, s36, s42
	s_cselect_b32 s42, s8, s75
	s_cselect_b32 s45, s37, s43
	s_cselect_b32 s43, s9, s76
	v_lshl_add_u64 v[126:127], v[124:125], 0, s[40:41]
	s_add_i32 m0, s48, 0xc000
	ds_read_b128 v[152:155], v240
	ds_read_b128 v[156:159], v240 offset:1024
	ds_read_b128 v[160:163], v240 offset:2048
	ds_read_b128 v[164:167], v240 offset:3072
	ds_read_b128 v[168:171], v240 offset:4096
	ds_read_b128 v[172:175], v240 offset:5120
	ds_read_b128 v[176:179], v240 offset:6144
	ds_read_b128 v[180:183], v240 offset:7168
	global_load_lds_dwordx4 v[126:127], off
	v_lshl_add_u64 v[126:127], v[122:123], 0, s[40:41]
	s_add_i32 m0, s48, 0xe000
	s_nop 0
	global_load_lds_dwordx4 v[126:127], off
	s_waitcnt lgkmcnt(8)
	s_barrier
	s_waitcnt lgkmcnt(0)
	s_setprio 1
	v_mfma_f32_16x16x32_bf16 v[148:151], v[132:135], v[152:155], v[148:151]
	v_mfma_f32_16x16x32_bf16 v[126:129], v[140:143], v[152:155], v[128:131]
	v_mfma_f32_16x16x32_bf16 v[108:111], v[132:135], v[160:163], v[108:111]
	v_mfma_f32_16x16x32_bf16 v[104:107], v[140:143], v[160:163], v[104:107]
	v_mfma_f32_16x16x32_bf16 v[92:95], v[132:135], v[168:171], v[92:95]
	v_mfma_f32_16x16x32_bf16 v[88:91], v[140:143], v[168:171], v[88:91]
	v_mfma_f32_16x16x32_bf16 v[76:79], v[132:135], v[176:179], v[76:79]
	v_mfma_f32_16x16x32_bf16 v[72:75], v[140:143], v[176:179], v[72:75]
	v_mfma_f32_16x16x32_bf16 v[148:151], v[136:139], v[156:159], v[148:151]
	v_mfma_f32_16x16x32_bf16 v[126:129], v[144:147], v[156:159], v[126:129]
	v_mfma_f32_16x16x32_bf16 v[108:111], v[136:139], v[164:167], v[108:111]
	v_mfma_f32_16x16x32_bf16 v[104:107], v[144:147], v[164:167], v[104:107]
	v_mfma_f32_16x16x32_bf16 v[92:95], v[136:139], v[172:175], v[92:95]
	v_mfma_f32_16x16x32_bf16 v[88:91], v[144:147], v[172:175], v[88:91]
	v_mfma_f32_16x16x32_bf16 v[76:79], v[136:139], v[180:183], v[76:79]
	v_mfma_f32_16x16x32_bf16 v[72:75], v[144:147], v[180:183], v[72:75]
	s_setprio 0
	s_barrier
	s_add_i32 s75, s63, s47
	v_lshl_add_u64 v[212:213], s[42:43], 0, v[194:195]
	s_mov_b32 m0, s75
	ds_read_b128 v[184:187], v242
	ds_read_b128 v[188:191], v242 offset:1024
	ds_read_b128 v[216:219], v242 offset:2048
	ds_read_b128 v[220:223], v242 offset:3072
	global_load_lds_dwordx4 v[212:213], off
	v_lshl_add_u64 v[224:225], s[42:43], 0, v[198:199]
	s_add_i32 m0, s75, 0x2000
	s_nop 0
	global_load_lds_dwordx4 v[224:225], off
	s_barrier
	s_waitcnt lgkmcnt(0)
	s_setprio 1
	v_mfma_f32_16x16x32_bf16 v[116:119], v[184:187], v[152:155], v[116:119]
	v_mfma_f32_16x16x32_bf16 v[112:115], v[216:219], v[152:155], v[112:115]
	v_mfma_f32_16x16x32_bf16 v[100:103], v[184:187], v[160:163], v[100:103]
	v_mfma_f32_16x16x32_bf16 v[96:99], v[216:219], v[160:163], v[96:99]
	v_mfma_f32_16x16x32_bf16 v[84:87], v[184:187], v[168:171], v[84:87]
	v_mfma_f32_16x16x32_bf16 v[80:83], v[216:219], v[168:171], v[80:83]
	v_mfma_f32_16x16x32_bf16 v[68:71], v[184:187], v[176:179], v[68:71]
	v_mfma_f32_16x16x32_bf16 v[64:67], v[216:219], v[176:179], v[64:67]
	v_mfma_f32_16x16x32_bf16 v[116:119], v[188:191], v[156:159], v[116:119]
	v_mfma_f32_16x16x32_bf16 v[112:115], v[220:223], v[156:159], v[112:115]
	v_mfma_f32_16x16x32_bf16 v[100:103], v[188:191], v[164:167], v[100:103]
	v_mfma_f32_16x16x32_bf16 v[96:99], v[220:223], v[164:167], v[96:99]
	v_mfma_f32_16x16x32_bf16 v[84:87], v[188:191], v[172:175], v[84:87]
	v_mfma_f32_16x16x32_bf16 v[80:83], v[220:223], v[172:175], v[80:83]
	v_mfma_f32_16x16x32_bf16 v[68:71], v[188:191], v[180:183], v[68:71]
	v_mfma_f32_16x16x32_bf16 v[64:67], v[220:223], v[180:183], v[64:67]
	s_setprio 0
	s_mov_b32 m0, s48
	v_lshl_add_u64 v[226:227], s[44:45], 0, v[192:193]
	s_barrier
	ds_read_b128 v[152:155], v240 offset:16384
	ds_read_b128 v[156:159], v240 offset:17408
	ds_read_b128 v[160:163], v240 offset:18432
	ds_read_b128 v[164:167], v240 offset:19456
	ds_read_b128 v[168:171], v240 offset:20480
	ds_read_b128 v[172:175], v240 offset:21504
	ds_read_b128 v[176:179], v240 offset:22528
	ds_read_b128 v[180:183], v240 offset:23552
	global_load_lds_dwordx4 v[226:227], off
	v_lshl_add_u64 v[228:229], s[44:45], 0, v[196:197]
	s_mov_b32 m0, s49
	s_nop 0
	global_load_lds_dwordx4 v[228:229], off
	s_barrier
	s_waitcnt lgkmcnt(0)
	s_setprio 1
	v_mfma_f32_16x16x32_bf16 v[60:63], v[132:135], v[152:155], v[60:63]
	v_mfma_f32_16x16x32_bf16 v[56:59], v[140:143], v[152:155], v[56:59]
	v_mfma_f32_16x16x32_bf16 v[44:47], v[132:135], v[160:163], v[44:47]
	v_mfma_f32_16x16x32_bf16 v[40:43], v[140:143], v[160:163], v[40:43]
	v_mfma_f32_16x16x32_bf16 v[28:31], v[132:135], v[168:171], v[28:31]
	v_mfma_f32_16x16x32_bf16 v[24:27], v[140:143], v[168:171], v[24:27]
	v_mfma_f32_16x16x32_bf16 v[12:15], v[132:135], v[176:179], v[12:15]
	v_mfma_f32_16x16x32_bf16 v[8:11], v[140:143], v[176:179], v[8:11]
	v_mfma_f32_16x16x32_bf16 v[60:63], v[136:139], v[156:159], v[60:63]
	v_mfma_f32_16x16x32_bf16 v[56:59], v[144:147], v[156:159], v[56:59]
	v_mfma_f32_16x16x32_bf16 v[44:47], v[136:139], v[164:167], v[44:47]
	v_mfma_f32_16x16x32_bf16 v[40:43], v[144:147], v[164:167], v[40:43]
	v_mfma_f32_16x16x32_bf16 v[28:31], v[136:139], v[172:175], v[28:31]
	v_mfma_f32_16x16x32_bf16 v[24:27], v[144:147], v[172:175], v[24:27]
	v_mfma_f32_16x16x32_bf16 v[12:15], v[136:139], v[180:183], v[12:15]
	v_mfma_f32_16x16x32_bf16 v[8:11], v[144:147], v[180:183], v[8:11]
	s_setprio 0
	s_barrier
; #define PG8_STAGE(bufoff, gbase, voff) do { _Pragma("unroll") for (int _i = 0; _i < 2; ++_i) \
;         __builtin_amdgcn_global_load_lds((const unsigned*)((const char*)(gbase) + (voff)[_i]), (LAS unsigned*)(lds + (bufoff) + ldsw + _i * 8192), 16, 0, 0); } while (0)
; #define PG8_LDA(dst, b, h) do { _Pragma("unroll") for (int m = 0; m < 4; ++m) _Pragma("unroll") for (int k = 0; k < 2; ++k) dst[m][k] = *(const LAS bf16x8*)(lds + PG8_SA(b, h) + aoff + m * 2048 + k * 1024); } while (0)
; #define PG8_LDB(dst, b, h) do { _Pragma("unroll") for (int n = 0; n < 2; ++n) _Pragma("unroll") for (int k = 0; k < 2; ++k) dst[n][k] = *(const LAS bf16x8*)(lds + PG8_SB(b, h) + boff + n * 2048 + k * 1024); } while (0)
; #define PG8_MMA(ai, bj, At, Bt) do { __builtin_amdgcn_s_setprio(1); _Pragma("unroll") for (int m = 0; m < 4; ++m) _Pragma("unroll") for (int n = 0; n < 2; ++n) _Pragma("unroll") for (int k = 0; k < 2; ++k) \
;         acc[ai][bj][m][n] = __builtin_amdgcn_mfma_f32_16x16x32_bf16(Bt[n][k], At[m][k], acc[ai][bj][m][n], 0, 0, 0); __builtin_amdgcn_s_setprio(0); } while (0)
; #define PG8_WAIT_V(n) asm volatile("s_waitcnt vmcnt(" #n ")" ::: "memory")
; #define PG8_WAIT_L(n) asm volatile("s_waitcnt lgkmcnt(" #n ")" ::: "memory")
; #define PG8_BAR __builtin_amdgcn_s_barrier()
; #define PG8_SCHED __builtin_amdgcn_sched_barrier(0)
; template <class Epi>
; __device__ __forceinline__ void gemm_phase(LAS unsigned char* lds, const GSched& S, const int K, const int lda, const int ldb, const Epi& E) {
;     ...
;             PG8_STAGE(PG8_SB(0, 1), b2 + hstepB, voffB);
;             PG8_WAIT_V(6); PG8_BAR; if constexpr (!Epi::NARROW) PG8_MMA(1, 1, At, B1); PG8_BAR;
;             PG8_LDB(B0, 1, 0); PG8_SCHED; PG8_LDA(At, 1, 0); PG8_STAGE(PG8_SA(0, 1), a2 + hstepA, voffA);
;             PG8_WAIT_L(8); PG8_BAR; PG8_WAIT_L(0); PG8_MMA(0, 0, At, B0); PG8_BAR; PG8_SCHED;
;             if constexpr (!Epi::NARROW) PG8_LDB(B1, 1, 1); PG8_STAGE(PG8_SB(1, 0), b3, voffB);
;             PG8_BAR; PG8_WAIT_L(0); if constexpr (!Epi::NARROW) PG8_MMA(0, 1, At, B1); PG8_BAR;
;             PG8_LDA(At, 1, 1); PG8_STAGE(PG8_SA(1, 0), a3, voffA);
;             PG8_BAR; PG8_WAIT_L(0); PG8_MMA(1, 0, At, B0); PG8_BAR; PG8_SCHED;
;             PG8_STAGE(PG8_SB(1, 1), b3 + hstepB, voffB);
	s_add_u32 s76, s42, 0x90000
	s_addc_u32 s77, s43, 0
	s_add_i32 s75, s64, s47
	v_lshl_add_u64 v[130:131], s[76:77], 0, v[194:195]
	s_mov_b32 m0, s75
	s_nop 0
	global_load_lds_dwordx4 v[130:131], off
	v_lshl_add_u64 v[130:131], s[76:77], 0, v[198:199]
	s_add_i32 m0, s75, 0x2000
	s_nop 0
	global_load_lds_dwordx4 v[130:131], off
	s_waitcnt vmcnt(6)
	s_barrier
	s_setprio 1
	v_mfma_f32_16x16x32_bf16 v[52:55], v[184:187], v[152:155], v[52:55]
	v_mfma_f32_16x16x32_bf16 v[48:51], v[216:219], v[152:155], v[48:51]
	v_mfma_f32_16x16x32_bf16 v[36:39], v[184:187], v[160:163], v[36:39]
	v_mfma_f32_16x16x32_bf16 v[32:35], v[216:219], v[160:163], v[32:35]
	v_mfma_f32_16x16x32_bf16 v[20:23], v[184:187], v[168:171], v[20:23]
	v_mfma_f32_16x16x32_bf16 v[16:19], v[216:219], v[168:171], v[16:19]
	v_mfma_f32_16x16x32_bf16 v[4:7], v[184:187], v[176:179], v[4:7]
	v_mfma_f32_16x16x32_bf16 v[0:3], v[216:219], v[176:179], v[0:3]
	v_mfma_f32_16x16x32_bf16 v[52:55], v[188:191], v[156:159], v[52:55]
	v_mfma_f32_16x16x32_bf16 v[48:51], v[220:223], v[156:159], v[48:51]
	v_mfma_f32_16x16x32_bf16 v[36:39], v[188:191], v[164:167], v[36:39]
	v_mfma_f32_16x16x32_bf16 v[32:35], v[220:223], v[164:167], v[32:35]
	v_mfma_f32_16x16x32_bf16 v[20:23], v[188:191], v[172:175], v[20:23]
	v_mfma_f32_16x16x32_bf16 v[16:19], v[220:223], v[172:175], v[16:19]
	v_mfma_f32_16x16x32_bf16 v[4:7], v[188:191], v[180:183], v[4:7]
	v_mfma_f32_16x16x32_bf16 v[0:3], v[220:223], v[180:183], v[0:3]
	s_setprio 0
	s_add_i32 s75, 0, 0x18000
	v_add_u32_e32 v130, s75, v238
	s_barrier
	ds_read_b128 v[132:135], v130
	ds_read_b128 v[136:139], v130 offset:1024
	ds_read_b128 v[140:143], v130 offset:2048
	ds_read_b128 v[144:147], v130 offset:3072
	s_add_u32 s44, s44, 0x94000
	s_addc_u32 s45, s45, 0
	s_mov_b32 m0, s50
	v_lshl_add_u64 v[130:131], s[44:45], 0, v[192:193]
	ds_read_b128 v[152:155], v240 offset:32768
	ds_read_b128 v[156:159], v240 offset:33792
	ds_read_b128 v[160:163], v240 offset:34816
	ds_read_b128 v[164:167], v240 offset:35840
	ds_read_b128 v[168:171], v240 offset:36864
	ds_read_b128 v[172:175], v240 offset:37888
	ds_read_b128 v[176:179], v240 offset:38912
	ds_read_b128 v[180:183], v240 offset:39936
	global_load_lds_dwordx4 v[130:131], off
	v_lshl_add_u64 v[130:131], s[44:45], 0, v[196:197]
	s_mov_b32 m0, s51
	s_nop 0
	global_load_lds_dwordx4 v[130:131], off
	s_waitcnt lgkmcnt(8)
	s_barrier
	s_waitcnt lgkmcnt(0)
	s_setprio 1
	s_waitcnt lgkmcnt(0)
	v_mfma_f32_16x16x32_bf16 v[148:151], v[132:135], v[152:155], v[148:151]
	v_mfma_f32_16x16x32_bf16 v[126:129], v[140:143], v[152:155], v[126:129]
	v_mfma_f32_16x16x32_bf16 v[108:111], v[132:135], v[160:163], v[108:111]
	v_mfma_f32_16x16x32_bf16 v[104:107], v[140:143], v[160:163], v[104:107]
	v_mfma_f32_16x16x32_bf16 v[92:95], v[132:135], v[168:171], v[92:95]
	v_mfma_f32_16x16x32_bf16 v[88:91], v[140:143], v[168:171], v[88:91]
	v_mfma_f32_16x16x32_bf16 v[76:79], v[132:135], v[176:179], v[76:79]
	v_mfma_f32_16x16x32_bf16 v[72:75], v[140:143], v[176:179], v[72:75]
	v_mfma_f32_16x16x32_bf16 v[148:151], v[136:139], v[156:159], v[148:151]
	v_mfma_f32_16x16x32_bf16 v[128:131], v[144:147], v[156:159], v[126:129]
	v_mfma_f32_16x16x32_bf16 v[108:111], v[136:139], v[164:167], v[108:111]
	v_mfma_f32_16x16x32_bf16 v[104:107], v[144:147], v[164:167], v[104:107]
	v_mfma_f32_16x16x32_bf16 v[92:95], v[136:139], v[172:175], v[92:95]
	v_mfma_f32_16x16x32_bf16 v[88:91], v[144:147], v[172:175], v[88:91]
	v_mfma_f32_16x16x32_bf16 v[76:79], v[136:139], v[180:183], v[76:79]
	v_mfma_f32_16x16x32_bf16 v[72:75], v[144:147], v[180:183], v[72:75]
	s_setprio 0
	s_barrier
	s_add_i32 s44, 0, 0x1c000
	v_add_u32_e32 v126, s44, v238
	s_add_i32 s45, s75, s47
	ds_read_b128 v[184:187], v126
	ds_read_b128 v[188:191], v126 offset:1024
	ds_read_b128 v[216:219], v126 offset:2048
	ds_read_b128 v[220:223], v126 offset:3072
	v_lshl_add_u64 v[126:127], v[212:213], 0, s[34:35]
	s_mov_b32 m0, s45
	s_nop 0
	global_load_lds_dwordx4 v[126:127], off
	v_lshl_add_u64 v[126:127], v[224:225], 0, s[34:35]
	s_add_i32 m0, s45, 0x2000
	s_nop 0
	global_load_lds_dwordx4 v[126:127], off
	s_barrier
	s_waitcnt lgkmcnt(0)
	s_setprio 1
	v_mfma_f32_16x16x32_bf16 v[116:119], v[184:187], v[152:155], v[116:119]
	v_mfma_f32_16x16x32_bf16 v[112:115], v[216:219], v[152:155], v[112:115]
	v_mfma_f32_16x16x32_bf16 v[100:103], v[184:187], v[160:163], v[100:103]
	v_mfma_f32_16x16x32_bf16 v[96:99], v[216:219], v[160:163], v[96:99]
	v_mfma_f32_16x16x32_bf16 v[84:87], v[184:187], v[168:171], v[84:87]
	v_mfma_f32_16x16x32_bf16 v[80:83], v[216:219], v[168:171], v[80:83]
	v_mfma_f32_16x16x32_bf16 v[68:71], v[184:187], v[176:179], v[68:71]
	v_mfma_f32_16x16x32_bf16 v[64:67], v[216:219], v[176:179], v[64:67]
	v_mfma_f32_16x16x32_bf16 v[116:119], v[188:191], v[156:159], v[116:119]
	v_mfma_f32_16x16x32_bf16 v[112:115], v[220:223], v[156:159], v[112:115]
	v_mfma_f32_16x16x32_bf16 v[100:103], v[188:191], v[164:167], v[100:103]
	v_mfma_f32_16x16x32_bf16 v[96:99], v[220:223], v[164:167], v[96:99]
	v_mfma_f32_16x16x32_bf16 v[84:87], v[188:191], v[172:175], v[84:87]
	v_mfma_f32_16x16x32_bf16 v[80:83], v[220:223], v[172:175], v[80:83]
	v_mfma_f32_16x16x32_bf16 v[68:71], v[188:191], v[180:183], v[68:71]
	v_mfma_f32_16x16x32_bf16 v[64:67], v[220:223], v[180:183], v[64:67]
	s_setprio 0
	s_mov_b32 m0, s58
	v_lshl_add_u64 v[126:127], v[226:227], 0, s[34:35]
	s_barrier
	ds_read_b128 v[152:155], v240 offset:49152
	ds_read_b128 v[156:159], v240 offset:50176
	ds_read_b128 v[160:163], v240 offset:51200
	ds_read_b128 v[164:167], v240 offset:52224
	ds_read_b128 v[168:171], v240 offset:53248
	ds_read_b128 v[172:175], v240 offset:54272
	ds_read_b128 v[176:179], v240 offset:55296
	ds_read_b128 v[180:183], v240 offset:56320
	global_load_lds_dwordx4 v[126:127], off
	v_lshl_add_u64 v[126:127], v[228:229], 0, s[34:35]
	s_mov_b32 m0, s59
	s_nop 0
	global_load_lds_dwordx4 v[126:127], off
	s_barrier
; #define PG8_STAGE(bufoff, gbase, voff) do { _Pragma("unroll") for (int _i = 0; _i < 2; ++_i) \
;         __builtin_amdgcn_global_load_lds((const unsigned*)((const char*)(gbase) + (voff)[_i]), (LAS unsigned*)(lds + (bufoff) + ldsw + _i * 8192), 16, 0, 0); } while (0)
; #define PG8_MMA(ai, bj, At, Bt) do { __builtin_amdgcn_s_setprio(1); _Pragma("unroll") for (int m = 0; m < 4; ++m) _Pragma("unroll") for (int n = 0; n < 2; ++n) _Pragma("unroll") for (int k = 0; k < 2; ++k) \
;         acc[ai][bj][m][n] = __builtin_amdgcn_mfma_f32_16x16x32_bf16(Bt[n][k], At[m][k], acc[ai][bj][m][n], 0, 0, 0); __builtin_amdgcn_s_setprio(0); } while (0)
; #define PG8_WAIT_V(n) asm volatile("s_waitcnt vmcnt(" #n ")" ::: "memory")
; #define PG8_WAIT_L(n) asm volatile("s_waitcnt lgkmcnt(" #n ")" ::: "memory")
; #define PG8_BAR __builtin_amdgcn_s_barrier()
; #define PG8_SCHED __builtin_amdgcn_sched_barrier(0)
; template <class Epi>
; __device__ __forceinline__ void gemm_phase(LAS unsigned char* lds, const GSched& S, const int K, const int lda, const int ldb, const Epi& E) {
;     ...
;             PG8_BAR; PG8_WAIT_L(0); PG8_MMA(1, 0, At, B0); PG8_BAR; PG8_SCHED;
;             PG8_STAGE(PG8_SB(1, 1), b3 + hstepB, voffB);
;             PG8_WAIT_V(6); PG8_BAR; if constexpr (!Epi::NARROW) PG8_MMA(1, 1, At, B1); PG8_BAR;
;             if constexpr (Epi::HAS_MID) { if (t + 2 == E.mid_t) { PG8_SCHED; E.mid(acc, cur, wr, wc, fr, fq); PG8_SCHED; } }
	s_waitcnt lgkmcnt(0)
	s_setprio 1
	v_mfma_f32_16x16x32_bf16 v[60:63], v[132:135], v[152:155], v[60:63]
	v_mfma_f32_16x16x32_bf16 v[56:59], v[140:143], v[152:155], v[56:59]
	v_mfma_f32_16x16x32_bf16 v[44:47], v[132:135], v[160:163], v[44:47]
	v_mfma_f32_16x16x32_bf16 v[40:43], v[140:143], v[160:163], v[40:43]
	v_mfma_f32_16x16x32_bf16 v[28:31], v[132:135], v[168:171], v[28:31]
	v_mfma_f32_16x16x32_bf16 v[24:27], v[140:143], v[168:171], v[24:27]
	v_mfma_f32_16x16x32_bf16 v[12:15], v[132:135], v[176:179], v[12:15]
	v_mfma_f32_16x16x32_bf16 v[8:11], v[140:143], v[176:179], v[8:11]
	v_mfma_f32_16x16x32_bf16 v[60:63], v[136:139], v[156:159], v[60:63]
	v_mfma_f32_16x16x32_bf16 v[56:59], v[144:147], v[156:159], v[56:59]
	v_mfma_f32_16x16x32_bf16 v[44:47], v[136:139], v[164:167], v[44:47]
	v_mfma_f32_16x16x32_bf16 v[40:43], v[144:147], v[164:167], v[40:43]
	v_mfma_f32_16x16x32_bf16 v[28:31], v[136:139], v[172:175], v[28:31]
	v_mfma_f32_16x16x32_bf16 v[24:27], v[144:147], v[172:175], v[24:27]
	v_mfma_f32_16x16x32_bf16 v[12:15], v[136:139], v[180:183], v[12:15]
	v_mfma_f32_16x16x32_bf16 v[8:11], v[144:147], v[180:183], v[8:11]
	s_setprio 0
	s_barrier
	s_add_u32 s42, s42, 0x90080
	s_addc_u32 s43, s43, 0
	s_add_i32 s44, s44, s47
	v_lshl_add_u64 v[126:127], s[42:43], 0, v[194:195]
	s_mov_b32 m0, s44
	s_nop 0
	global_load_lds_dwordx4 v[126:127], off
	v_lshl_add_u64 v[126:127], s[42:43], 0, v[198:199]
	s_add_i32 m0, s44, 0x2000
	s_nop 0
	global_load_lds_dwordx4 v[126:127], off
	s_waitcnt vmcnt(6)
	s_barrier
	s_setprio 1
	v_mfma_f32_16x16x32_bf16 v[52:55], v[184:187], v[152:155], v[52:55]
	v_mfma_f32_16x16x32_bf16 v[48:51], v[216:219], v[152:155], v[48:51]
	v_mfma_f32_16x16x32_bf16 v[36:39], v[184:187], v[160:163], v[36:39]
	v_mfma_f32_16x16x32_bf16 v[32:35], v[216:219], v[160:163], v[32:35]
	v_mfma_f32_16x16x32_bf16 v[20:23], v[184:187], v[168:171], v[20:23]
	v_mfma_f32_16x16x32_bf16 v[16:19], v[216:219], v[168:171], v[16:19]
	v_mfma_f32_16x16x32_bf16 v[4:7], v[184:187], v[176:179], v[4:7]
	v_mfma_f32_16x16x32_bf16 v[0:3], v[216:219], v[176:179], v[0:3]
	v_mfma_f32_16x16x32_bf16 v[52:55], v[188:191], v[156:159], v[52:55]
	v_mfma_f32_16x16x32_bf16 v[48:51], v[220:223], v[156:159], v[48:51]
	v_mfma_f32_16x16x32_bf16 v[36:39], v[188:191], v[164:167], v[36:39]
	v_mfma_f32_16x16x32_bf16 v[32:35], v[220:223], v[164:167], v[32:35]
	v_mfma_f32_16x16x32_bf16 v[20:23], v[188:191], v[172:175], v[20:23]
	v_mfma_f32_16x16x32_bf16 v[16:19], v[220:223], v[172:175], v[16:19]
	v_mfma_f32_16x16x32_bf16 v[4:7], v[188:191], v[180:183], v[4:7]
	v_mfma_f32_16x16x32_bf16 v[0:3], v[220:223], v[180:183], v[0:3]
	s_setprio 0
	s_add_i32 s42, s39, 2
	s_cmp_lg_u32 s42, 4
	s_barrier
	s_cbranch_scc1 .LBB0_1204
; __device__ __forceinline__ u32x4 pack8(const f32x4 a, const f32x4 b) { u32x4 w; w.x = cvt_pk_bf16(a[0], a[1]); w.y = cvt_pk_bf16(a[2], a[3]); w.z = cvt_pk_bf16(b[0], b[1]); w.w = cvt_pk_bf16(b[2], b[3]); return w; }
;     __device__ __forceinline__ void mid(Acc& acc, const Unit& u, int wr, int wc, int fr, int fq) const {
;         int row0 = u.pm * BM + wr * 64 + fr; asm volatile("" : "+v"(row0));
;         bf16_t* eb = etmp + (size_t)row0 * 2048 + u.pn * BM + wc * 32 + 8 * fq;
; #pragma unroll
;         for (int ai = 0; ai < 2; ++ai)
; #pragma unroll
;             for (int m = 0; m < 4; ++m) {
; #pragma unroll
;                 for (int bj = 0; bj < 2; ++bj) { *(u32x4*)(eb + (size_t)(ai * HALF + m * 16) * 2048 + bj * HALF) = pack8(acc[ai][bj][m][0], acc[ai][bj][m][1]);
;                     acc[ai][bj][m][0] = (f32x4){0.f, 0.f, 0.f, 0.f}; acc[ai][bj][m][1] = (f32x4){0.f, 0.f, 0.f, 0.f}; } }
;     }
	v_mov_b32_e32 v126, v214
	v_cvt_pk_bf16_f32 v108, v108, v109
	v_ashrrev_i32_e32 v127, 31, v126
	v_lshlrev_b64 v[126:127], 12, v[126:127]
	v_lshl_add_u64 v[132:133], v[120:121], 0, v[126:127]
	v_cvt_pk_bf16_f32 v109, v110, v111
	v_cvt_pk_bf16_f32 v110, v104, v105
	v_add_co_u32_e32 v104, vcc, s52, v132
	v_cvt_pk_bf16_f32 v92, v92, v93
	s_nop 0
	v_addc_co_u32_e32 v105, vcc, 0, v133, vcc
	v_cvt_pk_bf16_f32 v93, v94, v95
	v_cvt_pk_bf16_f32 v94, v88, v89
	v_add_co_u32_e32 v88, vcc, s65, v132
	v_cvt_pk_bf16_f32 v76, v76, v77
	s_nop 0
	v_addc_co_u32_e32 v89, vcc, 0, v133, vcc
	v_cvt_pk_bf16_f32 v77, v78, v79
	v_cvt_pk_bf16_f32 v78, v72, v73
	v_add_co_u32_e32 v72, vcc, s66, v132
	v_cvt_pk_bf16_f32 v60, v60, v61
	s_nop 0
	v_addc_co_u32_e32 v73, vcc, 0, v133, vcc
	v_cvt_pk_bf16_f32 v61, v62, v63
	v_cvt_pk_bf16_f32 v62, v56, v57
	v_add_co_u32_e32 v56, vcc, s67, v132
	v_cvt_pk_bf16_f32 v44, v44, v45
	s_nop 0
	v_addc_co_u32_e32 v57, vcc, 0, v133, vcc
	v_cvt_pk_bf16_f32 v45, v46, v47
	v_cvt_pk_bf16_f32 v46, v40, v41
	v_add_co_u32_e32 v40, vcc, s68, v132
	v_cvt_pk_bf16_f32 v28, v28, v29
	s_nop 0
	v_addc_co_u32_e32 v41, vcc, 0, v133, vcc
	v_cvt_pk_bf16_f32 v29, v30, v31
	v_cvt_pk_bf16_f32 v30, v24, v25
	v_add_co_u32_e32 v24, vcc, s69, v132
	v_cvt_pk_bf16_f32 v12, v12, v13
	s_nop 0
	v_addc_co_u32_e32 v25, vcc, 0, v133, vcc
	v_cvt_pk_bf16_f32 v13, v14, v15
	v_cvt_pk_bf16_f32 v14, v8, v9
	v_add_co_u32_e32 v8, vcc, s70, v132
	v_cvt_pk_bf16_f32 v126, v148, v149
	v_cvt_pk_bf16_f32 v127, v150, v151
	v_cvt_pk_bf16_f32 v128, v128, v129
	v_cvt_pk_bf16_f32 v129, v130, v131
	v_cvt_pk_bf16_f32 v116, v116, v117
	v_cvt_pk_bf16_f32 v117, v118, v119
	v_cvt_pk_bf16_f32 v118, v112, v113
	v_cvt_pk_bf16_f32 v119, v114, v115
	v_cvt_pk_bf16_f32 v111, v106, v107
	v_cvt_pk_bf16_f32 v100, v100, v101
	v_cvt_pk_bf16_f32 v101, v102, v103
	v_cvt_pk_bf16_f32 v102, v96, v97
	v_cvt_pk_bf16_f32 v103, v98, v99
	v_cvt_pk_bf16_f32 v95, v90, v91
	v_cvt_pk_bf16_f32 v84, v84, v85
	v_cvt_pk_bf16_f32 v85, v86, v87
	v_cvt_pk_bf16_f32 v86, v80, v81
	v_cvt_pk_bf16_f32 v87, v82, v83
	v_cvt_pk_bf16_f32 v79, v74, v75
	v_cvt_pk_bf16_f32 v68, v68, v69
	v_cvt_pk_bf16_f32 v69, v70, v71
	v_cvt_pk_bf16_f32 v70, v64, v65
	v_cvt_pk_bf16_f32 v71, v66, v67
	v_cvt_pk_bf16_f32 v63, v58, v59
	v_cvt_pk_bf16_f32 v52, v52, v53
	v_cvt_pk_bf16_f32 v53, v54, v55
	v_cvt_pk_bf16_f32 v54, v48, v49
	v_cvt_pk_bf16_f32 v55, v50, v51
	v_cvt_pk_bf16_f32 v47, v42, v43
	v_cvt_pk_bf16_f32 v36, v36, v37
	v_cvt_pk_bf16_f32 v37, v38, v39
	v_cvt_pk_bf16_f32 v38, v32, v33
	v_cvt_pk_bf16_f32 v39, v34, v35
	v_cvt_pk_bf16_f32 v31, v26, v27
	v_cvt_pk_bf16_f32 v20, v20, v21
	v_cvt_pk_bf16_f32 v21, v22, v23
	v_cvt_pk_bf16_f32 v22, v16, v17
	v_cvt_pk_bf16_f32 v23, v18, v19
	v_cvt_pk_bf16_f32 v15, v10, v11
	v_addc_co_u32_e32 v9, vcc, 0, v133, vcc
	v_cvt_pk_bf16_f32 v4, v4, v5
	v_cvt_pk_bf16_f32 v5, v6, v7
	v_cvt_pk_bf16_f32 v6, v0, v1
	v_cvt_pk_bf16_f32 v7, v2, v3
	global_store_dwordx4 v[132:133], v[126:129], off
	global_store_dwordx4 v[132:133], v[116:119], off offset:256
	global_store_dwordx4 v[104:105], v[108:111], off
	global_store_dwordx4 v[104:105], v[100:103], off offset:256
	global_store_dwordx4 v[88:89], v[92:95], off
	global_store_dwordx4 v[88:89], v[84:87], off offset:256
	global_store_dwordx4 v[72:73], v[76:79], off
	global_store_dwordx4 v[72:73], v[68:71], off offset:256
	global_store_dwordx4 v[56:57], v[60:63], off
	global_store_dwordx4 v[56:57], v[52:55], off offset:256
	global_store_dwordx4 v[40:41], v[44:47], off
	global_store_dwordx4 v[40:41], v[36:39], off offset:256
	global_store_dwordx4 v[24:25], v[28:31], off
	global_store_dwordx4 v[24:25], v[20:23], off offset:256
	global_store_dwordx4 v[8:9], v[12:15], off
	global_store_dwordx4 v[8:9], v[4:7], off offset:256
	v_mov_b32_e32 v0, 0
	v_mov_b32_e32 v1, v0
	v_mov_b32_e32 v2, v0
	v_mov_b32_e32 v3, v0
	v_mov_b32_e32 v4, v0
	v_mov_b32_e32 v5, v0
	v_mov_b32_e32 v6, v0
	v_mov_b32_e32 v7, v0
	v_mov_b32_e32 v16, v0
	v_mov_b32_e32 v17, v0
	v_mov_b32_e32 v18, v0
	v_mov_b32_e32 v19, v0
	v_mov_b32_e32 v20, v0
	v_mov_b32_e32 v21, v0
	v_mov_b32_e32 v22, v0
	v_mov_b32_e32 v23, v0
	v_mov_b32_e32 v32, v0
	v_mov_b32_e32 v33, v0
	v_mov_b32_e32 v34, v0
	v_mov_b32_e32 v35, v0
	v_mov_b32_e32 v36, v0
	v_mov_b32_e32 v37, v0
	v_mov_b32_e32 v38, v0
	v_mov_b32_e32 v39, v0
	v_mov_b32_e32 v48, v0
	v_mov_b32_e32 v49, v0
	v_mov_b32_e32 v50, v0
	v_mov_b32_e32 v51, v0
	v_mov_b32_e32 v52, v0
	v_mov_b32_e32 v53, v0
	v_mov_b32_e32 v54, v0
	v_mov_b32_e32 v55, v0
	v_mov_b32_e32 v8, v0
	v_mov_b32_e32 v9, v0
	v_mov_b32_e32 v10, v0
	v_mov_b32_e32 v11, v0
	v_mov_b32_e32 v12, v0
	v_mov_b32_e32 v13, v0
	v_mov_b32_e32 v14, v0
	v_mov_b32_e32 v15, v0
	v_mov_b32_e32 v24, v0
	v_mov_b32_e32 v25, v0
	v_mov_b32_e32 v26, v0
	v_mov_b32_e32 v27, v0
	v_mov_b32_e32 v28, v0
	v_mov_b32_e32 v29, v0
	v_mov_b32_e32 v30, v0
	v_mov_b32_e32 v31, v0
	v_mov_b32_e32 v40, v0
	v_mov_b32_e32 v41, v0
	v_mov_b32_e32 v42, v0
	v_mov_b32_e32 v43, v0
	v_mov_b32_e32 v44, v0
	v_mov_b32_e32 v45, v0
	v_mov_b32_e32 v46, v0
	v_mov_b32_e32 v47, v0
	v_mov_b32_e32 v56, v0
	v_mov_b32_e32 v57, v0
	v_mov_b32_e32 v58, v0
	v_mov_b32_e32 v59, v0
	v_mov_b32_e32 v60, v0
	v_mov_b32_e32 v61, v0
	v_mov_b32_e32 v62, v0
	v_mov_b32_e32 v63, v0
	v_mov_b32_e32 v64, v0
	v_mov_b32_e32 v65, v0
	v_mov_b32_e32 v66, v0
	v_mov_b32_e32 v67, v0
	v_mov_b32_e32 v68, v0
	v_mov_b32_e32 v69, v0
	v_mov_b32_e32 v70, v0
	v_mov_b32_e32 v71, v0
	v_mov_b32_e32 v80, v0
	v_mov_b32_e32 v81, v0
	v_mov_b32_e32 v82, v0
	v_mov_b32_e32 v83, v0
	v_mov_b32_e32 v84, v0
	v_mov_b32_e32 v85, v0
	v_mov_b32_e32 v86, v0
	v_mov_b32_e32 v87, v0
	v_mov_b32_e32 v96, v0
	v_mov_b32_e32 v97, v0
	v_mov_b32_e32 v98, v0
	v_mov_b32_e32 v99, v0
	v_mov_b32_e32 v100, v0
	v_mov_b32_e32 v101, v0
	v_mov_b32_e32 v102, v0
	v_mov_b32_e32 v103, v0
	v_mov_b32_e32 v112, v0
	v_mov_b32_e32 v113, v0
	v_mov_b32_e32 v114, v0
	v_mov_b32_e32 v115, v0
	v_mov_b32_e32 v116, v0
	v_mov_b32_e32 v117, v0
	v_mov_b32_e32 v118, v0
	v_mov_b32_e32 v119, v0
	v_mov_b32_e32 v72, v0
	v_mov_b32_e32 v73, v0
	v_mov_b32_e32 v74, v0
	v_mov_b32_e32 v75, v0
	v_mov_b32_e32 v76, v0
	v_mov_b32_e32 v77, v0
	v_mov_b32_e32 v78, v0
	v_mov_b32_e32 v79, v0
	v_mov_b32_e32 v88, v0
	v_mov_b32_e32 v89, v0
	v_mov_b32_e32 v90, v0
	v_mov_b32_e32 v91, v0
	v_mov_b32_e32 v92, v0
	v_mov_b32_e32 v93, v0
	v_mov_b32_e32 v94, v0
	v_mov_b32_e32 v95, v0
	v_mov_b32_e32 v104, v0
	v_mov_b32_e32 v105, v0
	v_mov_b32_e32 v106, v0
	v_mov_b32_e32 v107, v0
	v_mov_b32_e32 v108, v0
	v_mov_b32_e32 v109, v0
	v_mov_b32_e32 v110, v0
	v_mov_b32_e32 v111, v0
	v_mov_b32_e32 v128, v0
	v_mov_b32_e32 v129, v0
	v_mov_b32_e32 v130, v0
	v_mov_b32_e32 v131, v0
	v_mov_b32_e32 v148, v0
	v_mov_b32_e32 v149, v0
	v_mov_b32_e32 v150, v0
	v_mov_b32_e32 v151, v0
